# P2 signal-job tail: 8 gate loads software-pipelined (6 in flight up front, counted waits) instead of 4 serialized pairs
# baseline (speedup 1.0000x reference)
; __device__ __forceinline__ f2 cmulw(f2 a, float wr, float wi) { const f2 s = __builtin_shufflevector(a, a, 1, 0); return s * (f2){-wi, wi} + a * (f2){wr, wr}; }
; __device__ __forceinline__ void fft32(f2 (&x)[32]) {
;     ...
;     for (int h = 16; h >= 1; h >>= 1) {
; #pragma unroll
;         for (int i0 = 0; i0 < 32; i0 += 2 * h) {
; #pragma unroll
;             for (int j = 0; j < h; ++j) {
;                 const int i = i0 + j, k = i + h, m = j * (32 / h);
;                 const f2 a = x[i], b = x[k], d = a - b;
;                 x[i] = a + b;
;                 if (m == 0) x[k] = d;
;                 else if (m == 16) x[k] = (f2){d.y, -d.x};
;                 else x[k] = cmulw(d, TWR[m], TWI[m]);
;             }
.LBB0_339:
	v_pk_add_f32 v[72:73], v[68:69], v[38:39] neg_lo:[0,1] neg_hi:[0,1]
	v_pk_add_f32 v[38:39], v[38:39], v[68:69]
	v_pk_add_f32 v[68:69], v[40:41], v[0:1]
	v_pk_add_f32 v[0:1], v[0:1], v[40:41] neg_lo:[0,1] neg_hi:[0,1]
	s_mov_b32 s94, s63
	v_pk_mul_f32 v[40:41], v[0:1], s[46:47]
	s_mov_b32 s65, s60
	v_pk_fma_f32 v[0:1], v[0:1], s[52:53], v[40:41] op_sel:[0,0,1] op_sel_hi:[1,0,0]
	v_pk_add_f32 v[40:41], v[42:43], v[2:3]
	v_pk_add_f32 v[2:3], v[2:3], v[42:43] neg_lo:[0,1] neg_hi:[0,1]
	s_mov_b32 s20, s59
	v_pk_mul_f32 v[42:43], v[2:3], s[54:55]
	s_mov_b32 s67, s56
	v_pk_fma_f32 v[2:3], v[2:3], s[56:57], v[42:43] op_sel:[0,0,1] op_sel_hi:[1,0,0]
	v_pk_add_f32 v[42:43], v[44:45], v[4:5]
	v_pk_add_f32 v[4:5], v[4:5], v[44:45] neg_lo:[0,1] neg_hi:[0,1]
	s_mov_b32 s6, s55
	v_pk_mul_f32 v[44:45], v[4:5], s[58:59]
	s_mov_b32 s79, s52
	v_pk_fma_f32 v[4:5], v[4:5], s[60:61], v[44:45] op_sel:[0,0,1] op_sel_hi:[1,0,0]
	v_pk_add_f32 v[44:45], v[46:47], v[6:7]
	v_pk_add_f32 v[6:7], v[6:7], v[46:47] neg_lo:[0,1] neg_hi:[0,1]
	s_mov_b32 s76, s47
	v_pk_mul_f32 v[46:47], v[6:7], s[62:63]
	v_lshrrev_b32_e32 v16, 4, v12
	v_pk_fma_f32 v[6:7], v[6:7], s[94:95], v[46:47] op_sel:[0,0,1] op_sel_hi:[1,0,0]
	v_pk_add_f32 v[46:47], v[48:49], v[8:9]
	v_pk_add_f32 v[8:9], v[8:9], v[48:49] neg_lo:[0,1] neg_hi:[0,1]
	v_lshl_add_u32 v213, v12, 3, 0
	v_pk_mul_f32 v[48:49], v[8:9], s[64:65]
	v_add_u32_e32 v212, 0x10800, v213
	v_pk_fma_f32 v[8:9], v[8:9], s[20:21], v[48:49] op_sel:[0,0,1] op_sel_hi:[1,0,0]
	v_pk_add_f32 v[48:49], v[50:51], v[10:11]
	v_pk_add_f32 v[10:11], v[10:11], v[50:51] neg_lo:[0,1] neg_hi:[0,1]
	s_cmp_lt_u32 s10, 2
	v_pk_mul_f32 v[50:51], v[10:11], s[66:67]
	s_nop 0
	v_pk_fma_f32 v[10:11], v[10:11], s[6:7], v[50:51] op_sel:[0,0,1] op_sel_hi:[1,0,0]
	v_pk_add_f32 v[50:51], v[52:53], v[14:15]
	v_pk_add_f32 v[14:15], v[14:15], v[52:53] neg_lo:[0,1] neg_hi:[0,1]
	s_nop 0
	v_pk_mul_f32 v[52:53], v[14:15], s[78:79]
	s_nop 0
	v_pk_fma_f32 v[14:15], v[14:15], s[76:77], v[52:53] op_sel:[0,0,1] op_sel_hi:[1,0,0]
	v_pk_add_f32 v[52:53], v[54:55], v[22:23]
	v_pk_add_f32 v[22:23], v[22:23], v[54:55] neg_lo:[0,1] neg_hi:[0,1]
	s_nop 0
	v_xor_b32_e32 v55, 0x80000000, v22
	v_mov_b32_e32 v54, v23
	v_pk_add_f32 v[22:23], v[56:57], v[24:25]
	v_pk_add_f32 v[24:25], v[24:25], v[56:57] neg_lo:[0,1] neg_hi:[0,1]
	s_nop 0
	v_pk_mul_f32 v[56:57], v[24:25], s[78:79]
	s_nop 0
	v_pk_fma_f32 v[24:25], v[24:25], s[76:77], v[56:57] op_sel:[0,0,1] op_sel_hi:[1,0,0] neg_lo:[1,0,0] neg_hi:[1,0,0]
	v_pk_add_f32 v[56:57], v[58:59], v[26:27]
	v_pk_add_f32 v[26:27], v[26:27], v[58:59] neg_lo:[0,1] neg_hi:[0,1]
	s_nop 0
	v_pk_mul_f32 v[58:59], v[26:27], s[66:67]
	s_nop 0
	v_pk_fma_f32 v[26:27], v[26:27], s[6:7], v[58:59] op_sel:[0,0,1] op_sel_hi:[1,0,0] neg_lo:[1,0,0] neg_hi:[1,0,0]
	v_pk_add_f32 v[58:59], v[60:61], v[28:29]
	v_pk_add_f32 v[28:29], v[28:29], v[60:61] neg_lo:[0,1] neg_hi:[0,1]
	s_nop 0
	v_pk_mul_f32 v[60:61], v[28:29], s[64:65]
	s_nop 0
	v_pk_fma_f32 v[28:29], v[28:29], s[20:21], v[60:61] op_sel:[0,0,1] op_sel_hi:[1,0,0] neg_lo:[1,0,0] neg_hi:[1,0,0]
	v_pk_add_f32 v[60:61], v[62:63], v[30:31]
	v_pk_add_f32 v[30:31], v[30:31], v[62:63] neg_lo:[0,1] neg_hi:[0,1]
	s_nop 0
	v_pk_mul_f32 v[62:63], v[30:31], s[62:63]
	s_nop 0
	v_pk_fma_f32 v[30:31], v[30:31], s[94:95], v[62:63] op_sel:[0,0,1] op_sel_hi:[1,0,0] neg_lo:[1,0,0] neg_hi:[1,0,0]
	v_pk_add_f32 v[62:63], v[64:65], v[32:33]
	v_pk_add_f32 v[32:33], v[32:33], v[64:65] neg_lo:[0,1] neg_hi:[0,1]
	s_nop 0
	v_pk_mul_f32 v[64:65], v[32:33], s[58:59]
	s_nop 0
	v_pk_fma_f32 v[32:33], v[32:33], s[60:61], v[64:65] op_sel:[0,0,1] op_sel_hi:[1,0,0] neg_lo:[1,0,0] neg_hi:[1,0,0]
	v_pk_add_f32 v[64:65], v[66:67], v[34:35]
	v_pk_add_f32 v[34:35], v[34:35], v[66:67] neg_lo:[0,1] neg_hi:[0,1]
	s_nop 0
	v_pk_mul_f32 v[66:67], v[34:35], s[54:55]
	s_nop 0
	v_pk_fma_f32 v[34:35], v[34:35], s[56:57], v[66:67] op_sel:[0,0,1] op_sel_hi:[1,0,0] neg_lo:[1,0,0] neg_hi:[1,0,0]
	v_pk_add_f32 v[66:67], v[70:71], v[36:37]
	v_pk_add_f32 v[36:37], v[36:37], v[70:71] neg_lo:[0,1] neg_hi:[0,1]
	s_nop 0
	v_pk_mul_f32 v[70:71], v[36:37], s[46:47]
	s_nop 0
	v_pk_fma_f32 v[36:37], v[36:37], s[52:53], v[70:71] op_sel:[0,0,1] op_sel_hi:[1,0,0] neg_lo:[1,0,0] neg_hi:[1,0,0]
	v_pk_add_f32 v[70:71], v[38:39], v[52:53] neg_lo:[0,1] neg_hi:[0,1]
	v_pk_add_f32 v[38:39], v[52:53], v[38:39]
	v_pk_add_f32 v[52:53], v[22:23], v[68:69]
	v_pk_add_f32 v[22:23], v[68:69], v[22:23] neg_lo:[0,1] neg_hi:[0,1]
	s_nop 0
	v_pk_mul_f32 v[68:69], v[22:23], s[54:55]
	s_nop 0
	v_pk_fma_f32 v[22:23], v[22:23], s[56:57], v[68:69] op_sel:[0,0,1] op_sel_hi:[1,0,0]
	v_pk_add_f32 v[68:69], v[56:57], v[40:41]
	v_pk_add_f32 v[40:41], v[40:41], v[56:57] neg_lo:[0,1] neg_hi:[0,1]
	s_nop 0
	v_pk_mul_f32 v[56:57], v[40:41], s[62:63]
	s_nop 0
	v_pk_fma_f32 v[40:41], v[40:41], s[94:95], v[56:57] op_sel:[0,0,1] op_sel_hi:[1,0,0]
	v_pk_add_f32 v[56:57], v[58:59], v[42:43]
	v_pk_add_f32 v[42:43], v[42:43], v[58:59] neg_lo:[0,1] neg_hi:[0,1]
	s_nop 0
	v_pk_mul_f32 v[58:59], v[42:43], s[66:67]
	s_nop 0
	v_pk_fma_f32 v[42:43], v[42:43], s[6:7], v[58:59] op_sel:[0,0,1] op_sel_hi:[1,0,0]
	v_pk_add_f32 v[58:59], v[60:61], v[44:45]
	v_pk_add_f32 v[44:45], v[44:45], v[60:61] neg_lo:[0,1] neg_hi:[0,1]
	s_nop 0
	v_xor_b32_e32 v61, 0x80000000, v44
	v_mov_b32_e32 v60, v45
	v_pk_add_f32 v[44:45], v[62:63], v[46:47]
	v_pk_add_f32 v[46:47], v[46:47], v[62:63] neg_lo:[0,1] neg_hi:[0,1]
	s_nop 0
	v_pk_mul_f32 v[62:63], v[46:47], s[66:67]
	s_nop 0
	v_pk_fma_f32 v[46:47], v[46:47], s[6:7], v[62:63] op_sel:[0,0,1] op_sel_hi:[1,0,0] neg_lo:[1,0,0] neg_hi:[1,0,0]
	v_pk_add_f32 v[62:63], v[64:65], v[48:49]
; __device__ __forceinline__ f2 cmulw(f2 a, float wr, float wi) { const f2 s = __builtin_shufflevector(a, a, 1, 0); return s * (f2){-wi, wi} + a * (f2){wr, wr}; }
; __device__ __forceinline__ void fft32(f2 (&x)[32]) {
;     ...
;     for (int h = 16; h >= 1; h >>= 1) {
; #pragma unroll
;         for (int i0 = 0; i0 < 32; i0 += 2 * h) {
; #pragma unroll
;             for (int j = 0; j < h; ++j) {
;                 const int i = i0 + j, k = i + h, m = j * (32 / h);
;                 const f2 a = x[i], b = x[k], d = a - b;
;                 x[i] = a + b;
;                 if (m == 0) x[k] = d;
;                 else if (m == 16) x[k] = (f2){d.y, -d.x};
;                 else x[k] = cmulw(d, TWR[m], TWI[m]);
;             }
	v_pk_add_f32 v[48:49], v[48:49], v[64:65] neg_lo:[0,1] neg_hi:[0,1]
	s_nop 0
	v_pk_mul_f32 v[64:65], v[48:49], s[62:63]
	s_nop 0
	v_pk_fma_f32 v[48:49], v[48:49], s[94:95], v[64:65] op_sel:[0,0,1] op_sel_hi:[1,0,0] neg_lo:[1,0,0] neg_hi:[1,0,0]
	v_pk_add_f32 v[64:65], v[66:67], v[50:51]
	v_pk_add_f32 v[50:51], v[50:51], v[66:67] neg_lo:[0,1] neg_hi:[0,1]
	s_nop 0
	v_pk_mul_f32 v[66:67], v[50:51], s[54:55]
	s_nop 0
	v_pk_fma_f32 v[50:51], v[50:51], s[56:57], v[66:67] op_sel:[0,0,1] op_sel_hi:[1,0,0] neg_lo:[1,0,0] neg_hi:[1,0,0]
	v_pk_add_f32 v[66:67], v[72:73], v[54:55] neg_lo:[0,1] neg_hi:[0,1]
	v_pk_add_f32 v[54:55], v[54:55], v[72:73]
	v_pk_add_f32 v[72:73], v[24:25], v[0:1]
	v_pk_add_f32 v[0:1], v[0:1], v[24:25] neg_lo:[0,1] neg_hi:[0,1]
	s_nop 0
	v_pk_mul_f32 v[24:25], v[0:1], s[54:55]
	s_nop 0
	v_pk_fma_f32 v[0:1], v[0:1], s[56:57], v[24:25] op_sel:[0,0,1] op_sel_hi:[1,0,0]
	v_pk_add_f32 v[24:25], v[26:27], v[2:3]
	v_pk_add_f32 v[2:3], v[2:3], v[26:27] neg_lo:[0,1] neg_hi:[0,1]
	s_nop 0
	v_pk_mul_f32 v[26:27], v[2:3], s[62:63]
	s_nop 0
	v_pk_fma_f32 v[2:3], v[2:3], s[94:95], v[26:27] op_sel:[0,0,1] op_sel_hi:[1,0,0]
	v_pk_add_f32 v[26:27], v[28:29], v[4:5]
	v_pk_add_f32 v[4:5], v[4:5], v[28:29] neg_lo:[0,1] neg_hi:[0,1]
	s_nop 0
	v_pk_mul_f32 v[28:29], v[4:5], s[66:67]
	s_nop 0
	v_pk_fma_f32 v[4:5], v[4:5], s[6:7], v[28:29] op_sel:[0,0,1] op_sel_hi:[1,0,0]
	v_pk_add_f32 v[28:29], v[30:31], v[6:7]
	v_pk_add_f32 v[6:7], v[6:7], v[30:31] neg_lo:[0,1] neg_hi:[0,1]
	s_nop 0
	v_xor_b32_e32 v31, 0x80000000, v6
	v_mov_b32_e32 v30, v7
	v_pk_add_f32 v[6:7], v[32:33], v[8:9]
	v_pk_add_f32 v[8:9], v[8:9], v[32:33] neg_lo:[0,1] neg_hi:[0,1]
	s_nop 0
	v_pk_mul_f32 v[32:33], v[8:9], s[66:67]
	s_nop 0
	v_pk_fma_f32 v[8:9], v[8:9], s[6:7], v[32:33] op_sel:[0,0,1] op_sel_hi:[1,0,0] neg_lo:[1,0,0] neg_hi:[1,0,0]
	v_pk_add_f32 v[32:33], v[34:35], v[10:11]
	v_pk_add_f32 v[10:11], v[10:11], v[34:35] neg_lo:[0,1] neg_hi:[0,1]
	s_movk_i32 s7, 0x1080
	v_pk_mul_f32 v[34:35], v[10:11], s[62:63]
	v_mul_lo_u32 v16, v16, s7
	v_pk_fma_f32 v[10:11], v[10:11], s[94:95], v[34:35] op_sel:[0,0,1] op_sel_hi:[1,0,0] neg_lo:[1,0,0] neg_hi:[1,0,0]
	v_pk_add_f32 v[34:35], v[36:37], v[14:15]
	v_pk_add_f32 v[14:15], v[14:15], v[36:37] neg_lo:[0,1] neg_hi:[0,1]
	s_nop 0
	v_pk_mul_f32 v[36:37], v[14:15], s[54:55]
	s_nop 0
	v_pk_fma_f32 v[14:15], v[14:15], s[56:57], v[36:37] op_sel:[0,0,1] op_sel_hi:[1,0,0] neg_lo:[1,0,0] neg_hi:[1,0,0]
	v_pk_add_f32 v[36:37], v[38:39], v[58:59] neg_lo:[0,1] neg_hi:[0,1]
	v_pk_add_f32 v[38:39], v[58:59], v[38:39]
	v_pk_add_f32 v[58:59], v[44:45], v[52:53]
	v_pk_add_f32 v[44:45], v[52:53], v[44:45] neg_lo:[0,1] neg_hi:[0,1]
	s_nop 0
	v_pk_mul_f32 v[52:53], v[44:45], s[62:63]
	s_nop 0
	v_pk_fma_f32 v[44:45], v[44:45], s[94:95], v[52:53] op_sel:[0,0,1] op_sel_hi:[1,0,0]
	v_pk_add_f32 v[52:53], v[62:63], v[68:69]
	v_pk_add_f32 v[62:63], v[68:69], v[62:63] neg_lo:[0,1] neg_hi:[0,1]
	s_nop 0
	v_xor_b32_e32 v69, 0x80000000, v62
	v_mov_b32_e32 v68, v63
	v_pk_add_f32 v[62:63], v[64:65], v[56:57]
	v_pk_add_f32 v[56:57], v[56:57], v[64:65] neg_lo:[0,1] neg_hi:[0,1]
	s_nop 0
	v_pk_mul_f32 v[64:65], v[56:57], s[62:63]
	s_nop 0
	v_pk_fma_f32 v[56:57], v[56:57], s[94:95], v[64:65] op_sel:[0,0,1] op_sel_hi:[1,0,0] neg_lo:[1,0,0] neg_hi:[1,0,0]
	v_pk_add_f32 v[64:65], v[70:71], v[60:61] neg_lo:[0,1] neg_hi:[0,1]
	v_pk_add_f32 v[60:61], v[60:61], v[70:71]
	v_pk_add_f32 v[70:71], v[46:47], v[22:23]
	v_pk_add_f32 v[22:23], v[22:23], v[46:47] neg_lo:[0,1] neg_hi:[0,1]
	s_nop 0
	v_pk_mul_f32 v[46:47], v[22:23], s[62:63]
	s_nop 0
	v_pk_fma_f32 v[22:23], v[22:23], s[94:95], v[46:47] op_sel:[0,0,1] op_sel_hi:[1,0,0]
	v_pk_add_f32 v[46:47], v[48:49], v[40:41]
	v_pk_add_f32 v[40:41], v[40:41], v[48:49] neg_lo:[0,1] neg_hi:[0,1]
	s_nop 0
	v_xor_b32_e32 v49, 0x80000000, v40
	v_mov_b32_e32 v48, v41
	v_pk_add_f32 v[40:41], v[50:51], v[42:43]
	v_pk_add_f32 v[42:43], v[42:43], v[50:51] neg_lo:[0,1] neg_hi:[0,1]
	s_nop 0
	v_pk_mul_f32 v[50:51], v[42:43], s[62:63]
	s_nop 0
	v_pk_fma_f32 v[42:43], v[42:43], s[94:95], v[50:51] op_sel:[0,0,1] op_sel_hi:[1,0,0] neg_lo:[1,0,0] neg_hi:[1,0,0]
	v_pk_add_f32 v[50:51], v[54:55], v[28:29] neg_lo:[0,1] neg_hi:[0,1]
	v_pk_add_f32 v[28:29], v[28:29], v[54:55]
	v_pk_add_f32 v[54:55], v[6:7], v[72:73]
	v_pk_add_f32 v[6:7], v[72:73], v[6:7] neg_lo:[0,1] neg_hi:[0,1]
	s_nop 0
	v_pk_mul_f32 v[72:73], v[6:7], s[62:63]
	s_nop 0
	v_pk_fma_f32 v[6:7], v[6:7], s[94:95], v[72:73] op_sel:[0,0,1] op_sel_hi:[1,0,0]
	v_pk_add_f32 v[72:73], v[32:33], v[24:25]
	v_pk_add_f32 v[24:25], v[24:25], v[32:33] neg_lo:[0,1] neg_hi:[0,1]
	s_nop 0
	v_xor_b32_e32 v33, 0x80000000, v24
	v_mov_b32_e32 v32, v25
	v_pk_add_f32 v[24:25], v[34:35], v[26:27]
	v_pk_add_f32 v[26:27], v[26:27], v[34:35] neg_lo:[0,1] neg_hi:[0,1]
	s_nop 0
	v_pk_mul_f32 v[34:35], v[26:27], s[62:63]
	s_nop 0
	v_pk_fma_f32 v[26:27], v[26:27], s[94:95], v[34:35] op_sel:[0,0,1] op_sel_hi:[1,0,0] neg_lo:[1,0,0] neg_hi:[1,0,0]
	v_pk_add_f32 v[34:35], v[66:67], v[30:31] neg_lo:[0,1] neg_hi:[0,1]
	v_pk_add_f32 v[30:31], v[66:67], v[30:31]
	v_pk_add_f32 v[66:67], v[8:9], v[0:1]
	v_pk_add_f32 v[0:1], v[0:1], v[8:9] neg_lo:[0,1] neg_hi:[0,1]
	s_nop 0
	v_pk_mul_f32 v[8:9], v[0:1], s[62:63]
	s_nop 0
	v_pk_fma_f32 v[0:1], v[0:1], s[94:95], v[8:9] op_sel:[0,0,1] op_sel_hi:[1,0,0]
	v_pk_add_f32 v[8:9], v[10:11], v[2:3]
	v_pk_add_f32 v[2:3], v[2:3], v[10:11] neg_lo:[0,1] neg_hi:[0,1]
	s_nop 0
	v_xor_b32_e32 v11, 0x80000000, v2
	v_mov_b32_e32 v10, v3
	v_pk_add_f32 v[2:3], v[14:15], v[4:5]
	v_pk_add_f32 v[4:5], v[4:5], v[14:15] neg_lo:[0,1] neg_hi:[0,1]
	s_nop 0
	v_pk_mul_f32 v[14:15], v[4:5], s[62:63]
	s_nop 0
; __device__ __forceinline__ f2 cmulw(f2 a, float wr, float wi) { const f2 s = __builtin_shufflevector(a, a, 1, 0); return s * (f2){-wi, wi} + a * (f2){wr, wr}; }
; __device__ __forceinline__ void fft32(f2 (&x)[32]) {
;     ...
;     for (int h = 16; h >= 1; h >>= 1) {
; #pragma unroll
;         for (int i0 = 0; i0 < 32; i0 += 2 * h) {
; #pragma unroll
;             for (int j = 0; j < h; ++j) {
;                 const int i = i0 + j, k = i + h, m = j * (32 / h);
;                 const f2 a = x[i], b = x[k], d = a - b;
;                 x[i] = a + b;
;                 if (m == 0) x[k] = d;
;                 else if (m == 16) x[k] = (f2){d.y, -d.x};
;                 else x[k] = cmulw(d, TWR[m], TWI[m]);
;             }
; __device__ __forceinline__ void fft_forward(f2 (&x)[32], LAS f2* X, int t, LAS const float* W1, LAS const M2C* MC) {
;     ...
;     { const float wr = W1[0], wi = W1[1]; twiddle32<false>(x, wr * wr - wi * wi, 2.f * wr * wi); }
	v_pk_fma_f32 v[4:5], v[4:5], s[94:95], v[14:15] op_sel:[0,0,1] op_sel_hi:[1,0,0] neg_lo:[1,0,0] neg_hi:[1,0,0]
	v_pk_add_f32 v[14:15], v[38:39], v[52:53] neg_lo:[0,1] neg_hi:[0,1]
	v_pk_add_f32 v[38:39], v[52:53], v[38:39]
	v_pk_add_f32 v[52:53], v[62:63], v[58:59]
	v_pk_add_f32 v[58:59], v[58:59], v[62:63] neg_lo:[0,1] neg_hi:[0,1]
	s_nop 0
	v_xor_b32_e32 v63, 0x80000000, v58
	v_mov_b32_e32 v62, v59
	v_pk_add_f32 v[58:59], v[36:37], v[68:69] neg_lo:[0,1] neg_hi:[0,1]
	v_pk_add_f32 v[36:37], v[36:37], v[68:69]
	v_pk_add_f32 v[68:69], v[56:57], v[44:45]
	v_pk_add_f32 v[44:45], v[44:45], v[56:57] neg_lo:[0,1] neg_hi:[0,1]
	s_nop 0
	v_xor_b32_e32 v57, 0x80000000, v44
	v_mov_b32_e32 v56, v45
	v_pk_add_f32 v[44:45], v[60:61], v[46:47] neg_lo:[0,1] neg_hi:[0,1]
	v_pk_add_f32 v[46:47], v[60:61], v[46:47]
	v_pk_add_f32 v[60:61], v[40:41], v[70:71]
	v_pk_add_f32 v[40:41], v[70:71], v[40:41] neg_lo:[0,1] neg_hi:[0,1]
	s_nop 0
	v_xor_b32_e32 v71, 0x80000000, v40
	v_mov_b32_e32 v70, v41
	v_pk_add_f32 v[40:41], v[64:65], v[48:49] neg_lo:[0,1] neg_hi:[0,1]
	v_pk_add_f32 v[48:49], v[64:65], v[48:49]
	v_pk_add_f32 v[64:65], v[42:43], v[22:23]
	v_pk_add_f32 v[22:23], v[22:23], v[42:43] neg_lo:[0,1] neg_hi:[0,1]
	s_nop 0
	v_xor_b32_e32 v43, 0x80000000, v22
	v_mov_b32_e32 v42, v23
	v_pk_add_f32 v[22:23], v[28:29], v[72:73] neg_lo:[0,1] neg_hi:[0,1]
	v_pk_add_f32 v[28:29], v[28:29], v[72:73]
	v_pk_add_f32 v[72:73], v[24:25], v[54:55]
	v_pk_add_f32 v[24:25], v[54:55], v[24:25] neg_lo:[0,1] neg_hi:[0,1]
	s_nop 0
	v_xor_b32_e32 v55, 0x80000000, v24
	v_mov_b32_e32 v54, v25
	v_pk_add_f32 v[24:25], v[50:51], v[32:33] neg_lo:[0,1] neg_hi:[0,1]
	v_pk_add_f32 v[32:33], v[50:51], v[32:33]
	v_pk_add_f32 v[50:51], v[26:27], v[6:7]
	v_pk_add_f32 v[6:7], v[6:7], v[26:27] neg_lo:[0,1] neg_hi:[0,1]
	s_nop 0
	v_xor_b32_e32 v27, 0x80000000, v6
	v_mov_b32_e32 v26, v7
	v_pk_add_f32 v[6:7], v[30:31], v[8:9] neg_lo:[0,1] neg_hi:[0,1]
	v_pk_add_f32 v[8:9], v[30:31], v[8:9]
	v_pk_add_f32 v[30:31], v[2:3], v[66:67]
	v_pk_add_f32 v[2:3], v[66:67], v[2:3] neg_lo:[0,1] neg_hi:[0,1]
	s_nop 0
	v_xor_b32_e32 v67, 0x80000000, v2
	v_mov_b32_e32 v66, v3
	v_pk_add_f32 v[2:3], v[34:35], v[10:11] neg_lo:[0,1] neg_hi:[0,1]
	v_pk_add_f32 v[10:11], v[34:35], v[10:11]
	v_pk_add_f32 v[34:35], v[4:5], v[0:1]
	v_pk_add_f32 v[0:1], v[0:1], v[4:5] neg_lo:[0,1] neg_hi:[0,1]
	s_nop 0
	v_xor_b32_e32 v5, 0x80000000, v0
	v_mov_b32_e32 v4, v1
	v_pk_add_f32 v[0:1], v[52:53], v[38:39]
	v_pk_add_f32 v[38:39], v[38:39], v[52:53] neg_lo:[0,1] neg_hi:[0,1]
	v_pk_add_f32 v[52:53], v[14:15], v[62:63]
	v_pk_add_f32 v[14:15], v[14:15], v[62:63] neg_lo:[0,1] neg_hi:[0,1]
	v_pk_add_f32 v[62:63], v[36:37], v[68:69]
	v_pk_add_f32 v[36:37], v[36:37], v[68:69] neg_lo:[0,1] neg_hi:[0,1]
	v_pk_add_f32 v[68:69], v[58:59], v[56:57]
	v_pk_add_f32 v[56:57], v[58:59], v[56:57] neg_lo:[0,1] neg_hi:[0,1]
	v_pk_add_f32 v[58:59], v[46:47], v[60:61]
	v_pk_add_f32 v[46:47], v[46:47], v[60:61] neg_lo:[0,1] neg_hi:[0,1]
	v_pk_add_f32 v[60:61], v[44:45], v[70:71]
	v_pk_add_f32 v[44:45], v[44:45], v[70:71] neg_lo:[0,1] neg_hi:[0,1]
	v_pk_add_f32 v[70:71], v[48:49], v[64:65]
	v_pk_add_f32 v[48:49], v[48:49], v[64:65] neg_lo:[0,1] neg_hi:[0,1]
	v_pk_add_f32 v[64:65], v[40:41], v[42:43]
	v_pk_add_f32 v[40:41], v[40:41], v[42:43] neg_lo:[0,1] neg_hi:[0,1]
	v_pk_add_f32 v[42:43], v[28:29], v[72:73]
	v_pk_add_f32 v[28:29], v[28:29], v[72:73] neg_lo:[0,1] neg_hi:[0,1]
	v_pk_add_f32 v[72:73], v[22:23], v[54:55]
	v_pk_add_f32 v[22:23], v[22:23], v[54:55] neg_lo:[0,1] neg_hi:[0,1]
	v_pk_add_f32 v[54:55], v[32:33], v[50:51]
	v_pk_add_f32 v[32:33], v[32:33], v[50:51] neg_lo:[0,1] neg_hi:[0,1]
	v_pk_add_f32 v[50:51], v[24:25], v[26:27]
	v_pk_add_f32 v[24:25], v[24:25], v[26:27] neg_lo:[0,1] neg_hi:[0,1]
	v_pk_add_f32 v[26:27], v[8:9], v[30:31]
	v_pk_add_f32 v[8:9], v[8:9], v[30:31] neg_lo:[0,1] neg_hi:[0,1]
	v_pk_add_f32 v[30:31], v[6:7], v[66:67]
	v_pk_add_f32 v[6:7], v[6:7], v[66:67] neg_lo:[0,1] neg_hi:[0,1]
	v_pk_add_f32 v[66:67], v[10:11], v[34:35]
	v_pk_add_f32 v[10:11], v[10:11], v[34:35] neg_lo:[0,1] neg_hi:[0,1]
	v_pk_add_f32 v[34:35], v[2:3], v[4:5]
	v_pk_add_f32 v[2:3], v[2:3], v[4:5] neg_lo:[0,1] neg_hi:[0,1]
	ds_read_b64 v[4:5], v211
	s_waitcnt lgkmcnt(0)
; #define LAS __attribute__((address_space(3)))
; template <bool CONJ> __device__ __forceinline__ void twiddle32(f2 (&x)[32], float wr, float wi) {
;     asm volatile("" : "+v"(wr), "+v"(wi));
;     f2 c = (f2){wr, CONJ ? -wi : wi}; const f2 w = c;
; #pragma unroll
;     for (int k = 1; k < 32; ++k) { const int p = brev5(k); x[p] = cmulr(x[p], c); if (k < 31) c = cmulr(c, w); }
; }
; __device__ __forceinline__ void fft_forward(f2 (&x)[32], LAS f2* X, int t, LAS const float* W1, LAS const M2C* MC) {
;     ...
;     { const float wr = W1[0], wi = W1[1]; twiddle32<false>(x, wr * wr - wi * wi, 2.f * wr * wi); }
;     LAS f2* wp = X + t; LAS const f2* rp = X + (t >> 4) * XP + (t & 15); LAS f2* wp1 = wp + 16 * XP; LAS const f2* rp1 = rp + 256;
;     asm volatile("" : "+v"(wp), "+v"(rp), "+v"(wp1), "+v"(rp1));
; #pragma unroll
;     for (int k = 0; k < 16; ++k) { wp[k * XP] = x[brev5(k)]; wp1[k * XP] = x[brev5(k + 16)]; }
	v_pk_mul_f32 v[74:75], v[4:5], v[4:5]
	v_add_f32_e32 v4, v4, v4
	v_sub_f32_e32 v74, v74, v75
	v_mul_f32_e32 v75, v4, v5
	s_nop 0
	v_pk_mul_f32 v[4:5], v[42:43], v[74:75] op_sel_hi:[1,0]
	s_nop 0
	v_pk_fma_f32 v[4:5], v[42:43], v[74:75], v[4:5] op_sel:[1,1,0] op_sel_hi:[0,1,1] neg_lo:[0,1,0]
	ds_write_b64 v213, v[4:5] offset:4224
	v_pk_mul_f32 v[42:43], v[74:75], v[74:75] op_sel_hi:[1,0]
	s_nop 0
	v_pk_fma_f32 v[42:43], v[74:75], v[74:75], v[42:43] op_sel:[1,1,0] op_sel_hi:[0,1,1] neg_lo:[0,1,0]
	s_nop 0
	v_pk_mul_f32 v[76:77], v[58:59], v[42:43] op_sel_hi:[1,0]
	s_nop 0
	v_pk_fma_f32 v[58:59], v[58:59], v[42:43], v[76:77] op_sel:[1,1,0] op_sel_hi:[0,1,1] neg_lo:[0,1,0]
	ds_write_b64 v213, v[58:59] offset:8448
	v_pk_mul_f32 v[76:77], v[42:43], v[74:75] op_sel_hi:[1,0]
	s_nop 0
	v_pk_fma_f32 v[42:43], v[42:43], v[74:75], v[76:77] op_sel:[1,1,0] op_sel_hi:[0,1,1] neg_lo:[0,1,0]
	s_nop 0
	v_pk_mul_f32 v[76:77], v[26:27], v[42:43] op_sel_hi:[1,0]
	s_nop 0
	v_pk_fma_f32 v[26:27], v[26:27], v[42:43], v[76:77] op_sel:[1,1,0] op_sel_hi:[0,1,1] neg_lo:[0,1,0]
	ds_write_b64 v213, v[26:27] offset:12672
	v_pk_mul_f32 v[76:77], v[42:43], v[74:75] op_sel_hi:[1,0]
	s_nop 0
	v_pk_fma_f32 v[42:43], v[42:43], v[74:75], v[76:77] op_sel:[1,1,0] op_sel_hi:[0,1,1] neg_lo:[0,1,0]
	s_nop 0
	v_pk_mul_f32 v[76:77], v[62:63], v[42:43] op_sel_hi:[1,0]
	s_nop 0
	v_pk_fma_f32 v[62:63], v[62:63], v[42:43], v[76:77] op_sel:[1,1,0] op_sel_hi:[0,1,1] neg_lo:[0,1,0]
	ds_write_b64 v213, v[62:63] offset:16896
	v_pk_mul_f32 v[76:77], v[42:43], v[74:75] op_sel_hi:[1,0]
	s_nop 0
	v_pk_fma_f32 v[42:43], v[42:43], v[74:75], v[76:77] op_sel:[1,1,0] op_sel_hi:[0,1,1] neg_lo:[0,1,0]
	s_nop 0
	v_pk_mul_f32 v[76:77], v[54:55], v[42:43] op_sel_hi:[1,0]
	s_nop 0
	v_pk_fma_f32 v[54:55], v[54:55], v[42:43], v[76:77] op_sel:[1,1,0] op_sel_hi:[0,1,1] neg_lo:[0,1,0]
	ds_write_b64 v213, v[54:55] offset:21120
	v_pk_mul_f32 v[76:77], v[42:43], v[74:75] op_sel_hi:[1,0]
	s_nop 0
	v_pk_fma_f32 v[42:43], v[42:43], v[74:75], v[76:77] op_sel:[1,1,0] op_sel_hi:[0,1,1] neg_lo:[0,1,0]
	s_nop 0
	v_pk_mul_f32 v[76:77], v[70:71], v[42:43] op_sel_hi:[1,0]
	s_nop 0
	v_pk_fma_f32 v[70:71], v[70:71], v[42:43], v[76:77] op_sel:[1,1,0] op_sel_hi:[0,1,1] neg_lo:[0,1,0]
	ds_write_b64 v213, v[70:71] offset:25344
	v_pk_mul_f32 v[76:77], v[42:43], v[74:75] op_sel_hi:[1,0]
	s_nop 0
	v_pk_fma_f32 v[42:43], v[42:43], v[74:75], v[76:77] op_sel:[1,1,0] op_sel_hi:[0,1,1] neg_lo:[0,1,0]
	s_nop 0
	v_pk_mul_f32 v[76:77], v[66:67], v[42:43] op_sel_hi:[1,0]
	s_nop 0
	v_pk_fma_f32 v[66:67], v[66:67], v[42:43], v[76:77] op_sel:[1,1,0] op_sel_hi:[0,1,1] neg_lo:[0,1,0]
	ds_write_b64 v213, v[66:67] offset:29568
	v_pk_mul_f32 v[76:77], v[42:43], v[74:75] op_sel_hi:[1,0]
	s_nop 0
	v_pk_fma_f32 v[42:43], v[42:43], v[74:75], v[76:77] op_sel:[1,1,0] op_sel_hi:[0,1,1] neg_lo:[0,1,0]
	s_nop 0
	v_pk_mul_f32 v[76:77], v[52:53], v[42:43] op_sel_hi:[1,0]
	s_nop 0
	v_pk_fma_f32 v[52:53], v[52:53], v[42:43], v[76:77] op_sel:[1,1,0] op_sel_hi:[0,1,1] neg_lo:[0,1,0]
	ds_write_b64 v213, v[52:53] offset:33792
	v_pk_mul_f32 v[76:77], v[42:43], v[74:75] op_sel_hi:[1,0]
	s_nop 0
	v_pk_fma_f32 v[42:43], v[42:43], v[74:75], v[76:77] op_sel:[1,1,0] op_sel_hi:[0,1,1] neg_lo:[0,1,0]
	s_nop 0
	v_pk_mul_f32 v[76:77], v[72:73], v[42:43] op_sel_hi:[1,0]
	s_nop 0
	v_pk_fma_f32 v[72:73], v[72:73], v[42:43], v[76:77] op_sel:[1,1,0] op_sel_hi:[0,1,1] neg_lo:[0,1,0]
	ds_write_b64 v213, v[72:73] offset:38016
	v_pk_mul_f32 v[76:77], v[42:43], v[74:75] op_sel_hi:[1,0]
	s_nop 0
	v_pk_fma_f32 v[42:43], v[42:43], v[74:75], v[76:77] op_sel:[1,1,0] op_sel_hi:[0,1,1] neg_lo:[0,1,0]
	s_nop 0
	v_pk_mul_f32 v[76:77], v[60:61], v[42:43] op_sel_hi:[1,0]
	s_nop 0
	v_pk_fma_f32 v[60:61], v[60:61], v[42:43], v[76:77] op_sel:[1,1,0] op_sel_hi:[0,1,1] neg_lo:[0,1,0]
	ds_write_b64 v213, v[60:61] offset:42240
	v_pk_mul_f32 v[76:77], v[42:43], v[74:75] op_sel_hi:[1,0]
	s_nop 0
	v_pk_fma_f32 v[42:43], v[42:43], v[74:75], v[76:77] op_sel:[1,1,0] op_sel_hi:[0,1,1] neg_lo:[0,1,0]
	s_nop 0
	v_pk_mul_f32 v[76:77], v[30:31], v[42:43] op_sel_hi:[1,0]
	s_nop 0
	v_pk_fma_f32 v[30:31], v[30:31], v[42:43], v[76:77] op_sel:[1,1,0] op_sel_hi:[0,1,1] neg_lo:[0,1,0]
	ds_write_b64 v213, v[30:31] offset:46464
	v_pk_mul_f32 v[76:77], v[42:43], v[74:75] op_sel_hi:[1,0]
	s_nop 0
	v_pk_fma_f32 v[42:43], v[42:43], v[74:75], v[76:77] op_sel:[1,1,0] op_sel_hi:[0,1,1] neg_lo:[0,1,0]
	s_nop 0
	v_pk_mul_f32 v[76:77], v[68:69], v[42:43] op_sel_hi:[1,0]
	s_nop 0
	v_pk_fma_f32 v[68:69], v[68:69], v[42:43], v[76:77] op_sel:[1,1,0] op_sel_hi:[0,1,1] neg_lo:[0,1,0]
	ds_write_b64 v213, v[68:69] offset:50688
	v_pk_mul_f32 v[76:77], v[42:43], v[74:75] op_sel_hi:[1,0]
	s_nop 0
	v_pk_fma_f32 v[42:43], v[42:43], v[74:75], v[76:77] op_sel:[1,1,0] op_sel_hi:[0,1,1] neg_lo:[0,1,0]
	s_nop 0
	v_pk_mul_f32 v[76:77], v[50:51], v[42:43] op_sel_hi:[1,0]
	s_nop 0
	v_pk_fma_f32 v[50:51], v[50:51], v[42:43], v[76:77] op_sel:[1,1,0] op_sel_hi:[0,1,1] neg_lo:[0,1,0]
	ds_write_b64 v213, v[50:51] offset:54912
	v_pk_mul_f32 v[76:77], v[42:43], v[74:75] op_sel_hi:[1,0]
	s_nop 0
	v_pk_fma_f32 v[42:43], v[42:43], v[74:75], v[76:77] op_sel:[1,1,0] op_sel_hi:[0,1,1] neg_lo:[0,1,0]
	s_nop 0
	v_pk_mul_f32 v[76:77], v[64:65], v[42:43] op_sel_hi:[1,0]
	s_nop 0
	v_pk_fma_f32 v[64:65], v[64:65], v[42:43], v[76:77] op_sel:[1,1,0] op_sel_hi:[0,1,1] neg_lo:[0,1,0]
	ds_write_b64 v213, v[64:65] offset:59136
	v_pk_mul_f32 v[76:77], v[42:43], v[74:75] op_sel_hi:[1,0]
	s_nop 0
	v_pk_fma_f32 v[42:43], v[42:43], v[74:75], v[76:77] op_sel:[1,1,0] op_sel_hi:[0,1,1] neg_lo:[0,1,0]
	s_nop 0
	v_pk_mul_f32 v[76:77], v[34:35], v[42:43] op_sel_hi:[1,0]
	s_nop 0
; #define LAS __attribute__((address_space(3)))
; #define LBAR() do { asm volatile("s_waitcnt lgkmcnt(0)" ::: "memory"); __builtin_amdgcn_s_barrier(); asm volatile("" ::: "memory"); } while (0)
; template <bool CONJ> __device__ __forceinline__ void twiddle32(f2 (&x)[32], float wr, float wi) {
;     asm volatile("" : "+v"(wr), "+v"(wi));
;     f2 c = (f2){wr, CONJ ? -wi : wi}; const f2 w = c;
; #pragma unroll
;     for (int k = 1; k < 32; ++k) { const int p = brev5(k); x[p] = cmulr(x[p], c); if (k < 31) c = cmulr(c, w); }
; }
; __device__ __forceinline__ void fft_forward(f2 (&x)[32], LAS f2* X, int t, LAS const float* W1, LAS const M2C* MC) {
;     ...
;     { const float wr = W1[0], wi = W1[1]; twiddle32<false>(x, wr * wr - wi * wi, 2.f * wr * wi); }
;     LAS f2* wp = X + t; LAS const f2* rp = X + (t >> 4) * XP + (t & 15); LAS f2* wp1 = wp + 16 * XP; LAS const f2* rp1 = rp + 256;
;     asm volatile("" : "+v"(wp), "+v"(rp), "+v"(wp1), "+v"(rp1));
; #pragma unroll
;     for (int k = 0; k < 16; ++k) { wp[k * XP] = x[brev5(k)]; wp1[k * XP] = x[brev5(k + 16)]; }
;     LBAR();
	v_pk_fma_f32 v[34:35], v[34:35], v[42:43], v[76:77] op_sel:[1,1,0] op_sel_hi:[0,1,1] neg_lo:[0,1,0]
	ds_write_b64 v213, v[34:35] offset:63360
	v_pk_mul_f32 v[76:77], v[42:43], v[74:75] op_sel_hi:[1,0]
	s_nop 0
	v_pk_fma_f32 v[42:43], v[42:43], v[74:75], v[76:77] op_sel:[1,1,0] op_sel_hi:[0,1,1] neg_lo:[0,1,0]
	s_nop 0
	v_pk_mul_f32 v[76:77], v[38:39], v[42:43] op_sel_hi:[1,0]
	s_nop 0
	v_pk_fma_f32 v[38:39], v[38:39], v[42:43], v[76:77] op_sel:[1,1,0] op_sel_hi:[0,1,1] neg_lo:[0,1,0]
	ds_write_b64 v212, v[38:39]
	v_pk_mul_f32 v[76:77], v[42:43], v[74:75] op_sel_hi:[1,0]
	s_nop 0
	v_pk_fma_f32 v[42:43], v[42:43], v[74:75], v[76:77] op_sel:[1,1,0] op_sel_hi:[0,1,1] neg_lo:[0,1,0]
	s_nop 0
	v_pk_mul_f32 v[76:77], v[28:29], v[42:43] op_sel_hi:[1,0]
	s_nop 0
	v_pk_fma_f32 v[28:29], v[28:29], v[42:43], v[76:77] op_sel:[1,1,0] op_sel_hi:[0,1,1] neg_lo:[0,1,0]
	ds_write_b64 v212, v[28:29] offset:4224
	v_pk_mul_f32 v[76:77], v[42:43], v[74:75] op_sel_hi:[1,0]
	s_nop 0
	v_pk_fma_f32 v[42:43], v[42:43], v[74:75], v[76:77] op_sel:[1,1,0] op_sel_hi:[0,1,1] neg_lo:[0,1,0]
	s_nop 0
	v_pk_mul_f32 v[76:77], v[46:47], v[42:43] op_sel_hi:[1,0]
	s_nop 0
	v_pk_fma_f32 v[46:47], v[46:47], v[42:43], v[76:77] op_sel:[1,1,0] op_sel_hi:[0,1,1] neg_lo:[0,1,0]
	ds_write_b64 v212, v[46:47] offset:8448
	v_pk_mul_f32 v[76:77], v[42:43], v[74:75] op_sel_hi:[1,0]
	s_nop 0
	v_pk_fma_f32 v[42:43], v[42:43], v[74:75], v[76:77] op_sel:[1,1,0] op_sel_hi:[0,1,1] neg_lo:[0,1,0]
	s_nop 0
	v_pk_mul_f32 v[76:77], v[8:9], v[42:43] op_sel_hi:[1,0]
	s_nop 0
	v_pk_fma_f32 v[8:9], v[8:9], v[42:43], v[76:77] op_sel:[1,1,0] op_sel_hi:[0,1,1] neg_lo:[0,1,0]
	ds_write_b64 v212, v[8:9] offset:12672
	v_pk_mul_f32 v[76:77], v[42:43], v[74:75] op_sel_hi:[1,0]
	s_nop 0
	v_pk_fma_f32 v[42:43], v[42:43], v[74:75], v[76:77] op_sel:[1,1,0] op_sel_hi:[0,1,1] neg_lo:[0,1,0]
	s_nop 0
	v_pk_mul_f32 v[76:77], v[36:37], v[42:43] op_sel_hi:[1,0]
	s_nop 0
	v_pk_fma_f32 v[36:37], v[36:37], v[42:43], v[76:77] op_sel:[1,1,0] op_sel_hi:[0,1,1] neg_lo:[0,1,0]
	ds_write_b64 v212, v[36:37] offset:16896
	v_pk_mul_f32 v[76:77], v[42:43], v[74:75] op_sel_hi:[1,0]
	s_nop 0
	v_pk_fma_f32 v[42:43], v[42:43], v[74:75], v[76:77] op_sel:[1,1,0] op_sel_hi:[0,1,1] neg_lo:[0,1,0]
	s_nop 0
	v_pk_mul_f32 v[76:77], v[32:33], v[42:43] op_sel_hi:[1,0]
	s_nop 0
	v_pk_fma_f32 v[32:33], v[32:33], v[42:43], v[76:77] op_sel:[1,1,0] op_sel_hi:[0,1,1] neg_lo:[0,1,0]
	ds_write_b64 v212, v[32:33] offset:21120
	v_pk_mul_f32 v[76:77], v[42:43], v[74:75] op_sel_hi:[1,0]
	s_nop 0
	v_pk_fma_f32 v[42:43], v[42:43], v[74:75], v[76:77] op_sel:[1,1,0] op_sel_hi:[0,1,1] neg_lo:[0,1,0]
	s_nop 0
	v_pk_mul_f32 v[76:77], v[48:49], v[42:43] op_sel_hi:[1,0]
	s_nop 0
	v_pk_fma_f32 v[48:49], v[48:49], v[42:43], v[76:77] op_sel:[1,1,0] op_sel_hi:[0,1,1] neg_lo:[0,1,0]
	ds_write_b64 v212, v[48:49] offset:25344
	v_pk_mul_f32 v[76:77], v[42:43], v[74:75] op_sel_hi:[1,0]
	s_nop 0
	v_pk_fma_f32 v[42:43], v[42:43], v[74:75], v[76:77] op_sel:[1,1,0] op_sel_hi:[0,1,1] neg_lo:[0,1,0]
	s_nop 0
	v_pk_mul_f32 v[76:77], v[10:11], v[42:43] op_sel_hi:[1,0]
	s_nop 0
	v_pk_fma_f32 v[10:11], v[10:11], v[42:43], v[76:77] op_sel:[1,1,0] op_sel_hi:[0,1,1] neg_lo:[0,1,0]
	ds_write_b64 v212, v[10:11] offset:29568
	v_pk_mul_f32 v[76:77], v[42:43], v[74:75] op_sel_hi:[1,0]
	s_nop 0
	v_pk_fma_f32 v[42:43], v[42:43], v[74:75], v[76:77] op_sel:[1,1,0] op_sel_hi:[0,1,1] neg_lo:[0,1,0]
	s_nop 0
	v_pk_mul_f32 v[76:77], v[14:15], v[42:43] op_sel_hi:[1,0]
	s_nop 0
	v_pk_fma_f32 v[14:15], v[14:15], v[42:43], v[76:77] op_sel:[1,1,0] op_sel_hi:[0,1,1] neg_lo:[0,1,0]
	ds_write_b64 v212, v[14:15] offset:33792
	v_pk_mul_f32 v[76:77], v[42:43], v[74:75] op_sel_hi:[1,0]
	s_nop 0
	v_pk_fma_f32 v[42:43], v[42:43], v[74:75], v[76:77] op_sel:[1,1,0] op_sel_hi:[0,1,1] neg_lo:[0,1,0]
	s_nop 0
	v_pk_mul_f32 v[76:77], v[22:23], v[42:43] op_sel_hi:[1,0]
	s_nop 0
	v_pk_fma_f32 v[22:23], v[22:23], v[42:43], v[76:77] op_sel:[1,1,0] op_sel_hi:[0,1,1] neg_lo:[0,1,0]
	ds_write_b64 v212, v[22:23] offset:38016
	v_pk_mul_f32 v[76:77], v[42:43], v[74:75] op_sel_hi:[1,0]
	s_nop 0
	v_pk_fma_f32 v[42:43], v[42:43], v[74:75], v[76:77] op_sel:[1,1,0] op_sel_hi:[0,1,1] neg_lo:[0,1,0]
	s_nop 0
	v_pk_mul_f32 v[76:77], v[44:45], v[42:43] op_sel_hi:[1,0]
	s_nop 0
	v_pk_fma_f32 v[44:45], v[44:45], v[42:43], v[76:77] op_sel:[1,1,0] op_sel_hi:[0,1,1] neg_lo:[0,1,0]
	ds_write_b64 v212, v[44:45] offset:42240
	v_pk_mul_f32 v[76:77], v[42:43], v[74:75] op_sel_hi:[1,0]
	s_nop 0
	v_pk_fma_f32 v[42:43], v[42:43], v[74:75], v[76:77] op_sel:[1,1,0] op_sel_hi:[0,1,1] neg_lo:[0,1,0]
	s_nop 0
	v_pk_mul_f32 v[76:77], v[6:7], v[42:43] op_sel_hi:[1,0]
	s_nop 0
	v_pk_fma_f32 v[6:7], v[6:7], v[42:43], v[76:77] op_sel:[1,1,0] op_sel_hi:[0,1,1] neg_lo:[0,1,0]
	ds_write_b64 v212, v[6:7] offset:46464
	v_pk_mul_f32 v[76:77], v[42:43], v[74:75] op_sel_hi:[1,0]
	s_nop 0
	v_pk_fma_f32 v[42:43], v[42:43], v[74:75], v[76:77] op_sel:[1,1,0] op_sel_hi:[0,1,1] neg_lo:[0,1,0]
	s_nop 0
	v_pk_mul_f32 v[76:77], v[56:57], v[42:43] op_sel_hi:[1,0]
	s_nop 0
	v_pk_fma_f32 v[56:57], v[56:57], v[42:43], v[76:77] op_sel:[1,1,0] op_sel_hi:[0,1,1] neg_lo:[0,1,0]
	ds_write_b64 v212, v[56:57] offset:50688
	v_pk_mul_f32 v[76:77], v[42:43], v[74:75] op_sel_hi:[1,0]
	s_nop 0
	v_pk_fma_f32 v[42:43], v[42:43], v[74:75], v[76:77] op_sel:[1,1,0] op_sel_hi:[0,1,1] neg_lo:[0,1,0]
	s_nop 0
	v_pk_mul_f32 v[76:77], v[24:25], v[42:43] op_sel_hi:[1,0]
	s_nop 0
	v_pk_fma_f32 v[24:25], v[24:25], v[42:43], v[76:77] op_sel:[1,1,0] op_sel_hi:[0,1,1] neg_lo:[0,1,0]
	ds_write_b64 v212, v[24:25] offset:54912
	v_pk_mul_f32 v[76:77], v[42:43], v[74:75] op_sel_hi:[1,0]
	s_nop 0
	v_pk_fma_f32 v[42:43], v[42:43], v[74:75], v[76:77] op_sel:[1,1,0] op_sel_hi:[0,1,1] neg_lo:[0,1,0]
	s_nop 0
	v_pk_mul_f32 v[76:77], v[40:41], v[42:43] op_sel_hi:[1,0]
	s_nop 0
	v_pk_fma_f32 v[40:41], v[40:41], v[42:43], v[76:77] op_sel:[1,1,0] op_sel_hi:[0,1,1] neg_lo:[0,1,0]
	ds_write_b64 v212, v[40:41] offset:59136
	v_pk_mul_f32 v[76:77], v[42:43], v[74:75] op_sel_hi:[1,0]
	s_nop 0
	v_pk_fma_f32 v[42:43], v[42:43], v[74:75], v[76:77] op_sel:[1,1,0] op_sel_hi:[0,1,1] neg_lo:[0,1,0]
	s_nop 0
	v_pk_mul_f32 v[74:75], v[2:3], v[42:43] op_sel_hi:[1,0]
	s_nop 0
	v_pk_fma_f32 v[2:3], v[2:3], v[42:43], v[74:75] op_sel:[1,1,0] op_sel_hi:[0,1,1] neg_lo:[0,1,0]
	ds_write_b64 v212, v[2:3] offset:63360
	v_and_b32_e32 v42, 15, v12
	v_lshlrev_b32_e32 v42, 3, v42
	v_add3_u32 v214, 0, v16, v42
	v_add_u32_e32 v215, 0x800, v214
	v_mov_b32_e32 v16, v213
	v_mov_b32_e32 v42, v212
	v_mov_b32_e32 v74, v214
	v_mov_b32_e32 v75, v215
	ds_write_b64 v213, v[0:1]
	s_waitcnt lgkmcnt(0)
	s_barrier
; __device__ __forceinline__ f2 cmulw(f2 a, float wr, float wi) { const f2 s = __builtin_shufflevector(a, a, 1, 0); return s * (f2){-wi, wi} + a * (f2){wr, wr}; }
; #define LBAR() do { asm volatile("s_waitcnt lgkmcnt(0)" ::: "memory"); __builtin_amdgcn_s_barrier(); asm volatile("" ::: "memory"); } while (0)
; __device__ __forceinline__ void fft32(f2 (&x)[32]) {
;     ...
;     for (int h = 16; h >= 1; h >>= 1) {
; #pragma unroll
;         for (int i0 = 0; i0 < 32; i0 += 2 * h) {
; #pragma unroll
;             for (int j = 0; j < h; ++j) {
;                 const int i = i0 + j, k = i + h, m = j * (32 / h);
;                 const f2 a = x[i], b = x[k], d = a - b;
;                 x[i] = a + b;
;                 if (m == 0) x[k] = d;
;                 else if (m == 16) x[k] = (f2){d.y, -d.x};
;                 else x[k] = cmulw(d, TWR[m], TWI[m]);
;             }
; __device__ __forceinline__ void fft_forward(f2 (&x)[32], LAS f2* X, int t, LAS const float* W1, LAS const M2C* MC) {
;     ...
; #pragma unroll
;     for (int m = 0; m < 16; ++m) { x[m] = rp[16 * m]; x[m + 16] = rp1[16 * m]; }
;     LBAR();
;     fft32(x);
	ds_read2_b64 v[0:3], v74 offset1:16
	ds_read2_b64 v[4:7], v75 offset1:16
	ds_read2_b64 v[8:11], v74 offset0:32 offset1:48
	ds_read2_b64 v[22:25], v75 offset0:32 offset1:48
	ds_read2_b64 v[26:29], v74 offset0:64 offset1:80
	ds_read2_b64 v[30:33], v75 offset0:64 offset1:80
	ds_read2_b64 v[34:37], v74 offset0:96 offset1:112
	ds_read2_b64 v[38:41], v75 offset0:96 offset1:112
	ds_read2_b64 v[42:45], v74 offset0:128 offset1:144
	ds_read2_b64 v[46:49], v75 offset0:128 offset1:144
	ds_read2_b64 v[50:53], v74 offset0:160 offset1:176
	ds_read2_b64 v[54:57], v75 offset0:160 offset1:176
	ds_read2_b64 v[58:61], v74 offset0:192 offset1:208
	ds_read2_b64 v[62:65], v75 offset0:192 offset1:208
	ds_read2_b64 v[66:69], v74 offset0:224 offset1:240
	ds_read2_b64 v[70:73], v75 offset0:224 offset1:240
	s_waitcnt lgkmcnt(14)
	v_pk_add_f32 v[14:15], v[0:1], v[4:5] neg_lo:[0,1] neg_hi:[0,1]
	v_pk_add_f32 v[0:1], v[0:1], v[4:5]
	v_pk_add_f32 v[4:5], v[2:3], v[6:7]
	v_pk_add_f32 v[2:3], v[2:3], v[6:7] neg_lo:[0,1] neg_hi:[0,1]
	s_waitcnt lgkmcnt(0)
	s_barrier
	v_pk_mul_f32 v[6:7], v[2:3], s[46:47]
	s_nop 0
	v_pk_fma_f32 v[2:3], v[2:3], s[52:53], v[6:7] op_sel:[0,0,1] op_sel_hi:[1,0,0]
	s_waitcnt lgkmcnt(12)
	v_pk_add_f32 v[6:7], v[8:9], v[22:23]
	v_pk_add_f32 v[8:9], v[8:9], v[22:23] neg_lo:[0,1] neg_hi:[0,1]
	s_nop 0
	v_pk_mul_f32 v[22:23], v[8:9], s[54:55]
	s_nop 0
	v_pk_fma_f32 v[8:9], v[8:9], s[56:57], v[22:23] op_sel:[0,0,1] op_sel_hi:[1,0,0]
	v_pk_add_f32 v[22:23], v[10:11], v[24:25]
	v_pk_add_f32 v[10:11], v[10:11], v[24:25] neg_lo:[0,1] neg_hi:[0,1]
	s_nop 0
	v_pk_mul_f32 v[24:25], v[10:11], s[58:59]
	s_nop 0
	v_pk_fma_f32 v[10:11], v[10:11], s[60:61], v[24:25] op_sel:[0,0,1] op_sel_hi:[1,0,0]
	s_waitcnt lgkmcnt(10)
	v_pk_add_f32 v[24:25], v[26:27], v[30:31]
	v_pk_add_f32 v[26:27], v[26:27], v[30:31] neg_lo:[0,1] neg_hi:[0,1]
	s_nop 0
	v_pk_mul_f32 v[30:31], v[26:27], s[62:63]
	s_nop 0
	v_pk_fma_f32 v[26:27], v[26:27], s[94:95], v[30:31] op_sel:[0,0,1] op_sel_hi:[1,0,0]
	v_pk_add_f32 v[30:31], v[28:29], v[32:33]
	v_pk_add_f32 v[28:29], v[28:29], v[32:33] neg_lo:[0,1] neg_hi:[0,1]
	s_nop 0
	v_pk_mul_f32 v[32:33], v[28:29], s[64:65]
	s_nop 0
	v_pk_fma_f32 v[28:29], v[28:29], s[20:21], v[32:33] op_sel:[0,0,1] op_sel_hi:[1,0,0]
	s_waitcnt lgkmcnt(8)
	v_pk_add_f32 v[32:33], v[34:35], v[38:39]
	v_pk_add_f32 v[34:35], v[34:35], v[38:39] neg_lo:[0,1] neg_hi:[0,1]
	s_nop 0
	v_pk_mul_f32 v[38:39], v[34:35], s[66:67]
	s_nop 0
	v_pk_fma_f32 v[34:35], v[34:35], s[6:7], v[38:39] op_sel:[0,0,1] op_sel_hi:[1,0,0]
	v_pk_add_f32 v[38:39], v[36:37], v[40:41]
	v_pk_add_f32 v[36:37], v[36:37], v[40:41] neg_lo:[0,1] neg_hi:[0,1]
	s_nop 0
	v_pk_mul_f32 v[40:41], v[36:37], s[78:79]
	s_nop 0
	v_pk_fma_f32 v[36:37], v[36:37], s[76:77], v[40:41] op_sel:[0,0,1] op_sel_hi:[1,0,0]
	s_waitcnt lgkmcnt(6)
	v_pk_add_f32 v[40:41], v[42:43], v[46:47]
	v_pk_add_f32 v[42:43], v[42:43], v[46:47] neg_lo:[0,1] neg_hi:[0,1]
	s_nop 0
	v_xor_b32_e32 v47, 0x80000000, v42
	v_mov_b32_e32 v46, v43
	v_pk_add_f32 v[42:43], v[44:45], v[48:49]
	v_pk_add_f32 v[44:45], v[44:45], v[48:49] neg_lo:[0,1] neg_hi:[0,1]
	s_nop 0
	v_pk_mul_f32 v[48:49], v[44:45], s[78:79]
	s_nop 0
	v_pk_fma_f32 v[44:45], v[44:45], s[76:77], v[48:49] op_sel:[0,0,1] op_sel_hi:[1,0,0] neg_lo:[1,0,0] neg_hi:[1,0,0]
	s_waitcnt lgkmcnt(4)
	v_pk_add_f32 v[48:49], v[50:51], v[54:55]
	v_pk_add_f32 v[50:51], v[50:51], v[54:55] neg_lo:[0,1] neg_hi:[0,1]
	s_nop 0
	v_pk_mul_f32 v[54:55], v[50:51], s[66:67]
	s_nop 0
	v_pk_fma_f32 v[50:51], v[50:51], s[6:7], v[54:55] op_sel:[0,0,1] op_sel_hi:[1,0,0] neg_lo:[1,0,0] neg_hi:[1,0,0]
	v_pk_add_f32 v[54:55], v[52:53], v[56:57]
	v_pk_add_f32 v[52:53], v[52:53], v[56:57] neg_lo:[0,1] neg_hi:[0,1]
	s_nop 0
	v_pk_mul_f32 v[56:57], v[52:53], s[64:65]
	s_nop 0
	v_pk_fma_f32 v[52:53], v[52:53], s[20:21], v[56:57] op_sel:[0,0,1] op_sel_hi:[1,0,0] neg_lo:[1,0,0] neg_hi:[1,0,0]
	s_waitcnt lgkmcnt(2)
	v_pk_add_f32 v[56:57], v[58:59], v[62:63]
	v_pk_add_f32 v[58:59], v[58:59], v[62:63] neg_lo:[0,1] neg_hi:[0,1]
	s_nop 0
	v_pk_mul_f32 v[62:63], v[58:59], s[62:63]
	s_nop 0
	v_pk_fma_f32 v[58:59], v[58:59], s[94:95], v[62:63] op_sel:[0,0,1] op_sel_hi:[1,0,0] neg_lo:[1,0,0] neg_hi:[1,0,0]
	v_pk_add_f32 v[62:63], v[60:61], v[64:65]
	v_pk_add_f32 v[60:61], v[60:61], v[64:65] neg_lo:[0,1] neg_hi:[0,1]
	s_nop 0
	v_pk_mul_f32 v[64:65], v[60:61], s[58:59]
	s_nop 0
	v_pk_fma_f32 v[60:61], v[60:61], s[60:61], v[64:65] op_sel:[0,0,1] op_sel_hi:[1,0,0] neg_lo:[1,0,0] neg_hi:[1,0,0]
	s_waitcnt lgkmcnt(0)
; __device__ __forceinline__ f2 cmulw(f2 a, float wr, float wi) { const f2 s = __builtin_shufflevector(a, a, 1, 0); return s * (f2){-wi, wi} + a * (f2){wr, wr}; }
; __device__ __forceinline__ void fft32(f2 (&x)[32]) {
;     ...
;     for (int h = 16; h >= 1; h >>= 1) {
; #pragma unroll
;         for (int i0 = 0; i0 < 32; i0 += 2 * h) {
; #pragma unroll
;             for (int j = 0; j < h; ++j) {
;                 const int i = i0 + j, k = i + h, m = j * (32 / h);
;                 const f2 a = x[i], b = x[k], d = a - b;
;                 x[i] = a + b;
;                 if (m == 0) x[k] = d;
;                 else if (m == 16) x[k] = (f2){d.y, -d.x};
;                 else x[k] = cmulw(d, TWR[m], TWI[m]);
;             }
	v_pk_add_f32 v[64:65], v[66:67], v[70:71]
	v_pk_add_f32 v[66:67], v[66:67], v[70:71] neg_lo:[0,1] neg_hi:[0,1]
	s_nop 0
	v_pk_mul_f32 v[70:71], v[66:67], s[54:55]
	s_nop 0
	v_pk_fma_f32 v[66:67], v[66:67], s[56:57], v[70:71] op_sel:[0,0,1] op_sel_hi:[1,0,0] neg_lo:[1,0,0] neg_hi:[1,0,0]
	v_pk_add_f32 v[70:71], v[68:69], v[72:73]
	v_pk_add_f32 v[68:69], v[68:69], v[72:73] neg_lo:[0,1] neg_hi:[0,1]
	s_nop 0
	v_pk_mul_f32 v[72:73], v[68:69], s[46:47]
	s_nop 0
	v_pk_fma_f32 v[68:69], v[68:69], s[52:53], v[72:73] op_sel:[0,0,1] op_sel_hi:[1,0,0] neg_lo:[1,0,0] neg_hi:[1,0,0]
	v_pk_add_f32 v[72:73], v[0:1], v[40:41] neg_lo:[0,1] neg_hi:[0,1]
	v_pk_add_f32 v[0:1], v[0:1], v[40:41]
	v_pk_add_f32 v[40:41], v[4:5], v[42:43]
	v_pk_add_f32 v[4:5], v[4:5], v[42:43] neg_lo:[0,1] neg_hi:[0,1]
	s_nop 0
	v_pk_mul_f32 v[42:43], v[4:5], s[54:55]
	s_nop 0
	v_pk_fma_f32 v[4:5], v[4:5], s[56:57], v[42:43] op_sel:[0,0,1] op_sel_hi:[1,0,0]
	v_pk_add_f32 v[42:43], v[6:7], v[48:49]
	v_pk_add_f32 v[6:7], v[6:7], v[48:49] neg_lo:[0,1] neg_hi:[0,1]
	s_nop 0
	v_pk_mul_f32 v[48:49], v[6:7], s[62:63]
	s_nop 0
	v_pk_fma_f32 v[6:7], v[6:7], s[94:95], v[48:49] op_sel:[0,0,1] op_sel_hi:[1,0,0]
	v_pk_add_f32 v[48:49], v[22:23], v[54:55]
	v_pk_add_f32 v[22:23], v[22:23], v[54:55] neg_lo:[0,1] neg_hi:[0,1]
	s_nop 0
	v_pk_mul_f32 v[54:55], v[22:23], s[66:67]
	s_nop 0
	v_pk_fma_f32 v[22:23], v[22:23], s[6:7], v[54:55] op_sel:[0,0,1] op_sel_hi:[1,0,0]
	v_pk_add_f32 v[54:55], v[24:25], v[56:57]
	v_pk_add_f32 v[24:25], v[24:25], v[56:57] neg_lo:[0,1] neg_hi:[0,1]
	s_nop 0
	v_xor_b32_e32 v57, 0x80000000, v24
	v_mov_b32_e32 v56, v25
	v_pk_add_f32 v[24:25], v[30:31], v[62:63]
	v_pk_add_f32 v[30:31], v[30:31], v[62:63] neg_lo:[0,1] neg_hi:[0,1]
	s_nop 0
	v_pk_mul_f32 v[62:63], v[30:31], s[66:67]
	s_nop 0
	v_pk_fma_f32 v[30:31], v[30:31], s[6:7], v[62:63] op_sel:[0,0,1] op_sel_hi:[1,0,0] neg_lo:[1,0,0] neg_hi:[1,0,0]
	v_pk_add_f32 v[62:63], v[32:33], v[64:65]
	v_pk_add_f32 v[32:33], v[32:33], v[64:65] neg_lo:[0,1] neg_hi:[0,1]
	s_nop 0
	v_pk_mul_f32 v[64:65], v[32:33], s[62:63]
	s_nop 0
	v_pk_fma_f32 v[32:33], v[32:33], s[94:95], v[64:65] op_sel:[0,0,1] op_sel_hi:[1,0,0] neg_lo:[1,0,0] neg_hi:[1,0,0]
	v_pk_add_f32 v[64:65], v[38:39], v[70:71]
	v_pk_add_f32 v[38:39], v[38:39], v[70:71] neg_lo:[0,1] neg_hi:[0,1]
	s_nop 0
	v_pk_mul_f32 v[70:71], v[38:39], s[54:55]
	s_nop 0
	v_pk_fma_f32 v[38:39], v[38:39], s[56:57], v[70:71] op_sel:[0,0,1] op_sel_hi:[1,0,0] neg_lo:[1,0,0] neg_hi:[1,0,0]
	v_pk_add_f32 v[70:71], v[14:15], v[46:47] neg_lo:[0,1] neg_hi:[0,1]
	v_pk_add_f32 v[14:15], v[14:15], v[46:47]
	v_pk_add_f32 v[46:47], v[2:3], v[44:45]
	v_pk_add_f32 v[2:3], v[2:3], v[44:45] neg_lo:[0,1] neg_hi:[0,1]
	s_nop 0
	v_pk_mul_f32 v[44:45], v[2:3], s[54:55]
	s_nop 0
	v_pk_fma_f32 v[2:3], v[2:3], s[56:57], v[44:45] op_sel:[0,0,1] op_sel_hi:[1,0,0]
	v_pk_add_f32 v[44:45], v[8:9], v[50:51]
	v_pk_add_f32 v[8:9], v[8:9], v[50:51] neg_lo:[0,1] neg_hi:[0,1]
	s_nop 0
	v_pk_mul_f32 v[50:51], v[8:9], s[62:63]
	s_nop 0
	v_pk_fma_f32 v[8:9], v[8:9], s[94:95], v[50:51] op_sel:[0,0,1] op_sel_hi:[1,0,0]
	v_pk_add_f32 v[50:51], v[10:11], v[52:53]
	v_pk_add_f32 v[10:11], v[10:11], v[52:53] neg_lo:[0,1] neg_hi:[0,1]
	s_nop 0
	v_pk_mul_f32 v[52:53], v[10:11], s[66:67]
	s_nop 0
	v_pk_fma_f32 v[10:11], v[10:11], s[6:7], v[52:53] op_sel:[0,0,1] op_sel_hi:[1,0,0]
	v_pk_add_f32 v[52:53], v[26:27], v[58:59]
	v_pk_add_f32 v[26:27], v[26:27], v[58:59] neg_lo:[0,1] neg_hi:[0,1]
	s_nop 0
	v_xor_b32_e32 v59, 0x80000000, v26
	v_mov_b32_e32 v58, v27
	v_pk_add_f32 v[26:27], v[28:29], v[60:61]
	v_pk_add_f32 v[28:29], v[28:29], v[60:61] neg_lo:[0,1] neg_hi:[0,1]
	s_nop 0
	v_pk_mul_f32 v[60:61], v[28:29], s[66:67]
	s_nop 0
	v_pk_fma_f32 v[28:29], v[28:29], s[6:7], v[60:61] op_sel:[0,0,1] op_sel_hi:[1,0,0] neg_lo:[1,0,0] neg_hi:[1,0,0]
	v_pk_add_f32 v[60:61], v[34:35], v[66:67]
	v_pk_add_f32 v[34:35], v[34:35], v[66:67] neg_lo:[0,1] neg_hi:[0,1]
	s_mov_b64 s[6:7], -1
	v_pk_mul_f32 v[66:67], v[34:35], s[62:63]
	s_nop 0
	v_pk_fma_f32 v[34:35], v[34:35], s[94:95], v[66:67] op_sel:[0,0,1] op_sel_hi:[1,0,0] neg_lo:[1,0,0] neg_hi:[1,0,0]
	v_pk_add_f32 v[66:67], v[36:37], v[68:69]
	v_pk_add_f32 v[36:37], v[36:37], v[68:69] neg_lo:[0,1] neg_hi:[0,1]
	s_nop 0
	v_pk_mul_f32 v[68:69], v[36:37], s[54:55]
	s_nop 0
	v_pk_fma_f32 v[36:37], v[36:37], s[56:57], v[68:69] op_sel:[0,0,1] op_sel_hi:[1,0,0] neg_lo:[1,0,0] neg_hi:[1,0,0]
	v_pk_add_f32 v[68:69], v[0:1], v[54:55] neg_lo:[0,1] neg_hi:[0,1]
	v_pk_add_f32 v[0:1], v[0:1], v[54:55]
	v_pk_add_f32 v[54:55], v[40:41], v[24:25]
	v_pk_add_f32 v[24:25], v[40:41], v[24:25] neg_lo:[0,1] neg_hi:[0,1]
	s_nop 0
	v_pk_mul_f32 v[40:41], v[24:25], s[62:63]
	s_nop 0
	v_pk_fma_f32 v[24:25], v[24:25], s[94:95], v[40:41] op_sel:[0,0,1] op_sel_hi:[1,0,0]
	v_pk_add_f32 v[40:41], v[42:43], v[62:63]
	v_pk_add_f32 v[42:43], v[42:43], v[62:63] neg_lo:[0,1] neg_hi:[0,1]
	s_nop 0
	v_xor_b32_e32 v63, 0x80000000, v42
	v_mov_b32_e32 v62, v43
	v_pk_add_f32 v[42:43], v[48:49], v[64:65]
	v_pk_add_f32 v[48:49], v[48:49], v[64:65] neg_lo:[0,1] neg_hi:[0,1]
	s_nop 0
	v_pk_mul_f32 v[64:65], v[48:49], s[62:63]
	s_nop 0
	v_pk_fma_f32 v[48:49], v[48:49], s[94:95], v[64:65] op_sel:[0,0,1] op_sel_hi:[1,0,0] neg_lo:[1,0,0] neg_hi:[1,0,0]
	v_pk_add_f32 v[64:65], v[72:73], v[56:57] neg_lo:[0,1] neg_hi:[0,1]
	v_pk_add_f32 v[56:57], v[72:73], v[56:57]
	v_pk_add_f32 v[72:73], v[4:5], v[30:31]
	v_pk_add_f32 v[4:5], v[4:5], v[30:31] neg_lo:[0,1] neg_hi:[0,1]
	s_nop 0
	v_pk_mul_f32 v[30:31], v[4:5], s[62:63]
	s_nop 0
	v_pk_fma_f32 v[4:5], v[4:5], s[94:95], v[30:31] op_sel:[0,0,1] op_sel_hi:[1,0,0]
	v_pk_add_f32 v[30:31], v[6:7], v[32:33]
; __device__ __forceinline__ f2 cmulw(f2 a, float wr, float wi) { const f2 s = __builtin_shufflevector(a, a, 1, 0); return s * (f2){-wi, wi} + a * (f2){wr, wr}; }
; __device__ __forceinline__ void fft32(f2 (&x)[32]) {
;     ...
;     for (int h = 16; h >= 1; h >>= 1) {
; #pragma unroll
;         for (int i0 = 0; i0 < 32; i0 += 2 * h) {
; #pragma unroll
;             for (int j = 0; j < h; ++j) {
;                 const int i = i0 + j, k = i + h, m = j * (32 / h);
;                 const f2 a = x[i], b = x[k], d = a - b;
;                 x[i] = a + b;
;                 if (m == 0) x[k] = d;
;                 else if (m == 16) x[k] = (f2){d.y, -d.x};
;                 else x[k] = cmulw(d, TWR[m], TWI[m]);
;             }
	v_pk_add_f32 v[6:7], v[6:7], v[32:33] neg_lo:[0,1] neg_hi:[0,1]
	s_nop 0
	v_xor_b32_e32 v33, 0x80000000, v6
	v_mov_b32_e32 v32, v7
	v_pk_add_f32 v[6:7], v[22:23], v[38:39]
	v_pk_add_f32 v[22:23], v[22:23], v[38:39] neg_lo:[0,1] neg_hi:[0,1]
	s_nop 0
	v_pk_mul_f32 v[38:39], v[22:23], s[62:63]
	s_nop 0
	v_pk_fma_f32 v[22:23], v[22:23], s[94:95], v[38:39] op_sel:[0,0,1] op_sel_hi:[1,0,0] neg_lo:[1,0,0] neg_hi:[1,0,0]
	v_pk_add_f32 v[38:39], v[14:15], v[52:53] neg_lo:[0,1] neg_hi:[0,1]
	v_pk_add_f32 v[14:15], v[14:15], v[52:53]
	v_pk_add_f32 v[52:53], v[46:47], v[26:27]
	v_pk_add_f32 v[26:27], v[46:47], v[26:27] neg_lo:[0,1] neg_hi:[0,1]
	s_nop 0
	v_pk_mul_f32 v[46:47], v[26:27], s[62:63]
	s_nop 0
	v_pk_fma_f32 v[26:27], v[26:27], s[94:95], v[46:47] op_sel:[0,0,1] op_sel_hi:[1,0,0]
	v_pk_add_f32 v[46:47], v[44:45], v[60:61]
	v_pk_add_f32 v[44:45], v[44:45], v[60:61] neg_lo:[0,1] neg_hi:[0,1]
	s_nop 0
	v_xor_b32_e32 v61, 0x80000000, v44
	v_mov_b32_e32 v60, v45
	v_pk_add_f32 v[44:45], v[50:51], v[66:67]
	v_pk_add_f32 v[50:51], v[50:51], v[66:67] neg_lo:[0,1] neg_hi:[0,1]
	v_pk_add_f32 v[74:75], v[52:53], v[44:45]
	v_pk_mul_f32 v[66:67], v[50:51], s[62:63]
	s_nop 0
	v_pk_fma_f32 v[50:51], v[50:51], s[94:95], v[66:67] op_sel:[0,0,1] op_sel_hi:[1,0,0] neg_lo:[1,0,0] neg_hi:[1,0,0]
	v_pk_add_f32 v[66:67], v[70:71], v[58:59] neg_lo:[0,1] neg_hi:[0,1]
	v_pk_add_f32 v[58:59], v[70:71], v[58:59]
	v_pk_add_f32 v[70:71], v[2:3], v[28:29]
	v_pk_add_f32 v[2:3], v[2:3], v[28:29] neg_lo:[0,1] neg_hi:[0,1]
	s_nop 0
	v_pk_mul_f32 v[28:29], v[2:3], s[62:63]
	s_nop 0
	v_pk_fma_f32 v[2:3], v[2:3], s[94:95], v[28:29] op_sel:[0,0,1] op_sel_hi:[1,0,0]
	v_pk_add_f32 v[28:29], v[8:9], v[34:35]
	v_pk_add_f32 v[8:9], v[8:9], v[34:35] neg_lo:[0,1] neg_hi:[0,1]
	s_nop 0
	v_xor_b32_e32 v35, 0x80000000, v8
	v_mov_b32_e32 v34, v9
	v_pk_add_f32 v[8:9], v[10:11], v[36:37]
	v_pk_add_f32 v[10:11], v[10:11], v[36:37] neg_lo:[0,1] neg_hi:[0,1]
	s_nop 0
	v_pk_mul_f32 v[36:37], v[10:11], s[62:63]
	s_nop 0
	v_pk_fma_f32 v[10:11], v[10:11], s[94:95], v[36:37] op_sel:[0,0,1] op_sel_hi:[1,0,0] neg_lo:[1,0,0] neg_hi:[1,0,0]
	v_pk_add_f32 v[36:37], v[0:1], v[40:41] neg_lo:[0,1] neg_hi:[0,1]
	v_pk_add_f32 v[0:1], v[0:1], v[40:41]
	v_pk_add_f32 v[40:41], v[54:55], v[42:43]
	v_pk_add_f32 v[42:43], v[54:55], v[42:43] neg_lo:[0,1] neg_hi:[0,1]
	v_pk_add_f32 v[78:79], v[0:1], v[40:41] neg_lo:[0,1] neg_hi:[0,1]
	v_xor_b32_e32 v55, 0x80000000, v42
	v_mov_b32_e32 v54, v43
	v_pk_add_f32 v[42:43], v[68:69], v[62:63] neg_lo:[0,1] neg_hi:[0,1]
	v_pk_add_f32 v[62:63], v[68:69], v[62:63]
	v_pk_add_f32 v[68:69], v[24:25], v[48:49]
	v_pk_add_f32 v[24:25], v[24:25], v[48:49] neg_lo:[0,1] neg_hi:[0,1]
	v_pk_add_f32 v[82:83], v[36:37], v[54:55] neg_lo:[0,1] neg_hi:[0,1]
	v_xor_b32_e32 v49, 0x80000000, v24
	v_mov_b32_e32 v48, v25
	v_pk_add_f32 v[24:25], v[56:57], v[30:31] neg_lo:[0,1] neg_hi:[0,1]
	v_pk_add_f32 v[30:31], v[56:57], v[30:31]
	v_pk_add_f32 v[56:57], v[72:73], v[6:7]
	v_pk_add_f32 v[6:7], v[72:73], v[6:7] neg_lo:[0,1] neg_hi:[0,1]
	v_pk_add_f32 v[80:81], v[42:43], v[48:49]
	v_xor_b32_e32 v73, 0x80000000, v6
	v_mov_b32_e32 v72, v7
	v_pk_add_f32 v[6:7], v[64:65], v[32:33] neg_lo:[0,1] neg_hi:[0,1]
	v_pk_add_f32 v[32:33], v[64:65], v[32:33]
	v_pk_add_f32 v[64:65], v[4:5], v[22:23]
	v_pk_add_f32 v[4:5], v[4:5], v[22:23] neg_lo:[0,1] neg_hi:[0,1]
	v_pk_add_f32 v[84:85], v[42:43], v[48:49] neg_lo:[0,1] neg_hi:[0,1]
	v_xor_b32_e32 v23, 0x80000000, v4
	v_mov_b32_e32 v22, v5
	v_pk_add_f32 v[4:5], v[14:15], v[46:47] neg_lo:[0,1] neg_hi:[0,1]
	v_pk_add_f32 v[46:47], v[14:15], v[46:47]
	v_pk_add_f32 v[14:15], v[52:53], v[44:45] neg_lo:[0,1] neg_hi:[0,1]
	v_pk_add_f32 v[52:53], v[38:39], v[60:61] neg_lo:[0,1] neg_hi:[0,1]
	v_xor_b32_e32 v45, 0x80000000, v14
	v_mov_b32_e32 v44, v15
	v_pk_add_f32 v[38:39], v[38:39], v[60:61]
	v_pk_add_f32 v[60:61], v[26:27], v[50:51]
	v_pk_add_f32 v[14:15], v[26:27], v[50:51] neg_lo:[0,1] neg_hi:[0,1]
	v_pk_add_f32 v[50:51], v[58:59], v[28:29] neg_lo:[0,1] neg_hi:[0,1]
	v_pk_add_f32 v[28:29], v[58:59], v[28:29]
	v_pk_add_f32 v[58:59], v[70:71], v[8:9]
	v_pk_add_f32 v[8:9], v[70:71], v[8:9] neg_lo:[0,1] neg_hi:[0,1]
	v_xor_b32_e32 v27, 0x80000000, v14
	v_xor_b32_e32 v71, 0x80000000, v8
	v_mov_b32_e32 v70, v9
	v_pk_add_f32 v[8:9], v[66:67], v[34:35] neg_lo:[0,1] neg_hi:[0,1]
	v_pk_add_f32 v[34:35], v[66:67], v[34:35]
	v_pk_add_f32 v[66:67], v[2:3], v[10:11]
	v_pk_add_f32 v[2:3], v[2:3], v[10:11] neg_lo:[0,1] neg_hi:[0,1]
	v_mov_b32_e32 v26, v15
	v_xor_b32_e32 v11, 0x80000000, v2
	v_mov_b32_e32 v10, v3
	v_pk_add_f32 v[14:15], v[0:1], v[40:41]
	v_pk_add_f32 v[40:41], v[36:37], v[54:55]
	v_pk_add_f32 v[36:37], v[30:31], v[56:57]
	v_pk_add_f32 v[30:31], v[30:31], v[56:57] neg_lo:[0,1] neg_hi:[0,1]
	v_pk_add_f32 v[42:43], v[24:25], v[72:73]
	v_pk_add_f32 v[86:87], v[24:25], v[72:73] neg_lo:[0,1] neg_hi:[0,1]
	v_pk_add_f32 v[24:25], v[32:33], v[64:65]
	v_pk_add_f32 v[88:89], v[32:33], v[64:65] neg_lo:[0,1] neg_hi:[0,1]
	v_pk_add_f32 v[48:49], v[6:7], v[22:23]
	v_pk_add_f32 v[22:23], v[6:7], v[22:23] neg_lo:[0,1] neg_hi:[0,1]
	v_pk_add_f32 v[32:33], v[46:47], v[74:75]
	v_pk_add_f32 v[46:47], v[46:47], v[74:75] neg_lo:[0,1] neg_hi:[0,1]
	v_pk_add_f32 v[56:57], v[4:5], v[44:45]
	v_pk_add_f32 v[74:75], v[4:5], v[44:45] neg_lo:[0,1] neg_hi:[0,1]
	v_pk_add_f32 v[64:65], v[50:51], v[70:71]
	v_pk_add_f32 v[50:51], v[50:51], v[70:71] neg_lo:[0,1] neg_hi:[0,1]
	v_pk_add_f32 v[70:71], v[34:35], v[66:67]
	v_pk_add_f32 v[34:35], v[34:35], v[66:67] neg_lo:[0,1] neg_hi:[0,1]
	v_pk_add_f32 v[66:67], v[8:9], v[10:11]
	v_pk_add_f32 v[92:93], v[8:9], v[10:11] neg_lo:[0,1] neg_hi:[0,1]
	ds_read_b128 v[8:11], v151
	ds_read_b128 v[0:3], v151 offset:16
	ds_read_b128 v[4:7], v151 offset:32
	v_pk_add_f32 v[44:45], v[38:39], v[60:61]
	v_pk_add_f32 v[90:91], v[38:39], v[60:61] neg_lo:[0,1] neg_hi:[0,1]
	v_pk_add_f32 v[60:61], v[28:29], v[58:59]
	v_pk_add_f32 v[58:59], v[28:29], v[58:59] neg_lo:[0,1] neg_hi:[0,1]
	s_waitcnt lgkmcnt(2)
; template <bool CONJ> __device__ __forceinline__ void twiddle32(f2 (&x)[32], float wr, float wi) {
;     asm volatile("" : "+v"(wr), "+v"(wi));
;     f2 c = (f2){wr, CONJ ? -wi : wi}; const f2 w = c;
; #pragma unroll
;     for (int k = 1; k < 32; ++k) { const int p = brev5(k); x[p] = cmulr(x[p], c); if (k < 31) c = cmulr(c, w); }
; }
; __device__ __forceinline__ void fft_forward(f2 (&x)[32], LAS f2* X, int t, LAS const float* W1, LAS const M2C* MC) {
;     ...
;     twiddle32<false>(x, c.w2r, c.w2i);
	v_pk_add_f32 v[38:39], v[52:53], v[26:27]
	v_pk_mul_f32 v[28:29], v[32:33], v[8:9] op_sel_hi:[1,0]
	v_pk_add_f32 v[26:27], v[52:53], v[26:27] neg_lo:[0,1] neg_hi:[0,1]
	v_pk_fma_f32 v[52:53], v[32:33], v[8:9], v[28:29] op_sel:[1,1,0] op_sel_hi:[0,1,1] neg_lo:[0,1,0]
	v_pk_mul_f32 v[28:29], v[8:9], v[8:9] op_sel_hi:[1,0]
	v_pk_add_f32 v[54:55], v[62:63], v[68:69]
	v_pk_fma_f32 v[28:29], v[8:9], v[8:9], v[28:29] op_sel:[1,1,0] op_sel_hi:[0,1,1] neg_lo:[0,1,0]
	v_pk_add_f32 v[62:63], v[62:63], v[68:69] neg_lo:[0,1] neg_hi:[0,1]
	v_pk_mul_f32 v[32:33], v[36:37], v[28:29] op_sel_hi:[1,0]
	s_nop 0
	v_pk_fma_f32 v[36:37], v[36:37], v[28:29], v[32:33] op_sel:[1,1,0] op_sel_hi:[0,1,1] neg_lo:[0,1,0]
	v_pk_mul_f32 v[32:33], v[28:29], v[8:9] op_sel_hi:[1,0]
	s_nop 0
	v_pk_fma_f32 v[28:29], v[28:29], v[8:9], v[32:33] op_sel:[1,1,0] op_sel_hi:[0,1,1] neg_lo:[0,1,0]
	s_nop 0
	v_pk_mul_f32 v[32:33], v[60:61], v[28:29] op_sel_hi:[1,0]
	s_nop 0
	v_pk_fma_f32 v[68:69], v[60:61], v[28:29], v[32:33] op_sel:[1,1,0] op_sel_hi:[0,1,1] neg_lo:[0,1,0]
	v_pk_mul_f32 v[32:33], v[28:29], v[8:9] op_sel_hi:[1,0]
	s_nop 0
	v_pk_fma_f32 v[32:33], v[28:29], v[8:9], v[32:33] op_sel:[1,1,0] op_sel_hi:[0,1,1] neg_lo:[0,1,0]
	s_nop 0
	v_pk_mul_f32 v[28:29], v[54:55], v[32:33] op_sel_hi:[1,0]
	s_nop 0
	v_pk_fma_f32 v[28:29], v[54:55], v[32:33], v[28:29] op_sel:[1,1,0] op_sel_hi:[0,1,1] neg_lo:[0,1,0]
	v_pk_mul_f32 v[54:55], v[32:33], v[8:9] op_sel_hi:[1,0]
	s_nop 0
	v_pk_fma_f32 v[32:33], v[32:33], v[8:9], v[54:55] op_sel:[1,1,0] op_sel_hi:[0,1,1] neg_lo:[0,1,0]
	s_nop 0
	v_pk_mul_f32 v[54:55], v[44:45], v[32:33] op_sel_hi:[1,0]
	s_nop 0
	v_pk_fma_f32 v[60:61], v[44:45], v[32:33], v[54:55] op_sel:[1,1,0] op_sel_hi:[0,1,1] neg_lo:[0,1,0]
	v_pk_mul_f32 v[44:45], v[32:33], v[8:9] op_sel_hi:[1,0]
	s_nop 0
	v_pk_fma_f32 v[32:33], v[32:33], v[8:9], v[44:45] op_sel:[1,1,0] op_sel_hi:[0,1,1] neg_lo:[0,1,0]
	s_nop 0
	v_pk_mul_f32 v[44:45], v[24:25], v[32:33] op_sel_hi:[1,0]
	s_nop 0
	v_pk_fma_f32 v[44:45], v[24:25], v[32:33], v[44:45] op_sel:[1,1,0] op_sel_hi:[0,1,1] neg_lo:[0,1,0]
	v_pk_mul_f32 v[24:25], v[32:33], v[8:9] op_sel_hi:[1,0]
	s_nop 0
	v_pk_fma_f32 v[24:25], v[32:33], v[8:9], v[24:25] op_sel:[1,1,0] op_sel_hi:[0,1,1] neg_lo:[0,1,0]
	s_nop 0
	v_pk_mul_f32 v[32:33], v[70:71], v[24:25] op_sel_hi:[1,0]
	s_nop 0
	v_pk_fma_f32 v[76:77], v[70:71], v[24:25], v[32:33] op_sel:[1,1,0] op_sel_hi:[0,1,1] neg_lo:[0,1,0]
	v_pk_mul_f32 v[32:33], v[24:25], v[8:9] op_sel_hi:[1,0]
	s_nop 0
	v_pk_fma_f32 v[32:33], v[24:25], v[8:9], v[32:33] op_sel:[1,1,0] op_sel_hi:[0,1,1] neg_lo:[0,1,0]
	s_nop 0
	v_pk_mul_f32 v[24:25], v[40:41], v[32:33] op_sel_hi:[1,0]
	s_nop 0
	v_pk_fma_f32 v[24:25], v[40:41], v[32:33], v[24:25] op_sel:[1,1,0] op_sel_hi:[0,1,1] neg_lo:[0,1,0]
	v_pk_mul_f32 v[40:41], v[32:33], v[8:9] op_sel_hi:[1,0]
	s_nop 0
	v_pk_fma_f32 v[32:33], v[32:33], v[8:9], v[40:41] op_sel:[1,1,0] op_sel_hi:[0,1,1] neg_lo:[0,1,0]
	s_nop 0
	v_pk_mul_f32 v[40:41], v[56:57], v[32:33] op_sel_hi:[1,0]
	s_nop 0
	v_pk_fma_f32 v[56:57], v[56:57], v[32:33], v[40:41] op_sel:[1,1,0] op_sel_hi:[0,1,1] neg_lo:[0,1,0]
	v_pk_mul_f32 v[40:41], v[32:33], v[8:9] op_sel_hi:[1,0]
	s_nop 0
	v_pk_fma_f32 v[32:33], v[32:33], v[8:9], v[40:41] op_sel:[1,1,0] op_sel_hi:[0,1,1] neg_lo:[0,1,0]
	s_nop 0
	v_pk_mul_f32 v[40:41], v[42:43], v[32:33] op_sel_hi:[1,0]
	s_nop 0
	v_pk_fma_f32 v[40:41], v[42:43], v[32:33], v[40:41] op_sel:[1,1,0] op_sel_hi:[0,1,1] neg_lo:[0,1,0]
	v_pk_mul_f32 v[42:43], v[32:33], v[8:9] op_sel_hi:[1,0]
	s_nop 0
	v_pk_fma_f32 v[32:33], v[32:33], v[8:9], v[42:43] op_sel:[1,1,0] op_sel_hi:[0,1,1] neg_lo:[0,1,0]
	s_nop 0
	v_pk_mul_f32 v[42:43], v[64:65], v[32:33] op_sel_hi:[1,0]
	s_nop 0
	v_pk_fma_f32 v[72:73], v[64:65], v[32:33], v[42:43] op_sel:[1,1,0] op_sel_hi:[0,1,1] neg_lo:[0,1,0]
	v_pk_mul_f32 v[42:43], v[32:33], v[8:9] op_sel_hi:[1,0]
	s_nop 0
	v_pk_fma_f32 v[42:43], v[32:33], v[8:9], v[42:43] op_sel:[1,1,0] op_sel_hi:[0,1,1] neg_lo:[0,1,0]
	s_nop 0
	v_pk_mul_f32 v[32:33], v[80:81], v[42:43] op_sel_hi:[1,0]
	v_pk_mul_f32 v[54:55], v[42:43], v[8:9] op_sel_hi:[1,0]
	s_nop 0
	v_pk_fma_f32 v[32:33], v[80:81], v[42:43], v[32:33] op_sel:[1,1,0] op_sel_hi:[0,1,1] neg_lo:[0,1,0]
	v_pk_fma_f32 v[42:43], v[42:43], v[8:9], v[54:55] op_sel:[1,1,0] op_sel_hi:[0,1,1] neg_lo:[0,1,0]
	s_nop 0
	v_pk_mul_f32 v[54:55], v[38:39], v[42:43] op_sel_hi:[1,0]
	s_nop 0
	v_pk_fma_f32 v[64:65], v[38:39], v[42:43], v[54:55] op_sel:[1,1,0] op_sel_hi:[0,1,1] neg_lo:[0,1,0]
	v_pk_mul_f32 v[38:39], v[42:43], v[8:9] op_sel_hi:[1,0]
	s_nop 0
	v_pk_fma_f32 v[38:39], v[42:43], v[8:9], v[38:39] op_sel:[1,1,0] op_sel_hi:[0,1,1] neg_lo:[0,1,0]
	s_nop 0
	v_pk_mul_f32 v[42:43], v[48:49], v[38:39] op_sel_hi:[1,0]
	s_nop 0
	v_pk_fma_f32 v[48:49], v[48:49], v[38:39], v[42:43] op_sel:[1,1,0] op_sel_hi:[0,1,1] neg_lo:[0,1,0]
	v_pk_mul_f32 v[42:43], v[38:39], v[8:9] op_sel_hi:[1,0]
	s_nop 0
	v_pk_fma_f32 v[38:39], v[38:39], v[8:9], v[42:43] op_sel:[1,1,0] op_sel_hi:[0,1,1] neg_lo:[0,1,0]
	s_nop 0
	v_pk_mul_f32 v[42:43], v[66:67], v[38:39] op_sel_hi:[1,0]
	s_nop 0
	v_pk_fma_f32 v[80:81], v[66:67], v[38:39], v[42:43] op_sel:[1,1,0] op_sel_hi:[0,1,1] neg_lo:[0,1,0]
	v_pk_mul_f32 v[42:43], v[38:39], v[8:9] op_sel_hi:[1,0]
	s_nop 0
	v_pk_fma_f32 v[38:39], v[38:39], v[8:9], v[42:43] op_sel:[1,1,0] op_sel_hi:[0,1,1] neg_lo:[0,1,0]
	s_nop 0
	v_pk_mul_f32 v[42:43], v[78:79], v[38:39] op_sel_hi:[1,0]
	s_nop 0
	v_pk_fma_f32 v[94:95], v[78:79], v[38:39], v[42:43] op_sel:[1,1,0] op_sel_hi:[0,1,1] neg_lo:[0,1,0]
	v_pk_mul_f32 v[42:43], v[38:39], v[8:9] op_sel_hi:[1,0]
	s_nop 0
	v_pk_fma_f32 v[38:39], v[38:39], v[8:9], v[42:43] op_sel:[1,1,0] op_sel_hi:[0,1,1] neg_lo:[0,1,0]
; __device__ __forceinline__ float lx1(float v) { return __int_as_float(__builtin_amdgcn_update_dpp(0, __float_as_int(v), 0xB1, 0xF, 0xF, true)); }
; __device__ __forceinline__ float lx2(float v) { return __int_as_float(__builtin_amdgcn_update_dpp(0, __float_as_int(v), 0x4E, 0xF, 0xF, true)); }
; __device__ __forceinline__ float lx4(float v) { return __int_as_float(__builtin_amdgcn_ds_swizzle(__float_as_int(v), 0x101F)); }
; __device__ __forceinline__ float lx8(float v) { return __int_as_float(__builtin_amdgcn_update_dpp(0, __float_as_int(v), 0x128, 0xF, 0xF, true)); }
; template <bool CONJ> __device__ __forceinline__ void twiddle32(f2 (&x)[32], float wr, float wi) {
;     asm volatile("" : "+v"(wr), "+v"(wi));
;     f2 c = (f2){wr, CONJ ? -wi : wi}; const f2 w = c;
; #pragma unroll
;     for (int k = 1; k < 32; ++k) { const int p = brev5(k); x[p] = cmulr(x[p], c); if (k < 31) c = cmulr(c, w); }
; }
; __device__ __forceinline__ void fft_forward(f2 (&x)[32], LAS f2* X, int t, LAS const float* W1, LAS const M2C* MC) {
;     ...
;     for (int p = 0; p < 32; ++p) {
;         f2 v = x[p], pr;
;         pr = (f2){lx8(v.x), lx8(v.y)}; v = cmulr(pr + v * c.s8, t8);
;         pr = (f2){lx4(v.x), lx4(v.y)}; v = cmulr(pr + v * c.s4, t4);
;         pr = (f2){lx2(v.x), lx2(v.y)}; v = cmulr(pr + v * c.s2, t2);
;         pr = (f2){lx1(v.x), lx1(v.y)}; x[p] = pr + v * c.s1;
;     }
	s_nop 0
	v_pk_mul_f32 v[42:43], v[46:47], v[38:39] op_sel_hi:[1,0]
	s_nop 0
	v_pk_fma_f32 v[54:55], v[46:47], v[38:39], v[42:43] op_sel:[1,1,0] op_sel_hi:[0,1,1] neg_lo:[0,1,0]
	v_pk_mul_f32 v[42:43], v[38:39], v[8:9] op_sel_hi:[1,0]
	s_nop 0
	v_pk_fma_f32 v[42:43], v[38:39], v[8:9], v[42:43] op_sel:[1,1,0] op_sel_hi:[0,1,1] neg_lo:[0,1,0]
	s_nop 0
	v_pk_mul_f32 v[38:39], v[30:31], v[42:43] op_sel_hi:[1,0]
	s_nop 0
	v_pk_fma_f32 v[38:39], v[30:31], v[42:43], v[38:39] op_sel:[1,1,0] op_sel_hi:[0,1,1] neg_lo:[0,1,0]
	v_pk_mul_f32 v[30:31], v[42:43], v[8:9] op_sel_hi:[1,0]
	s_nop 0
	v_pk_fma_f32 v[30:31], v[42:43], v[8:9], v[30:31] op_sel:[1,1,0] op_sel_hi:[0,1,1] neg_lo:[0,1,0]
	s_nop 0
	v_pk_mul_f32 v[42:43], v[58:59], v[30:31] op_sel_hi:[1,0]
	s_nop 0
	v_pk_fma_f32 v[70:71], v[58:59], v[30:31], v[42:43] op_sel:[1,1,0] op_sel_hi:[0,1,1] neg_lo:[0,1,0]
	v_pk_mul_f32 v[42:43], v[30:31], v[8:9] op_sel_hi:[1,0]
	s_nop 0
	v_pk_fma_f32 v[42:43], v[30:31], v[8:9], v[42:43] op_sel:[1,1,0] op_sel_hi:[0,1,1] neg_lo:[0,1,0]
	s_nop 0
	v_pk_mul_f32 v[30:31], v[62:63], v[42:43] op_sel_hi:[1,0]
	v_pk_mul_f32 v[46:47], v[42:43], v[8:9] op_sel_hi:[1,0]
	s_nop 0
	v_pk_fma_f32 v[30:31], v[62:63], v[42:43], v[30:31] op_sel:[1,1,0] op_sel_hi:[0,1,1] neg_lo:[0,1,0]
	v_pk_fma_f32 v[42:43], v[42:43], v[8:9], v[46:47] op_sel:[1,1,0] op_sel_hi:[0,1,1] neg_lo:[0,1,0]
	s_nop 0
	v_pk_mul_f32 v[46:47], v[90:91], v[42:43] op_sel_hi:[1,0]
	s_nop 0
	v_pk_fma_f32 v[62:63], v[90:91], v[42:43], v[46:47] op_sel:[1,1,0] op_sel_hi:[0,1,1] neg_lo:[0,1,0]
	v_pk_mul_f32 v[46:47], v[42:43], v[8:9] op_sel_hi:[1,0]
	s_nop 0
	v_pk_fma_f32 v[42:43], v[42:43], v[8:9], v[46:47] op_sel:[1,1,0] op_sel_hi:[0,1,1] neg_lo:[0,1,0]
	s_nop 0
	v_pk_mul_f32 v[46:47], v[88:89], v[42:43] op_sel_hi:[1,0]
	v_pk_mul_f32 v[58:59], v[42:43], v[8:9] op_sel_hi:[1,0]
	s_nop 0
	v_pk_fma_f32 v[46:47], v[88:89], v[42:43], v[46:47] op_sel:[1,1,0] op_sel_hi:[0,1,1] neg_lo:[0,1,0]
	v_pk_fma_f32 v[42:43], v[42:43], v[8:9], v[58:59] op_sel:[1,1,0] op_sel_hi:[0,1,1] neg_lo:[0,1,0]
	s_nop 0
	v_pk_mul_f32 v[58:59], v[34:35], v[42:43] op_sel_hi:[1,0]
	s_nop 0
	v_pk_fma_f32 v[78:79], v[34:35], v[42:43], v[58:59] op_sel:[1,1,0] op_sel_hi:[0,1,1] neg_lo:[0,1,0]
	v_pk_mul_f32 v[34:35], v[42:43], v[8:9] op_sel_hi:[1,0]
	s_nop 0
	v_pk_fma_f32 v[34:35], v[42:43], v[8:9], v[34:35] op_sel:[1,1,0] op_sel_hi:[0,1,1] neg_lo:[0,1,0]
	s_nop 0
	v_pk_mul_f32 v[42:43], v[82:83], v[34:35] op_sel_hi:[1,0]
	s_nop 0
	v_pk_fma_f32 v[88:89], v[82:83], v[34:35], v[42:43] op_sel:[1,1,0] op_sel_hi:[0,1,1] neg_lo:[0,1,0]
	v_pk_mul_f32 v[42:43], v[34:35], v[8:9] op_sel_hi:[1,0]
	s_nop 0
	v_pk_fma_f32 v[34:35], v[34:35], v[8:9], v[42:43] op_sel:[1,1,0] op_sel_hi:[0,1,1] neg_lo:[0,1,0]
	s_nop 0
	v_pk_mul_f32 v[42:43], v[74:75], v[34:35] op_sel_hi:[1,0]
	s_nop 0
	v_pk_fma_f32 v[58:59], v[74:75], v[34:35], v[42:43] op_sel:[1,1,0] op_sel_hi:[0,1,1] neg_lo:[0,1,0]
	v_pk_mul_f32 v[42:43], v[34:35], v[8:9] op_sel_hi:[1,0]
	s_nop 0
	v_pk_fma_f32 v[34:35], v[34:35], v[8:9], v[42:43] op_sel:[1,1,0] op_sel_hi:[0,1,1] neg_lo:[0,1,0]
	s_nop 0
	v_pk_mul_f32 v[42:43], v[86:87], v[34:35] op_sel_hi:[1,0]
	v_pk_mul_f32 v[66:67], v[34:35], v[8:9] op_sel_hi:[1,0]
	s_nop 0
	v_pk_fma_f32 v[42:43], v[86:87], v[34:35], v[42:43] op_sel:[1,1,0] op_sel_hi:[0,1,1] neg_lo:[0,1,0]
	v_pk_fma_f32 v[34:35], v[34:35], v[8:9], v[66:67] op_sel:[1,1,0] op_sel_hi:[0,1,1] neg_lo:[0,1,0]
	s_nop 0
	v_pk_mul_f32 v[66:67], v[50:51], v[34:35] op_sel_hi:[1,0]
	s_nop 0
	v_pk_fma_f32 v[74:75], v[50:51], v[34:35], v[66:67] op_sel:[1,1,0] op_sel_hi:[0,1,1] neg_lo:[0,1,0]
	v_pk_mul_f32 v[50:51], v[34:35], v[8:9] op_sel_hi:[1,0]
	s_nop 0
	v_pk_fma_f32 v[50:51], v[34:35], v[8:9], v[50:51] op_sel:[1,1,0] op_sel_hi:[0,1,1] neg_lo:[0,1,0]
	s_nop 0
	v_pk_mul_f32 v[34:35], v[84:85], v[50:51] op_sel_hi:[1,0]
	v_pk_mul_f32 v[66:67], v[50:51], v[8:9] op_sel_hi:[1,0]
	s_nop 0
	v_pk_fma_f32 v[34:35], v[84:85], v[50:51], v[34:35] op_sel:[1,1,0] op_sel_hi:[0,1,1] neg_lo:[0,1,0]
	v_pk_fma_f32 v[50:51], v[50:51], v[8:9], v[66:67] op_sel:[1,1,0] op_sel_hi:[0,1,1] neg_lo:[0,1,0]
	s_nop 0
	v_pk_mul_f32 v[66:67], v[26:27], v[50:51] op_sel_hi:[1,0]
	s_nop 0
	v_pk_fma_f32 v[66:67], v[26:27], v[50:51], v[66:67] op_sel:[1,1,0] op_sel_hi:[0,1,1] neg_lo:[0,1,0]
	v_pk_mul_f32 v[26:27], v[50:51], v[8:9] op_sel_hi:[1,0]
	s_nop 0
	v_pk_fma_f32 v[26:27], v[50:51], v[8:9], v[26:27] op_sel:[1,1,0] op_sel_hi:[0,1,1] neg_lo:[0,1,0]
	s_nop 0
	v_pk_mul_f32 v[50:51], v[22:23], v[26:27] op_sel_hi:[1,0]
	s_nop 0
	v_pk_fma_f32 v[50:51], v[22:23], v[26:27], v[50:51] op_sel:[1,1,0] op_sel_hi:[0,1,1] neg_lo:[0,1,0]
	v_pk_mul_f32 v[22:23], v[26:27], v[8:9] op_sel_hi:[1,0]
	s_nop 0
	v_pk_fma_f32 v[8:9], v[26:27], v[8:9], v[22:23] op_sel:[1,1,0] op_sel_hi:[0,1,1] neg_lo:[0,1,0]
	s_nop 0
	v_pk_mul_f32 v[22:23], v[92:93], v[8:9] op_sel_hi:[1,0]
	s_nop 0
	v_pk_fma_f32 v[82:83], v[92:93], v[8:9], v[22:23] op_sel:[1,1,0] op_sel_hi:[0,1,1] neg_lo:[0,1,0]
	s_waitcnt lgkmcnt(0)
	v_mov_b32_e32 v8, v7
	v_mov_b32_dpp v22, v14 row_ror:8 row_mask:0xf bank_mask:0xf bound_ctrl:1
	v_mov_b32_dpp v23, v15 row_ror:8 row_mask:0xf bank_mask:0xf bound_ctrl:1
	v_pk_fma_f32 v[14:15], v[14:15], v[4:5], v[22:23] op_sel_hi:[1,0,1]
	s_nop 0
	v_pk_mul_f32 v[22:23], v[14:15], v[10:11] op_sel_hi:[1,0]
	s_nop 0
	v_pk_fma_f32 v[14:15], v[14:15], v[10:11], v[22:23] op_sel:[1,1,0] op_sel_hi:[0,1,1] neg_lo:[0,1,0]
	ds_swizzle_b32 v22, v14 offset:swizzle(SWAP,4)
	ds_swizzle_b32 v23, v15 offset:swizzle(SWAP,4)
	s_waitcnt lgkmcnt(0)
; __device__ __forceinline__ float lx1(float v) { return __int_as_float(__builtin_amdgcn_update_dpp(0, __float_as_int(v), 0xB1, 0xF, 0xF, true)); }
; __device__ __forceinline__ float lx2(float v) { return __int_as_float(__builtin_amdgcn_update_dpp(0, __float_as_int(v), 0x4E, 0xF, 0xF, true)); }
; __device__ __forceinline__ float lx4(float v) { return __int_as_float(__builtin_amdgcn_ds_swizzle(__float_as_int(v), 0x101F)); }
; __device__ __forceinline__ float lx8(float v) { return __int_as_float(__builtin_amdgcn_update_dpp(0, __float_as_int(v), 0x128, 0xF, 0xF, true)); }
; __device__ __forceinline__ void fft_forward(f2 (&x)[32], LAS f2* X, int t, LAS const float* W1, LAS const M2C* MC) {
;     ...
;     for (int p = 0; p < 32; ++p) {
;         f2 v = x[p], pr;
;         pr = (f2){lx8(v.x), lx8(v.y)}; v = cmulr(pr + v * c.s8, t8);
;         pr = (f2){lx4(v.x), lx4(v.y)}; v = cmulr(pr + v * c.s4, t4);
;         pr = (f2){lx2(v.x), lx2(v.y)}; v = cmulr(pr + v * c.s2, t2);
;         pr = (f2){lx1(v.x), lx1(v.y)}; x[p] = pr + v * c.s1;
;     }
	v_pk_fma_f32 v[14:15], v[4:5], v[14:15], v[22:23] op_sel:[1,0,0]
	s_nop 0
	v_pk_mul_f32 v[22:23], v[14:15], v[0:1] op_sel_hi:[1,0]
	s_nop 0
	v_pk_fma_f32 v[14:15], v[14:15], v[0:1], v[22:23] op_sel:[1,1,0] op_sel_hi:[0,1,1] neg_lo:[0,1,0]
	s_nop 1
	v_mov_b32_dpp v22, v14 quad_perm:[2,3,0,1] row_mask:0xf bank_mask:0xf bound_ctrl:1
	v_mov_b32_dpp v23, v15 quad_perm:[2,3,0,1] row_mask:0xf bank_mask:0xf bound_ctrl:1
	v_pk_fma_f32 v[14:15], v[6:7], v[14:15], v[22:23] op_sel_hi:[0,1,1]
	v_pk_mul_f32 v[22:23], v[14:15], v[2:3] op_sel_hi:[1,0]
	s_nop 0
	v_pk_fma_f32 v[14:15], v[14:15], v[2:3], v[22:23] op_sel:[1,1,0] op_sel_hi:[0,1,1] neg_lo:[0,1,0]
	s_nop 1
	v_mov_b32_dpp v22, v14 quad_perm:[1,0,3,2] row_mask:0xf bank_mask:0xf bound_ctrl:1
	v_mov_b32_dpp v23, v15 quad_perm:[1,0,3,2] row_mask:0xf bank_mask:0xf bound_ctrl:1
	v_pk_fma_f32 v[14:15], v[8:9], v[14:15], v[22:23] op_sel_hi:[0,1,1]
	v_mov_b32_dpp v22, v94 row_ror:8 row_mask:0xf bank_mask:0xf bound_ctrl:1
	v_mov_b32_dpp v23, v95 row_ror:8 row_mask:0xf bank_mask:0xf bound_ctrl:1
	v_pk_fma_f32 v[22:23], v[4:5], v[94:95], v[22:23] op_sel_hi:[0,1,1]
	v_pk_mul_f32 v[26:27], v[22:23], v[10:11] op_sel_hi:[1,0]
	s_nop 0
	v_pk_fma_f32 v[22:23], v[22:23], v[10:11], v[26:27] op_sel:[1,1,0] op_sel_hi:[0,1,1] neg_lo:[0,1,0]
	ds_swizzle_b32 v26, v22 offset:swizzle(SWAP,4)
	ds_swizzle_b32 v27, v23 offset:swizzle(SWAP,4)
	s_waitcnt lgkmcnt(0)
	v_pk_fma_f32 v[22:23], v[4:5], v[22:23], v[26:27] op_sel:[1,0,0]
	s_nop 0
	v_pk_mul_f32 v[26:27], v[22:23], v[0:1] op_sel_hi:[1,0]
	s_nop 0
	v_pk_fma_f32 v[22:23], v[22:23], v[0:1], v[26:27] op_sel:[1,1,0] op_sel_hi:[0,1,1] neg_lo:[0,1,0]
	s_nop 1
	v_mov_b32_dpp v26, v22 quad_perm:[2,3,0,1] row_mask:0xf bank_mask:0xf bound_ctrl:1
	v_mov_b32_dpp v27, v23 quad_perm:[2,3,0,1] row_mask:0xf bank_mask:0xf bound_ctrl:1
	v_pk_fma_f32 v[22:23], v[6:7], v[22:23], v[26:27] op_sel_hi:[0,1,1]
	v_pk_mul_f32 v[26:27], v[22:23], v[2:3] op_sel_hi:[1,0]
	s_nop 0
	v_pk_fma_f32 v[22:23], v[22:23], v[2:3], v[26:27] op_sel:[1,1,0] op_sel_hi:[0,1,1] neg_lo:[0,1,0]
	s_nop 1
	v_mov_b32_dpp v26, v22 quad_perm:[1,0,3,2] row_mask:0xf bank_mask:0xf bound_ctrl:1
	v_mov_b32_dpp v27, v23 quad_perm:[1,0,3,2] row_mask:0xf bank_mask:0xf bound_ctrl:1
	v_pk_fma_f32 v[22:23], v[8:9], v[22:23], v[26:27] op_sel_hi:[0,1,1]
	v_mov_b32_dpp v26, v24 row_ror:8 row_mask:0xf bank_mask:0xf bound_ctrl:1
	v_mov_b32_dpp v27, v25 row_ror:8 row_mask:0xf bank_mask:0xf bound_ctrl:1
	v_pk_fma_f32 v[24:25], v[4:5], v[24:25], v[26:27] op_sel_hi:[0,1,1]
	v_pk_mul_f32 v[26:27], v[24:25], v[10:11] op_sel_hi:[1,0]
	s_nop 0
	v_pk_fma_f32 v[24:25], v[24:25], v[10:11], v[26:27] op_sel:[1,1,0] op_sel_hi:[0,1,1] neg_lo:[0,1,0]
	ds_swizzle_b32 v26, v24 offset:swizzle(SWAP,4)
	ds_swizzle_b32 v27, v25 offset:swizzle(SWAP,4)
	s_waitcnt lgkmcnt(0)
	v_pk_fma_f32 v[24:25], v[4:5], v[24:25], v[26:27] op_sel:[1,0,0]
	s_nop 0
	v_pk_mul_f32 v[26:27], v[24:25], v[0:1] op_sel_hi:[1,0]
	s_nop 0
	v_pk_fma_f32 v[24:25], v[24:25], v[0:1], v[26:27] op_sel:[1,1,0] op_sel_hi:[0,1,1] neg_lo:[0,1,0]
	s_nop 1
	v_mov_b32_dpp v26, v24 quad_perm:[2,3,0,1] row_mask:0xf bank_mask:0xf bound_ctrl:1
	v_mov_b32_dpp v27, v25 quad_perm:[2,3,0,1] row_mask:0xf bank_mask:0xf bound_ctrl:1
	v_pk_fma_f32 v[24:25], v[6:7], v[24:25], v[26:27] op_sel_hi:[0,1,1]
	v_pk_mul_f32 v[26:27], v[24:25], v[2:3] op_sel_hi:[1,0]
	s_nop 0
	v_pk_fma_f32 v[24:25], v[24:25], v[2:3], v[26:27] op_sel:[1,1,0] op_sel_hi:[0,1,1] neg_lo:[0,1,0]
	s_nop 1
	v_mov_b32_dpp v26, v24 quad_perm:[1,0,3,2] row_mask:0xf bank_mask:0xf bound_ctrl:1
	v_mov_b32_dpp v27, v25 quad_perm:[1,0,3,2] row_mask:0xf bank_mask:0xf bound_ctrl:1
	v_pk_fma_f32 v[24:25], v[8:9], v[24:25], v[26:27] op_sel_hi:[0,1,1]
	v_mov_b32_dpp v26, v88 row_ror:8 row_mask:0xf bank_mask:0xf bound_ctrl:1
	v_mov_b32_dpp v27, v89 row_ror:8 row_mask:0xf bank_mask:0xf bound_ctrl:1
	v_pk_fma_f32 v[26:27], v[4:5], v[88:89], v[26:27] op_sel_hi:[0,1,1]
	v_pk_mul_f32 v[84:85], v[26:27], v[10:11] op_sel_hi:[1,0]
	s_nop 0
	v_pk_fma_f32 v[26:27], v[26:27], v[10:11], v[84:85] op_sel:[1,1,0] op_sel_hi:[0,1,1] neg_lo:[0,1,0]
	ds_swizzle_b32 v84, v26 offset:swizzle(SWAP,4)
	ds_swizzle_b32 v85, v27 offset:swizzle(SWAP,4)
	s_waitcnt lgkmcnt(0)
	v_pk_fma_f32 v[26:27], v[4:5], v[26:27], v[84:85] op_sel:[1,0,0]
	s_nop 0
	v_pk_mul_f32 v[84:85], v[26:27], v[0:1] op_sel_hi:[1,0]
	s_nop 0
	v_pk_fma_f32 v[26:27], v[26:27], v[0:1], v[84:85] op_sel:[1,1,0] op_sel_hi:[0,1,1] neg_lo:[0,1,0]
	s_nop 1
	v_mov_b32_dpp v84, v26 quad_perm:[2,3,0,1] row_mask:0xf bank_mask:0xf bound_ctrl:1
	v_mov_b32_dpp v85, v27 quad_perm:[2,3,0,1] row_mask:0xf bank_mask:0xf bound_ctrl:1
	v_pk_fma_f32 v[26:27], v[6:7], v[26:27], v[84:85] op_sel_hi:[0,1,1]
	v_pk_mul_f32 v[84:85], v[26:27], v[2:3] op_sel_hi:[1,0]
	s_nop 0
	v_pk_fma_f32 v[26:27], v[26:27], v[2:3], v[84:85] op_sel:[1,1,0] op_sel_hi:[0,1,1] neg_lo:[0,1,0]
	s_nop 1
	v_mov_b32_dpp v84, v26 quad_perm:[1,0,3,2] row_mask:0xf bank_mask:0xf bound_ctrl:1
	v_mov_b32_dpp v85, v27 quad_perm:[1,0,3,2] row_mask:0xf bank_mask:0xf bound_ctrl:1
	v_pk_fma_f32 v[26:27], v[8:9], v[26:27], v[84:85] op_sel_hi:[0,1,1]
	v_mov_b32_dpp v84, v28 row_ror:8 row_mask:0xf bank_mask:0xf bound_ctrl:1
	v_mov_b32_dpp v85, v29 row_ror:8 row_mask:0xf bank_mask:0xf bound_ctrl:1
	v_pk_fma_f32 v[28:29], v[4:5], v[28:29], v[84:85] op_sel_hi:[0,1,1]
	v_pk_mul_f32 v[84:85], v[28:29], v[10:11] op_sel_hi:[1,0]
	s_nop 0
	v_pk_fma_f32 v[28:29], v[28:29], v[10:11], v[84:85] op_sel:[1,1,0] op_sel_hi:[0,1,1] neg_lo:[0,1,0]
	ds_swizzle_b32 v84, v28 offset:swizzle(SWAP,4)
	ds_swizzle_b32 v85, v29 offset:swizzle(SWAP,4)
	s_waitcnt lgkmcnt(0)
; __device__ __forceinline__ float lx1(float v) { return __int_as_float(__builtin_amdgcn_update_dpp(0, __float_as_int(v), 0xB1, 0xF, 0xF, true)); }
; __device__ __forceinline__ float lx2(float v) { return __int_as_float(__builtin_amdgcn_update_dpp(0, __float_as_int(v), 0x4E, 0xF, 0xF, true)); }
; __device__ __forceinline__ float lx4(float v) { return __int_as_float(__builtin_amdgcn_ds_swizzle(__float_as_int(v), 0x101F)); }
; __device__ __forceinline__ float lx8(float v) { return __int_as_float(__builtin_amdgcn_update_dpp(0, __float_as_int(v), 0x128, 0xF, 0xF, true)); }
; __device__ __forceinline__ void fft_forward(f2 (&x)[32], LAS f2* X, int t, LAS const float* W1, LAS const M2C* MC) {
;     ...
;     for (int p = 0; p < 32; ++p) {
;         f2 v = x[p], pr;
;         pr = (f2){lx8(v.x), lx8(v.y)}; v = cmulr(pr + v * c.s8, t8);
;         pr = (f2){lx4(v.x), lx4(v.y)}; v = cmulr(pr + v * c.s4, t4);
;         pr = (f2){lx2(v.x), lx2(v.y)}; v = cmulr(pr + v * c.s2, t2);
;         pr = (f2){lx1(v.x), lx1(v.y)}; x[p] = pr + v * c.s1;
;     }
	v_pk_fma_f32 v[28:29], v[4:5], v[28:29], v[84:85] op_sel:[1,0,0]
	s_nop 0
	v_pk_mul_f32 v[84:85], v[28:29], v[0:1] op_sel_hi:[1,0]
	s_nop 0
	v_pk_fma_f32 v[28:29], v[28:29], v[0:1], v[84:85] op_sel:[1,1,0] op_sel_hi:[0,1,1] neg_lo:[0,1,0]
	s_nop 1
	v_mov_b32_dpp v84, v28 quad_perm:[2,3,0,1] row_mask:0xf bank_mask:0xf bound_ctrl:1
	v_mov_b32_dpp v85, v29 quad_perm:[2,3,0,1] row_mask:0xf bank_mask:0xf bound_ctrl:1
	v_pk_fma_f32 v[28:29], v[6:7], v[28:29], v[84:85] op_sel_hi:[0,1,1]
	v_pk_mul_f32 v[84:85], v[28:29], v[2:3] op_sel_hi:[1,0]
	s_nop 0
	v_pk_fma_f32 v[28:29], v[28:29], v[2:3], v[84:85] op_sel:[1,1,0] op_sel_hi:[0,1,1] neg_lo:[0,1,0]
	s_nop 1
	v_mov_b32_dpp v84, v28 quad_perm:[1,0,3,2] row_mask:0xf bank_mask:0xf bound_ctrl:1
	v_mov_b32_dpp v85, v29 quad_perm:[1,0,3,2] row_mask:0xf bank_mask:0xf bound_ctrl:1
	v_pk_fma_f32 v[28:29], v[8:9], v[28:29], v[84:85] op_sel_hi:[0,1,1]
	v_mov_b32_dpp v84, v30 row_ror:8 row_mask:0xf bank_mask:0xf bound_ctrl:1
	v_mov_b32_dpp v85, v31 row_ror:8 row_mask:0xf bank_mask:0xf bound_ctrl:1
	v_pk_fma_f32 v[30:31], v[4:5], v[30:31], v[84:85] op_sel_hi:[0,1,1]
	v_pk_mul_f32 v[84:85], v[30:31], v[10:11] op_sel_hi:[1,0]
	s_nop 0
	v_pk_fma_f32 v[30:31], v[30:31], v[10:11], v[84:85] op_sel:[1,1,0] op_sel_hi:[0,1,1] neg_lo:[0,1,0]
	ds_swizzle_b32 v84, v30 offset:swizzle(SWAP,4)
	ds_swizzle_b32 v85, v31 offset:swizzle(SWAP,4)
	s_waitcnt lgkmcnt(0)
	v_pk_fma_f32 v[30:31], v[4:5], v[30:31], v[84:85] op_sel:[1,0,0]
	s_nop 0
	v_pk_mul_f32 v[84:85], v[30:31], v[0:1] op_sel_hi:[1,0]
	s_nop 0
	v_pk_fma_f32 v[30:31], v[30:31], v[0:1], v[84:85] op_sel:[1,1,0] op_sel_hi:[0,1,1] neg_lo:[0,1,0]
	s_nop 1
	v_mov_b32_dpp v84, v30 quad_perm:[2,3,0,1] row_mask:0xf bank_mask:0xf bound_ctrl:1
	v_mov_b32_dpp v85, v31 quad_perm:[2,3,0,1] row_mask:0xf bank_mask:0xf bound_ctrl:1
	v_pk_fma_f32 v[30:31], v[6:7], v[30:31], v[84:85] op_sel_hi:[0,1,1]
	v_pk_mul_f32 v[84:85], v[30:31], v[2:3] op_sel_hi:[1,0]
	s_nop 0
	v_pk_fma_f32 v[30:31], v[30:31], v[2:3], v[84:85] op_sel:[1,1,0] op_sel_hi:[0,1,1] neg_lo:[0,1,0]
	s_nop 1
	v_mov_b32_dpp v84, v30 quad_perm:[1,0,3,2] row_mask:0xf bank_mask:0xf bound_ctrl:1
	v_mov_b32_dpp v85, v31 quad_perm:[1,0,3,2] row_mask:0xf bank_mask:0xf bound_ctrl:1
	v_pk_fma_f32 v[30:31], v[8:9], v[30:31], v[84:85] op_sel_hi:[0,1,1]
	v_mov_b32_dpp v84, v32 row_ror:8 row_mask:0xf bank_mask:0xf bound_ctrl:1
	v_mov_b32_dpp v85, v33 row_ror:8 row_mask:0xf bank_mask:0xf bound_ctrl:1
	v_pk_fma_f32 v[32:33], v[4:5], v[32:33], v[84:85] op_sel_hi:[0,1,1]
	v_pk_mul_f32 v[84:85], v[32:33], v[10:11] op_sel_hi:[1,0]
	s_nop 0
	v_pk_fma_f32 v[32:33], v[32:33], v[10:11], v[84:85] op_sel:[1,1,0] op_sel_hi:[0,1,1] neg_lo:[0,1,0]
	ds_swizzle_b32 v84, v32 offset:swizzle(SWAP,4)
	ds_swizzle_b32 v85, v33 offset:swizzle(SWAP,4)
	s_waitcnt lgkmcnt(0)
	v_pk_fma_f32 v[32:33], v[4:5], v[32:33], v[84:85] op_sel:[1,0,0]
	s_nop 0
	v_pk_mul_f32 v[84:85], v[32:33], v[0:1] op_sel_hi:[1,0]
	s_nop 0
	v_pk_fma_f32 v[32:33], v[32:33], v[0:1], v[84:85] op_sel:[1,1,0] op_sel_hi:[0,1,1] neg_lo:[0,1,0]
	s_nop 1
	v_mov_b32_dpp v84, v32 quad_perm:[2,3,0,1] row_mask:0xf bank_mask:0xf bound_ctrl:1
	v_mov_b32_dpp v85, v33 quad_perm:[2,3,0,1] row_mask:0xf bank_mask:0xf bound_ctrl:1
	v_pk_fma_f32 v[32:33], v[6:7], v[32:33], v[84:85] op_sel_hi:[0,1,1]
	v_pk_mul_f32 v[84:85], v[32:33], v[2:3] op_sel_hi:[1,0]
	s_nop 0
	v_pk_fma_f32 v[32:33], v[32:33], v[2:3], v[84:85] op_sel:[1,1,0] op_sel_hi:[0,1,1] neg_lo:[0,1,0]
	s_nop 1
	v_mov_b32_dpp v84, v32 quad_perm:[1,0,3,2] row_mask:0xf bank_mask:0xf bound_ctrl:1
	v_mov_b32_dpp v85, v33 quad_perm:[1,0,3,2] row_mask:0xf bank_mask:0xf bound_ctrl:1
	v_pk_fma_f32 v[32:33], v[8:9], v[32:33], v[84:85] op_sel_hi:[0,1,1]
	v_mov_b32_dpp v84, v34 row_ror:8 row_mask:0xf bank_mask:0xf bound_ctrl:1
	v_mov_b32_dpp v85, v35 row_ror:8 row_mask:0xf bank_mask:0xf bound_ctrl:1
	v_pk_fma_f32 v[34:35], v[4:5], v[34:35], v[84:85] op_sel_hi:[0,1,1]
	v_pk_mul_f32 v[84:85], v[34:35], v[10:11] op_sel_hi:[1,0]
	s_nop 0
	v_pk_fma_f32 v[34:35], v[34:35], v[10:11], v[84:85] op_sel:[1,1,0] op_sel_hi:[0,1,1] neg_lo:[0,1,0]
	ds_swizzle_b32 v84, v34 offset:swizzle(SWAP,4)
	ds_swizzle_b32 v85, v35 offset:swizzle(SWAP,4)
	s_waitcnt lgkmcnt(0)
	v_pk_fma_f32 v[34:35], v[4:5], v[34:35], v[84:85] op_sel:[1,0,0]
	s_nop 0
	v_pk_mul_f32 v[84:85], v[34:35], v[0:1] op_sel_hi:[1,0]
	s_nop 0
	v_pk_fma_f32 v[34:35], v[34:35], v[0:1], v[84:85] op_sel:[1,1,0] op_sel_hi:[0,1,1] neg_lo:[0,1,0]
	s_nop 1
	v_mov_b32_dpp v84, v34 quad_perm:[2,3,0,1] row_mask:0xf bank_mask:0xf bound_ctrl:1
	v_mov_b32_dpp v85, v35 quad_perm:[2,3,0,1] row_mask:0xf bank_mask:0xf bound_ctrl:1
	v_pk_fma_f32 v[34:35], v[6:7], v[34:35], v[84:85] op_sel_hi:[0,1,1]
	v_pk_mul_f32 v[84:85], v[34:35], v[2:3] op_sel_hi:[1,0]
	s_nop 0
	v_pk_fma_f32 v[34:35], v[34:35], v[2:3], v[84:85] op_sel:[1,1,0] op_sel_hi:[0,1,1] neg_lo:[0,1,0]
	s_nop 1
	v_mov_b32_dpp v84, v34 quad_perm:[1,0,3,2] row_mask:0xf bank_mask:0xf bound_ctrl:1
	v_mov_b32_dpp v85, v35 quad_perm:[1,0,3,2] row_mask:0xf bank_mask:0xf bound_ctrl:1
	v_pk_fma_f32 v[34:35], v[8:9], v[34:35], v[84:85] op_sel_hi:[0,1,1]
	v_mov_b32_dpp v84, v36 row_ror:8 row_mask:0xf bank_mask:0xf bound_ctrl:1
	v_mov_b32_dpp v85, v37 row_ror:8 row_mask:0xf bank_mask:0xf bound_ctrl:1
	v_pk_fma_f32 v[36:37], v[4:5], v[36:37], v[84:85] op_sel_hi:[0,1,1]
	v_pk_mul_f32 v[84:85], v[36:37], v[10:11] op_sel_hi:[1,0]
	s_nop 0
	v_pk_fma_f32 v[36:37], v[36:37], v[10:11], v[84:85] op_sel:[1,1,0] op_sel_hi:[0,1,1] neg_lo:[0,1,0]
	ds_swizzle_b32 v84, v36 offset:swizzle(SWAP,4)
	ds_swizzle_b32 v85, v37 offset:swizzle(SWAP,4)
	s_waitcnt lgkmcnt(0)
; __device__ __forceinline__ float lx1(float v) { return __int_as_float(__builtin_amdgcn_update_dpp(0, __float_as_int(v), 0xB1, 0xF, 0xF, true)); }
; __device__ __forceinline__ float lx2(float v) { return __int_as_float(__builtin_amdgcn_update_dpp(0, __float_as_int(v), 0x4E, 0xF, 0xF, true)); }
; __device__ __forceinline__ float lx4(float v) { return __int_as_float(__builtin_amdgcn_ds_swizzle(__float_as_int(v), 0x101F)); }
; __device__ __forceinline__ float lx8(float v) { return __int_as_float(__builtin_amdgcn_update_dpp(0, __float_as_int(v), 0x128, 0xF, 0xF, true)); }
; __device__ __forceinline__ void fft_forward(f2 (&x)[32], LAS f2* X, int t, LAS const float* W1, LAS const M2C* MC) {
;     ...
;     for (int p = 0; p < 32; ++p) {
;         f2 v = x[p], pr;
;         pr = (f2){lx8(v.x), lx8(v.y)}; v = cmulr(pr + v * c.s8, t8);
;         pr = (f2){lx4(v.x), lx4(v.y)}; v = cmulr(pr + v * c.s4, t4);
;         pr = (f2){lx2(v.x), lx2(v.y)}; v = cmulr(pr + v * c.s2, t2);
;         pr = (f2){lx1(v.x), lx1(v.y)}; x[p] = pr + v * c.s1;
;     }
	v_pk_fma_f32 v[36:37], v[4:5], v[36:37], v[84:85] op_sel:[1,0,0]
	s_nop 0
	v_pk_mul_f32 v[84:85], v[36:37], v[0:1] op_sel_hi:[1,0]
	s_nop 0
	v_pk_fma_f32 v[36:37], v[36:37], v[0:1], v[84:85] op_sel:[1,1,0] op_sel_hi:[0,1,1] neg_lo:[0,1,0]
	s_nop 1
	v_mov_b32_dpp v84, v36 quad_perm:[2,3,0,1] row_mask:0xf bank_mask:0xf bound_ctrl:1
	v_mov_b32_dpp v85, v37 quad_perm:[2,3,0,1] row_mask:0xf bank_mask:0xf bound_ctrl:1
	v_pk_fma_f32 v[36:37], v[6:7], v[36:37], v[84:85] op_sel_hi:[0,1,1]
	v_pk_mul_f32 v[84:85], v[36:37], v[2:3] op_sel_hi:[1,0]
	s_nop 0
	v_pk_fma_f32 v[36:37], v[36:37], v[2:3], v[84:85] op_sel:[1,1,0] op_sel_hi:[0,1,1] neg_lo:[0,1,0]
	s_nop 1
	v_mov_b32_dpp v84, v36 quad_perm:[1,0,3,2] row_mask:0xf bank_mask:0xf bound_ctrl:1
	v_mov_b32_dpp v85, v37 quad_perm:[1,0,3,2] row_mask:0xf bank_mask:0xf bound_ctrl:1
	v_pk_fma_f32 v[36:37], v[8:9], v[36:37], v[84:85] op_sel_hi:[0,1,1]
	v_mov_b32_dpp v84, v38 row_ror:8 row_mask:0xf bank_mask:0xf bound_ctrl:1
	v_mov_b32_dpp v85, v39 row_ror:8 row_mask:0xf bank_mask:0xf bound_ctrl:1
	v_pk_fma_f32 v[38:39], v[4:5], v[38:39], v[84:85] op_sel_hi:[0,1,1]
	v_pk_mul_f32 v[84:85], v[38:39], v[10:11] op_sel_hi:[1,0]
	s_nop 0
	v_pk_fma_f32 v[38:39], v[38:39], v[10:11], v[84:85] op_sel:[1,1,0] op_sel_hi:[0,1,1] neg_lo:[0,1,0]
	ds_swizzle_b32 v84, v38 offset:swizzle(SWAP,4)
	ds_swizzle_b32 v85, v39 offset:swizzle(SWAP,4)
	s_waitcnt lgkmcnt(0)
	v_pk_fma_f32 v[38:39], v[4:5], v[38:39], v[84:85] op_sel:[1,0,0]
	s_nop 0
	v_pk_mul_f32 v[84:85], v[38:39], v[0:1] op_sel_hi:[1,0]
	s_nop 0
	v_pk_fma_f32 v[38:39], v[38:39], v[0:1], v[84:85] op_sel:[1,1,0] op_sel_hi:[0,1,1] neg_lo:[0,1,0]
	s_nop 1
	v_mov_b32_dpp v84, v38 quad_perm:[2,3,0,1] row_mask:0xf bank_mask:0xf bound_ctrl:1
	v_mov_b32_dpp v85, v39 quad_perm:[2,3,0,1] row_mask:0xf bank_mask:0xf bound_ctrl:1
	v_pk_fma_f32 v[38:39], v[6:7], v[38:39], v[84:85] op_sel_hi:[0,1,1]
	v_pk_mul_f32 v[84:85], v[38:39], v[2:3] op_sel_hi:[1,0]
	s_nop 0
	v_pk_fma_f32 v[38:39], v[38:39], v[2:3], v[84:85] op_sel:[1,1,0] op_sel_hi:[0,1,1] neg_lo:[0,1,0]
	s_nop 1
	v_mov_b32_dpp v84, v38 quad_perm:[1,0,3,2] row_mask:0xf bank_mask:0xf bound_ctrl:1
	v_mov_b32_dpp v85, v39 quad_perm:[1,0,3,2] row_mask:0xf bank_mask:0xf bound_ctrl:1
	v_pk_fma_f32 v[38:39], v[8:9], v[38:39], v[84:85] op_sel_hi:[0,1,1]
	v_mov_b32_dpp v84, v40 row_ror:8 row_mask:0xf bank_mask:0xf bound_ctrl:1
	v_mov_b32_dpp v85, v41 row_ror:8 row_mask:0xf bank_mask:0xf bound_ctrl:1
	v_pk_fma_f32 v[40:41], v[4:5], v[40:41], v[84:85] op_sel_hi:[0,1,1]
	v_pk_mul_f32 v[84:85], v[40:41], v[10:11] op_sel_hi:[1,0]
	s_nop 0
	v_pk_fma_f32 v[40:41], v[40:41], v[10:11], v[84:85] op_sel:[1,1,0] op_sel_hi:[0,1,1] neg_lo:[0,1,0]
	ds_swizzle_b32 v84, v40 offset:swizzle(SWAP,4)
	ds_swizzle_b32 v85, v41 offset:swizzle(SWAP,4)
	s_waitcnt lgkmcnt(0)
	v_pk_fma_f32 v[40:41], v[4:5], v[40:41], v[84:85] op_sel:[1,0,0]
	s_nop 0
	v_pk_mul_f32 v[84:85], v[40:41], v[0:1] op_sel_hi:[1,0]
	s_nop 0
	v_pk_fma_f32 v[40:41], v[40:41], v[0:1], v[84:85] op_sel:[1,1,0] op_sel_hi:[0,1,1] neg_lo:[0,1,0]
	s_nop 1
	v_mov_b32_dpp v84, v40 quad_perm:[2,3,0,1] row_mask:0xf bank_mask:0xf bound_ctrl:1
	v_mov_b32_dpp v85, v41 quad_perm:[2,3,0,1] row_mask:0xf bank_mask:0xf bound_ctrl:1
	v_pk_fma_f32 v[40:41], v[6:7], v[40:41], v[84:85] op_sel_hi:[0,1,1]
	v_pk_mul_f32 v[84:85], v[40:41], v[2:3] op_sel_hi:[1,0]
	s_nop 0
	v_pk_fma_f32 v[40:41], v[40:41], v[2:3], v[84:85] op_sel:[1,1,0] op_sel_hi:[0,1,1] neg_lo:[0,1,0]
	s_nop 1
	v_mov_b32_dpp v84, v40 quad_perm:[1,0,3,2] row_mask:0xf bank_mask:0xf bound_ctrl:1
	v_mov_b32_dpp v85, v41 quad_perm:[1,0,3,2] row_mask:0xf bank_mask:0xf bound_ctrl:1
	v_pk_fma_f32 v[40:41], v[8:9], v[40:41], v[84:85] op_sel_hi:[0,1,1]
	v_mov_b32_dpp v84, v42 row_ror:8 row_mask:0xf bank_mask:0xf bound_ctrl:1
	v_mov_b32_dpp v85, v43 row_ror:8 row_mask:0xf bank_mask:0xf bound_ctrl:1
	v_pk_fma_f32 v[42:43], v[4:5], v[42:43], v[84:85] op_sel_hi:[0,1,1]
	v_pk_mul_f32 v[84:85], v[42:43], v[10:11] op_sel_hi:[1,0]
	s_nop 0
	v_pk_fma_f32 v[42:43], v[42:43], v[10:11], v[84:85] op_sel:[1,1,0] op_sel_hi:[0,1,1] neg_lo:[0,1,0]
	ds_swizzle_b32 v84, v42 offset:swizzle(SWAP,4)
	ds_swizzle_b32 v85, v43 offset:swizzle(SWAP,4)
	s_waitcnt lgkmcnt(0)
	v_pk_fma_f32 v[42:43], v[4:5], v[42:43], v[84:85] op_sel:[1,0,0]
	s_nop 0
	v_pk_mul_f32 v[84:85], v[42:43], v[0:1] op_sel_hi:[1,0]
	s_nop 0
	v_pk_fma_f32 v[42:43], v[42:43], v[0:1], v[84:85] op_sel:[1,1,0] op_sel_hi:[0,1,1] neg_lo:[0,1,0]
	s_nop 1
	v_mov_b32_dpp v84, v42 quad_perm:[2,3,0,1] row_mask:0xf bank_mask:0xf bound_ctrl:1
	v_mov_b32_dpp v85, v43 quad_perm:[2,3,0,1] row_mask:0xf bank_mask:0xf bound_ctrl:1
	v_pk_fma_f32 v[42:43], v[6:7], v[42:43], v[84:85] op_sel_hi:[0,1,1]
	v_pk_mul_f32 v[84:85], v[42:43], v[2:3] op_sel_hi:[1,0]
	s_nop 0
	v_pk_fma_f32 v[42:43], v[42:43], v[2:3], v[84:85] op_sel:[1,1,0] op_sel_hi:[0,1,1] neg_lo:[0,1,0]
	s_nop 1
	v_mov_b32_dpp v84, v42 quad_perm:[1,0,3,2] row_mask:0xf bank_mask:0xf bound_ctrl:1
	v_mov_b32_dpp v85, v43 quad_perm:[1,0,3,2] row_mask:0xf bank_mask:0xf bound_ctrl:1
	v_pk_fma_f32 v[42:43], v[8:9], v[42:43], v[84:85] op_sel_hi:[0,1,1]
	v_mov_b32_dpp v84, v44 row_ror:8 row_mask:0xf bank_mask:0xf bound_ctrl:1
	v_mov_b32_dpp v85, v45 row_ror:8 row_mask:0xf bank_mask:0xf bound_ctrl:1
	v_pk_fma_f32 v[44:45], v[4:5], v[44:45], v[84:85] op_sel_hi:[0,1,1]
	v_pk_mul_f32 v[84:85], v[44:45], v[10:11] op_sel_hi:[1,0]
	s_nop 0
	v_pk_fma_f32 v[44:45], v[44:45], v[10:11], v[84:85] op_sel:[1,1,0] op_sel_hi:[0,1,1] neg_lo:[0,1,0]
	ds_swizzle_b32 v84, v44 offset:swizzle(SWAP,4)
	ds_swizzle_b32 v85, v45 offset:swizzle(SWAP,4)
	s_waitcnt lgkmcnt(0)
; __device__ __forceinline__ float lx1(float v) { return __int_as_float(__builtin_amdgcn_update_dpp(0, __float_as_int(v), 0xB1, 0xF, 0xF, true)); }
; __device__ __forceinline__ float lx2(float v) { return __int_as_float(__builtin_amdgcn_update_dpp(0, __float_as_int(v), 0x4E, 0xF, 0xF, true)); }
; __device__ __forceinline__ float lx4(float v) { return __int_as_float(__builtin_amdgcn_ds_swizzle(__float_as_int(v), 0x101F)); }
; __device__ __forceinline__ float lx8(float v) { return __int_as_float(__builtin_amdgcn_update_dpp(0, __float_as_int(v), 0x128, 0xF, 0xF, true)); }
; __device__ __forceinline__ void fft_forward(f2 (&x)[32], LAS f2* X, int t, LAS const float* W1, LAS const M2C* MC) {
;     ...
;     for (int p = 0; p < 32; ++p) {
;         f2 v = x[p], pr;
;         pr = (f2){lx8(v.x), lx8(v.y)}; v = cmulr(pr + v * c.s8, t8);
;         pr = (f2){lx4(v.x), lx4(v.y)}; v = cmulr(pr + v * c.s4, t4);
;         pr = (f2){lx2(v.x), lx2(v.y)}; v = cmulr(pr + v * c.s2, t2);
;         pr = (f2){lx1(v.x), lx1(v.y)}; x[p] = pr + v * c.s1;
;     }
	v_pk_fma_f32 v[44:45], v[4:5], v[44:45], v[84:85] op_sel:[1,0,0]
	s_nop 0
	v_pk_mul_f32 v[84:85], v[44:45], v[0:1] op_sel_hi:[1,0]
	s_nop 0
	v_pk_fma_f32 v[44:45], v[44:45], v[0:1], v[84:85] op_sel:[1,1,0] op_sel_hi:[0,1,1] neg_lo:[0,1,0]
	s_nop 1
	v_mov_b32_dpp v84, v44 quad_perm:[2,3,0,1] row_mask:0xf bank_mask:0xf bound_ctrl:1
	v_mov_b32_dpp v85, v45 quad_perm:[2,3,0,1] row_mask:0xf bank_mask:0xf bound_ctrl:1
	v_pk_fma_f32 v[44:45], v[6:7], v[44:45], v[84:85] op_sel_hi:[0,1,1]
	v_pk_mul_f32 v[84:85], v[44:45], v[2:3] op_sel_hi:[1,0]
	s_nop 0
	v_pk_fma_f32 v[44:45], v[44:45], v[2:3], v[84:85] op_sel:[1,1,0] op_sel_hi:[0,1,1] neg_lo:[0,1,0]
	s_nop 1
	v_mov_b32_dpp v84, v44 quad_perm:[1,0,3,2] row_mask:0xf bank_mask:0xf bound_ctrl:1
	v_mov_b32_dpp v85, v45 quad_perm:[1,0,3,2] row_mask:0xf bank_mask:0xf bound_ctrl:1
	v_pk_fma_f32 v[44:45], v[8:9], v[44:45], v[84:85] op_sel_hi:[0,1,1]
	v_mov_b32_dpp v84, v46 row_ror:8 row_mask:0xf bank_mask:0xf bound_ctrl:1
	v_mov_b32_dpp v85, v47 row_ror:8 row_mask:0xf bank_mask:0xf bound_ctrl:1
	v_pk_fma_f32 v[46:47], v[4:5], v[46:47], v[84:85] op_sel_hi:[0,1,1]
	v_pk_mul_f32 v[84:85], v[46:47], v[10:11] op_sel_hi:[1,0]
	s_nop 0
	v_pk_fma_f32 v[46:47], v[46:47], v[10:11], v[84:85] op_sel:[1,1,0] op_sel_hi:[0,1,1] neg_lo:[0,1,0]
	ds_swizzle_b32 v84, v46 offset:swizzle(SWAP,4)
	ds_swizzle_b32 v85, v47 offset:swizzle(SWAP,4)
	s_waitcnt lgkmcnt(0)
	v_pk_fma_f32 v[46:47], v[4:5], v[46:47], v[84:85] op_sel:[1,0,0]
	s_nop 0
	v_pk_mul_f32 v[84:85], v[46:47], v[0:1] op_sel_hi:[1,0]
	s_nop 0
	v_pk_fma_f32 v[46:47], v[46:47], v[0:1], v[84:85] op_sel:[1,1,0] op_sel_hi:[0,1,1] neg_lo:[0,1,0]
	s_nop 1
	v_mov_b32_dpp v84, v46 quad_perm:[2,3,0,1] row_mask:0xf bank_mask:0xf bound_ctrl:1
	v_mov_b32_dpp v85, v47 quad_perm:[2,3,0,1] row_mask:0xf bank_mask:0xf bound_ctrl:1
	v_pk_fma_f32 v[46:47], v[6:7], v[46:47], v[84:85] op_sel_hi:[0,1,1]
	v_pk_mul_f32 v[84:85], v[46:47], v[2:3] op_sel_hi:[1,0]
	s_nop 0
	v_pk_fma_f32 v[46:47], v[46:47], v[2:3], v[84:85] op_sel:[1,1,0] op_sel_hi:[0,1,1] neg_lo:[0,1,0]
	s_nop 1
	v_mov_b32_dpp v84, v46 quad_perm:[1,0,3,2] row_mask:0xf bank_mask:0xf bound_ctrl:1
	v_mov_b32_dpp v85, v47 quad_perm:[1,0,3,2] row_mask:0xf bank_mask:0xf bound_ctrl:1
	v_pk_fma_f32 v[46:47], v[8:9], v[46:47], v[84:85] op_sel_hi:[0,1,1]
	v_mov_b32_dpp v84, v48 row_ror:8 row_mask:0xf bank_mask:0xf bound_ctrl:1
	v_mov_b32_dpp v85, v49 row_ror:8 row_mask:0xf bank_mask:0xf bound_ctrl:1
	v_pk_fma_f32 v[48:49], v[4:5], v[48:49], v[84:85] op_sel_hi:[0,1,1]
	v_pk_mul_f32 v[84:85], v[48:49], v[10:11] op_sel_hi:[1,0]
	s_nop 0
	v_pk_fma_f32 v[48:49], v[48:49], v[10:11], v[84:85] op_sel:[1,1,0] op_sel_hi:[0,1,1] neg_lo:[0,1,0]
	ds_swizzle_b32 v84, v48 offset:swizzle(SWAP,4)
	ds_swizzle_b32 v85, v49 offset:swizzle(SWAP,4)
	s_waitcnt lgkmcnt(0)
	v_pk_fma_f32 v[48:49], v[4:5], v[48:49], v[84:85] op_sel:[1,0,0]
	s_nop 0
	v_pk_mul_f32 v[84:85], v[48:49], v[0:1] op_sel_hi:[1,0]
	s_nop 0
	v_pk_fma_f32 v[48:49], v[48:49], v[0:1], v[84:85] op_sel:[1,1,0] op_sel_hi:[0,1,1] neg_lo:[0,1,0]
	s_nop 1
	v_mov_b32_dpp v84, v48 quad_perm:[2,3,0,1] row_mask:0xf bank_mask:0xf bound_ctrl:1
	v_mov_b32_dpp v85, v49 quad_perm:[2,3,0,1] row_mask:0xf bank_mask:0xf bound_ctrl:1
	v_pk_fma_f32 v[48:49], v[6:7], v[48:49], v[84:85] op_sel_hi:[0,1,1]
	v_pk_mul_f32 v[84:85], v[48:49], v[2:3] op_sel_hi:[1,0]
	s_nop 0
	v_pk_fma_f32 v[48:49], v[48:49], v[2:3], v[84:85] op_sel:[1,1,0] op_sel_hi:[0,1,1] neg_lo:[0,1,0]
	s_nop 1
	v_mov_b32_dpp v84, v48 quad_perm:[1,0,3,2] row_mask:0xf bank_mask:0xf bound_ctrl:1
	v_mov_b32_dpp v85, v49 quad_perm:[1,0,3,2] row_mask:0xf bank_mask:0xf bound_ctrl:1
	v_pk_fma_f32 v[48:49], v[8:9], v[48:49], v[84:85] op_sel_hi:[0,1,1]
	v_mov_b32_dpp v84, v50 row_ror:8 row_mask:0xf bank_mask:0xf bound_ctrl:1
	v_mov_b32_dpp v85, v51 row_ror:8 row_mask:0xf bank_mask:0xf bound_ctrl:1
	v_pk_fma_f32 v[50:51], v[4:5], v[50:51], v[84:85] op_sel_hi:[0,1,1]
	v_pk_mul_f32 v[84:85], v[50:51], v[10:11] op_sel_hi:[1,0]
	s_nop 0
	v_pk_fma_f32 v[50:51], v[50:51], v[10:11], v[84:85] op_sel:[1,1,0] op_sel_hi:[0,1,1] neg_lo:[0,1,0]
	ds_swizzle_b32 v84, v50 offset:swizzle(SWAP,4)
	ds_swizzle_b32 v85, v51 offset:swizzle(SWAP,4)
	s_waitcnt lgkmcnt(0)
	v_pk_fma_f32 v[50:51], v[4:5], v[50:51], v[84:85] op_sel:[1,0,0]
	s_nop 0
	v_pk_mul_f32 v[84:85], v[50:51], v[0:1] op_sel_hi:[1,0]
	s_nop 0
	v_pk_fma_f32 v[50:51], v[50:51], v[0:1], v[84:85] op_sel:[1,1,0] op_sel_hi:[0,1,1] neg_lo:[0,1,0]
	s_nop 1
	v_mov_b32_dpp v84, v50 quad_perm:[2,3,0,1] row_mask:0xf bank_mask:0xf bound_ctrl:1
	v_mov_b32_dpp v85, v51 quad_perm:[2,3,0,1] row_mask:0xf bank_mask:0xf bound_ctrl:1
	v_pk_fma_f32 v[50:51], v[6:7], v[50:51], v[84:85] op_sel_hi:[0,1,1]
	v_pk_mul_f32 v[84:85], v[50:51], v[2:3] op_sel_hi:[1,0]
	s_nop 0
	v_pk_fma_f32 v[50:51], v[50:51], v[2:3], v[84:85] op_sel:[1,1,0] op_sel_hi:[0,1,1] neg_lo:[0,1,0]
	s_nop 1
	v_mov_b32_dpp v84, v50 quad_perm:[1,0,3,2] row_mask:0xf bank_mask:0xf bound_ctrl:1
	v_mov_b32_dpp v85, v51 quad_perm:[1,0,3,2] row_mask:0xf bank_mask:0xf bound_ctrl:1
	v_pk_fma_f32 v[50:51], v[8:9], v[50:51], v[84:85] op_sel_hi:[0,1,1]
	v_mov_b32_dpp v84, v52 row_ror:8 row_mask:0xf bank_mask:0xf bound_ctrl:1
	v_mov_b32_dpp v85, v53 row_ror:8 row_mask:0xf bank_mask:0xf bound_ctrl:1
	v_pk_fma_f32 v[52:53], v[4:5], v[52:53], v[84:85] op_sel_hi:[0,1,1]
	v_pk_mul_f32 v[84:85], v[52:53], v[10:11] op_sel_hi:[1,0]
	s_nop 0
	v_pk_fma_f32 v[52:53], v[52:53], v[10:11], v[84:85] op_sel:[1,1,0] op_sel_hi:[0,1,1] neg_lo:[0,1,0]
	ds_swizzle_b32 v84, v52 offset:swizzle(SWAP,4)
	ds_swizzle_b32 v85, v53 offset:swizzle(SWAP,4)
	s_waitcnt lgkmcnt(0)
; __device__ __forceinline__ float lx1(float v) { return __int_as_float(__builtin_amdgcn_update_dpp(0, __float_as_int(v), 0xB1, 0xF, 0xF, true)); }
; __device__ __forceinline__ float lx2(float v) { return __int_as_float(__builtin_amdgcn_update_dpp(0, __float_as_int(v), 0x4E, 0xF, 0xF, true)); }
; __device__ __forceinline__ float lx4(float v) { return __int_as_float(__builtin_amdgcn_ds_swizzle(__float_as_int(v), 0x101F)); }
; __device__ __forceinline__ float lx8(float v) { return __int_as_float(__builtin_amdgcn_update_dpp(0, __float_as_int(v), 0x128, 0xF, 0xF, true)); }
; __device__ __forceinline__ void fft_forward(f2 (&x)[32], LAS f2* X, int t, LAS const float* W1, LAS const M2C* MC) {
;     ...
;     for (int p = 0; p < 32; ++p) {
;         f2 v = x[p], pr;
;         pr = (f2){lx8(v.x), lx8(v.y)}; v = cmulr(pr + v * c.s8, t8);
;         pr = (f2){lx4(v.x), lx4(v.y)}; v = cmulr(pr + v * c.s4, t4);
;         pr = (f2){lx2(v.x), lx2(v.y)}; v = cmulr(pr + v * c.s2, t2);
;         pr = (f2){lx1(v.x), lx1(v.y)}; x[p] = pr + v * c.s1;
;     }
	v_pk_fma_f32 v[52:53], v[4:5], v[52:53], v[84:85] op_sel:[1,0,0]
	s_nop 0
	v_pk_mul_f32 v[84:85], v[52:53], v[0:1] op_sel_hi:[1,0]
	s_nop 0
	v_pk_fma_f32 v[52:53], v[52:53], v[0:1], v[84:85] op_sel:[1,1,0] op_sel_hi:[0,1,1] neg_lo:[0,1,0]
	s_nop 1
	v_mov_b32_dpp v84, v52 quad_perm:[2,3,0,1] row_mask:0xf bank_mask:0xf bound_ctrl:1
	v_mov_b32_dpp v85, v53 quad_perm:[2,3,0,1] row_mask:0xf bank_mask:0xf bound_ctrl:1
	v_pk_fma_f32 v[52:53], v[6:7], v[52:53], v[84:85] op_sel_hi:[0,1,1]
	v_pk_mul_f32 v[84:85], v[52:53], v[2:3] op_sel_hi:[1,0]
	s_nop 0
	v_pk_fma_f32 v[52:53], v[52:53], v[2:3], v[84:85] op_sel:[1,1,0] op_sel_hi:[0,1,1] neg_lo:[0,1,0]
	s_nop 1
	v_mov_b32_dpp v84, v52 quad_perm:[1,0,3,2] row_mask:0xf bank_mask:0xf bound_ctrl:1
	v_mov_b32_dpp v85, v53 quad_perm:[1,0,3,2] row_mask:0xf bank_mask:0xf bound_ctrl:1
	v_pk_fma_f32 v[52:53], v[8:9], v[52:53], v[84:85] op_sel_hi:[0,1,1]
	v_mov_b32_dpp v84, v54 row_ror:8 row_mask:0xf bank_mask:0xf bound_ctrl:1
	v_mov_b32_dpp v85, v55 row_ror:8 row_mask:0xf bank_mask:0xf bound_ctrl:1
	v_pk_fma_f32 v[54:55], v[4:5], v[54:55], v[84:85] op_sel_hi:[0,1,1]
	v_pk_mul_f32 v[84:85], v[54:55], v[10:11] op_sel_hi:[1,0]
	s_nop 0
	v_pk_fma_f32 v[54:55], v[54:55], v[10:11], v[84:85] op_sel:[1,1,0] op_sel_hi:[0,1,1] neg_lo:[0,1,0]
	ds_swizzle_b32 v84, v54 offset:swizzle(SWAP,4)
	ds_swizzle_b32 v85, v55 offset:swizzle(SWAP,4)
	s_waitcnt lgkmcnt(0)
	v_pk_fma_f32 v[54:55], v[4:5], v[54:55], v[84:85] op_sel:[1,0,0]
	s_nop 0
	v_pk_mul_f32 v[84:85], v[54:55], v[0:1] op_sel_hi:[1,0]
	s_nop 0
	v_pk_fma_f32 v[54:55], v[54:55], v[0:1], v[84:85] op_sel:[1,1,0] op_sel_hi:[0,1,1] neg_lo:[0,1,0]
	s_nop 1
	v_mov_b32_dpp v84, v54 quad_perm:[2,3,0,1] row_mask:0xf bank_mask:0xf bound_ctrl:1
	v_mov_b32_dpp v85, v55 quad_perm:[2,3,0,1] row_mask:0xf bank_mask:0xf bound_ctrl:1
	v_pk_fma_f32 v[54:55], v[6:7], v[54:55], v[84:85] op_sel_hi:[0,1,1]
	v_pk_mul_f32 v[84:85], v[54:55], v[2:3] op_sel_hi:[1,0]
	s_nop 0
	v_pk_fma_f32 v[54:55], v[54:55], v[2:3], v[84:85] op_sel:[1,1,0] op_sel_hi:[0,1,1] neg_lo:[0,1,0]
	s_nop 1
	v_mov_b32_dpp v84, v54 quad_perm:[1,0,3,2] row_mask:0xf bank_mask:0xf bound_ctrl:1
	v_mov_b32_dpp v85, v55 quad_perm:[1,0,3,2] row_mask:0xf bank_mask:0xf bound_ctrl:1
	v_pk_fma_f32 v[54:55], v[8:9], v[54:55], v[84:85] op_sel_hi:[0,1,1]
	v_mov_b32_dpp v84, v56 row_ror:8 row_mask:0xf bank_mask:0xf bound_ctrl:1
	v_mov_b32_dpp v85, v57 row_ror:8 row_mask:0xf bank_mask:0xf bound_ctrl:1
	v_pk_fma_f32 v[56:57], v[4:5], v[56:57], v[84:85] op_sel_hi:[0,1,1]
	v_pk_mul_f32 v[84:85], v[56:57], v[10:11] op_sel_hi:[1,0]
	s_nop 0
	v_pk_fma_f32 v[56:57], v[56:57], v[10:11], v[84:85] op_sel:[1,1,0] op_sel_hi:[0,1,1] neg_lo:[0,1,0]
	ds_swizzle_b32 v84, v56 offset:swizzle(SWAP,4)
	ds_swizzle_b32 v85, v57 offset:swizzle(SWAP,4)
	s_waitcnt lgkmcnt(0)
	v_pk_fma_f32 v[56:57], v[4:5], v[56:57], v[84:85] op_sel:[1,0,0]
	s_nop 0
	v_pk_mul_f32 v[84:85], v[56:57], v[0:1] op_sel_hi:[1,0]
	s_nop 0
	v_pk_fma_f32 v[56:57], v[56:57], v[0:1], v[84:85] op_sel:[1,1,0] op_sel_hi:[0,1,1] neg_lo:[0,1,0]
	s_nop 1
	v_mov_b32_dpp v84, v56 quad_perm:[2,3,0,1] row_mask:0xf bank_mask:0xf bound_ctrl:1
	v_mov_b32_dpp v85, v57 quad_perm:[2,3,0,1] row_mask:0xf bank_mask:0xf bound_ctrl:1
	v_pk_fma_f32 v[56:57], v[6:7], v[56:57], v[84:85] op_sel_hi:[0,1,1]
	v_pk_mul_f32 v[84:85], v[56:57], v[2:3] op_sel_hi:[1,0]
	s_nop 0
	v_pk_fma_f32 v[56:57], v[56:57], v[2:3], v[84:85] op_sel:[1,1,0] op_sel_hi:[0,1,1] neg_lo:[0,1,0]
	s_nop 1
	v_mov_b32_dpp v84, v56 quad_perm:[1,0,3,2] row_mask:0xf bank_mask:0xf bound_ctrl:1
	v_mov_b32_dpp v85, v57 quad_perm:[1,0,3,2] row_mask:0xf bank_mask:0xf bound_ctrl:1
	v_pk_fma_f32 v[56:57], v[8:9], v[56:57], v[84:85] op_sel_hi:[0,1,1]
	v_mov_b32_dpp v84, v58 row_ror:8 row_mask:0xf bank_mask:0xf bound_ctrl:1
	v_mov_b32_dpp v85, v59 row_ror:8 row_mask:0xf bank_mask:0xf bound_ctrl:1
	v_pk_fma_f32 v[58:59], v[4:5], v[58:59], v[84:85] op_sel_hi:[0,1,1]
	v_pk_mul_f32 v[84:85], v[58:59], v[10:11] op_sel_hi:[1,0]
	s_nop 0
	v_pk_fma_f32 v[58:59], v[58:59], v[10:11], v[84:85] op_sel:[1,1,0] op_sel_hi:[0,1,1] neg_lo:[0,1,0]
	ds_swizzle_b32 v84, v58 offset:swizzle(SWAP,4)
	ds_swizzle_b32 v85, v59 offset:swizzle(SWAP,4)
	s_waitcnt lgkmcnt(0)
	v_pk_fma_f32 v[58:59], v[4:5], v[58:59], v[84:85] op_sel:[1,0,0]
	s_nop 0
	v_pk_mul_f32 v[84:85], v[58:59], v[0:1] op_sel_hi:[1,0]
	s_nop 0
	v_pk_fma_f32 v[58:59], v[58:59], v[0:1], v[84:85] op_sel:[1,1,0] op_sel_hi:[0,1,1] neg_lo:[0,1,0]
	s_nop 1
	v_mov_b32_dpp v84, v58 quad_perm:[2,3,0,1] row_mask:0xf bank_mask:0xf bound_ctrl:1
	v_mov_b32_dpp v85, v59 quad_perm:[2,3,0,1] row_mask:0xf bank_mask:0xf bound_ctrl:1
	v_pk_fma_f32 v[58:59], v[6:7], v[58:59], v[84:85] op_sel_hi:[0,1,1]
	v_pk_mul_f32 v[84:85], v[58:59], v[2:3] op_sel_hi:[1,0]
	s_nop 0
	v_pk_fma_f32 v[58:59], v[58:59], v[2:3], v[84:85] op_sel:[1,1,0] op_sel_hi:[0,1,1] neg_lo:[0,1,0]
	s_nop 1
	v_mov_b32_dpp v84, v58 quad_perm:[1,0,3,2] row_mask:0xf bank_mask:0xf bound_ctrl:1
	v_mov_b32_dpp v85, v59 quad_perm:[1,0,3,2] row_mask:0xf bank_mask:0xf bound_ctrl:1
	v_pk_fma_f32 v[58:59], v[8:9], v[58:59], v[84:85] op_sel_hi:[0,1,1]
	v_mov_b32_dpp v84, v60 row_ror:8 row_mask:0xf bank_mask:0xf bound_ctrl:1
	v_mov_b32_dpp v85, v61 row_ror:8 row_mask:0xf bank_mask:0xf bound_ctrl:1
	v_pk_fma_f32 v[60:61], v[4:5], v[60:61], v[84:85] op_sel_hi:[0,1,1]
	v_pk_mul_f32 v[84:85], v[60:61], v[10:11] op_sel_hi:[1,0]
	s_nop 0
	v_pk_fma_f32 v[60:61], v[60:61], v[10:11], v[84:85] op_sel:[1,1,0] op_sel_hi:[0,1,1] neg_lo:[0,1,0]
	ds_swizzle_b32 v84, v60 offset:swizzle(SWAP,4)
	ds_swizzle_b32 v85, v61 offset:swizzle(SWAP,4)
	s_waitcnt lgkmcnt(0)
; __device__ __forceinline__ float lx1(float v) { return __int_as_float(__builtin_amdgcn_update_dpp(0, __float_as_int(v), 0xB1, 0xF, 0xF, true)); }
; __device__ __forceinline__ float lx2(float v) { return __int_as_float(__builtin_amdgcn_update_dpp(0, __float_as_int(v), 0x4E, 0xF, 0xF, true)); }
; __device__ __forceinline__ float lx4(float v) { return __int_as_float(__builtin_amdgcn_ds_swizzle(__float_as_int(v), 0x101F)); }
; __device__ __forceinline__ float lx8(float v) { return __int_as_float(__builtin_amdgcn_update_dpp(0, __float_as_int(v), 0x128, 0xF, 0xF, true)); }
; __device__ __forceinline__ void fft_forward(f2 (&x)[32], LAS f2* X, int t, LAS const float* W1, LAS const M2C* MC) {
;     ...
;     for (int p = 0; p < 32; ++p) {
;         f2 v = x[p], pr;
;         pr = (f2){lx8(v.x), lx8(v.y)}; v = cmulr(pr + v * c.s8, t8);
;         pr = (f2){lx4(v.x), lx4(v.y)}; v = cmulr(pr + v * c.s4, t4);
;         pr = (f2){lx2(v.x), lx2(v.y)}; v = cmulr(pr + v * c.s2, t2);
;         pr = (f2){lx1(v.x), lx1(v.y)}; x[p] = pr + v * c.s1;
;     }
	v_pk_fma_f32 v[60:61], v[4:5], v[60:61], v[84:85] op_sel:[1,0,0]
	s_nop 0
	v_pk_mul_f32 v[84:85], v[60:61], v[0:1] op_sel_hi:[1,0]
	s_nop 0
	v_pk_fma_f32 v[60:61], v[60:61], v[0:1], v[84:85] op_sel:[1,1,0] op_sel_hi:[0,1,1] neg_lo:[0,1,0]
	s_nop 1
	v_mov_b32_dpp v84, v60 quad_perm:[2,3,0,1] row_mask:0xf bank_mask:0xf bound_ctrl:1
	v_mov_b32_dpp v85, v61 quad_perm:[2,3,0,1] row_mask:0xf bank_mask:0xf bound_ctrl:1
	v_pk_fma_f32 v[60:61], v[6:7], v[60:61], v[84:85] op_sel_hi:[0,1,1]
	v_pk_mul_f32 v[84:85], v[60:61], v[2:3] op_sel_hi:[1,0]
	s_nop 0
	v_pk_fma_f32 v[60:61], v[60:61], v[2:3], v[84:85] op_sel:[1,1,0] op_sel_hi:[0,1,1] neg_lo:[0,1,0]
	s_nop 1
	v_mov_b32_dpp v84, v60 quad_perm:[1,0,3,2] row_mask:0xf bank_mask:0xf bound_ctrl:1
	v_mov_b32_dpp v85, v61 quad_perm:[1,0,3,2] row_mask:0xf bank_mask:0xf bound_ctrl:1
	v_pk_fma_f32 v[60:61], v[8:9], v[60:61], v[84:85] op_sel_hi:[0,1,1]
	v_mov_b32_dpp v84, v62 row_ror:8 row_mask:0xf bank_mask:0xf bound_ctrl:1
	v_mov_b32_dpp v85, v63 row_ror:8 row_mask:0xf bank_mask:0xf bound_ctrl:1
	v_pk_fma_f32 v[62:63], v[4:5], v[62:63], v[84:85] op_sel_hi:[0,1,1]
	v_pk_mul_f32 v[84:85], v[62:63], v[10:11] op_sel_hi:[1,0]
	s_nop 0
	v_pk_fma_f32 v[62:63], v[62:63], v[10:11], v[84:85] op_sel:[1,1,0] op_sel_hi:[0,1,1] neg_lo:[0,1,0]
	ds_swizzle_b32 v84, v62 offset:swizzle(SWAP,4)
	ds_swizzle_b32 v85, v63 offset:swizzle(SWAP,4)
	s_waitcnt lgkmcnt(0)
	v_pk_fma_f32 v[62:63], v[4:5], v[62:63], v[84:85] op_sel:[1,0,0]
	s_nop 0
	v_pk_mul_f32 v[84:85], v[62:63], v[0:1] op_sel_hi:[1,0]
	s_nop 0
	v_pk_fma_f32 v[62:63], v[62:63], v[0:1], v[84:85] op_sel:[1,1,0] op_sel_hi:[0,1,1] neg_lo:[0,1,0]
	s_nop 1
	v_mov_b32_dpp v84, v62 quad_perm:[2,3,0,1] row_mask:0xf bank_mask:0xf bound_ctrl:1
	v_mov_b32_dpp v85, v63 quad_perm:[2,3,0,1] row_mask:0xf bank_mask:0xf bound_ctrl:1
	v_pk_fma_f32 v[62:63], v[6:7], v[62:63], v[84:85] op_sel_hi:[0,1,1]
	v_pk_mul_f32 v[84:85], v[62:63], v[2:3] op_sel_hi:[1,0]
	s_nop 0
	v_pk_fma_f32 v[62:63], v[62:63], v[2:3], v[84:85] op_sel:[1,1,0] op_sel_hi:[0,1,1] neg_lo:[0,1,0]
	s_nop 1
	v_mov_b32_dpp v84, v62 quad_perm:[1,0,3,2] row_mask:0xf bank_mask:0xf bound_ctrl:1
	v_mov_b32_dpp v85, v63 quad_perm:[1,0,3,2] row_mask:0xf bank_mask:0xf bound_ctrl:1
	v_pk_fma_f32 v[62:63], v[8:9], v[62:63], v[84:85] op_sel_hi:[0,1,1]
	v_mov_b32_dpp v84, v64 row_ror:8 row_mask:0xf bank_mask:0xf bound_ctrl:1
	v_mov_b32_dpp v85, v65 row_ror:8 row_mask:0xf bank_mask:0xf bound_ctrl:1
	v_pk_fma_f32 v[64:65], v[4:5], v[64:65], v[84:85] op_sel_hi:[0,1,1]
	v_pk_mul_f32 v[84:85], v[64:65], v[10:11] op_sel_hi:[1,0]
	s_nop 0
	v_pk_fma_f32 v[64:65], v[64:65], v[10:11], v[84:85] op_sel:[1,1,0] op_sel_hi:[0,1,1] neg_lo:[0,1,0]
	ds_swizzle_b32 v84, v64 offset:swizzle(SWAP,4)
	ds_swizzle_b32 v85, v65 offset:swizzle(SWAP,4)
	s_waitcnt lgkmcnt(0)
	v_pk_fma_f32 v[64:65], v[4:5], v[64:65], v[84:85] op_sel:[1,0,0]
	s_nop 0
	v_pk_mul_f32 v[84:85], v[64:65], v[0:1] op_sel_hi:[1,0]
	s_nop 0
	v_pk_fma_f32 v[64:65], v[64:65], v[0:1], v[84:85] op_sel:[1,1,0] op_sel_hi:[0,1,1] neg_lo:[0,1,0]
	s_nop 1
	v_mov_b32_dpp v84, v64 quad_perm:[2,3,0,1] row_mask:0xf bank_mask:0xf bound_ctrl:1
	v_mov_b32_dpp v85, v65 quad_perm:[2,3,0,1] row_mask:0xf bank_mask:0xf bound_ctrl:1
	v_pk_fma_f32 v[64:65], v[6:7], v[64:65], v[84:85] op_sel_hi:[0,1,1]
	v_pk_mul_f32 v[84:85], v[64:65], v[2:3] op_sel_hi:[1,0]
	s_nop 0
	v_pk_fma_f32 v[64:65], v[64:65], v[2:3], v[84:85] op_sel:[1,1,0] op_sel_hi:[0,1,1] neg_lo:[0,1,0]
	s_nop 1
	v_mov_b32_dpp v84, v64 quad_perm:[1,0,3,2] row_mask:0xf bank_mask:0xf bound_ctrl:1
	v_mov_b32_dpp v85, v65 quad_perm:[1,0,3,2] row_mask:0xf bank_mask:0xf bound_ctrl:1
	v_pk_fma_f32 v[64:65], v[8:9], v[64:65], v[84:85] op_sel_hi:[0,1,1]
	v_mov_b32_dpp v84, v66 row_ror:8 row_mask:0xf bank_mask:0xf bound_ctrl:1
	v_mov_b32_dpp v85, v67 row_ror:8 row_mask:0xf bank_mask:0xf bound_ctrl:1
	v_pk_fma_f32 v[66:67], v[4:5], v[66:67], v[84:85] op_sel_hi:[0,1,1]
	v_pk_mul_f32 v[84:85], v[66:67], v[10:11] op_sel_hi:[1,0]
	s_nop 0
	v_pk_fma_f32 v[66:67], v[66:67], v[10:11], v[84:85] op_sel:[1,1,0] op_sel_hi:[0,1,1] neg_lo:[0,1,0]
	ds_swizzle_b32 v84, v66 offset:swizzle(SWAP,4)
	ds_swizzle_b32 v85, v67 offset:swizzle(SWAP,4)
	s_waitcnt lgkmcnt(0)
	v_pk_fma_f32 v[66:67], v[4:5], v[66:67], v[84:85] op_sel:[1,0,0]
	s_nop 0
	v_pk_mul_f32 v[84:85], v[66:67], v[0:1] op_sel_hi:[1,0]
	s_nop 0
	v_pk_fma_f32 v[66:67], v[66:67], v[0:1], v[84:85] op_sel:[1,1,0] op_sel_hi:[0,1,1] neg_lo:[0,1,0]
	s_nop 1
	v_mov_b32_dpp v84, v66 quad_perm:[2,3,0,1] row_mask:0xf bank_mask:0xf bound_ctrl:1
	v_mov_b32_dpp v85, v67 quad_perm:[2,3,0,1] row_mask:0xf bank_mask:0xf bound_ctrl:1
	v_pk_fma_f32 v[66:67], v[6:7], v[66:67], v[84:85] op_sel_hi:[0,1,1]
	v_pk_mul_f32 v[84:85], v[66:67], v[2:3] op_sel_hi:[1,0]
	s_nop 0
	v_pk_fma_f32 v[66:67], v[66:67], v[2:3], v[84:85] op_sel:[1,1,0] op_sel_hi:[0,1,1] neg_lo:[0,1,0]
	s_nop 1
	v_mov_b32_dpp v84, v66 quad_perm:[1,0,3,2] row_mask:0xf bank_mask:0xf bound_ctrl:1
	v_mov_b32_dpp v85, v67 quad_perm:[1,0,3,2] row_mask:0xf bank_mask:0xf bound_ctrl:1
	v_pk_fma_f32 v[66:67], v[8:9], v[66:67], v[84:85] op_sel_hi:[0,1,1]
	v_mov_b32_dpp v84, v68 row_ror:8 row_mask:0xf bank_mask:0xf bound_ctrl:1
	v_mov_b32_dpp v85, v69 row_ror:8 row_mask:0xf bank_mask:0xf bound_ctrl:1
	v_pk_fma_f32 v[68:69], v[4:5], v[68:69], v[84:85] op_sel_hi:[0,1,1]
	v_pk_mul_f32 v[84:85], v[68:69], v[10:11] op_sel_hi:[1,0]
	s_nop 0
	v_pk_fma_f32 v[68:69], v[68:69], v[10:11], v[84:85] op_sel:[1,1,0] op_sel_hi:[0,1,1] neg_lo:[0,1,0]
	ds_swizzle_b32 v84, v68 offset:swizzle(SWAP,4)
	ds_swizzle_b32 v85, v69 offset:swizzle(SWAP,4)
	s_waitcnt lgkmcnt(0)
; __device__ __forceinline__ float lx1(float v) { return __int_as_float(__builtin_amdgcn_update_dpp(0, __float_as_int(v), 0xB1, 0xF, 0xF, true)); }
; __device__ __forceinline__ float lx2(float v) { return __int_as_float(__builtin_amdgcn_update_dpp(0, __float_as_int(v), 0x4E, 0xF, 0xF, true)); }
; __device__ __forceinline__ float lx4(float v) { return __int_as_float(__builtin_amdgcn_ds_swizzle(__float_as_int(v), 0x101F)); }
; __device__ __forceinline__ float lx8(float v) { return __int_as_float(__builtin_amdgcn_update_dpp(0, __float_as_int(v), 0x128, 0xF, 0xF, true)); }
; __device__ __forceinline__ void fft_forward(f2 (&x)[32], LAS f2* X, int t, LAS const float* W1, LAS const M2C* MC) {
;     ...
;     for (int p = 0; p < 32; ++p) {
;         f2 v = x[p], pr;
;         pr = (f2){lx8(v.x), lx8(v.y)}; v = cmulr(pr + v * c.s8, t8);
;         pr = (f2){lx4(v.x), lx4(v.y)}; v = cmulr(pr + v * c.s4, t4);
;         pr = (f2){lx2(v.x), lx2(v.y)}; v = cmulr(pr + v * c.s2, t2);
;         pr = (f2){lx1(v.x), lx1(v.y)}; x[p] = pr + v * c.s1;
;     }
	v_pk_fma_f32 v[68:69], v[4:5], v[68:69], v[84:85] op_sel:[1,0,0]
	s_nop 0
	v_pk_mul_f32 v[84:85], v[68:69], v[0:1] op_sel_hi:[1,0]
	s_nop 0
	v_pk_fma_f32 v[68:69], v[68:69], v[0:1], v[84:85] op_sel:[1,1,0] op_sel_hi:[0,1,1] neg_lo:[0,1,0]
	s_nop 1
	v_mov_b32_dpp v84, v68 quad_perm:[2,3,0,1] row_mask:0xf bank_mask:0xf bound_ctrl:1
	v_mov_b32_dpp v85, v69 quad_perm:[2,3,0,1] row_mask:0xf bank_mask:0xf bound_ctrl:1
	v_pk_fma_f32 v[68:69], v[6:7], v[68:69], v[84:85] op_sel_hi:[0,1,1]
	v_pk_mul_f32 v[84:85], v[68:69], v[2:3] op_sel_hi:[1,0]
	s_nop 0
	v_pk_fma_f32 v[68:69], v[68:69], v[2:3], v[84:85] op_sel:[1,1,0] op_sel_hi:[0,1,1] neg_lo:[0,1,0]
	s_nop 1
	v_mov_b32_dpp v84, v68 quad_perm:[1,0,3,2] row_mask:0xf bank_mask:0xf bound_ctrl:1
	v_mov_b32_dpp v85, v69 quad_perm:[1,0,3,2] row_mask:0xf bank_mask:0xf bound_ctrl:1
	v_pk_fma_f32 v[68:69], v[8:9], v[68:69], v[84:85] op_sel_hi:[0,1,1]
	v_mov_b32_dpp v84, v70 row_ror:8 row_mask:0xf bank_mask:0xf bound_ctrl:1
	v_mov_b32_dpp v85, v71 row_ror:8 row_mask:0xf bank_mask:0xf bound_ctrl:1
	v_pk_fma_f32 v[70:71], v[4:5], v[70:71], v[84:85] op_sel_hi:[0,1,1]
	v_pk_mul_f32 v[84:85], v[70:71], v[10:11] op_sel_hi:[1,0]
	s_nop 0
	v_pk_fma_f32 v[70:71], v[70:71], v[10:11], v[84:85] op_sel:[1,1,0] op_sel_hi:[0,1,1] neg_lo:[0,1,0]
	ds_swizzle_b32 v84, v70 offset:swizzle(SWAP,4)
	ds_swizzle_b32 v85, v71 offset:swizzle(SWAP,4)
	s_waitcnt lgkmcnt(0)
	v_pk_fma_f32 v[70:71], v[4:5], v[70:71], v[84:85] op_sel:[1,0,0]
	s_nop 0
	v_pk_mul_f32 v[84:85], v[70:71], v[0:1] op_sel_hi:[1,0]
	s_nop 0
	v_pk_fma_f32 v[70:71], v[70:71], v[0:1], v[84:85] op_sel:[1,1,0] op_sel_hi:[0,1,1] neg_lo:[0,1,0]
	s_nop 1
	v_mov_b32_dpp v84, v70 quad_perm:[2,3,0,1] row_mask:0xf bank_mask:0xf bound_ctrl:1
	v_mov_b32_dpp v85, v71 quad_perm:[2,3,0,1] row_mask:0xf bank_mask:0xf bound_ctrl:1
	v_pk_fma_f32 v[70:71], v[6:7], v[70:71], v[84:85] op_sel_hi:[0,1,1]
	v_pk_mul_f32 v[84:85], v[70:71], v[2:3] op_sel_hi:[1,0]
	s_nop 0
	v_pk_fma_f32 v[70:71], v[70:71], v[2:3], v[84:85] op_sel:[1,1,0] op_sel_hi:[0,1,1] neg_lo:[0,1,0]
	s_nop 1
	v_mov_b32_dpp v84, v70 quad_perm:[1,0,3,2] row_mask:0xf bank_mask:0xf bound_ctrl:1
	v_mov_b32_dpp v85, v71 quad_perm:[1,0,3,2] row_mask:0xf bank_mask:0xf bound_ctrl:1
	v_pk_fma_f32 v[70:71], v[8:9], v[70:71], v[84:85] op_sel_hi:[0,1,1]
	v_mov_b32_dpp v84, v72 row_ror:8 row_mask:0xf bank_mask:0xf bound_ctrl:1
	v_mov_b32_dpp v85, v73 row_ror:8 row_mask:0xf bank_mask:0xf bound_ctrl:1
	v_pk_fma_f32 v[72:73], v[4:5], v[72:73], v[84:85] op_sel_hi:[0,1,1]
	v_pk_mul_f32 v[84:85], v[72:73], v[10:11] op_sel_hi:[1,0]
	s_nop 0
	v_pk_fma_f32 v[72:73], v[72:73], v[10:11], v[84:85] op_sel:[1,1,0] op_sel_hi:[0,1,1] neg_lo:[0,1,0]
	ds_swizzle_b32 v84, v72 offset:swizzle(SWAP,4)
	ds_swizzle_b32 v85, v73 offset:swizzle(SWAP,4)
	s_waitcnt lgkmcnt(0)
	v_pk_fma_f32 v[72:73], v[4:5], v[72:73], v[84:85] op_sel:[1,0,0]
	s_nop 0
	v_pk_mul_f32 v[84:85], v[72:73], v[0:1] op_sel_hi:[1,0]
	s_nop 0
	v_pk_fma_f32 v[72:73], v[72:73], v[0:1], v[84:85] op_sel:[1,1,0] op_sel_hi:[0,1,1] neg_lo:[0,1,0]
	s_nop 1
	v_mov_b32_dpp v84, v72 quad_perm:[2,3,0,1] row_mask:0xf bank_mask:0xf bound_ctrl:1
	v_mov_b32_dpp v85, v73 quad_perm:[2,3,0,1] row_mask:0xf bank_mask:0xf bound_ctrl:1
	v_pk_fma_f32 v[72:73], v[6:7], v[72:73], v[84:85] op_sel_hi:[0,1,1]
	v_pk_mul_f32 v[84:85], v[72:73], v[2:3] op_sel_hi:[1,0]
	s_nop 0
	v_pk_fma_f32 v[72:73], v[72:73], v[2:3], v[84:85] op_sel:[1,1,0] op_sel_hi:[0,1,1] neg_lo:[0,1,0]
	s_nop 1
	v_mov_b32_dpp v84, v72 quad_perm:[1,0,3,2] row_mask:0xf bank_mask:0xf bound_ctrl:1
	v_mov_b32_dpp v85, v73 quad_perm:[1,0,3,2] row_mask:0xf bank_mask:0xf bound_ctrl:1
	v_pk_fma_f32 v[72:73], v[8:9], v[72:73], v[84:85] op_sel_hi:[0,1,1]
	v_mov_b32_dpp v84, v74 row_ror:8 row_mask:0xf bank_mask:0xf bound_ctrl:1
	v_mov_b32_dpp v85, v75 row_ror:8 row_mask:0xf bank_mask:0xf bound_ctrl:1
	v_pk_fma_f32 v[74:75], v[4:5], v[74:75], v[84:85] op_sel_hi:[0,1,1]
	v_pk_mul_f32 v[84:85], v[74:75], v[10:11] op_sel_hi:[1,0]
	s_nop 0
	v_pk_fma_f32 v[74:75], v[74:75], v[10:11], v[84:85] op_sel:[1,1,0] op_sel_hi:[0,1,1] neg_lo:[0,1,0]
	ds_swizzle_b32 v84, v74 offset:swizzle(SWAP,4)
	ds_swizzle_b32 v85, v75 offset:swizzle(SWAP,4)
	s_waitcnt lgkmcnt(0)
	v_pk_fma_f32 v[74:75], v[4:5], v[74:75], v[84:85] op_sel:[1,0,0]
	s_nop 0
	v_pk_mul_f32 v[84:85], v[74:75], v[0:1] op_sel_hi:[1,0]
	s_nop 0
	v_pk_fma_f32 v[74:75], v[74:75], v[0:1], v[84:85] op_sel:[1,1,0] op_sel_hi:[0,1,1] neg_lo:[0,1,0]
	s_nop 1
	v_mov_b32_dpp v84, v74 quad_perm:[2,3,0,1] row_mask:0xf bank_mask:0xf bound_ctrl:1
	v_mov_b32_dpp v85, v75 quad_perm:[2,3,0,1] row_mask:0xf bank_mask:0xf bound_ctrl:1
	v_pk_fma_f32 v[74:75], v[6:7], v[74:75], v[84:85] op_sel_hi:[0,1,1]
	v_pk_mul_f32 v[84:85], v[74:75], v[2:3] op_sel_hi:[1,0]
	s_nop 0
	v_pk_fma_f32 v[74:75], v[74:75], v[2:3], v[84:85] op_sel:[1,1,0] op_sel_hi:[0,1,1] neg_lo:[0,1,0]
	s_nop 1
	v_mov_b32_dpp v84, v74 quad_perm:[1,0,3,2] row_mask:0xf bank_mask:0xf bound_ctrl:1
	v_mov_b32_dpp v85, v75 quad_perm:[1,0,3,2] row_mask:0xf bank_mask:0xf bound_ctrl:1
	v_pk_fma_f32 v[74:75], v[8:9], v[74:75], v[84:85] op_sel_hi:[0,1,1]
	v_mov_b32_dpp v84, v76 row_ror:8 row_mask:0xf bank_mask:0xf bound_ctrl:1
	v_mov_b32_dpp v85, v77 row_ror:8 row_mask:0xf bank_mask:0xf bound_ctrl:1
	v_pk_fma_f32 v[76:77], v[4:5], v[76:77], v[84:85] op_sel_hi:[0,1,1]
	v_pk_mul_f32 v[84:85], v[76:77], v[10:11] op_sel_hi:[1,0]
	s_nop 0
	v_pk_fma_f32 v[76:77], v[76:77], v[10:11], v[84:85] op_sel:[1,1,0] op_sel_hi:[0,1,1] neg_lo:[0,1,0]
	ds_swizzle_b32 v84, v76 offset:swizzle(SWAP,4)
	ds_swizzle_b32 v85, v77 offset:swizzle(SWAP,4)
	s_waitcnt lgkmcnt(0)
; __device__ __forceinline__ float lx1(float v) { return __int_as_float(__builtin_amdgcn_update_dpp(0, __float_as_int(v), 0xB1, 0xF, 0xF, true)); }
; __device__ __forceinline__ float lx2(float v) { return __int_as_float(__builtin_amdgcn_update_dpp(0, __float_as_int(v), 0x4E, 0xF, 0xF, true)); }
; __device__ __forceinline__ float lx4(float v) { return __int_as_float(__builtin_amdgcn_ds_swizzle(__float_as_int(v), 0x101F)); }
; __device__ __forceinline__ float lx8(float v) { return __int_as_float(__builtin_amdgcn_update_dpp(0, __float_as_int(v), 0x128, 0xF, 0xF, true)); }
; __device__ __forceinline__ void fft_forward(f2 (&x)[32], LAS f2* X, int t, LAS const float* W1, LAS const M2C* MC) {
;     ...
;     for (int p = 0; p < 32; ++p) {
;         f2 v = x[p], pr;
;         pr = (f2){lx8(v.x), lx8(v.y)}; v = cmulr(pr + v * c.s8, t8);
;         pr = (f2){lx4(v.x), lx4(v.y)}; v = cmulr(pr + v * c.s4, t4);
;         pr = (f2){lx2(v.x), lx2(v.y)}; v = cmulr(pr + v * c.s2, t2);
;         pr = (f2){lx1(v.x), lx1(v.y)}; x[p] = pr + v * c.s1;
;     }
; template <int VAR> __device__ __forceinline__ void hyena_conv_phase(const Frame& F, const bf16* ZT, const bf16* GT, const float* conv_w, const float* conv_b, const float* skip, float* gscr, float* zscr, bf16* UT) {
;     ...
;             if (job < 2) {
	v_pk_fma_f32 v[76:77], v[4:5], v[76:77], v[84:85] op_sel:[1,0,0]
	s_nop 0
	v_pk_mul_f32 v[84:85], v[76:77], v[0:1] op_sel_hi:[1,0]
	s_nop 0
	v_pk_fma_f32 v[76:77], v[76:77], v[0:1], v[84:85] op_sel:[1,1,0] op_sel_hi:[0,1,1] neg_lo:[0,1,0]
	s_nop 1
	v_mov_b32_dpp v84, v76 quad_perm:[2,3,0,1] row_mask:0xf bank_mask:0xf bound_ctrl:1
	v_mov_b32_dpp v85, v77 quad_perm:[2,3,0,1] row_mask:0xf bank_mask:0xf bound_ctrl:1
	v_pk_fma_f32 v[76:77], v[6:7], v[76:77], v[84:85] op_sel_hi:[0,1,1]
	v_pk_mul_f32 v[84:85], v[76:77], v[2:3] op_sel_hi:[1,0]
	s_nop 0
	v_pk_fma_f32 v[76:77], v[76:77], v[2:3], v[84:85] op_sel:[1,1,0] op_sel_hi:[0,1,1] neg_lo:[0,1,0]
	s_nop 1
	v_mov_b32_dpp v84, v76 quad_perm:[1,0,3,2] row_mask:0xf bank_mask:0xf bound_ctrl:1
	v_mov_b32_dpp v85, v77 quad_perm:[1,0,3,2] row_mask:0xf bank_mask:0xf bound_ctrl:1
	v_pk_fma_f32 v[76:77], v[8:9], v[76:77], v[84:85] op_sel_hi:[0,1,1]
	v_mov_b32_dpp v84, v78 row_ror:8 row_mask:0xf bank_mask:0xf bound_ctrl:1
	v_mov_b32_dpp v85, v79 row_ror:8 row_mask:0xf bank_mask:0xf bound_ctrl:1
	v_pk_fma_f32 v[78:79], v[4:5], v[78:79], v[84:85] op_sel_hi:[0,1,1]
	v_pk_mul_f32 v[84:85], v[78:79], v[10:11] op_sel_hi:[1,0]
	s_nop 0
	v_pk_fma_f32 v[78:79], v[78:79], v[10:11], v[84:85] op_sel:[1,1,0] op_sel_hi:[0,1,1] neg_lo:[0,1,0]
	ds_swizzle_b32 v84, v78 offset:swizzle(SWAP,4)
	ds_swizzle_b32 v85, v79 offset:swizzle(SWAP,4)
	s_waitcnt lgkmcnt(0)
	v_pk_fma_f32 v[78:79], v[4:5], v[78:79], v[84:85] op_sel:[1,0,0]
	s_nop 0
	v_pk_mul_f32 v[84:85], v[78:79], v[0:1] op_sel_hi:[1,0]
	s_nop 0
	v_pk_fma_f32 v[78:79], v[78:79], v[0:1], v[84:85] op_sel:[1,1,0] op_sel_hi:[0,1,1] neg_lo:[0,1,0]
	s_nop 1
	v_mov_b32_dpp v84, v78 quad_perm:[2,3,0,1] row_mask:0xf bank_mask:0xf bound_ctrl:1
	v_mov_b32_dpp v85, v79 quad_perm:[2,3,0,1] row_mask:0xf bank_mask:0xf bound_ctrl:1
	v_pk_fma_f32 v[78:79], v[6:7], v[78:79], v[84:85] op_sel_hi:[0,1,1]
	v_pk_mul_f32 v[84:85], v[78:79], v[2:3] op_sel_hi:[1,0]
	s_nop 0
	v_pk_fma_f32 v[78:79], v[78:79], v[2:3], v[84:85] op_sel:[1,1,0] op_sel_hi:[0,1,1] neg_lo:[0,1,0]
	s_nop 1
	v_mov_b32_dpp v84, v78 quad_perm:[1,0,3,2] row_mask:0xf bank_mask:0xf bound_ctrl:1
	v_mov_b32_dpp v85, v79 quad_perm:[1,0,3,2] row_mask:0xf bank_mask:0xf bound_ctrl:1
	v_pk_fma_f32 v[78:79], v[8:9], v[78:79], v[84:85] op_sel_hi:[0,1,1]
	v_mov_b32_dpp v84, v80 row_ror:8 row_mask:0xf bank_mask:0xf bound_ctrl:1
	v_mov_b32_dpp v85, v81 row_ror:8 row_mask:0xf bank_mask:0xf bound_ctrl:1
	v_pk_fma_f32 v[80:81], v[4:5], v[80:81], v[84:85] op_sel_hi:[0,1,1]
	v_pk_mul_f32 v[84:85], v[80:81], v[10:11] op_sel_hi:[1,0]
	s_nop 0
	v_pk_fma_f32 v[80:81], v[80:81], v[10:11], v[84:85] op_sel:[1,1,0] op_sel_hi:[0,1,1] neg_lo:[0,1,0]
	ds_swizzle_b32 v84, v80 offset:swizzle(SWAP,4)
	ds_swizzle_b32 v85, v81 offset:swizzle(SWAP,4)
	s_waitcnt lgkmcnt(0)
	v_pk_fma_f32 v[80:81], v[4:5], v[80:81], v[84:85] op_sel:[1,0,0]
	s_nop 0
	v_pk_mul_f32 v[84:85], v[80:81], v[0:1] op_sel_hi:[1,0]
	s_nop 0
	v_pk_fma_f32 v[80:81], v[80:81], v[0:1], v[84:85] op_sel:[1,1,0] op_sel_hi:[0,1,1] neg_lo:[0,1,0]
	s_nop 1
	v_mov_b32_dpp v84, v80 quad_perm:[2,3,0,1] row_mask:0xf bank_mask:0xf bound_ctrl:1
	v_mov_b32_dpp v85, v81 quad_perm:[2,3,0,1] row_mask:0xf bank_mask:0xf bound_ctrl:1
	v_pk_fma_f32 v[80:81], v[6:7], v[80:81], v[84:85] op_sel_hi:[0,1,1]
	v_pk_mul_f32 v[84:85], v[80:81], v[2:3] op_sel_hi:[1,0]
	s_nop 0
	v_pk_fma_f32 v[80:81], v[80:81], v[2:3], v[84:85] op_sel:[1,1,0] op_sel_hi:[0,1,1] neg_lo:[0,1,0]
	s_nop 1
	v_mov_b32_dpp v84, v80 quad_perm:[1,0,3,2] row_mask:0xf bank_mask:0xf bound_ctrl:1
	v_mov_b32_dpp v85, v81 quad_perm:[1,0,3,2] row_mask:0xf bank_mask:0xf bound_ctrl:1
	v_pk_fma_f32 v[80:81], v[8:9], v[80:81], v[84:85] op_sel_hi:[0,1,1]
	v_mov_b32_dpp v84, v82 row_ror:8 row_mask:0xf bank_mask:0xf bound_ctrl:1
	v_mov_b32_dpp v85, v83 row_ror:8 row_mask:0xf bank_mask:0xf bound_ctrl:1
	v_pk_fma_f32 v[82:83], v[4:5], v[82:83], v[84:85] op_sel_hi:[0,1,1]
	v_pk_mul_f32 v[84:85], v[82:83], v[10:11] op_sel_hi:[1,0]
	s_nop 0
	v_pk_fma_f32 v[10:11], v[82:83], v[10:11], v[84:85] op_sel:[1,1,0] op_sel_hi:[0,1,1] neg_lo:[0,1,0]
	ds_swizzle_b32 v82, v10 offset:swizzle(SWAP,4)
	ds_swizzle_b32 v83, v11 offset:swizzle(SWAP,4)
	s_waitcnt lgkmcnt(0)
	v_pk_fma_f32 v[4:5], v[4:5], v[10:11], v[82:83] op_sel:[1,0,0]
	s_nop 0
	v_pk_mul_f32 v[10:11], v[4:5], v[0:1] op_sel_hi:[1,0]
	s_nop 0
	v_pk_fma_f32 v[0:1], v[4:5], v[0:1], v[10:11] op_sel:[1,1,0] op_sel_hi:[0,1,1] neg_lo:[0,1,0]
	s_nop 1
	v_mov_b32_dpp v4, v0 quad_perm:[2,3,0,1] row_mask:0xf bank_mask:0xf bound_ctrl:1
	v_mov_b32_dpp v5, v1 quad_perm:[2,3,0,1] row_mask:0xf bank_mask:0xf bound_ctrl:1
	v_pk_fma_f32 v[0:1], v[6:7], v[0:1], v[4:5] op_sel_hi:[0,1,1]
	v_pk_mul_f32 v[4:5], v[0:1], v[2:3] op_sel_hi:[1,0]
	s_nop 0
	v_pk_fma_f32 v[0:1], v[0:1], v[2:3], v[4:5] op_sel:[1,1,0] op_sel_hi:[0,1,1] neg_lo:[0,1,0]
	s_nop 1
	v_mov_b32_dpp v2, v0 quad_perm:[1,0,3,2] row_mask:0xf bank_mask:0xf bound_ctrl:1
	v_mov_b32_dpp v3, v1 quad_perm:[1,0,3,2] row_mask:0xf bank_mask:0xf bound_ctrl:1
	v_pk_fma_f32 v[82:83], v[8:9], v[0:1], v[2:3] op_sel_hi:[0,1,1]
	s_cbranch_scc1 .LBB0_345
; __device__ __forceinline__ float bflo(unsigned w) { return __uint_as_float(w << 16); }
; __device__ __forceinline__ float bfhi(unsigned w) { return __uint_as_float(w & 0xffff0000u); }
; template <int VAR> __device__ __forceinline__ void hyena_conv_phase(const Frame& F, const bf16* ZT, const bf16* GT, const float* conv_w, const float* conv_b, const float* skip, float* gscr, float* zscr, bf16* UT) {
;     ...
; #pragma unroll
;                 for (int p = 0; p < 32; ++p) { const unsigned w = gpre[p]; x[p] = cmulr(x[p], (f2){bflo(w), bfhi(w)}); }
;                 gv4* py = (gv4*)(zs + 16384) + t;
	v_lshlrev_b32_e32 v0, 16, v161
	v_and_b32_e32 v1, 0xffff0000, v161
	v_pk_mul_f32 v[2:3], v[14:15], v[0:1] op_sel_hi:[1,0]
	s_mov_b32 s96, s63
	v_pk_fma_f32 v[86:87], v[14:15], v[0:1], v[2:3] op_sel:[1,1,0] op_sel_hi:[0,1,1] neg_lo:[0,1,0]
	v_lshlrev_b32_e32 v0, 16, v162
	v_and_b32_e32 v1, 0xffff0000, v162
	v_pk_mul_f32 v[2:3], v[22:23], v[0:1] op_sel_hi:[1,0]
	v_mov_b32_dpp v216, v86 quad_perm:[1,0,3,2] row_mask:0xf bank_mask:0xf bound_ctrl:1
	v_pk_fma_f32 v[90:91], v[22:23], v[0:1], v[2:3] op_sel:[1,1,0] op_sel_hi:[0,1,1] neg_lo:[0,1,0]
	v_lshlrev_b32_e32 v0, 16, v163
	v_and_b32_e32 v1, 0xffff0000, v163
	v_pk_mul_f32 v[2:3], v[24:25], v[0:1] op_sel_hi:[1,0]
	v_mov_b32_dpp v217, v87 quad_perm:[1,0,3,2] row_mask:0xf bank_mask:0xf bound_ctrl:1
	v_pk_fma_f32 v[98:99], v[24:25], v[0:1], v[2:3] op_sel:[1,1,0] op_sel_hi:[0,1,1] neg_lo:[0,1,0]
	v_lshlrev_b32_e32 v0, 16, v164
	v_and_b32_e32 v1, 0xffff0000, v164
	v_pk_mul_f32 v[2:3], v[26:27], v[0:1] op_sel_hi:[1,0]
	s_mov_b32 s97, s62
	v_pk_fma_f32 v[96:97], v[26:27], v[0:1], v[2:3] op_sel:[1,1,0] op_sel_hi:[0,1,1] neg_lo:[0,1,0]
	v_lshlrev_b32_e32 v0, 16, v165
	v_and_b32_e32 v1, 0xffff0000, v165
	v_pk_mul_f32 v[2:3], v[28:29], v[0:1] op_sel_hi:[1,0]
	s_mov_b32 s94, s63
	v_pk_fma_f32 v[108:109], v[28:29], v[0:1], v[2:3] op_sel:[1,1,0] op_sel_hi:[0,1,1] neg_lo:[0,1,0]
	v_lshlrev_b32_e32 v0, 16, v166
	v_and_b32_e32 v1, 0xffff0000, v166
	v_pk_mul_f32 v[2:3], v[30:31], v[0:1] op_sel_hi:[1,0]
	s_mov_b32 s6, s55
	v_pk_fma_f32 v[104:105], v[30:31], v[0:1], v[2:3] op_sel:[1,1,0] op_sel_hi:[0,1,1] neg_lo:[0,1,0]
	v_lshlrev_b32_e32 v0, 16, v167
	v_and_b32_e32 v1, 0xffff0000, v167
	v_pk_mul_f32 v[2:3], v[32:33], v[0:1] op_sel_hi:[1,0]
	s_mov_b32 s7, s54
	v_pk_fma_f32 v[114:115], v[32:33], v[0:1], v[2:3] op_sel:[1,1,0] op_sel_hi:[0,1,1] neg_lo:[0,1,0]
	v_lshlrev_b32_e32 v0, 16, v168
	v_and_b32_e32 v1, 0xffff0000, v168
	v_pk_mul_f32 v[2:3], v[34:35], v[0:1] op_sel_hi:[1,0]
	s_mov_b32 s84, s55
	v_pk_fma_f32 v[112:113], v[34:35], v[0:1], v[2:3] op_sel:[1,1,0] op_sel_hi:[0,1,1] neg_lo:[0,1,0]
	v_lshlrev_b32_e32 v0, 16, v169
	v_and_b32_e32 v1, 0xffff0000, v169
	v_pk_mul_f32 v[2:3], v[36:37], v[0:1] op_sel_hi:[1,0]
	s_mov_b32 s76, s47
	v_pk_fma_f32 v[126:127], v[36:37], v[0:1], v[2:3] op_sel:[1,1,0] op_sel_hi:[0,1,1] neg_lo:[0,1,0]
	v_lshlrev_b32_e32 v0, 16, v170
	v_and_b32_e32 v1, 0xffff0000, v170
	v_pk_mul_f32 v[2:3], v[38:39], v[0:1] op_sel_hi:[1,0]
	s_mov_b32 s77, s46
	v_pk_fma_f32 v[122:123], v[38:39], v[0:1], v[2:3] op_sel:[1,1,0] op_sel_hi:[0,1,1] neg_lo:[0,1,0]
	v_lshlrev_b32_e32 v0, 16, v171
	v_and_b32_e32 v1, 0xffff0000, v171
	v_pk_mul_f32 v[2:3], v[40:41], v[0:1] op_sel_hi:[1,0]
	s_mov_b32 s20, s59
	v_pk_fma_f32 v[132:133], v[40:41], v[0:1], v[2:3] op_sel:[1,1,0] op_sel_hi:[0,1,1] neg_lo:[0,1,0]
	v_lshlrev_b32_e32 v0, 16, v172
	v_and_b32_e32 v1, 0xffff0000, v172
	v_pk_mul_f32 v[2:3], v[42:43], v[0:1] op_sel_hi:[1,0]
	s_mov_b32 s21, s58
	v_pk_fma_f32 v[130:131], v[42:43], v[0:1], v[2:3] op_sel:[1,1,0] op_sel_hi:[0,1,1] neg_lo:[0,1,0]
	v_lshlrev_b32_e32 v0, 16, v173
	v_and_b32_e32 v1, 0xffff0000, v173
	v_pk_mul_f32 v[2:3], v[44:45], v[0:1] op_sel_hi:[1,0]
	s_mov_b32 s86, s59
	v_pk_fma_f32 v[142:143], v[44:45], v[0:1], v[2:3] op_sel:[1,1,0] op_sel_hi:[0,1,1] neg_lo:[0,1,0]
	v_lshlrev_b32_e32 v0, 16, v174
	v_and_b32_e32 v1, 0xffff0000, v174
	v_pk_mul_f32 v[2:3], v[46:47], v[0:1] op_sel_hi:[1,0]
	s_mov_b32 s10, s47
	v_pk_fma_f32 v[138:139], v[46:47], v[0:1], v[2:3] op_sel:[1,1,0] op_sel_hi:[0,1,1] neg_lo:[0,1,0]
	v_lshlrev_b32_e32 v0, 16, v175
	v_and_b32_e32 v1, 0xffff0000, v175
	v_pk_mul_f32 v[2:3], v[48:49], v[0:1] op_sel_hi:[1,0]
	v_lshl_add_u64 v[84:85], v[12:13], 4, s[8:9]
	v_pk_fma_f32 v[148:149], v[48:49], v[0:1], v[2:3] op_sel:[1,1,0] op_sel_hi:[0,1,1] neg_lo:[0,1,0]
	v_lshlrev_b32_e32 v0, 16, v176
	v_and_b32_e32 v1, 0xffff0000, v176
	v_pk_mul_f32 v[2:3], v[50:51], v[0:1] op_sel_hi:[1,0]
	s_and_b64 vcc, exec, s[92:93]
	v_pk_fma_f32 v[146:147], v[50:51], v[0:1], v[2:3] op_sel:[1,1,0] op_sel_hi:[0,1,1] neg_lo:[0,1,0]
	v_lshlrev_b32_e32 v0, 16, v177
	v_and_b32_e32 v1, 0xffff0000, v177
	v_pk_mul_f32 v[2:3], v[52:53], v[0:1] op_sel_hi:[1,0]
	s_nop 0
	v_pk_fma_f32 v[144:145], v[52:53], v[0:1], v[2:3] op_sel:[1,1,0] op_sel_hi:[0,1,1] neg_lo:[0,1,0]
	v_lshlrev_b32_e32 v0, 16, v178
	v_and_b32_e32 v1, 0xffff0000, v178
	v_pk_mul_f32 v[2:3], v[54:55], v[0:1] op_sel_hi:[1,0]
	s_nop 0
	v_pk_fma_f32 v[140:141], v[54:55], v[0:1], v[2:3] op_sel:[1,1,0] op_sel_hi:[0,1,1] neg_lo:[0,1,0]
	v_lshlrev_b32_e32 v0, 16, v179
	v_and_b32_e32 v1, 0xffff0000, v179
	v_pk_mul_f32 v[2:3], v[56:57], v[0:1] op_sel_hi:[1,0]
	s_nop 0
	v_pk_fma_f32 v[136:137], v[56:57], v[0:1], v[2:3] op_sel:[1,1,0] op_sel_hi:[0,1,1] neg_lo:[0,1,0]
	v_lshlrev_b32_e32 v0, 16, v180
	v_and_b32_e32 v1, 0xffff0000, v180
	v_pk_mul_f32 v[2:3], v[58:59], v[0:1] op_sel_hi:[1,0]
	s_nop 0
	v_pk_fma_f32 v[134:135], v[58:59], v[0:1], v[2:3] op_sel:[1,1,0] op_sel_hi:[0,1,1] neg_lo:[0,1,0]
	v_lshlrev_b32_e32 v0, 16, v181
	v_and_b32_e32 v1, 0xffff0000, v181
	v_pk_mul_f32 v[2:3], v[60:61], v[0:1] op_sel_hi:[1,0]
	s_nop 0
	v_pk_fma_f32 v[128:129], v[60:61], v[0:1], v[2:3] op_sel:[1,1,0] op_sel_hi:[0,1,1] neg_lo:[0,1,0]
	v_lshlrev_b32_e32 v0, 16, v182
	v_and_b32_e32 v1, 0xffff0000, v182
	v_pk_mul_f32 v[2:3], v[62:63], v[0:1] op_sel_hi:[1,0]
	s_nop 0
	v_pk_fma_f32 v[124:125], v[62:63], v[0:1], v[2:3] op_sel:[1,1,0] op_sel_hi:[0,1,1] neg_lo:[0,1,0]
	v_lshlrev_b32_e32 v0, 16, v183
	v_and_b32_e32 v1, 0xffff0000, v183
	v_pk_mul_f32 v[2:3], v[64:65], v[0:1] op_sel_hi:[1,0]
	s_nop 0
	v_pk_fma_f32 v[120:121], v[64:65], v[0:1], v[2:3] op_sel:[1,1,0] op_sel_hi:[0,1,1] neg_lo:[0,1,0]
; __device__ __forceinline__ float bflo(unsigned w) { return __uint_as_float(w << 16); }
; __device__ __forceinline__ float bfhi(unsigned w) { return __uint_as_float(w & 0xffff0000u); }
; __device__ __forceinline__ float lx1(float v) { return __int_as_float(__builtin_amdgcn_update_dpp(0, __float_as_int(v), 0xB1, 0xF, 0xF, true)); }
; __device__ __forceinline__ float lx2(float v) { return __int_as_float(__builtin_amdgcn_update_dpp(0, __float_as_int(v), 0x4E, 0xF, 0xF, true)); }
; __device__ __forceinline__ float lx4(float v) { return __int_as_float(__builtin_amdgcn_ds_swizzle(__float_as_int(v), 0x101F)); }
; __device__ __forceinline__ float lx8(float v) { return __int_as_float(__builtin_amdgcn_update_dpp(0, __float_as_int(v), 0x128, 0xF, 0xF, true)); }
; __device__ __forceinline__ void fft_inverse(f2 (&x)[32], LAS f2* X, int t, LAS const float* W1, LAS const M2C* MC) {
;     const M2C c = m2c_load(MC); const f2 t8 = (f2){c.t8r, c.t8i}, t4 = (f2){c.t4r, c.t4i}, t2 = (f2){c.t2r, c.t2i};
; #pragma unroll
;     for (int p = 0; p < 32; ++p) {
;         f2 v = x[p], pr;
;         pr = (f2){lx1(v.x), lx1(v.y)}; v = cmulrc(pr + v * c.s1, t2);
;         pr = (f2){lx2(v.x), lx2(v.y)}; v = cmulrc(pr + v * c.s2, t4);
;         pr = (f2){lx4(v.x), lx4(v.y)}; v = cmulrc(pr + v * c.s4, t8);
;         pr = (f2){lx8(v.x), lx8(v.y)}; x[p] = pr + v * c.s8;
;     }
; template <int VAR> __device__ __forceinline__ void hyena_conv_phase(const Frame& F, const bf16* ZT, const bf16* GT, const float* conv_w, const float* conv_b, const float* skip, float* gscr, float* zscr, bf16* UT) {
;     ...
; #pragma unroll
;                 for (int p = 0; p < 32; ++p) { const unsigned w = gpre[p]; x[p] = cmulr(x[p], (f2){bflo(w), bfhi(w)}); }
	v_lshlrev_b32_e32 v0, 16, v184
	v_and_b32_e32 v1, 0xffff0000, v184
	v_pk_mul_f32 v[2:3], v[66:67], v[0:1] op_sel_hi:[1,0]
	s_nop 0
	v_pk_fma_f32 v[118:119], v[66:67], v[0:1], v[2:3] op_sel:[1,1,0] op_sel_hi:[0,1,1] neg_lo:[0,1,0]
	v_lshlrev_b32_e32 v0, 16, v185
	v_and_b32_e32 v1, 0xffff0000, v185
	v_pk_mul_f32 v[2:3], v[68:69], v[0:1] op_sel_hi:[1,0]
	s_nop 0
	v_pk_fma_f32 v[116:117], v[68:69], v[0:1], v[2:3] op_sel:[1,1,0] op_sel_hi:[0,1,1] neg_lo:[0,1,0]
	v_lshlrev_b32_e32 v0, 16, v186
	v_and_b32_e32 v1, 0xffff0000, v186
	v_pk_mul_f32 v[2:3], v[70:71], v[0:1] op_sel_hi:[1,0]
	s_nop 0
	v_pk_fma_f32 v[110:111], v[70:71], v[0:1], v[2:3] op_sel:[1,1,0] op_sel_hi:[0,1,1] neg_lo:[0,1,0]
	v_lshlrev_b32_e32 v0, 16, v187
	v_and_b32_e32 v1, 0xffff0000, v187
	v_pk_mul_f32 v[2:3], v[72:73], v[0:1] op_sel_hi:[1,0]
	s_nop 0
	v_pk_fma_f32 v[106:107], v[72:73], v[0:1], v[2:3] op_sel:[1,1,0] op_sel_hi:[0,1,1] neg_lo:[0,1,0]
	v_lshlrev_b32_e32 v0, 16, v188
	v_and_b32_e32 v1, 0xffff0000, v188
	v_pk_mul_f32 v[2:3], v[74:75], v[0:1] op_sel_hi:[1,0]
	s_nop 0
	v_pk_fma_f32 v[102:103], v[74:75], v[0:1], v[2:3] op_sel:[1,1,0] op_sel_hi:[0,1,1] neg_lo:[0,1,0]
	v_lshlrev_b32_e32 v0, 16, v189
	v_and_b32_e32 v1, 0xffff0000, v189
	v_pk_mul_f32 v[2:3], v[76:77], v[0:1] op_sel_hi:[1,0]
	s_nop 0
	v_pk_fma_f32 v[100:101], v[76:77], v[0:1], v[2:3] op_sel:[1,1,0] op_sel_hi:[0,1,1] neg_lo:[0,1,0]
	v_lshlrev_b32_e32 v0, 16, v190
	v_and_b32_e32 v1, 0xffff0000, v190
	v_pk_mul_f32 v[2:3], v[78:79], v[0:1] op_sel_hi:[1,0]
	s_nop 0
	v_pk_fma_f32 v[94:95], v[78:79], v[0:1], v[2:3] op_sel:[1,1,0] op_sel_hi:[0,1,1] neg_lo:[0,1,0]
	v_lshlrev_b32_e32 v0, 16, v191
	v_and_b32_e32 v1, 0xffff0000, v191
	v_pk_mul_f32 v[2:3], v[80:81], v[0:1] op_sel_hi:[1,0]
	s_nop 0
	v_pk_fma_f32 v[92:93], v[80:81], v[0:1], v[2:3] op_sel:[1,1,0] op_sel_hi:[0,1,1] neg_lo:[0,1,0]
	v_lshlrev_b32_e32 v0, 16, v192
	v_and_b32_e32 v1, 0xffff0000, v192
	v_pk_mul_f32 v[2:3], v[82:83], v[0:1] op_sel_hi:[1,0]
	s_nop 0
	v_pk_fma_f32 v[88:89], v[82:83], v[0:1], v[2:3] op_sel:[1,1,0] op_sel_hi:[0,1,1] neg_lo:[0,1,0]
	ds_read_b128 v[0:3], v151
	ds_read_b128 v[4:7], v151 offset:16
	ds_read_b128 v[8:11], v151 offset:32
	s_waitcnt lgkmcnt(2)
	s_nop 0
	v_xor_b32_e32 v1, 0x80000000, v1
	s_waitcnt lgkmcnt(0)
	v_mov_b32_e32 v16, v11
	v_pk_fma_f32 v[86:87], v[86:87], v[16:17], v[216:217] op_sel_hi:[1,0,1]
	s_nop 0
	v_pk_mul_f32 v[216:217], v[86:87], v[6:7] op_sel_hi:[1,0]
	s_nop 0
	v_pk_fma_f32 v[86:87], v[86:87], v[6:7], v[216:217] op_sel:[1,1,0] op_sel_hi:[0,1,1] neg_hi:[0,1,0]
	s_nop 1
	v_mov_b32_dpp v216, v86 quad_perm:[2,3,0,1] row_mask:0xf bank_mask:0xf bound_ctrl:1
	v_mov_b32_dpp v217, v87 quad_perm:[2,3,0,1] row_mask:0xf bank_mask:0xf bound_ctrl:1
	v_pk_fma_f32 v[86:87], v[10:11], v[86:87], v[216:217] op_sel_hi:[0,1,1]
	v_pk_mul_f32 v[216:217], v[86:87], v[4:5] op_sel_hi:[1,0]
	s_nop 0
	v_pk_fma_f32 v[86:87], v[86:87], v[4:5], v[216:217] op_sel:[1,1,0] op_sel_hi:[0,1,1] neg_hi:[0,1,0]
	ds_swizzle_b32 v216, v86 offset:swizzle(SWAP,4)
	ds_swizzle_b32 v217, v87 offset:swizzle(SWAP,4)
	s_waitcnt lgkmcnt(0)
	v_pk_fma_f32 v[86:87], v[8:9], v[86:87], v[216:217] op_sel:[1,0,0]
	s_nop 0
	v_pk_mul_f32 v[216:217], v[86:87], v[2:3] op_sel_hi:[1,0]
	s_nop 0
	v_pk_fma_f32 v[86:87], v[86:87], v[2:3], v[216:217] op_sel:[1,1,0] op_sel_hi:[0,1,1] neg_hi:[0,1,0]
	s_nop 1
	v_mov_b32_dpp v216, v86 row_ror:8 row_mask:0xf bank_mask:0xf bound_ctrl:1
	v_mov_b32_dpp v217, v87 row_ror:8 row_mask:0xf bank_mask:0xf bound_ctrl:1
	v_pk_fma_f32 v[86:87], v[8:9], v[86:87], v[216:217] op_sel_hi:[0,1,1]
	v_mov_b32_dpp v216, v90 quad_perm:[1,0,3,2] row_mask:0xf bank_mask:0xf bound_ctrl:1
	v_mov_b32_dpp v217, v91 quad_perm:[1,0,3,2] row_mask:0xf bank_mask:0xf bound_ctrl:1
	v_pk_fma_f32 v[90:91], v[90:91], v[16:17], v[216:217] op_sel_hi:[1,0,1]
	s_nop 0
	v_pk_mul_f32 v[216:217], v[90:91], v[6:7] op_sel_hi:[1,0]
	s_nop 0
	v_pk_fma_f32 v[90:91], v[90:91], v[6:7], v[216:217] op_sel:[1,1,0] op_sel_hi:[0,1,1] neg_hi:[0,1,0]
	s_nop 1
	v_mov_b32_dpp v216, v90 quad_perm:[2,3,0,1] row_mask:0xf bank_mask:0xf bound_ctrl:1
	v_mov_b32_dpp v217, v91 quad_perm:[2,3,0,1] row_mask:0xf bank_mask:0xf bound_ctrl:1
	v_pk_fma_f32 v[90:91], v[10:11], v[90:91], v[216:217] op_sel_hi:[0,1,1]
	v_pk_mul_f32 v[216:217], v[90:91], v[4:5] op_sel_hi:[1,0]
	s_nop 0
	v_pk_fma_f32 v[90:91], v[90:91], v[4:5], v[216:217] op_sel:[1,1,0] op_sel_hi:[0,1,1] neg_hi:[0,1,0]
	ds_swizzle_b32 v216, v90 offset:swizzle(SWAP,4)
	ds_swizzle_b32 v217, v91 offset:swizzle(SWAP,4)
	s_waitcnt lgkmcnt(0)
	v_pk_fma_f32 v[90:91], v[8:9], v[90:91], v[216:217] op_sel:[1,0,0]
	s_nop 0
	v_pk_mul_f32 v[216:217], v[90:91], v[2:3] op_sel_hi:[1,0]
	s_nop 0
	v_pk_fma_f32 v[90:91], v[90:91], v[2:3], v[216:217] op_sel:[1,1,0] op_sel_hi:[0,1,1] neg_hi:[0,1,0]
	s_nop 1
	v_mov_b32_dpp v216, v90 row_ror:8 row_mask:0xf bank_mask:0xf bound_ctrl:1
	v_mov_b32_dpp v217, v91 row_ror:8 row_mask:0xf bank_mask:0xf bound_ctrl:1
	v_pk_fma_f32 v[90:91], v[8:9], v[90:91], v[216:217] op_sel_hi:[0,1,1]
	v_mov_b32_dpp v216, v98 quad_perm:[1,0,3,2] row_mask:0xf bank_mask:0xf bound_ctrl:1
	v_mov_b32_dpp v217, v99 quad_perm:[1,0,3,2] row_mask:0xf bank_mask:0xf bound_ctrl:1
	v_pk_fma_f32 v[98:99], v[98:99], v[16:17], v[216:217] op_sel_hi:[1,0,1]
	s_nop 0
	v_pk_mul_f32 v[216:217], v[98:99], v[6:7] op_sel_hi:[1,0]
	s_nop 0
	v_pk_fma_f32 v[98:99], v[98:99], v[6:7], v[216:217] op_sel:[1,1,0] op_sel_hi:[0,1,1] neg_hi:[0,1,0]
	s_nop 1
	v_mov_b32_dpp v216, v98 quad_perm:[2,3,0,1] row_mask:0xf bank_mask:0xf bound_ctrl:1
	v_mov_b32_dpp v217, v99 quad_perm:[2,3,0,1] row_mask:0xf bank_mask:0xf bound_ctrl:1
	v_pk_fma_f32 v[98:99], v[10:11], v[98:99], v[216:217] op_sel_hi:[0,1,1]
	v_pk_mul_f32 v[216:217], v[98:99], v[4:5] op_sel_hi:[1,0]
	s_nop 0
	v_pk_fma_f32 v[98:99], v[98:99], v[4:5], v[216:217] op_sel:[1,1,0] op_sel_hi:[0,1,1] neg_hi:[0,1,0]
	ds_swizzle_b32 v216, v98 offset:swizzle(SWAP,4)
	ds_swizzle_b32 v217, v99 offset:swizzle(SWAP,4)
	s_waitcnt lgkmcnt(0)
; __device__ __forceinline__ float lx1(float v) { return __int_as_float(__builtin_amdgcn_update_dpp(0, __float_as_int(v), 0xB1, 0xF, 0xF, true)); }
; __device__ __forceinline__ float lx2(float v) { return __int_as_float(__builtin_amdgcn_update_dpp(0, __float_as_int(v), 0x4E, 0xF, 0xF, true)); }
; __device__ __forceinline__ float lx4(float v) { return __int_as_float(__builtin_amdgcn_ds_swizzle(__float_as_int(v), 0x101F)); }
; __device__ __forceinline__ float lx8(float v) { return __int_as_float(__builtin_amdgcn_update_dpp(0, __float_as_int(v), 0x128, 0xF, 0xF, true)); }
; __device__ __forceinline__ void fft_inverse(f2 (&x)[32], LAS f2* X, int t, LAS const float* W1, LAS const M2C* MC) {
;     ...
; #pragma unroll
;     for (int p = 0; p < 32; ++p) {
;         f2 v = x[p], pr;
;         pr = (f2){lx1(v.x), lx1(v.y)}; v = cmulrc(pr + v * c.s1, t2);
;         pr = (f2){lx2(v.x), lx2(v.y)}; v = cmulrc(pr + v * c.s2, t4);
;         pr = (f2){lx4(v.x), lx4(v.y)}; v = cmulrc(pr + v * c.s4, t8);
;         pr = (f2){lx8(v.x), lx8(v.y)}; x[p] = pr + v * c.s8;
;     }
	v_pk_fma_f32 v[98:99], v[8:9], v[98:99], v[216:217] op_sel:[1,0,0]
	s_nop 0
	v_pk_mul_f32 v[216:217], v[98:99], v[2:3] op_sel_hi:[1,0]
	s_nop 0
	v_pk_fma_f32 v[98:99], v[98:99], v[2:3], v[216:217] op_sel:[1,1,0] op_sel_hi:[0,1,1] neg_hi:[0,1,0]
	s_nop 1
	v_mov_b32_dpp v216, v98 row_ror:8 row_mask:0xf bank_mask:0xf bound_ctrl:1
	v_mov_b32_dpp v217, v99 row_ror:8 row_mask:0xf bank_mask:0xf bound_ctrl:1
	v_pk_fma_f32 v[98:99], v[8:9], v[98:99], v[216:217] op_sel_hi:[0,1,1]
	v_mov_b32_dpp v216, v96 quad_perm:[1,0,3,2] row_mask:0xf bank_mask:0xf bound_ctrl:1
	v_mov_b32_dpp v217, v97 quad_perm:[1,0,3,2] row_mask:0xf bank_mask:0xf bound_ctrl:1
	v_pk_fma_f32 v[96:97], v[96:97], v[16:17], v[216:217] op_sel_hi:[1,0,1]
	s_nop 0
	v_pk_mul_f32 v[216:217], v[96:97], v[6:7] op_sel_hi:[1,0]
	s_nop 0
	v_pk_fma_f32 v[96:97], v[96:97], v[6:7], v[216:217] op_sel:[1,1,0] op_sel_hi:[0,1,1] neg_hi:[0,1,0]
	s_nop 1
	v_mov_b32_dpp v216, v96 quad_perm:[2,3,0,1] row_mask:0xf bank_mask:0xf bound_ctrl:1
	v_mov_b32_dpp v217, v97 quad_perm:[2,3,0,1] row_mask:0xf bank_mask:0xf bound_ctrl:1
	v_pk_fma_f32 v[96:97], v[10:11], v[96:97], v[216:217] op_sel_hi:[0,1,1]
	v_pk_mul_f32 v[216:217], v[96:97], v[4:5] op_sel_hi:[1,0]
	s_nop 0
	v_pk_fma_f32 v[96:97], v[96:97], v[4:5], v[216:217] op_sel:[1,1,0] op_sel_hi:[0,1,1] neg_hi:[0,1,0]
	ds_swizzle_b32 v216, v96 offset:swizzle(SWAP,4)
	ds_swizzle_b32 v217, v97 offset:swizzle(SWAP,4)
	s_waitcnt lgkmcnt(0)
	v_pk_fma_f32 v[96:97], v[8:9], v[96:97], v[216:217] op_sel:[1,0,0]
	s_nop 0
	v_pk_mul_f32 v[216:217], v[96:97], v[2:3] op_sel_hi:[1,0]
	s_nop 0
	v_pk_fma_f32 v[96:97], v[96:97], v[2:3], v[216:217] op_sel:[1,1,0] op_sel_hi:[0,1,1] neg_hi:[0,1,0]
	s_nop 1
	v_mov_b32_dpp v216, v96 row_ror:8 row_mask:0xf bank_mask:0xf bound_ctrl:1
	v_mov_b32_dpp v217, v97 row_ror:8 row_mask:0xf bank_mask:0xf bound_ctrl:1
	v_pk_fma_f32 v[96:97], v[8:9], v[96:97], v[216:217] op_sel_hi:[0,1,1]
	v_mov_b32_dpp v216, v108 quad_perm:[1,0,3,2] row_mask:0xf bank_mask:0xf bound_ctrl:1
	v_mov_b32_dpp v217, v109 quad_perm:[1,0,3,2] row_mask:0xf bank_mask:0xf bound_ctrl:1
	v_pk_fma_f32 v[108:109], v[108:109], v[16:17], v[216:217] op_sel_hi:[1,0,1]
	s_nop 0
	v_pk_mul_f32 v[216:217], v[108:109], v[6:7] op_sel_hi:[1,0]
	s_nop 0
	v_pk_fma_f32 v[108:109], v[108:109], v[6:7], v[216:217] op_sel:[1,1,0] op_sel_hi:[0,1,1] neg_hi:[0,1,0]
	s_nop 1
	v_mov_b32_dpp v216, v108 quad_perm:[2,3,0,1] row_mask:0xf bank_mask:0xf bound_ctrl:1
	v_mov_b32_dpp v217, v109 quad_perm:[2,3,0,1] row_mask:0xf bank_mask:0xf bound_ctrl:1
	v_pk_fma_f32 v[108:109], v[10:11], v[108:109], v[216:217] op_sel_hi:[0,1,1]
	v_pk_mul_f32 v[216:217], v[108:109], v[4:5] op_sel_hi:[1,0]
	s_nop 0
	v_pk_fma_f32 v[108:109], v[108:109], v[4:5], v[216:217] op_sel:[1,1,0] op_sel_hi:[0,1,1] neg_hi:[0,1,0]
	ds_swizzle_b32 v216, v108 offset:swizzle(SWAP,4)
	ds_swizzle_b32 v217, v109 offset:swizzle(SWAP,4)
	s_waitcnt lgkmcnt(0)
	v_pk_fma_f32 v[108:109], v[8:9], v[108:109], v[216:217] op_sel:[1,0,0]
	s_nop 0
	v_pk_mul_f32 v[216:217], v[108:109], v[2:3] op_sel_hi:[1,0]
	s_nop 0
	v_pk_fma_f32 v[108:109], v[108:109], v[2:3], v[216:217] op_sel:[1,1,0] op_sel_hi:[0,1,1] neg_hi:[0,1,0]
	s_nop 1
	v_mov_b32_dpp v216, v108 row_ror:8 row_mask:0xf bank_mask:0xf bound_ctrl:1
	v_mov_b32_dpp v217, v109 row_ror:8 row_mask:0xf bank_mask:0xf bound_ctrl:1
	v_pk_fma_f32 v[108:109], v[8:9], v[108:109], v[216:217] op_sel_hi:[0,1,1]
	v_mov_b32_dpp v216, v104 quad_perm:[1,0,3,2] row_mask:0xf bank_mask:0xf bound_ctrl:1
	v_mov_b32_dpp v217, v105 quad_perm:[1,0,3,2] row_mask:0xf bank_mask:0xf bound_ctrl:1
	v_pk_fma_f32 v[104:105], v[104:105], v[16:17], v[216:217] op_sel_hi:[1,0,1]
	s_nop 0
	v_pk_mul_f32 v[216:217], v[104:105], v[6:7] op_sel_hi:[1,0]
	s_nop 0
	v_pk_fma_f32 v[104:105], v[104:105], v[6:7], v[216:217] op_sel:[1,1,0] op_sel_hi:[0,1,1] neg_hi:[0,1,0]
	s_nop 1
	v_mov_b32_dpp v216, v104 quad_perm:[2,3,0,1] row_mask:0xf bank_mask:0xf bound_ctrl:1
	v_mov_b32_dpp v217, v105 quad_perm:[2,3,0,1] row_mask:0xf bank_mask:0xf bound_ctrl:1
	v_pk_fma_f32 v[104:105], v[10:11], v[104:105], v[216:217] op_sel_hi:[0,1,1]
	v_pk_mul_f32 v[216:217], v[104:105], v[4:5] op_sel_hi:[1,0]
	s_nop 0
	v_pk_fma_f32 v[104:105], v[104:105], v[4:5], v[216:217] op_sel:[1,1,0] op_sel_hi:[0,1,1] neg_hi:[0,1,0]
	ds_swizzle_b32 v216, v104 offset:swizzle(SWAP,4)
	ds_swizzle_b32 v217, v105 offset:swizzle(SWAP,4)
	s_waitcnt lgkmcnt(0)
	v_pk_fma_f32 v[104:105], v[8:9], v[104:105], v[216:217] op_sel:[1,0,0]
	s_nop 0
	v_pk_mul_f32 v[216:217], v[104:105], v[2:3] op_sel_hi:[1,0]
	s_nop 0
	v_pk_fma_f32 v[104:105], v[104:105], v[2:3], v[216:217] op_sel:[1,1,0] op_sel_hi:[0,1,1] neg_hi:[0,1,0]
	s_nop 1
	v_mov_b32_dpp v216, v104 row_ror:8 row_mask:0xf bank_mask:0xf bound_ctrl:1
	v_mov_b32_dpp v217, v105 row_ror:8 row_mask:0xf bank_mask:0xf bound_ctrl:1
	v_pk_fma_f32 v[104:105], v[8:9], v[104:105], v[216:217] op_sel_hi:[0,1,1]
	v_mov_b32_dpp v216, v114 quad_perm:[1,0,3,2] row_mask:0xf bank_mask:0xf bound_ctrl:1
	v_mov_b32_dpp v217, v115 quad_perm:[1,0,3,2] row_mask:0xf bank_mask:0xf bound_ctrl:1
	v_pk_fma_f32 v[114:115], v[114:115], v[16:17], v[216:217] op_sel_hi:[1,0,1]
	s_nop 0
	v_pk_mul_f32 v[216:217], v[114:115], v[6:7] op_sel_hi:[1,0]
	s_nop 0
	v_pk_fma_f32 v[114:115], v[114:115], v[6:7], v[216:217] op_sel:[1,1,0] op_sel_hi:[0,1,1] neg_hi:[0,1,0]
	s_nop 1
	v_mov_b32_dpp v216, v114 quad_perm:[2,3,0,1] row_mask:0xf bank_mask:0xf bound_ctrl:1
	v_mov_b32_dpp v217, v115 quad_perm:[2,3,0,1] row_mask:0xf bank_mask:0xf bound_ctrl:1
	v_pk_fma_f32 v[114:115], v[10:11], v[114:115], v[216:217] op_sel_hi:[0,1,1]
	v_pk_mul_f32 v[216:217], v[114:115], v[4:5] op_sel_hi:[1,0]
	s_nop 0
	v_pk_fma_f32 v[114:115], v[114:115], v[4:5], v[216:217] op_sel:[1,1,0] op_sel_hi:[0,1,1] neg_hi:[0,1,0]
	ds_swizzle_b32 v216, v114 offset:swizzle(SWAP,4)
	ds_swizzle_b32 v217, v115 offset:swizzle(SWAP,4)
	s_waitcnt lgkmcnt(0)
; __device__ __forceinline__ float lx1(float v) { return __int_as_float(__builtin_amdgcn_update_dpp(0, __float_as_int(v), 0xB1, 0xF, 0xF, true)); }
; __device__ __forceinline__ float lx2(float v) { return __int_as_float(__builtin_amdgcn_update_dpp(0, __float_as_int(v), 0x4E, 0xF, 0xF, true)); }
; __device__ __forceinline__ float lx4(float v) { return __int_as_float(__builtin_amdgcn_ds_swizzle(__float_as_int(v), 0x101F)); }
; __device__ __forceinline__ float lx8(float v) { return __int_as_float(__builtin_amdgcn_update_dpp(0, __float_as_int(v), 0x128, 0xF, 0xF, true)); }
; __device__ __forceinline__ void fft_inverse(f2 (&x)[32], LAS f2* X, int t, LAS const float* W1, LAS const M2C* MC) {
;     ...
; #pragma unroll
;     for (int p = 0; p < 32; ++p) {
;         f2 v = x[p], pr;
;         pr = (f2){lx1(v.x), lx1(v.y)}; v = cmulrc(pr + v * c.s1, t2);
;         pr = (f2){lx2(v.x), lx2(v.y)}; v = cmulrc(pr + v * c.s2, t4);
;         pr = (f2){lx4(v.x), lx4(v.y)}; v = cmulrc(pr + v * c.s4, t8);
;         pr = (f2){lx8(v.x), lx8(v.y)}; x[p] = pr + v * c.s8;
;     }
	v_pk_fma_f32 v[114:115], v[8:9], v[114:115], v[216:217] op_sel:[1,0,0]
	s_nop 0
	v_pk_mul_f32 v[216:217], v[114:115], v[2:3] op_sel_hi:[1,0]
	s_nop 0
	v_pk_fma_f32 v[114:115], v[114:115], v[2:3], v[216:217] op_sel:[1,1,0] op_sel_hi:[0,1,1] neg_hi:[0,1,0]
	s_nop 1
	v_mov_b32_dpp v216, v114 row_ror:8 row_mask:0xf bank_mask:0xf bound_ctrl:1
	v_mov_b32_dpp v217, v115 row_ror:8 row_mask:0xf bank_mask:0xf bound_ctrl:1
	v_pk_fma_f32 v[114:115], v[8:9], v[114:115], v[216:217] op_sel_hi:[0,1,1]
	v_mov_b32_dpp v216, v112 quad_perm:[1,0,3,2] row_mask:0xf bank_mask:0xf bound_ctrl:1
	v_mov_b32_dpp v217, v113 quad_perm:[1,0,3,2] row_mask:0xf bank_mask:0xf bound_ctrl:1
	v_pk_fma_f32 v[112:113], v[112:113], v[16:17], v[216:217] op_sel_hi:[1,0,1]
	s_nop 0
	v_pk_mul_f32 v[216:217], v[112:113], v[6:7] op_sel_hi:[1,0]
	s_nop 0
	v_pk_fma_f32 v[112:113], v[112:113], v[6:7], v[216:217] op_sel:[1,1,0] op_sel_hi:[0,1,1] neg_hi:[0,1,0]
	s_nop 1
	v_mov_b32_dpp v216, v112 quad_perm:[2,3,0,1] row_mask:0xf bank_mask:0xf bound_ctrl:1
	v_mov_b32_dpp v217, v113 quad_perm:[2,3,0,1] row_mask:0xf bank_mask:0xf bound_ctrl:1
	v_pk_fma_f32 v[112:113], v[10:11], v[112:113], v[216:217] op_sel_hi:[0,1,1]
	v_pk_mul_f32 v[216:217], v[112:113], v[4:5] op_sel_hi:[1,0]
	s_nop 0
	v_pk_fma_f32 v[112:113], v[112:113], v[4:5], v[216:217] op_sel:[1,1,0] op_sel_hi:[0,1,1] neg_hi:[0,1,0]
	ds_swizzle_b32 v216, v112 offset:swizzle(SWAP,4)
	ds_swizzle_b32 v217, v113 offset:swizzle(SWAP,4)
	s_waitcnt lgkmcnt(0)
	v_pk_fma_f32 v[112:113], v[8:9], v[112:113], v[216:217] op_sel:[1,0,0]
	s_nop 0
	v_pk_mul_f32 v[216:217], v[112:113], v[2:3] op_sel_hi:[1,0]
	s_nop 0
	v_pk_fma_f32 v[112:113], v[112:113], v[2:3], v[216:217] op_sel:[1,1,0] op_sel_hi:[0,1,1] neg_hi:[0,1,0]
	s_nop 1
	v_mov_b32_dpp v216, v112 row_ror:8 row_mask:0xf bank_mask:0xf bound_ctrl:1
	v_mov_b32_dpp v217, v113 row_ror:8 row_mask:0xf bank_mask:0xf bound_ctrl:1
	v_pk_fma_f32 v[112:113], v[8:9], v[112:113], v[216:217] op_sel_hi:[0,1,1]
	v_mov_b32_dpp v216, v126 quad_perm:[1,0,3,2] row_mask:0xf bank_mask:0xf bound_ctrl:1
	v_mov_b32_dpp v217, v127 quad_perm:[1,0,3,2] row_mask:0xf bank_mask:0xf bound_ctrl:1
	v_pk_fma_f32 v[126:127], v[126:127], v[16:17], v[216:217] op_sel_hi:[1,0,1]
	s_nop 0
	v_pk_mul_f32 v[216:217], v[126:127], v[6:7] op_sel_hi:[1,0]
	s_nop 0
	v_pk_fma_f32 v[126:127], v[126:127], v[6:7], v[216:217] op_sel:[1,1,0] op_sel_hi:[0,1,1] neg_hi:[0,1,0]
	s_nop 1
	v_mov_b32_dpp v216, v126 quad_perm:[2,3,0,1] row_mask:0xf bank_mask:0xf bound_ctrl:1
	v_mov_b32_dpp v217, v127 quad_perm:[2,3,0,1] row_mask:0xf bank_mask:0xf bound_ctrl:1
	v_pk_fma_f32 v[126:127], v[10:11], v[126:127], v[216:217] op_sel_hi:[0,1,1]
	v_pk_mul_f32 v[216:217], v[126:127], v[4:5] op_sel_hi:[1,0]
	s_nop 0
	v_pk_fma_f32 v[126:127], v[126:127], v[4:5], v[216:217] op_sel:[1,1,0] op_sel_hi:[0,1,1] neg_hi:[0,1,0]
	ds_swizzle_b32 v216, v126 offset:swizzle(SWAP,4)
	ds_swizzle_b32 v217, v127 offset:swizzle(SWAP,4)
	s_waitcnt lgkmcnt(0)
	v_pk_fma_f32 v[126:127], v[8:9], v[126:127], v[216:217] op_sel:[1,0,0]
	s_nop 0
	v_pk_mul_f32 v[216:217], v[126:127], v[2:3] op_sel_hi:[1,0]
	s_nop 0
	v_pk_fma_f32 v[126:127], v[126:127], v[2:3], v[216:217] op_sel:[1,1,0] op_sel_hi:[0,1,1] neg_hi:[0,1,0]
	s_nop 1
	v_mov_b32_dpp v216, v126 row_ror:8 row_mask:0xf bank_mask:0xf bound_ctrl:1
	v_mov_b32_dpp v217, v127 row_ror:8 row_mask:0xf bank_mask:0xf bound_ctrl:1
	v_pk_fma_f32 v[126:127], v[8:9], v[126:127], v[216:217] op_sel_hi:[0,1,1]
	v_mov_b32_dpp v216, v122 quad_perm:[1,0,3,2] row_mask:0xf bank_mask:0xf bound_ctrl:1
	v_mov_b32_dpp v217, v123 quad_perm:[1,0,3,2] row_mask:0xf bank_mask:0xf bound_ctrl:1
	v_pk_fma_f32 v[122:123], v[122:123], v[16:17], v[216:217] op_sel_hi:[1,0,1]
	s_nop 0
	v_pk_mul_f32 v[216:217], v[122:123], v[6:7] op_sel_hi:[1,0]
	s_nop 0
	v_pk_fma_f32 v[122:123], v[122:123], v[6:7], v[216:217] op_sel:[1,1,0] op_sel_hi:[0,1,1] neg_hi:[0,1,0]
	s_nop 1
	v_mov_b32_dpp v216, v122 quad_perm:[2,3,0,1] row_mask:0xf bank_mask:0xf bound_ctrl:1
	v_mov_b32_dpp v217, v123 quad_perm:[2,3,0,1] row_mask:0xf bank_mask:0xf bound_ctrl:1
	v_pk_fma_f32 v[122:123], v[10:11], v[122:123], v[216:217] op_sel_hi:[0,1,1]
	v_pk_mul_f32 v[216:217], v[122:123], v[4:5] op_sel_hi:[1,0]
	s_nop 0
	v_pk_fma_f32 v[122:123], v[122:123], v[4:5], v[216:217] op_sel:[1,1,0] op_sel_hi:[0,1,1] neg_hi:[0,1,0]
	ds_swizzle_b32 v216, v122 offset:swizzle(SWAP,4)
	ds_swizzle_b32 v217, v123 offset:swizzle(SWAP,4)
	s_waitcnt lgkmcnt(0)
	v_pk_fma_f32 v[122:123], v[8:9], v[122:123], v[216:217] op_sel:[1,0,0]
	s_nop 0
	v_pk_mul_f32 v[216:217], v[122:123], v[2:3] op_sel_hi:[1,0]
	s_nop 0
	v_pk_fma_f32 v[122:123], v[122:123], v[2:3], v[216:217] op_sel:[1,1,0] op_sel_hi:[0,1,1] neg_hi:[0,1,0]
	s_nop 1
	v_mov_b32_dpp v216, v122 row_ror:8 row_mask:0xf bank_mask:0xf bound_ctrl:1
	v_mov_b32_dpp v217, v123 row_ror:8 row_mask:0xf bank_mask:0xf bound_ctrl:1
	v_pk_fma_f32 v[122:123], v[8:9], v[122:123], v[216:217] op_sel_hi:[0,1,1]
	v_mov_b32_dpp v216, v132 quad_perm:[1,0,3,2] row_mask:0xf bank_mask:0xf bound_ctrl:1
	v_mov_b32_dpp v217, v133 quad_perm:[1,0,3,2] row_mask:0xf bank_mask:0xf bound_ctrl:1
	v_pk_fma_f32 v[132:133], v[132:133], v[16:17], v[216:217] op_sel_hi:[1,0,1]
	s_nop 0
	v_pk_mul_f32 v[216:217], v[132:133], v[6:7] op_sel_hi:[1,0]
	s_nop 0
	v_pk_fma_f32 v[132:133], v[132:133], v[6:7], v[216:217] op_sel:[1,1,0] op_sel_hi:[0,1,1] neg_hi:[0,1,0]
	s_nop 1
	v_mov_b32_dpp v216, v132 quad_perm:[2,3,0,1] row_mask:0xf bank_mask:0xf bound_ctrl:1
	v_mov_b32_dpp v217, v133 quad_perm:[2,3,0,1] row_mask:0xf bank_mask:0xf bound_ctrl:1
	v_pk_fma_f32 v[132:133], v[10:11], v[132:133], v[216:217] op_sel_hi:[0,1,1]
	v_pk_mul_f32 v[216:217], v[132:133], v[4:5] op_sel_hi:[1,0]
	s_nop 0
	v_pk_fma_f32 v[132:133], v[132:133], v[4:5], v[216:217] op_sel:[1,1,0] op_sel_hi:[0,1,1] neg_hi:[0,1,0]
	ds_swizzle_b32 v216, v132 offset:swizzle(SWAP,4)
	ds_swizzle_b32 v217, v133 offset:swizzle(SWAP,4)
	s_waitcnt lgkmcnt(0)
; __device__ __forceinline__ float lx1(float v) { return __int_as_float(__builtin_amdgcn_update_dpp(0, __float_as_int(v), 0xB1, 0xF, 0xF, true)); }
; __device__ __forceinline__ float lx2(float v) { return __int_as_float(__builtin_amdgcn_update_dpp(0, __float_as_int(v), 0x4E, 0xF, 0xF, true)); }
; __device__ __forceinline__ float lx4(float v) { return __int_as_float(__builtin_amdgcn_ds_swizzle(__float_as_int(v), 0x101F)); }
; __device__ __forceinline__ float lx8(float v) { return __int_as_float(__builtin_amdgcn_update_dpp(0, __float_as_int(v), 0x128, 0xF, 0xF, true)); }
; __device__ __forceinline__ void fft_inverse(f2 (&x)[32], LAS f2* X, int t, LAS const float* W1, LAS const M2C* MC) {
;     ...
; #pragma unroll
;     for (int p = 0; p < 32; ++p) {
;         f2 v = x[p], pr;
;         pr = (f2){lx1(v.x), lx1(v.y)}; v = cmulrc(pr + v * c.s1, t2);
;         pr = (f2){lx2(v.x), lx2(v.y)}; v = cmulrc(pr + v * c.s2, t4);
;         pr = (f2){lx4(v.x), lx4(v.y)}; v = cmulrc(pr + v * c.s4, t8);
;         pr = (f2){lx8(v.x), lx8(v.y)}; x[p] = pr + v * c.s8;
;     }
	v_pk_fma_f32 v[132:133], v[8:9], v[132:133], v[216:217] op_sel:[1,0,0]
	s_nop 0
	v_pk_mul_f32 v[216:217], v[132:133], v[2:3] op_sel_hi:[1,0]
	s_nop 0
	v_pk_fma_f32 v[132:133], v[132:133], v[2:3], v[216:217] op_sel:[1,1,0] op_sel_hi:[0,1,1] neg_hi:[0,1,0]
	s_nop 1
	v_mov_b32_dpp v216, v132 row_ror:8 row_mask:0xf bank_mask:0xf bound_ctrl:1
	v_mov_b32_dpp v217, v133 row_ror:8 row_mask:0xf bank_mask:0xf bound_ctrl:1
	v_pk_fma_f32 v[132:133], v[8:9], v[132:133], v[216:217] op_sel_hi:[0,1,1]
	v_mov_b32_dpp v216, v130 quad_perm:[1,0,3,2] row_mask:0xf bank_mask:0xf bound_ctrl:1
	v_mov_b32_dpp v217, v131 quad_perm:[1,0,3,2] row_mask:0xf bank_mask:0xf bound_ctrl:1
	v_pk_fma_f32 v[130:131], v[130:131], v[16:17], v[216:217] op_sel_hi:[1,0,1]
	s_nop 0
	v_pk_mul_f32 v[216:217], v[130:131], v[6:7] op_sel_hi:[1,0]
	s_nop 0
	v_pk_fma_f32 v[130:131], v[130:131], v[6:7], v[216:217] op_sel:[1,1,0] op_sel_hi:[0,1,1] neg_hi:[0,1,0]
	s_nop 1
	v_mov_b32_dpp v216, v130 quad_perm:[2,3,0,1] row_mask:0xf bank_mask:0xf bound_ctrl:1
	v_mov_b32_dpp v217, v131 quad_perm:[2,3,0,1] row_mask:0xf bank_mask:0xf bound_ctrl:1
	v_pk_fma_f32 v[130:131], v[10:11], v[130:131], v[216:217] op_sel_hi:[0,1,1]
	v_pk_mul_f32 v[216:217], v[130:131], v[4:5] op_sel_hi:[1,0]
	s_nop 0
	v_pk_fma_f32 v[130:131], v[130:131], v[4:5], v[216:217] op_sel:[1,1,0] op_sel_hi:[0,1,1] neg_hi:[0,1,0]
	ds_swizzle_b32 v216, v130 offset:swizzle(SWAP,4)
	ds_swizzle_b32 v217, v131 offset:swizzle(SWAP,4)
	s_waitcnt lgkmcnt(0)
	v_pk_fma_f32 v[130:131], v[8:9], v[130:131], v[216:217] op_sel:[1,0,0]
	s_nop 0
	v_pk_mul_f32 v[216:217], v[130:131], v[2:3] op_sel_hi:[1,0]
	s_nop 0
	v_pk_fma_f32 v[130:131], v[130:131], v[2:3], v[216:217] op_sel:[1,1,0] op_sel_hi:[0,1,1] neg_hi:[0,1,0]
	s_nop 1
	v_mov_b32_dpp v216, v130 row_ror:8 row_mask:0xf bank_mask:0xf bound_ctrl:1
	v_mov_b32_dpp v217, v131 row_ror:8 row_mask:0xf bank_mask:0xf bound_ctrl:1
	v_pk_fma_f32 v[130:131], v[8:9], v[130:131], v[216:217] op_sel_hi:[0,1,1]
	v_mov_b32_dpp v216, v142 quad_perm:[1,0,3,2] row_mask:0xf bank_mask:0xf bound_ctrl:1
	v_mov_b32_dpp v217, v143 quad_perm:[1,0,3,2] row_mask:0xf bank_mask:0xf bound_ctrl:1
	v_pk_fma_f32 v[142:143], v[142:143], v[16:17], v[216:217] op_sel_hi:[1,0,1]
	s_nop 0
	v_pk_mul_f32 v[216:217], v[142:143], v[6:7] op_sel_hi:[1,0]
	s_nop 0
	v_pk_fma_f32 v[142:143], v[142:143], v[6:7], v[216:217] op_sel:[1,1,0] op_sel_hi:[0,1,1] neg_hi:[0,1,0]
	s_nop 1
	v_mov_b32_dpp v216, v142 quad_perm:[2,3,0,1] row_mask:0xf bank_mask:0xf bound_ctrl:1
	v_mov_b32_dpp v217, v143 quad_perm:[2,3,0,1] row_mask:0xf bank_mask:0xf bound_ctrl:1
	v_pk_fma_f32 v[142:143], v[10:11], v[142:143], v[216:217] op_sel_hi:[0,1,1]
	v_pk_mul_f32 v[216:217], v[142:143], v[4:5] op_sel_hi:[1,0]
	s_nop 0
	v_pk_fma_f32 v[142:143], v[142:143], v[4:5], v[216:217] op_sel:[1,1,0] op_sel_hi:[0,1,1] neg_hi:[0,1,0]
	ds_swizzle_b32 v216, v142 offset:swizzle(SWAP,4)
	ds_swizzle_b32 v217, v143 offset:swizzle(SWAP,4)
	s_waitcnt lgkmcnt(0)
	v_pk_fma_f32 v[142:143], v[8:9], v[142:143], v[216:217] op_sel:[1,0,0]
	s_nop 0
	v_pk_mul_f32 v[216:217], v[142:143], v[2:3] op_sel_hi:[1,0]
	s_nop 0
	v_pk_fma_f32 v[142:143], v[142:143], v[2:3], v[216:217] op_sel:[1,1,0] op_sel_hi:[0,1,1] neg_hi:[0,1,0]
	s_nop 1
	v_mov_b32_dpp v216, v142 row_ror:8 row_mask:0xf bank_mask:0xf bound_ctrl:1
	v_mov_b32_dpp v217, v143 row_ror:8 row_mask:0xf bank_mask:0xf bound_ctrl:1
	v_pk_fma_f32 v[142:143], v[8:9], v[142:143], v[216:217] op_sel_hi:[0,1,1]
	v_mov_b32_dpp v216, v138 quad_perm:[1,0,3,2] row_mask:0xf bank_mask:0xf bound_ctrl:1
	v_mov_b32_dpp v217, v139 quad_perm:[1,0,3,2] row_mask:0xf bank_mask:0xf bound_ctrl:1
	v_pk_fma_f32 v[138:139], v[138:139], v[16:17], v[216:217] op_sel_hi:[1,0,1]
	s_nop 0
	v_pk_mul_f32 v[216:217], v[138:139], v[6:7] op_sel_hi:[1,0]
	s_nop 0
	v_pk_fma_f32 v[138:139], v[138:139], v[6:7], v[216:217] op_sel:[1,1,0] op_sel_hi:[0,1,1] neg_hi:[0,1,0]
	s_nop 1
	v_mov_b32_dpp v216, v138 quad_perm:[2,3,0,1] row_mask:0xf bank_mask:0xf bound_ctrl:1
	v_mov_b32_dpp v217, v139 quad_perm:[2,3,0,1] row_mask:0xf bank_mask:0xf bound_ctrl:1
	v_pk_fma_f32 v[138:139], v[10:11], v[138:139], v[216:217] op_sel_hi:[0,1,1]
	v_pk_mul_f32 v[216:217], v[138:139], v[4:5] op_sel_hi:[1,0]
	s_nop 0
	v_pk_fma_f32 v[138:139], v[138:139], v[4:5], v[216:217] op_sel:[1,1,0] op_sel_hi:[0,1,1] neg_hi:[0,1,0]
	ds_swizzle_b32 v216, v138 offset:swizzle(SWAP,4)
	ds_swizzle_b32 v217, v139 offset:swizzle(SWAP,4)
	s_waitcnt lgkmcnt(0)
	v_pk_fma_f32 v[138:139], v[8:9], v[138:139], v[216:217] op_sel:[1,0,0]
	s_nop 0
	v_pk_mul_f32 v[216:217], v[138:139], v[2:3] op_sel_hi:[1,0]
	s_nop 0
	v_pk_fma_f32 v[138:139], v[138:139], v[2:3], v[216:217] op_sel:[1,1,0] op_sel_hi:[0,1,1] neg_hi:[0,1,0]
	s_nop 1
	v_mov_b32_dpp v216, v138 row_ror:8 row_mask:0xf bank_mask:0xf bound_ctrl:1
	v_mov_b32_dpp v217, v139 row_ror:8 row_mask:0xf bank_mask:0xf bound_ctrl:1
	v_pk_fma_f32 v[138:139], v[8:9], v[138:139], v[216:217] op_sel_hi:[0,1,1]
	v_mov_b32_dpp v216, v148 quad_perm:[1,0,3,2] row_mask:0xf bank_mask:0xf bound_ctrl:1
	v_mov_b32_dpp v217, v149 quad_perm:[1,0,3,2] row_mask:0xf bank_mask:0xf bound_ctrl:1
	v_pk_fma_f32 v[148:149], v[148:149], v[16:17], v[216:217] op_sel_hi:[1,0,1]
	s_nop 0
	v_pk_mul_f32 v[216:217], v[148:149], v[6:7] op_sel_hi:[1,0]
	s_nop 0
	v_pk_fma_f32 v[148:149], v[148:149], v[6:7], v[216:217] op_sel:[1,1,0] op_sel_hi:[0,1,1] neg_hi:[0,1,0]
	s_nop 1
	v_mov_b32_dpp v216, v148 quad_perm:[2,3,0,1] row_mask:0xf bank_mask:0xf bound_ctrl:1
	v_mov_b32_dpp v217, v149 quad_perm:[2,3,0,1] row_mask:0xf bank_mask:0xf bound_ctrl:1
	v_pk_fma_f32 v[148:149], v[10:11], v[148:149], v[216:217] op_sel_hi:[0,1,1]
	v_pk_mul_f32 v[216:217], v[148:149], v[4:5] op_sel_hi:[1,0]
	s_nop 0
	v_pk_fma_f32 v[148:149], v[148:149], v[4:5], v[216:217] op_sel:[1,1,0] op_sel_hi:[0,1,1] neg_hi:[0,1,0]
	ds_swizzle_b32 v216, v148 offset:swizzle(SWAP,4)
	ds_swizzle_b32 v217, v149 offset:swizzle(SWAP,4)
	s_waitcnt lgkmcnt(0)
; __device__ __forceinline__ float lx1(float v) { return __int_as_float(__builtin_amdgcn_update_dpp(0, __float_as_int(v), 0xB1, 0xF, 0xF, true)); }
; __device__ __forceinline__ float lx2(float v) { return __int_as_float(__builtin_amdgcn_update_dpp(0, __float_as_int(v), 0x4E, 0xF, 0xF, true)); }
; __device__ __forceinline__ float lx4(float v) { return __int_as_float(__builtin_amdgcn_ds_swizzle(__float_as_int(v), 0x101F)); }
; __device__ __forceinline__ float lx8(float v) { return __int_as_float(__builtin_amdgcn_update_dpp(0, __float_as_int(v), 0x128, 0xF, 0xF, true)); }
; __device__ __forceinline__ void fft_inverse(f2 (&x)[32], LAS f2* X, int t, LAS const float* W1, LAS const M2C* MC) {
;     ...
; #pragma unroll
;     for (int p = 0; p < 32; ++p) {
;         f2 v = x[p], pr;
;         pr = (f2){lx1(v.x), lx1(v.y)}; v = cmulrc(pr + v * c.s1, t2);
;         pr = (f2){lx2(v.x), lx2(v.y)}; v = cmulrc(pr + v * c.s2, t4);
;         pr = (f2){lx4(v.x), lx4(v.y)}; v = cmulrc(pr + v * c.s4, t8);
;         pr = (f2){lx8(v.x), lx8(v.y)}; x[p] = pr + v * c.s8;
;     }
	v_pk_fma_f32 v[148:149], v[8:9], v[148:149], v[216:217] op_sel:[1,0,0]
	s_nop 0
	v_pk_mul_f32 v[216:217], v[148:149], v[2:3] op_sel_hi:[1,0]
	s_nop 0
	v_pk_fma_f32 v[148:149], v[148:149], v[2:3], v[216:217] op_sel:[1,1,0] op_sel_hi:[0,1,1] neg_hi:[0,1,0]
	s_nop 1
	v_mov_b32_dpp v216, v148 row_ror:8 row_mask:0xf bank_mask:0xf bound_ctrl:1
	v_mov_b32_dpp v217, v149 row_ror:8 row_mask:0xf bank_mask:0xf bound_ctrl:1
	v_pk_fma_f32 v[148:149], v[8:9], v[148:149], v[216:217] op_sel_hi:[0,1,1]
	v_mov_b32_dpp v216, v146 quad_perm:[1,0,3,2] row_mask:0xf bank_mask:0xf bound_ctrl:1
	v_mov_b32_dpp v217, v147 quad_perm:[1,0,3,2] row_mask:0xf bank_mask:0xf bound_ctrl:1
	v_pk_fma_f32 v[146:147], v[146:147], v[16:17], v[216:217] op_sel_hi:[1,0,1]
	s_nop 0
	v_pk_mul_f32 v[216:217], v[146:147], v[6:7] op_sel_hi:[1,0]
	s_nop 0
	v_pk_fma_f32 v[146:147], v[146:147], v[6:7], v[216:217] op_sel:[1,1,0] op_sel_hi:[0,1,1] neg_hi:[0,1,0]
	s_nop 1
	v_mov_b32_dpp v216, v146 quad_perm:[2,3,0,1] row_mask:0xf bank_mask:0xf bound_ctrl:1
	v_mov_b32_dpp v217, v147 quad_perm:[2,3,0,1] row_mask:0xf bank_mask:0xf bound_ctrl:1
	v_pk_fma_f32 v[146:147], v[10:11], v[146:147], v[216:217] op_sel_hi:[0,1,1]
	v_pk_mul_f32 v[216:217], v[146:147], v[4:5] op_sel_hi:[1,0]
	s_nop 0
	v_pk_fma_f32 v[146:147], v[146:147], v[4:5], v[216:217] op_sel:[1,1,0] op_sel_hi:[0,1,1] neg_hi:[0,1,0]
	ds_swizzle_b32 v216, v146 offset:swizzle(SWAP,4)
	ds_swizzle_b32 v217, v147 offset:swizzle(SWAP,4)
	s_waitcnt lgkmcnt(0)
	v_pk_fma_f32 v[146:147], v[8:9], v[146:147], v[216:217] op_sel:[1,0,0]
	s_nop 0
	v_pk_mul_f32 v[216:217], v[146:147], v[2:3] op_sel_hi:[1,0]
	s_nop 0
	v_pk_fma_f32 v[146:147], v[146:147], v[2:3], v[216:217] op_sel:[1,1,0] op_sel_hi:[0,1,1] neg_hi:[0,1,0]
	s_nop 1
	v_mov_b32_dpp v216, v146 row_ror:8 row_mask:0xf bank_mask:0xf bound_ctrl:1
	v_mov_b32_dpp v217, v147 row_ror:8 row_mask:0xf bank_mask:0xf bound_ctrl:1
	v_pk_fma_f32 v[146:147], v[8:9], v[146:147], v[216:217] op_sel_hi:[0,1,1]
	v_mov_b32_dpp v216, v144 quad_perm:[1,0,3,2] row_mask:0xf bank_mask:0xf bound_ctrl:1
	v_mov_b32_dpp v217, v145 quad_perm:[1,0,3,2] row_mask:0xf bank_mask:0xf bound_ctrl:1
	v_pk_fma_f32 v[144:145], v[144:145], v[16:17], v[216:217] op_sel_hi:[1,0,1]
	s_nop 0
	v_pk_mul_f32 v[216:217], v[144:145], v[6:7] op_sel_hi:[1,0]
	s_nop 0
	v_pk_fma_f32 v[144:145], v[144:145], v[6:7], v[216:217] op_sel:[1,1,0] op_sel_hi:[0,1,1] neg_hi:[0,1,0]
	s_nop 1
	v_mov_b32_dpp v216, v144 quad_perm:[2,3,0,1] row_mask:0xf bank_mask:0xf bound_ctrl:1
	v_mov_b32_dpp v217, v145 quad_perm:[2,3,0,1] row_mask:0xf bank_mask:0xf bound_ctrl:1
	v_pk_fma_f32 v[144:145], v[10:11], v[144:145], v[216:217] op_sel_hi:[0,1,1]
	v_pk_mul_f32 v[216:217], v[144:145], v[4:5] op_sel_hi:[1,0]
	s_nop 0
	v_pk_fma_f32 v[144:145], v[144:145], v[4:5], v[216:217] op_sel:[1,1,0] op_sel_hi:[0,1,1] neg_hi:[0,1,0]
	ds_swizzle_b32 v216, v144 offset:swizzle(SWAP,4)
	ds_swizzle_b32 v217, v145 offset:swizzle(SWAP,4)
	s_waitcnt lgkmcnt(0)
	v_pk_fma_f32 v[144:145], v[8:9], v[144:145], v[216:217] op_sel:[1,0,0]
	s_nop 0
	v_pk_mul_f32 v[216:217], v[144:145], v[2:3] op_sel_hi:[1,0]
	s_nop 0
	v_pk_fma_f32 v[144:145], v[144:145], v[2:3], v[216:217] op_sel:[1,1,0] op_sel_hi:[0,1,1] neg_hi:[0,1,0]
	s_nop 1
	v_mov_b32_dpp v216, v144 row_ror:8 row_mask:0xf bank_mask:0xf bound_ctrl:1
	v_mov_b32_dpp v217, v145 row_ror:8 row_mask:0xf bank_mask:0xf bound_ctrl:1
	v_pk_fma_f32 v[144:145], v[8:9], v[144:145], v[216:217] op_sel_hi:[0,1,1]
	v_mov_b32_dpp v216, v140 quad_perm:[1,0,3,2] row_mask:0xf bank_mask:0xf bound_ctrl:1
	v_mov_b32_dpp v217, v141 quad_perm:[1,0,3,2] row_mask:0xf bank_mask:0xf bound_ctrl:1
	v_pk_fma_f32 v[140:141], v[140:141], v[16:17], v[216:217] op_sel_hi:[1,0,1]
	s_nop 0
	v_pk_mul_f32 v[216:217], v[140:141], v[6:7] op_sel_hi:[1,0]
	s_nop 0
	v_pk_fma_f32 v[140:141], v[140:141], v[6:7], v[216:217] op_sel:[1,1,0] op_sel_hi:[0,1,1] neg_hi:[0,1,0]
	s_nop 1
	v_mov_b32_dpp v216, v140 quad_perm:[2,3,0,1] row_mask:0xf bank_mask:0xf bound_ctrl:1
	v_mov_b32_dpp v217, v141 quad_perm:[2,3,0,1] row_mask:0xf bank_mask:0xf bound_ctrl:1
	v_pk_fma_f32 v[140:141], v[10:11], v[140:141], v[216:217] op_sel_hi:[0,1,1]
	v_pk_mul_f32 v[216:217], v[140:141], v[4:5] op_sel_hi:[1,0]
	s_nop 0
	v_pk_fma_f32 v[140:141], v[140:141], v[4:5], v[216:217] op_sel:[1,1,0] op_sel_hi:[0,1,1] neg_hi:[0,1,0]
	ds_swizzle_b32 v216, v140 offset:swizzle(SWAP,4)
	ds_swizzle_b32 v217, v141 offset:swizzle(SWAP,4)
	s_waitcnt lgkmcnt(0)
	v_pk_fma_f32 v[140:141], v[8:9], v[140:141], v[216:217] op_sel:[1,0,0]
	s_nop 0
	v_pk_mul_f32 v[216:217], v[140:141], v[2:3] op_sel_hi:[1,0]
	s_nop 0
	v_pk_fma_f32 v[140:141], v[140:141], v[2:3], v[216:217] op_sel:[1,1,0] op_sel_hi:[0,1,1] neg_hi:[0,1,0]
	s_nop 1
	v_mov_b32_dpp v216, v140 row_ror:8 row_mask:0xf bank_mask:0xf bound_ctrl:1
	v_mov_b32_dpp v217, v141 row_ror:8 row_mask:0xf bank_mask:0xf bound_ctrl:1
	v_pk_fma_f32 v[140:141], v[8:9], v[140:141], v[216:217] op_sel_hi:[0,1,1]
	v_mov_b32_dpp v216, v136 quad_perm:[1,0,3,2] row_mask:0xf bank_mask:0xf bound_ctrl:1
	v_mov_b32_dpp v217, v137 quad_perm:[1,0,3,2] row_mask:0xf bank_mask:0xf bound_ctrl:1
	v_pk_fma_f32 v[136:137], v[136:137], v[16:17], v[216:217] op_sel_hi:[1,0,1]
	s_nop 0
	v_pk_mul_f32 v[216:217], v[136:137], v[6:7] op_sel_hi:[1,0]
	s_nop 0
	v_pk_fma_f32 v[136:137], v[136:137], v[6:7], v[216:217] op_sel:[1,1,0] op_sel_hi:[0,1,1] neg_hi:[0,1,0]
	s_nop 1
	v_mov_b32_dpp v216, v136 quad_perm:[2,3,0,1] row_mask:0xf bank_mask:0xf bound_ctrl:1
	v_mov_b32_dpp v217, v137 quad_perm:[2,3,0,1] row_mask:0xf bank_mask:0xf bound_ctrl:1
	v_pk_fma_f32 v[136:137], v[10:11], v[136:137], v[216:217] op_sel_hi:[0,1,1]
	v_pk_mul_f32 v[216:217], v[136:137], v[4:5] op_sel_hi:[1,0]
	s_nop 0
	v_pk_fma_f32 v[136:137], v[136:137], v[4:5], v[216:217] op_sel:[1,1,0] op_sel_hi:[0,1,1] neg_hi:[0,1,0]
	ds_swizzle_b32 v216, v136 offset:swizzle(SWAP,4)
	ds_swizzle_b32 v217, v137 offset:swizzle(SWAP,4)
	s_waitcnt lgkmcnt(0)
; __device__ __forceinline__ float lx1(float v) { return __int_as_float(__builtin_amdgcn_update_dpp(0, __float_as_int(v), 0xB1, 0xF, 0xF, true)); }
; __device__ __forceinline__ float lx2(float v) { return __int_as_float(__builtin_amdgcn_update_dpp(0, __float_as_int(v), 0x4E, 0xF, 0xF, true)); }
; __device__ __forceinline__ float lx4(float v) { return __int_as_float(__builtin_amdgcn_ds_swizzle(__float_as_int(v), 0x101F)); }
; __device__ __forceinline__ float lx8(float v) { return __int_as_float(__builtin_amdgcn_update_dpp(0, __float_as_int(v), 0x128, 0xF, 0xF, true)); }
; __device__ __forceinline__ void fft_inverse(f2 (&x)[32], LAS f2* X, int t, LAS const float* W1, LAS const M2C* MC) {
;     ...
; #pragma unroll
;     for (int p = 0; p < 32; ++p) {
;         f2 v = x[p], pr;
;         pr = (f2){lx1(v.x), lx1(v.y)}; v = cmulrc(pr + v * c.s1, t2);
;         pr = (f2){lx2(v.x), lx2(v.y)}; v = cmulrc(pr + v * c.s2, t4);
;         pr = (f2){lx4(v.x), lx4(v.y)}; v = cmulrc(pr + v * c.s4, t8);
;         pr = (f2){lx8(v.x), lx8(v.y)}; x[p] = pr + v * c.s8;
;     }
	v_pk_fma_f32 v[136:137], v[8:9], v[136:137], v[216:217] op_sel:[1,0,0]
	s_nop 0
	v_pk_mul_f32 v[216:217], v[136:137], v[2:3] op_sel_hi:[1,0]
	s_nop 0
	v_pk_fma_f32 v[136:137], v[136:137], v[2:3], v[216:217] op_sel:[1,1,0] op_sel_hi:[0,1,1] neg_hi:[0,1,0]
	s_nop 1
	v_mov_b32_dpp v216, v136 row_ror:8 row_mask:0xf bank_mask:0xf bound_ctrl:1
	v_mov_b32_dpp v217, v137 row_ror:8 row_mask:0xf bank_mask:0xf bound_ctrl:1
	v_pk_fma_f32 v[136:137], v[8:9], v[136:137], v[216:217] op_sel_hi:[0,1,1]
	v_mov_b32_dpp v216, v134 quad_perm:[1,0,3,2] row_mask:0xf bank_mask:0xf bound_ctrl:1
	v_mov_b32_dpp v217, v135 quad_perm:[1,0,3,2] row_mask:0xf bank_mask:0xf bound_ctrl:1
	v_pk_fma_f32 v[134:135], v[134:135], v[16:17], v[216:217] op_sel_hi:[1,0,1]
	s_nop 0
	v_pk_mul_f32 v[216:217], v[134:135], v[6:7] op_sel_hi:[1,0]
	s_nop 0
	v_pk_fma_f32 v[134:135], v[134:135], v[6:7], v[216:217] op_sel:[1,1,0] op_sel_hi:[0,1,1] neg_hi:[0,1,0]
	s_nop 1
	v_mov_b32_dpp v216, v134 quad_perm:[2,3,0,1] row_mask:0xf bank_mask:0xf bound_ctrl:1
	v_mov_b32_dpp v217, v135 quad_perm:[2,3,0,1] row_mask:0xf bank_mask:0xf bound_ctrl:1
	v_pk_fma_f32 v[134:135], v[10:11], v[134:135], v[216:217] op_sel_hi:[0,1,1]
	v_pk_mul_f32 v[216:217], v[134:135], v[4:5] op_sel_hi:[1,0]
	s_nop 0
	v_pk_fma_f32 v[134:135], v[134:135], v[4:5], v[216:217] op_sel:[1,1,0] op_sel_hi:[0,1,1] neg_hi:[0,1,0]
	ds_swizzle_b32 v216, v134 offset:swizzle(SWAP,4)
	ds_swizzle_b32 v217, v135 offset:swizzle(SWAP,4)
	s_waitcnt lgkmcnt(0)
	v_pk_fma_f32 v[134:135], v[8:9], v[134:135], v[216:217] op_sel:[1,0,0]
	s_nop 0
	v_pk_mul_f32 v[216:217], v[134:135], v[2:3] op_sel_hi:[1,0]
	s_nop 0
	v_pk_fma_f32 v[134:135], v[134:135], v[2:3], v[216:217] op_sel:[1,1,0] op_sel_hi:[0,1,1] neg_hi:[0,1,0]
	s_nop 1
	v_mov_b32_dpp v216, v134 row_ror:8 row_mask:0xf bank_mask:0xf bound_ctrl:1
	v_mov_b32_dpp v217, v135 row_ror:8 row_mask:0xf bank_mask:0xf bound_ctrl:1
	v_pk_fma_f32 v[134:135], v[8:9], v[134:135], v[216:217] op_sel_hi:[0,1,1]
	v_mov_b32_dpp v216, v128 quad_perm:[1,0,3,2] row_mask:0xf bank_mask:0xf bound_ctrl:1
	v_mov_b32_dpp v217, v129 quad_perm:[1,0,3,2] row_mask:0xf bank_mask:0xf bound_ctrl:1
	v_pk_fma_f32 v[128:129], v[128:129], v[16:17], v[216:217] op_sel_hi:[1,0,1]
	s_nop 0
	v_pk_mul_f32 v[216:217], v[128:129], v[6:7] op_sel_hi:[1,0]
	s_nop 0
	v_pk_fma_f32 v[128:129], v[128:129], v[6:7], v[216:217] op_sel:[1,1,0] op_sel_hi:[0,1,1] neg_hi:[0,1,0]
	s_nop 1
	v_mov_b32_dpp v216, v128 quad_perm:[2,3,0,1] row_mask:0xf bank_mask:0xf bound_ctrl:1
	v_mov_b32_dpp v217, v129 quad_perm:[2,3,0,1] row_mask:0xf bank_mask:0xf bound_ctrl:1
	v_pk_fma_f32 v[128:129], v[10:11], v[128:129], v[216:217] op_sel_hi:[0,1,1]
	v_pk_mul_f32 v[216:217], v[128:129], v[4:5] op_sel_hi:[1,0]
	s_nop 0
	v_pk_fma_f32 v[128:129], v[128:129], v[4:5], v[216:217] op_sel:[1,1,0] op_sel_hi:[0,1,1] neg_hi:[0,1,0]
	ds_swizzle_b32 v216, v128 offset:swizzle(SWAP,4)
	ds_swizzle_b32 v217, v129 offset:swizzle(SWAP,4)
	s_waitcnt lgkmcnt(0)
	v_pk_fma_f32 v[128:129], v[8:9], v[128:129], v[216:217] op_sel:[1,0,0]
	s_nop 0
	v_pk_mul_f32 v[216:217], v[128:129], v[2:3] op_sel_hi:[1,0]
	s_nop 0
	v_pk_fma_f32 v[128:129], v[128:129], v[2:3], v[216:217] op_sel:[1,1,0] op_sel_hi:[0,1,1] neg_hi:[0,1,0]
	s_nop 1
	v_mov_b32_dpp v216, v128 row_ror:8 row_mask:0xf bank_mask:0xf bound_ctrl:1
	v_mov_b32_dpp v217, v129 row_ror:8 row_mask:0xf bank_mask:0xf bound_ctrl:1
	v_pk_fma_f32 v[128:129], v[8:9], v[128:129], v[216:217] op_sel_hi:[0,1,1]
	v_mov_b32_dpp v216, v124 quad_perm:[1,0,3,2] row_mask:0xf bank_mask:0xf bound_ctrl:1
	v_mov_b32_dpp v217, v125 quad_perm:[1,0,3,2] row_mask:0xf bank_mask:0xf bound_ctrl:1
	v_pk_fma_f32 v[124:125], v[124:125], v[16:17], v[216:217] op_sel_hi:[1,0,1]
	s_nop 0
	v_pk_mul_f32 v[216:217], v[124:125], v[6:7] op_sel_hi:[1,0]
	s_nop 0
	v_pk_fma_f32 v[124:125], v[124:125], v[6:7], v[216:217] op_sel:[1,1,0] op_sel_hi:[0,1,1] neg_hi:[0,1,0]
	s_nop 1
	v_mov_b32_dpp v216, v124 quad_perm:[2,3,0,1] row_mask:0xf bank_mask:0xf bound_ctrl:1
	v_mov_b32_dpp v217, v125 quad_perm:[2,3,0,1] row_mask:0xf bank_mask:0xf bound_ctrl:1
	v_pk_fma_f32 v[124:125], v[10:11], v[124:125], v[216:217] op_sel_hi:[0,1,1]
	v_pk_mul_f32 v[216:217], v[124:125], v[4:5] op_sel_hi:[1,0]
	s_nop 0
	v_pk_fma_f32 v[124:125], v[124:125], v[4:5], v[216:217] op_sel:[1,1,0] op_sel_hi:[0,1,1] neg_hi:[0,1,0]
	ds_swizzle_b32 v216, v124 offset:swizzle(SWAP,4)
	ds_swizzle_b32 v217, v125 offset:swizzle(SWAP,4)
	s_waitcnt lgkmcnt(0)
	v_pk_fma_f32 v[124:125], v[8:9], v[124:125], v[216:217] op_sel:[1,0,0]
	s_nop 0
	v_pk_mul_f32 v[216:217], v[124:125], v[2:3] op_sel_hi:[1,0]
	s_nop 0
	v_pk_fma_f32 v[124:125], v[124:125], v[2:3], v[216:217] op_sel:[1,1,0] op_sel_hi:[0,1,1] neg_hi:[0,1,0]
	s_nop 1
	v_mov_b32_dpp v216, v124 row_ror:8 row_mask:0xf bank_mask:0xf bound_ctrl:1
	v_mov_b32_dpp v217, v125 row_ror:8 row_mask:0xf bank_mask:0xf bound_ctrl:1
	v_pk_fma_f32 v[124:125], v[8:9], v[124:125], v[216:217] op_sel_hi:[0,1,1]
	v_mov_b32_dpp v216, v120 quad_perm:[1,0,3,2] row_mask:0xf bank_mask:0xf bound_ctrl:1
	v_mov_b32_dpp v217, v121 quad_perm:[1,0,3,2] row_mask:0xf bank_mask:0xf bound_ctrl:1
	v_pk_fma_f32 v[120:121], v[120:121], v[16:17], v[216:217] op_sel_hi:[1,0,1]
	s_nop 0
	v_pk_mul_f32 v[216:217], v[120:121], v[6:7] op_sel_hi:[1,0]
	s_nop 0
	v_pk_fma_f32 v[120:121], v[120:121], v[6:7], v[216:217] op_sel:[1,1,0] op_sel_hi:[0,1,1] neg_hi:[0,1,0]
	s_nop 1
	v_mov_b32_dpp v216, v120 quad_perm:[2,3,0,1] row_mask:0xf bank_mask:0xf bound_ctrl:1
	v_mov_b32_dpp v217, v121 quad_perm:[2,3,0,1] row_mask:0xf bank_mask:0xf bound_ctrl:1
	v_pk_fma_f32 v[120:121], v[10:11], v[120:121], v[216:217] op_sel_hi:[0,1,1]
	v_pk_mul_f32 v[216:217], v[120:121], v[4:5] op_sel_hi:[1,0]
	s_nop 0
	v_pk_fma_f32 v[120:121], v[120:121], v[4:5], v[216:217] op_sel:[1,1,0] op_sel_hi:[0,1,1] neg_hi:[0,1,0]
	ds_swizzle_b32 v216, v120 offset:swizzle(SWAP,4)
	ds_swizzle_b32 v217, v121 offset:swizzle(SWAP,4)
	s_waitcnt lgkmcnt(0)
; __device__ __forceinline__ float lx1(float v) { return __int_as_float(__builtin_amdgcn_update_dpp(0, __float_as_int(v), 0xB1, 0xF, 0xF, true)); }
; __device__ __forceinline__ float lx2(float v) { return __int_as_float(__builtin_amdgcn_update_dpp(0, __float_as_int(v), 0x4E, 0xF, 0xF, true)); }
; __device__ __forceinline__ float lx4(float v) { return __int_as_float(__builtin_amdgcn_ds_swizzle(__float_as_int(v), 0x101F)); }
; __device__ __forceinline__ float lx8(float v) { return __int_as_float(__builtin_amdgcn_update_dpp(0, __float_as_int(v), 0x128, 0xF, 0xF, true)); }
; __device__ __forceinline__ void fft_inverse(f2 (&x)[32], LAS f2* X, int t, LAS const float* W1, LAS const M2C* MC) {
;     ...
; #pragma unroll
;     for (int p = 0; p < 32; ++p) {
;         f2 v = x[p], pr;
;         pr = (f2){lx1(v.x), lx1(v.y)}; v = cmulrc(pr + v * c.s1, t2);
;         pr = (f2){lx2(v.x), lx2(v.y)}; v = cmulrc(pr + v * c.s2, t4);
;         pr = (f2){lx4(v.x), lx4(v.y)}; v = cmulrc(pr + v * c.s4, t8);
;         pr = (f2){lx8(v.x), lx8(v.y)}; x[p] = pr + v * c.s8;
;     }
	v_pk_fma_f32 v[120:121], v[8:9], v[120:121], v[216:217] op_sel:[1,0,0]
	s_nop 0
	v_pk_mul_f32 v[216:217], v[120:121], v[2:3] op_sel_hi:[1,0]
	s_nop 0
	v_pk_fma_f32 v[120:121], v[120:121], v[2:3], v[216:217] op_sel:[1,1,0] op_sel_hi:[0,1,1] neg_hi:[0,1,0]
	s_nop 1
	v_mov_b32_dpp v216, v120 row_ror:8 row_mask:0xf bank_mask:0xf bound_ctrl:1
	v_mov_b32_dpp v217, v121 row_ror:8 row_mask:0xf bank_mask:0xf bound_ctrl:1
	v_pk_fma_f32 v[120:121], v[8:9], v[120:121], v[216:217] op_sel_hi:[0,1,1]
	v_mov_b32_dpp v216, v118 quad_perm:[1,0,3,2] row_mask:0xf bank_mask:0xf bound_ctrl:1
	v_mov_b32_dpp v217, v119 quad_perm:[1,0,3,2] row_mask:0xf bank_mask:0xf bound_ctrl:1
	v_pk_fma_f32 v[118:119], v[118:119], v[16:17], v[216:217] op_sel_hi:[1,0,1]
	s_nop 0
	v_pk_mul_f32 v[216:217], v[118:119], v[6:7] op_sel_hi:[1,0]
	s_nop 0
	v_pk_fma_f32 v[118:119], v[118:119], v[6:7], v[216:217] op_sel:[1,1,0] op_sel_hi:[0,1,1] neg_hi:[0,1,0]
	s_nop 1
	v_mov_b32_dpp v216, v118 quad_perm:[2,3,0,1] row_mask:0xf bank_mask:0xf bound_ctrl:1
	v_mov_b32_dpp v217, v119 quad_perm:[2,3,0,1] row_mask:0xf bank_mask:0xf bound_ctrl:1
	v_pk_fma_f32 v[118:119], v[10:11], v[118:119], v[216:217] op_sel_hi:[0,1,1]
	v_pk_mul_f32 v[216:217], v[118:119], v[4:5] op_sel_hi:[1,0]
	s_nop 0
	v_pk_fma_f32 v[118:119], v[118:119], v[4:5], v[216:217] op_sel:[1,1,0] op_sel_hi:[0,1,1] neg_hi:[0,1,0]
	ds_swizzle_b32 v216, v118 offset:swizzle(SWAP,4)
	ds_swizzle_b32 v217, v119 offset:swizzle(SWAP,4)
	s_waitcnt lgkmcnt(0)
	v_pk_fma_f32 v[118:119], v[8:9], v[118:119], v[216:217] op_sel:[1,0,0]
	s_nop 0
	v_pk_mul_f32 v[216:217], v[118:119], v[2:3] op_sel_hi:[1,0]
	s_nop 0
	v_pk_fma_f32 v[118:119], v[118:119], v[2:3], v[216:217] op_sel:[1,1,0] op_sel_hi:[0,1,1] neg_hi:[0,1,0]
	s_nop 1
	v_mov_b32_dpp v216, v118 row_ror:8 row_mask:0xf bank_mask:0xf bound_ctrl:1
	v_mov_b32_dpp v217, v119 row_ror:8 row_mask:0xf bank_mask:0xf bound_ctrl:1
	v_pk_fma_f32 v[118:119], v[8:9], v[118:119], v[216:217] op_sel_hi:[0,1,1]
	v_mov_b32_dpp v216, v116 quad_perm:[1,0,3,2] row_mask:0xf bank_mask:0xf bound_ctrl:1
	v_mov_b32_dpp v217, v117 quad_perm:[1,0,3,2] row_mask:0xf bank_mask:0xf bound_ctrl:1
	v_pk_fma_f32 v[116:117], v[116:117], v[16:17], v[216:217] op_sel_hi:[1,0,1]
	s_nop 0
	v_pk_mul_f32 v[216:217], v[116:117], v[6:7] op_sel_hi:[1,0]
	s_nop 0
	v_pk_fma_f32 v[116:117], v[116:117], v[6:7], v[216:217] op_sel:[1,1,0] op_sel_hi:[0,1,1] neg_hi:[0,1,0]
	s_nop 1
	v_mov_b32_dpp v216, v116 quad_perm:[2,3,0,1] row_mask:0xf bank_mask:0xf bound_ctrl:1
	v_mov_b32_dpp v217, v117 quad_perm:[2,3,0,1] row_mask:0xf bank_mask:0xf bound_ctrl:1
	v_pk_fma_f32 v[116:117], v[10:11], v[116:117], v[216:217] op_sel_hi:[0,1,1]
	v_pk_mul_f32 v[216:217], v[116:117], v[4:5] op_sel_hi:[1,0]
	s_nop 0
	v_pk_fma_f32 v[116:117], v[116:117], v[4:5], v[216:217] op_sel:[1,1,0] op_sel_hi:[0,1,1] neg_hi:[0,1,0]
	ds_swizzle_b32 v216, v116 offset:swizzle(SWAP,4)
	ds_swizzle_b32 v217, v117 offset:swizzle(SWAP,4)
	s_waitcnt lgkmcnt(0)
	v_pk_fma_f32 v[116:117], v[8:9], v[116:117], v[216:217] op_sel:[1,0,0]
	s_nop 0
	v_pk_mul_f32 v[216:217], v[116:117], v[2:3] op_sel_hi:[1,0]
	s_nop 0
	v_pk_fma_f32 v[116:117], v[116:117], v[2:3], v[216:217] op_sel:[1,1,0] op_sel_hi:[0,1,1] neg_hi:[0,1,0]
	s_nop 1
	v_mov_b32_dpp v216, v116 row_ror:8 row_mask:0xf bank_mask:0xf bound_ctrl:1
	v_mov_b32_dpp v217, v117 row_ror:8 row_mask:0xf bank_mask:0xf bound_ctrl:1
	v_pk_fma_f32 v[116:117], v[8:9], v[116:117], v[216:217] op_sel_hi:[0,1,1]
	v_mov_b32_dpp v216, v110 quad_perm:[1,0,3,2] row_mask:0xf bank_mask:0xf bound_ctrl:1
	v_mov_b32_dpp v217, v111 quad_perm:[1,0,3,2] row_mask:0xf bank_mask:0xf bound_ctrl:1
	v_pk_fma_f32 v[110:111], v[110:111], v[16:17], v[216:217] op_sel_hi:[1,0,1]
	s_nop 0
	v_pk_mul_f32 v[216:217], v[110:111], v[6:7] op_sel_hi:[1,0]
	s_nop 0
	v_pk_fma_f32 v[110:111], v[110:111], v[6:7], v[216:217] op_sel:[1,1,0] op_sel_hi:[0,1,1] neg_hi:[0,1,0]
	s_nop 1
	v_mov_b32_dpp v216, v110 quad_perm:[2,3,0,1] row_mask:0xf bank_mask:0xf bound_ctrl:1
	v_mov_b32_dpp v217, v111 quad_perm:[2,3,0,1] row_mask:0xf bank_mask:0xf bound_ctrl:1
	v_pk_fma_f32 v[110:111], v[10:11], v[110:111], v[216:217] op_sel_hi:[0,1,1]
	v_pk_mul_f32 v[216:217], v[110:111], v[4:5] op_sel_hi:[1,0]
	s_nop 0
	v_pk_fma_f32 v[110:111], v[110:111], v[4:5], v[216:217] op_sel:[1,1,0] op_sel_hi:[0,1,1] neg_hi:[0,1,0]
	ds_swizzle_b32 v216, v110 offset:swizzle(SWAP,4)
	ds_swizzle_b32 v217, v111 offset:swizzle(SWAP,4)
	s_waitcnt lgkmcnt(0)
	v_pk_fma_f32 v[110:111], v[8:9], v[110:111], v[216:217] op_sel:[1,0,0]
	s_nop 0
	v_pk_mul_f32 v[216:217], v[110:111], v[2:3] op_sel_hi:[1,0]
	s_nop 0
	v_pk_fma_f32 v[110:111], v[110:111], v[2:3], v[216:217] op_sel:[1,1,0] op_sel_hi:[0,1,1] neg_hi:[0,1,0]
	s_nop 1
	v_mov_b32_dpp v216, v110 row_ror:8 row_mask:0xf bank_mask:0xf bound_ctrl:1
	v_mov_b32_dpp v217, v111 row_ror:8 row_mask:0xf bank_mask:0xf bound_ctrl:1
	v_pk_fma_f32 v[110:111], v[8:9], v[110:111], v[216:217] op_sel_hi:[0,1,1]
	v_mov_b32_dpp v216, v106 quad_perm:[1,0,3,2] row_mask:0xf bank_mask:0xf bound_ctrl:1
	v_mov_b32_dpp v217, v107 quad_perm:[1,0,3,2] row_mask:0xf bank_mask:0xf bound_ctrl:1
	v_pk_fma_f32 v[106:107], v[106:107], v[16:17], v[216:217] op_sel_hi:[1,0,1]
	s_nop 0
	v_pk_mul_f32 v[216:217], v[106:107], v[6:7] op_sel_hi:[1,0]
	s_nop 0
	v_pk_fma_f32 v[106:107], v[106:107], v[6:7], v[216:217] op_sel:[1,1,0] op_sel_hi:[0,1,1] neg_hi:[0,1,0]
	s_nop 1
	v_mov_b32_dpp v216, v106 quad_perm:[2,3,0,1] row_mask:0xf bank_mask:0xf bound_ctrl:1
	v_mov_b32_dpp v217, v107 quad_perm:[2,3,0,1] row_mask:0xf bank_mask:0xf bound_ctrl:1
	v_pk_fma_f32 v[106:107], v[10:11], v[106:107], v[216:217] op_sel_hi:[0,1,1]
	v_pk_mul_f32 v[216:217], v[106:107], v[4:5] op_sel_hi:[1,0]
	s_nop 0
	v_pk_fma_f32 v[106:107], v[106:107], v[4:5], v[216:217] op_sel:[1,1,0] op_sel_hi:[0,1,1] neg_hi:[0,1,0]
	ds_swizzle_b32 v216, v106 offset:swizzle(SWAP,4)
	ds_swizzle_b32 v217, v107 offset:swizzle(SWAP,4)
	s_waitcnt lgkmcnt(0)
; __device__ __forceinline__ float lx1(float v) { return __int_as_float(__builtin_amdgcn_update_dpp(0, __float_as_int(v), 0xB1, 0xF, 0xF, true)); }
; __device__ __forceinline__ float lx2(float v) { return __int_as_float(__builtin_amdgcn_update_dpp(0, __float_as_int(v), 0x4E, 0xF, 0xF, true)); }
; __device__ __forceinline__ float lx4(float v) { return __int_as_float(__builtin_amdgcn_ds_swizzle(__float_as_int(v), 0x101F)); }
; __device__ __forceinline__ float lx8(float v) { return __int_as_float(__builtin_amdgcn_update_dpp(0, __float_as_int(v), 0x128, 0xF, 0xF, true)); }
; __device__ __forceinline__ void fft_inverse(f2 (&x)[32], LAS f2* X, int t, LAS const float* W1, LAS const M2C* MC) {
;     ...
; #pragma unroll
;     for (int p = 0; p < 32; ++p) {
;         f2 v = x[p], pr;
;         pr = (f2){lx1(v.x), lx1(v.y)}; v = cmulrc(pr + v * c.s1, t2);
;         pr = (f2){lx2(v.x), lx2(v.y)}; v = cmulrc(pr + v * c.s2, t4);
;         pr = (f2){lx4(v.x), lx4(v.y)}; v = cmulrc(pr + v * c.s4, t8);
;         pr = (f2){lx8(v.x), lx8(v.y)}; x[p] = pr + v * c.s8;
;     }
	v_pk_fma_f32 v[106:107], v[8:9], v[106:107], v[216:217] op_sel:[1,0,0]
	s_nop 0
	v_pk_mul_f32 v[216:217], v[106:107], v[2:3] op_sel_hi:[1,0]
	s_nop 0
	v_pk_fma_f32 v[106:107], v[106:107], v[2:3], v[216:217] op_sel:[1,1,0] op_sel_hi:[0,1,1] neg_hi:[0,1,0]
	s_nop 1
	v_mov_b32_dpp v216, v106 row_ror:8 row_mask:0xf bank_mask:0xf bound_ctrl:1
	v_mov_b32_dpp v217, v107 row_ror:8 row_mask:0xf bank_mask:0xf bound_ctrl:1
	v_pk_fma_f32 v[106:107], v[8:9], v[106:107], v[216:217] op_sel_hi:[0,1,1]
	v_mov_b32_dpp v216, v102 quad_perm:[1,0,3,2] row_mask:0xf bank_mask:0xf bound_ctrl:1
	v_mov_b32_dpp v217, v103 quad_perm:[1,0,3,2] row_mask:0xf bank_mask:0xf bound_ctrl:1
	v_pk_fma_f32 v[102:103], v[102:103], v[16:17], v[216:217] op_sel_hi:[1,0,1]
	s_nop 0
	v_pk_mul_f32 v[216:217], v[102:103], v[6:7] op_sel_hi:[1,0]
	s_nop 0
	v_pk_fma_f32 v[102:103], v[102:103], v[6:7], v[216:217] op_sel:[1,1,0] op_sel_hi:[0,1,1] neg_hi:[0,1,0]
	s_nop 1
	v_mov_b32_dpp v216, v102 quad_perm:[2,3,0,1] row_mask:0xf bank_mask:0xf bound_ctrl:1
	v_mov_b32_dpp v217, v103 quad_perm:[2,3,0,1] row_mask:0xf bank_mask:0xf bound_ctrl:1
	v_pk_fma_f32 v[102:103], v[10:11], v[102:103], v[216:217] op_sel_hi:[0,1,1]
	v_pk_mul_f32 v[216:217], v[102:103], v[4:5] op_sel_hi:[1,0]
	s_nop 0
	v_pk_fma_f32 v[102:103], v[102:103], v[4:5], v[216:217] op_sel:[1,1,0] op_sel_hi:[0,1,1] neg_hi:[0,1,0]
	ds_swizzle_b32 v216, v102 offset:swizzle(SWAP,4)
	ds_swizzle_b32 v217, v103 offset:swizzle(SWAP,4)
	s_waitcnt lgkmcnt(0)
	v_pk_fma_f32 v[102:103], v[8:9], v[102:103], v[216:217] op_sel:[1,0,0]
	s_nop 0
	v_pk_mul_f32 v[216:217], v[102:103], v[2:3] op_sel_hi:[1,0]
	s_nop 0
	v_pk_fma_f32 v[102:103], v[102:103], v[2:3], v[216:217] op_sel:[1,1,0] op_sel_hi:[0,1,1] neg_hi:[0,1,0]
	s_nop 1
	v_mov_b32_dpp v216, v102 row_ror:8 row_mask:0xf bank_mask:0xf bound_ctrl:1
	v_mov_b32_dpp v217, v103 row_ror:8 row_mask:0xf bank_mask:0xf bound_ctrl:1
	v_pk_fma_f32 v[102:103], v[8:9], v[102:103], v[216:217] op_sel_hi:[0,1,1]
	v_mov_b32_dpp v216, v100 quad_perm:[1,0,3,2] row_mask:0xf bank_mask:0xf bound_ctrl:1
	v_mov_b32_dpp v217, v101 quad_perm:[1,0,3,2] row_mask:0xf bank_mask:0xf bound_ctrl:1
	v_pk_fma_f32 v[100:101], v[100:101], v[16:17], v[216:217] op_sel_hi:[1,0,1]
	s_nop 0
	v_pk_mul_f32 v[216:217], v[100:101], v[6:7] op_sel_hi:[1,0]
	s_nop 0
	v_pk_fma_f32 v[100:101], v[100:101], v[6:7], v[216:217] op_sel:[1,1,0] op_sel_hi:[0,1,1] neg_hi:[0,1,0]
	s_nop 1
	v_mov_b32_dpp v216, v100 quad_perm:[2,3,0,1] row_mask:0xf bank_mask:0xf bound_ctrl:1
	v_mov_b32_dpp v217, v101 quad_perm:[2,3,0,1] row_mask:0xf bank_mask:0xf bound_ctrl:1
	v_pk_fma_f32 v[100:101], v[10:11], v[100:101], v[216:217] op_sel_hi:[0,1,1]
	v_pk_mul_f32 v[216:217], v[100:101], v[4:5] op_sel_hi:[1,0]
	s_nop 0
	v_pk_fma_f32 v[100:101], v[100:101], v[4:5], v[216:217] op_sel:[1,1,0] op_sel_hi:[0,1,1] neg_hi:[0,1,0]
	ds_swizzle_b32 v216, v100 offset:swizzle(SWAP,4)
	ds_swizzle_b32 v217, v101 offset:swizzle(SWAP,4)
	s_waitcnt lgkmcnt(0)
	v_pk_fma_f32 v[100:101], v[8:9], v[100:101], v[216:217] op_sel:[1,0,0]
	s_nop 0
	v_pk_mul_f32 v[216:217], v[100:101], v[2:3] op_sel_hi:[1,0]
	s_nop 0
	v_pk_fma_f32 v[100:101], v[100:101], v[2:3], v[216:217] op_sel:[1,1,0] op_sel_hi:[0,1,1] neg_hi:[0,1,0]
	s_nop 1
	v_mov_b32_dpp v216, v100 row_ror:8 row_mask:0xf bank_mask:0xf bound_ctrl:1
	v_mov_b32_dpp v217, v101 row_ror:8 row_mask:0xf bank_mask:0xf bound_ctrl:1
	v_pk_fma_f32 v[100:101], v[8:9], v[100:101], v[216:217] op_sel_hi:[0,1,1]
	v_mov_b32_dpp v216, v94 quad_perm:[1,0,3,2] row_mask:0xf bank_mask:0xf bound_ctrl:1
	v_mov_b32_dpp v217, v95 quad_perm:[1,0,3,2] row_mask:0xf bank_mask:0xf bound_ctrl:1
	v_pk_fma_f32 v[94:95], v[94:95], v[16:17], v[216:217] op_sel_hi:[1,0,1]
	s_nop 0
	v_pk_mul_f32 v[216:217], v[94:95], v[6:7] op_sel_hi:[1,0]
	s_nop 0
	v_pk_fma_f32 v[94:95], v[94:95], v[6:7], v[216:217] op_sel:[1,1,0] op_sel_hi:[0,1,1] neg_hi:[0,1,0]
	s_nop 1
	v_mov_b32_dpp v216, v94 quad_perm:[2,3,0,1] row_mask:0xf bank_mask:0xf bound_ctrl:1
	v_mov_b32_dpp v217, v95 quad_perm:[2,3,0,1] row_mask:0xf bank_mask:0xf bound_ctrl:1
	v_pk_fma_f32 v[94:95], v[10:11], v[94:95], v[216:217] op_sel_hi:[0,1,1]
	v_pk_mul_f32 v[216:217], v[94:95], v[4:5] op_sel_hi:[1,0]
	s_nop 0
	v_pk_fma_f32 v[94:95], v[94:95], v[4:5], v[216:217] op_sel:[1,1,0] op_sel_hi:[0,1,1] neg_hi:[0,1,0]
	ds_swizzle_b32 v216, v94 offset:swizzle(SWAP,4)
	ds_swizzle_b32 v217, v95 offset:swizzle(SWAP,4)
	s_waitcnt lgkmcnt(0)
	v_pk_fma_f32 v[94:95], v[8:9], v[94:95], v[216:217] op_sel:[1,0,0]
	s_nop 0
	v_pk_mul_f32 v[216:217], v[94:95], v[2:3] op_sel_hi:[1,0]
	s_nop 0
	v_pk_fma_f32 v[94:95], v[94:95], v[2:3], v[216:217] op_sel:[1,1,0] op_sel_hi:[0,1,1] neg_hi:[0,1,0]
	s_nop 1
	v_mov_b32_dpp v216, v94 row_ror:8 row_mask:0xf bank_mask:0xf bound_ctrl:1
	v_mov_b32_dpp v217, v95 row_ror:8 row_mask:0xf bank_mask:0xf bound_ctrl:1
	v_pk_fma_f32 v[94:95], v[8:9], v[94:95], v[216:217] op_sel_hi:[0,1,1]
	v_mov_b32_dpp v216, v92 quad_perm:[1,0,3,2] row_mask:0xf bank_mask:0xf bound_ctrl:1
	v_mov_b32_dpp v217, v93 quad_perm:[1,0,3,2] row_mask:0xf bank_mask:0xf bound_ctrl:1
	v_pk_fma_f32 v[92:93], v[92:93], v[16:17], v[216:217] op_sel_hi:[1,0,1]
	s_nop 0
	v_pk_mul_f32 v[216:217], v[92:93], v[6:7] op_sel_hi:[1,0]
	s_nop 0
	v_pk_fma_f32 v[92:93], v[92:93], v[6:7], v[216:217] op_sel:[1,1,0] op_sel_hi:[0,1,1] neg_hi:[0,1,0]
	s_nop 1
	v_mov_b32_dpp v216, v92 quad_perm:[2,3,0,1] row_mask:0xf bank_mask:0xf bound_ctrl:1
	v_mov_b32_dpp v217, v93 quad_perm:[2,3,0,1] row_mask:0xf bank_mask:0xf bound_ctrl:1
	v_pk_fma_f32 v[92:93], v[10:11], v[92:93], v[216:217] op_sel_hi:[0,1,1]
	v_pk_mul_f32 v[216:217], v[92:93], v[4:5] op_sel_hi:[1,0]
	s_nop 0
	v_pk_fma_f32 v[92:93], v[92:93], v[4:5], v[216:217] op_sel:[1,1,0] op_sel_hi:[0,1,1] neg_hi:[0,1,0]
	ds_swizzle_b32 v216, v92 offset:swizzle(SWAP,4)
	ds_swizzle_b32 v217, v93 offset:swizzle(SWAP,4)
	s_waitcnt lgkmcnt(0)
; __device__ __forceinline__ float lx1(float v) { return __int_as_float(__builtin_amdgcn_update_dpp(0, __float_as_int(v), 0xB1, 0xF, 0xF, true)); }
; __device__ __forceinline__ float lx2(float v) { return __int_as_float(__builtin_amdgcn_update_dpp(0, __float_as_int(v), 0x4E, 0xF, 0xF, true)); }
; __device__ __forceinline__ float lx4(float v) { return __int_as_float(__builtin_amdgcn_ds_swizzle(__float_as_int(v), 0x101F)); }
; __device__ __forceinline__ float lx8(float v) { return __int_as_float(__builtin_amdgcn_update_dpp(0, __float_as_int(v), 0x128, 0xF, 0xF, true)); }
; template <bool CONJ> __device__ __forceinline__ void twiddle32(f2 (&x)[32], float wr, float wi) {
;     asm volatile("" : "+v"(wr), "+v"(wi));
;     f2 c = (f2){wr, CONJ ? -wi : wi}; const f2 w = c;
; #pragma unroll
;     for (int k = 1; k < 32; ++k) { const int p = brev5(k); x[p] = cmulr(x[p], c); if (k < 31) c = cmulr(c, w); }
; }
; __device__ __forceinline__ void fft_inverse(f2 (&x)[32], LAS f2* X, int t, LAS const float* W1, LAS const M2C* MC) {
;     ...
;     for (int p = 0; p < 32; ++p) {
;         f2 v = x[p], pr;
;         pr = (f2){lx1(v.x), lx1(v.y)}; v = cmulrc(pr + v * c.s1, t2);
;         pr = (f2){lx2(v.x), lx2(v.y)}; v = cmulrc(pr + v * c.s2, t4);
;         pr = (f2){lx4(v.x), lx4(v.y)}; v = cmulrc(pr + v * c.s4, t8);
;         pr = (f2){lx8(v.x), lx8(v.y)}; x[p] = pr + v * c.s8;
;     }
	v_pk_fma_f32 v[92:93], v[8:9], v[92:93], v[216:217] op_sel:[1,0,0]
	s_nop 0
	v_pk_mul_f32 v[216:217], v[92:93], v[2:3] op_sel_hi:[1,0]
	s_nop 0
	v_pk_fma_f32 v[92:93], v[92:93], v[2:3], v[216:217] op_sel:[1,1,0] op_sel_hi:[0,1,1] neg_hi:[0,1,0]
	s_nop 1
	v_mov_b32_dpp v216, v92 row_ror:8 row_mask:0xf bank_mask:0xf bound_ctrl:1
	v_mov_b32_dpp v217, v93 row_ror:8 row_mask:0xf bank_mask:0xf bound_ctrl:1
	v_pk_fma_f32 v[92:93], v[8:9], v[92:93], v[216:217] op_sel_hi:[0,1,1]
	v_mov_b32_dpp v216, v88 quad_perm:[1,0,3,2] row_mask:0xf bank_mask:0xf bound_ctrl:1
	v_mov_b32_dpp v217, v89 quad_perm:[1,0,3,2] row_mask:0xf bank_mask:0xf bound_ctrl:1
	v_pk_fma_f32 v[88:89], v[88:89], v[16:17], v[216:217] op_sel_hi:[1,0,1]
	s_nop 0
	v_pk_mul_f32 v[216:217], v[88:89], v[6:7] op_sel_hi:[1,0]
	s_nop 0
	v_pk_fma_f32 v[6:7], v[88:89], v[6:7], v[216:217] op_sel:[1,1,0] op_sel_hi:[0,1,1] neg_hi:[0,1,0]
	s_nop 1
	v_mov_b32_dpp v88, v6 quad_perm:[2,3,0,1] row_mask:0xf bank_mask:0xf bound_ctrl:1
	v_mov_b32_dpp v89, v7 quad_perm:[2,3,0,1] row_mask:0xf bank_mask:0xf bound_ctrl:1
	v_pk_fma_f32 v[6:7], v[10:11], v[6:7], v[88:89] op_sel_hi:[0,1,1]
	v_pk_mul_f32 v[10:11], v[6:7], v[4:5] op_sel_hi:[1,0]
	s_nop 0
	v_pk_fma_f32 v[4:5], v[6:7], v[4:5], v[10:11] op_sel:[1,1,0] op_sel_hi:[0,1,1] neg_hi:[0,1,0]
	ds_swizzle_b32 v6, v4 offset:swizzle(SWAP,4)
	ds_swizzle_b32 v7, v5 offset:swizzle(SWAP,4)
	s_waitcnt lgkmcnt(0)
	v_pk_fma_f32 v[4:5], v[8:9], v[4:5], v[6:7] op_sel:[1,0,0]
	s_nop 0
	v_pk_mul_f32 v[6:7], v[4:5], v[2:3] op_sel_hi:[1,0]
	s_nop 0
	v_pk_fma_f32 v[2:3], v[4:5], v[2:3], v[6:7] op_sel:[1,1,0] op_sel_hi:[0,1,1] neg_hi:[0,1,0]
	v_pk_mul_f32 v[6:7], v[0:1], v[0:1] op_sel_hi:[1,0]
	s_nop 0
	v_pk_fma_f32 v[6:7], v[0:1], v[0:1], v[6:7] op_sel:[1,1,0] op_sel_hi:[0,1,1] neg_lo:[0,1,0]
	s_nop 0
	v_mov_b32_dpp v4, v2 row_ror:8 row_mask:0xf bank_mask:0xf bound_ctrl:1
	v_mov_b32_dpp v5, v3 row_ror:8 row_mask:0xf bank_mask:0xf bound_ctrl:1
	v_pk_fma_f32 v[2:3], v[8:9], v[2:3], v[4:5] op_sel_hi:[0,1,1]
	v_pk_mul_f32 v[8:9], v[126:127], v[6:7] op_sel_hi:[1,0]
	v_pk_mul_f32 v[10:11], v[6:7], v[0:1] op_sel_hi:[1,0]
	v_pk_mul_f32 v[4:5], v[144:145], v[0:1] op_sel_hi:[1,0]
	s_nop 0
	v_pk_fma_f32 v[8:9], v[126:127], v[6:7], v[8:9] op_sel:[1,1,0] op_sel_hi:[0,1,1] neg_lo:[0,1,0]
	v_pk_fma_f32 v[6:7], v[6:7], v[0:1], v[10:11] op_sel:[1,1,0] op_sel_hi:[0,1,1] neg_lo:[0,1,0]
	v_pk_fma_f32 v[4:5], v[144:145], v[0:1], v[4:5] op_sel:[1,1,0] op_sel_hi:[0,1,1] neg_lo:[0,1,0]
	s_nop 0
	v_pk_mul_f32 v[10:11], v[116:117], v[6:7] op_sel_hi:[1,0]
	v_pk_mul_f32 v[88:89], v[6:7], v[0:1] op_sel_hi:[1,0]
	s_nop 0
	v_pk_fma_f32 v[10:11], v[116:117], v[6:7], v[10:11] op_sel:[1,1,0] op_sel_hi:[0,1,1] neg_lo:[0,1,0]
	v_pk_fma_f32 v[6:7], v[6:7], v[0:1], v[88:89] op_sel:[1,1,0] op_sel_hi:[0,1,1] neg_lo:[0,1,0]
	s_nop 0
	v_pk_mul_f32 v[88:89], v[108:109], v[6:7] op_sel_hi:[1,0]
	s_nop 0
	v_pk_fma_f32 v[88:89], v[108:109], v[6:7], v[88:89] op_sel:[1,1,0] op_sel_hi:[0,1,1] neg_lo:[0,1,0]
	v_pk_mul_f32 v[108:109], v[6:7], v[0:1] op_sel_hi:[1,0]
	s_nop 0
	v_pk_fma_f32 v[6:7], v[6:7], v[0:1], v[108:109] op_sel:[1,1,0] op_sel_hi:[0,1,1] neg_lo:[0,1,0]
	s_nop 0
	v_pk_mul_f32 v[108:109], v[128:129], v[6:7] op_sel_hi:[1,0]
	v_pk_mul_f32 v[116:117], v[6:7], v[0:1] op_sel_hi:[1,0]
	s_nop 0
	v_pk_fma_f32 v[108:109], v[128:129], v[6:7], v[108:109] op_sel:[1,1,0] op_sel_hi:[0,1,1] neg_lo:[0,1,0]
	v_pk_fma_f32 v[6:7], v[6:7], v[0:1], v[116:117] op_sel:[1,1,0] op_sel_hi:[0,1,1] neg_lo:[0,1,0]
	s_nop 0
	v_pk_mul_f32 v[116:117], v[142:143], v[6:7] op_sel_hi:[1,0]
	v_pk_mul_f32 v[126:127], v[6:7], v[0:1] op_sel_hi:[1,0]
	s_nop 0
	v_pk_fma_f32 v[116:117], v[142:143], v[6:7], v[116:117] op_sel:[1,1,0] op_sel_hi:[0,1,1] neg_lo:[0,1,0]
	v_pk_fma_f32 v[6:7], v[6:7], v[0:1], v[126:127] op_sel:[1,1,0] op_sel_hi:[0,1,1] neg_lo:[0,1,0]
	s_nop 0
	v_pk_mul_f32 v[126:127], v[100:101], v[6:7] op_sel_hi:[1,0]
	s_nop 0
	v_pk_fma_f32 v[100:101], v[100:101], v[6:7], v[126:127] op_sel:[1,1,0] op_sel_hi:[0,1,1] neg_lo:[0,1,0]
	v_pk_mul_f32 v[126:127], v[6:7], v[0:1] op_sel_hi:[1,0]
	s_nop 0
	v_pk_fma_f32 v[6:7], v[6:7], v[0:1], v[126:127] op_sel:[1,1,0] op_sel_hi:[0,1,1] neg_lo:[0,1,0]
	s_nop 0
	v_pk_mul_f32 v[126:127], v[98:99], v[6:7] op_sel_hi:[1,0]
	s_nop 0
	v_pk_fma_f32 v[98:99], v[98:99], v[6:7], v[126:127] op_sel:[1,1,0] op_sel_hi:[0,1,1] neg_lo:[0,1,0]
	v_pk_mul_f32 v[126:127], v[6:7], v[0:1] op_sel_hi:[1,0]
	s_nop 0
	v_pk_fma_f32 v[6:7], v[6:7], v[0:1], v[126:127] op_sel:[1,1,0] op_sel_hi:[0,1,1] neg_lo:[0,1,0]
	s_nop 0
	v_pk_mul_f32 v[126:127], v[136:137], v[6:7] op_sel_hi:[1,0]
	v_pk_mul_f32 v[128:129], v[6:7], v[0:1] op_sel_hi:[1,0]
	s_nop 0
	v_pk_fma_f32 v[126:127], v[136:137], v[6:7], v[126:127] op_sel:[1,1,0] op_sel_hi:[0,1,1] neg_lo:[0,1,0]
	v_pk_fma_f32 v[6:7], v[6:7], v[0:1], v[128:129] op_sel:[1,1,0] op_sel_hi:[0,1,1] neg_lo:[0,1,0]
	s_nop 0
	v_pk_mul_f32 v[128:129], v[132:133], v[6:7] op_sel_hi:[1,0]
	s_nop 0
	v_pk_fma_f32 v[128:129], v[132:133], v[6:7], v[128:129] op_sel:[1,1,0] op_sel_hi:[0,1,1] neg_lo:[0,1,0]
	v_pk_mul_f32 v[132:133], v[6:7], v[0:1] op_sel_hi:[1,0]
	s_nop 0
	v_pk_fma_f32 v[6:7], v[6:7], v[0:1], v[132:133] op_sel:[1,1,0] op_sel_hi:[0,1,1] neg_lo:[0,1,0]
	s_nop 0
	v_pk_mul_f32 v[132:133], v[106:107], v[6:7] op_sel_hi:[1,0]
	s_nop 0
	v_pk_fma_f32 v[106:107], v[106:107], v[6:7], v[132:133] op_sel:[1,1,0] op_sel_hi:[0,1,1] neg_lo:[0,1,0]
	v_pk_mul_f32 v[132:133], v[6:7], v[0:1] op_sel_hi:[1,0]
	s_nop 0
	v_pk_fma_f32 v[6:7], v[6:7], v[0:1], v[132:133] op_sel:[1,1,0] op_sel_hi:[0,1,1] neg_lo:[0,1,0]
	s_nop 0
	v_pk_mul_f32 v[132:133], v[114:115], v[6:7] op_sel_hi:[1,0]
	s_nop 0
; template <bool CONJ> __device__ __forceinline__ void twiddle32(f2 (&x)[32], float wr, float wi) {
;     asm volatile("" : "+v"(wr), "+v"(wi));
;     f2 c = (f2){wr, CONJ ? -wi : wi}; const f2 w = c;
; #pragma unroll
;     for (int k = 1; k < 32; ++k) { const int p = brev5(k); x[p] = cmulr(x[p], c); if (k < 31) c = cmulr(c, w); }
; }
	v_pk_fma_f32 v[114:115], v[114:115], v[6:7], v[132:133] op_sel:[1,1,0] op_sel_hi:[0,1,1] neg_lo:[0,1,0]
	v_pk_mul_f32 v[132:133], v[6:7], v[0:1] op_sel_hi:[1,0]
	s_nop 0
	v_pk_fma_f32 v[6:7], v[6:7], v[0:1], v[132:133] op_sel:[1,1,0] op_sel_hi:[0,1,1] neg_lo:[0,1,0]
	s_nop 0
	v_pk_mul_f32 v[132:133], v[120:121], v[6:7] op_sel_hi:[1,0]
	s_nop 0
	v_pk_fma_f32 v[120:121], v[120:121], v[6:7], v[132:133] op_sel:[1,1,0] op_sel_hi:[0,1,1] neg_lo:[0,1,0]
	v_pk_mul_f32 v[132:133], v[6:7], v[0:1] op_sel_hi:[1,0]
	s_nop 0
	v_pk_fma_f32 v[6:7], v[6:7], v[0:1], v[132:133] op_sel:[1,1,0] op_sel_hi:[0,1,1] neg_lo:[0,1,0]
	s_nop 0
	v_pk_mul_f32 v[132:133], v[148:149], v[6:7] op_sel_hi:[1,0]
	v_pk_mul_f32 v[136:137], v[6:7], v[0:1] op_sel_hi:[1,0]
	s_nop 0
	v_pk_fma_f32 v[132:133], v[148:149], v[6:7], v[132:133] op_sel:[1,1,0] op_sel_hi:[0,1,1] neg_lo:[0,1,0]
	v_pk_fma_f32 v[6:7], v[6:7], v[0:1], v[136:137] op_sel:[1,1,0] op_sel_hi:[0,1,1] neg_lo:[0,1,0]
	s_nop 0
	v_pk_mul_f32 v[136:137], v[92:93], v[6:7] op_sel_hi:[1,0]
	s_nop 0
	v_pk_fma_f32 v[92:93], v[92:93], v[6:7], v[136:137] op_sel:[1,1,0] op_sel_hi:[0,1,1] neg_lo:[0,1,0]
	v_pk_mul_f32 v[136:137], v[6:7], v[0:1] op_sel_hi:[1,0]
	s_nop 0
	v_pk_fma_f32 v[6:7], v[6:7], v[0:1], v[136:137] op_sel:[1,1,0] op_sel_hi:[0,1,1] neg_lo:[0,1,0]
	s_nop 0
	v_pk_mul_f32 v[136:137], v[90:91], v[6:7] op_sel_hi:[1,0]
	s_nop 0
	v_pk_fma_f32 v[90:91], v[90:91], v[6:7], v[136:137] op_sel:[1,1,0] op_sel_hi:[0,1,1] neg_lo:[0,1,0]
	v_pk_mul_f32 v[136:137], v[6:7], v[0:1] op_sel_hi:[1,0]
	s_nop 0
	v_pk_fma_f32 v[6:7], v[6:7], v[0:1], v[136:137] op_sel:[1,1,0] op_sel_hi:[0,1,1] neg_lo:[0,1,0]
	s_nop 0
	v_pk_mul_f32 v[136:137], v[140:141], v[6:7] op_sel_hi:[1,0]
	s_nop 0
	v_pk_fma_f32 v[136:137], v[140:141], v[6:7], v[136:137] op_sel:[1,1,0] op_sel_hi:[0,1,1] neg_lo:[0,1,0]
	v_pk_mul_f32 v[140:141], v[6:7], v[0:1] op_sel_hi:[1,0]
	s_nop 0
	v_pk_fma_f32 v[6:7], v[6:7], v[0:1], v[140:141] op_sel:[1,1,0] op_sel_hi:[0,1,1] neg_lo:[0,1,0]
	s_nop 0
	v_pk_mul_f32 v[140:141], v[122:123], v[6:7] op_sel_hi:[1,0]
	s_nop 0
	v_pk_fma_f32 v[122:123], v[122:123], v[6:7], v[140:141] op_sel:[1,1,0] op_sel_hi:[0,1,1] neg_lo:[0,1,0]
	v_pk_mul_f32 v[140:141], v[6:7], v[0:1] op_sel_hi:[1,0]
	s_nop 0
	v_pk_fma_f32 v[6:7], v[6:7], v[0:1], v[140:141] op_sel:[1,1,0] op_sel_hi:[0,1,1] neg_lo:[0,1,0]
	s_nop 0
	v_pk_mul_f32 v[140:141], v[110:111], v[6:7] op_sel_hi:[1,0]
	s_nop 0
	v_pk_fma_f32 v[110:111], v[110:111], v[6:7], v[140:141] op_sel:[1,1,0] op_sel_hi:[0,1,1] neg_lo:[0,1,0]
	v_pk_mul_f32 v[140:141], v[6:7], v[0:1] op_sel_hi:[1,0]
	s_nop 0
	v_pk_fma_f32 v[6:7], v[6:7], v[0:1], v[140:141] op_sel:[1,1,0] op_sel_hi:[0,1,1] neg_lo:[0,1,0]
	s_nop 0
	v_pk_mul_f32 v[140:141], v[104:105], v[6:7] op_sel_hi:[1,0]
	s_nop 0
	v_pk_fma_f32 v[104:105], v[104:105], v[6:7], v[140:141] op_sel:[1,1,0] op_sel_hi:[0,1,1] neg_lo:[0,1,0]
	v_pk_mul_f32 v[140:141], v[6:7], v[0:1] op_sel_hi:[1,0]
	s_nop 0
	v_pk_fma_f32 v[6:7], v[6:7], v[0:1], v[140:141] op_sel:[1,1,0] op_sel_hi:[0,1,1] neg_lo:[0,1,0]
	s_nop 0
	v_pk_mul_f32 v[140:141], v[124:125], v[6:7] op_sel_hi:[1,0]
	s_nop 0
	v_pk_fma_f32 v[124:125], v[124:125], v[6:7], v[140:141] op_sel:[1,1,0] op_sel_hi:[0,1,1] neg_lo:[0,1,0]
	v_pk_mul_f32 v[140:141], v[6:7], v[0:1] op_sel_hi:[1,0]
	s_nop 0
	v_pk_fma_f32 v[6:7], v[6:7], v[0:1], v[140:141] op_sel:[1,1,0] op_sel_hi:[0,1,1] neg_lo:[0,1,0]
	s_nop 0
	v_pk_mul_f32 v[140:141], v[138:139], v[6:7] op_sel_hi:[1,0]
	s_nop 0
	v_pk_fma_f32 v[138:139], v[138:139], v[6:7], v[140:141] op_sel:[1,1,0] op_sel_hi:[0,1,1] neg_lo:[0,1,0]
	v_pk_mul_f32 v[140:141], v[6:7], v[0:1] op_sel_hi:[1,0]
	s_nop 0
	v_pk_fma_f32 v[6:7], v[6:7], v[0:1], v[140:141] op_sel:[1,1,0] op_sel_hi:[0,1,1] neg_lo:[0,1,0]
	s_nop 0
	v_pk_mul_f32 v[140:141], v[94:95], v[6:7] op_sel_hi:[1,0]
	s_nop 0
	v_pk_fma_f32 v[94:95], v[94:95], v[6:7], v[140:141] op_sel:[1,1,0] op_sel_hi:[0,1,1] neg_lo:[0,1,0]
	v_pk_mul_f32 v[140:141], v[6:7], v[0:1] op_sel_hi:[1,0]
	s_nop 0
	v_pk_fma_f32 v[6:7], v[6:7], v[0:1], v[140:141] op_sel:[1,1,0] op_sel_hi:[0,1,1] neg_lo:[0,1,0]
	s_nop 0
	v_pk_mul_f32 v[140:141], v[96:97], v[6:7] op_sel_hi:[1,0]
	s_nop 0
	v_pk_fma_f32 v[96:97], v[96:97], v[6:7], v[140:141] op_sel:[1,1,0] op_sel_hi:[0,1,1] neg_lo:[0,1,0]
	v_pk_mul_f32 v[140:141], v[6:7], v[0:1] op_sel_hi:[1,0]
	s_nop 0
	v_pk_fma_f32 v[6:7], v[6:7], v[0:1], v[140:141] op_sel:[1,1,0] op_sel_hi:[0,1,1] neg_lo:[0,1,0]
	s_nop 0
	v_pk_mul_f32 v[140:141], v[134:135], v[6:7] op_sel_hi:[1,0]
	s_nop 0
	v_pk_fma_f32 v[134:135], v[134:135], v[6:7], v[140:141] op_sel:[1,1,0] op_sel_hi:[0,1,1] neg_lo:[0,1,0]
	v_pk_mul_f32 v[140:141], v[6:7], v[0:1] op_sel_hi:[1,0]
	s_nop 0
	v_pk_fma_f32 v[6:7], v[6:7], v[0:1], v[140:141] op_sel:[1,1,0] op_sel_hi:[0,1,1] neg_lo:[0,1,0]
	s_nop 0
	v_pk_mul_f32 v[140:141], v[130:131], v[6:7] op_sel_hi:[1,0]
	s_nop 0
	v_pk_fma_f32 v[130:131], v[130:131], v[6:7], v[140:141] op_sel:[1,1,0] op_sel_hi:[0,1,1] neg_lo:[0,1,0]
	v_pk_mul_f32 v[140:141], v[6:7], v[0:1] op_sel_hi:[1,0]
	s_nop 0
	v_pk_fma_f32 v[6:7], v[6:7], v[0:1], v[140:141] op_sel:[1,1,0] op_sel_hi:[0,1,1] neg_lo:[0,1,0]
	s_nop 0
	v_pk_mul_f32 v[140:141], v[102:103], v[6:7] op_sel_hi:[1,0]
	s_nop 0
	v_pk_fma_f32 v[102:103], v[102:103], v[6:7], v[140:141] op_sel:[1,1,0] op_sel_hi:[0,1,1] neg_lo:[0,1,0]
	v_pk_mul_f32 v[140:141], v[6:7], v[0:1] op_sel_hi:[1,0]
	s_nop 0
	v_pk_fma_f32 v[6:7], v[6:7], v[0:1], v[140:141] op_sel:[1,1,0] op_sel_hi:[0,1,1] neg_lo:[0,1,0]
	s_nop 0
	v_pk_mul_f32 v[140:141], v[112:113], v[6:7] op_sel_hi:[1,0]
	s_nop 0
	v_pk_fma_f32 v[112:113], v[112:113], v[6:7], v[140:141] op_sel:[1,1,0] op_sel_hi:[0,1,1] neg_lo:[0,1,0]
; __device__ __forceinline__ f2 cmulc(f2 a, float wr, float wi) { const f2 s = __builtin_shufflevector(a, a, 1, 0); return s * (f2){wi, -wi} + a * (f2){wr, wr}; }
; __device__ __forceinline__ void ifft32(f2 (&x)[32]) {
;     ...
; #pragma unroll
;     for (int h = 1; h <= 16; h <<= 1) {
; #pragma unroll
;         for (int i0 = 0; i0 < 32; i0 += 2 * h) {
; #pragma unroll
;             for (int j = 0; j < h; ++j) {
;                 const int i = i0 + j, k = i + h, m = j * (32 / h);
;                 const f2 a = x[i], y = x[k];
;                 f2 b;
;                 if (m == 0) b = y;
;                 else if (m == 16) b = (f2){-y.y, y.x};
;                 else b = cmulc(y, TWR[m], TWI[m]);
;                 x[i] = a + b; x[k] = a - b;
;             }
;         }
;     }
; template <bool CONJ> __device__ __forceinline__ void twiddle32(f2 (&x)[32], float wr, float wi) {
;     asm volatile("" : "+v"(wr), "+v"(wi));
;     f2 c = (f2){wr, CONJ ? -wi : wi}; const f2 w = c;
; #pragma unroll
;     for (int k = 1; k < 32; ++k) { const int p = brev5(k); x[p] = cmulr(x[p], c); if (k < 31) c = cmulr(c, w); }
; }
	v_pk_mul_f32 v[140:141], v[6:7], v[0:1] op_sel_hi:[1,0]
	s_nop 0
	v_pk_fma_f32 v[6:7], v[6:7], v[0:1], v[140:141] op_sel:[1,1,0] op_sel_hi:[0,1,1] neg_lo:[0,1,0]
	s_nop 0
	v_pk_mul_f32 v[140:141], v[118:119], v[6:7] op_sel_hi:[1,0]
	s_nop 0
	v_pk_fma_f32 v[118:119], v[118:119], v[6:7], v[140:141] op_sel:[1,1,0] op_sel_hi:[0,1,1] neg_lo:[0,1,0]
	v_pk_mul_f32 v[140:141], v[6:7], v[0:1] op_sel_hi:[1,0]
	s_nop 0
	v_pk_fma_f32 v[6:7], v[6:7], v[0:1], v[140:141] op_sel:[1,1,0] op_sel_hi:[0,1,1] neg_lo:[0,1,0]
	s_nop 0
	v_pk_mul_f32 v[140:141], v[146:147], v[6:7] op_sel_hi:[1,0]
	v_pk_mul_f32 v[142:143], v[6:7], v[0:1] op_sel_hi:[1,0]
	s_nop 0
	v_pk_fma_f32 v[140:141], v[146:147], v[6:7], v[140:141] op_sel:[1,1,0] op_sel_hi:[0,1,1] neg_lo:[0,1,0]
	v_pk_fma_f32 v[0:1], v[6:7], v[0:1], v[142:143] op_sel:[1,1,0] op_sel_hi:[0,1,1] neg_lo:[0,1,0]
	s_nop 0
	v_pk_mul_f32 v[6:7], v[2:3], v[0:1] op_sel_hi:[1,0]
	s_nop 0
	v_pk_fma_f32 v[0:1], v[2:3], v[0:1], v[6:7] op_sel:[1,1,0] op_sel_hi:[0,1,1] neg_lo:[0,1,0]
	v_pk_add_f32 v[2:3], v[86:87], v[90:91]
	v_pk_add_f32 v[6:7], v[86:87], v[90:91] neg_lo:[0,1] neg_hi:[0,1]
	v_pk_add_f32 v[86:87], v[98:99], v[96:97]
	v_pk_add_f32 v[90:91], v[98:99], v[96:97] neg_lo:[0,1] neg_hi:[0,1]
	v_pk_add_f32 v[96:97], v[88:89], v[104:105]
	v_pk_add_f32 v[88:89], v[88:89], v[104:105] neg_lo:[0,1] neg_hi:[0,1]
	v_pk_add_f32 v[98:99], v[114:115], v[112:113]
	v_pk_add_f32 v[104:105], v[114:115], v[112:113] neg_lo:[0,1] neg_hi:[0,1]
	v_pk_add_f32 v[112:113], v[8:9], v[122:123]
	v_pk_add_f32 v[8:9], v[8:9], v[122:123] neg_lo:[0,1] neg_hi:[0,1]
	v_pk_add_f32 v[114:115], v[128:129], v[130:131]
	v_pk_add_f32 v[122:123], v[128:129], v[130:131] neg_lo:[0,1] neg_hi:[0,1]
	v_pk_add_f32 v[128:129], v[116:117], v[138:139]
	v_pk_add_f32 v[116:117], v[116:117], v[138:139] neg_lo:[0,1] neg_hi:[0,1]
	v_pk_add_f32 v[138:139], v[4:5], v[136:137]
	v_pk_add_f32 v[4:5], v[4:5], v[136:137] neg_lo:[0,1] neg_hi:[0,1]
	v_pk_add_f32 v[136:137], v[126:127], v[134:135]
	v_pk_add_f32 v[126:127], v[126:127], v[134:135] neg_lo:[0,1] neg_hi:[0,1]
	v_pk_add_f32 v[134:135], v[108:109], v[124:125]
	v_pk_add_f32 v[108:109], v[108:109], v[124:125] neg_lo:[0,1] neg_hi:[0,1]
	v_pk_add_f32 v[124:125], v[120:121], v[118:119]
	v_pk_add_f32 v[118:119], v[120:121], v[118:119] neg_lo:[0,1] neg_hi:[0,1]
	v_pk_add_f32 v[120:121], v[10:11], v[110:111]
	v_pk_add_f32 v[10:11], v[10:11], v[110:111] neg_lo:[0,1] neg_hi:[0,1]
	v_pk_add_f32 v[110:111], v[106:107], v[102:103]
	v_pk_add_f32 v[102:103], v[106:107], v[102:103] neg_lo:[0,1] neg_hi:[0,1]
	v_pk_add_f32 v[106:107], v[100:101], v[94:95]
	v_pk_add_f32 v[94:95], v[100:101], v[94:95] neg_lo:[0,1] neg_hi:[0,1]
	v_pk_add_f32 v[100:101], v[92:93], v[0:1]
	v_pk_add_f32 v[0:1], v[92:93], v[0:1] neg_lo:[0,1] neg_hi:[0,1]
	v_pk_add_f32 v[92:93], v[2:3], v[86:87]
	v_pk_add_f32 v[2:3], v[2:3], v[86:87] neg_lo:[0,1] neg_hi:[0,1]
	v_xor_b32_e32 v86, 0x80000000, v91
	v_mov_b32_e32 v87, v90
	v_pk_add_f32 v[90:91], v[6:7], v[86:87]
	v_pk_add_f32 v[6:7], v[6:7], v[86:87] neg_lo:[0,1] neg_hi:[0,1]
	v_pk_add_f32 v[86:87], v[96:97], v[98:99]
	v_pk_add_f32 v[96:97], v[96:97], v[98:99] neg_lo:[0,1] neg_hi:[0,1]
	v_xor_b32_e32 v98, 0x80000000, v105
	v_mov_b32_e32 v99, v104
	v_pk_add_f32 v[130:131], v[132:133], v[140:141]
	v_pk_add_f32 v[132:133], v[132:133], v[140:141] neg_lo:[0,1] neg_hi:[0,1]
	v_pk_add_f32 v[104:105], v[88:89], v[98:99]
	v_pk_add_f32 v[88:89], v[88:89], v[98:99] neg_lo:[0,1] neg_hi:[0,1]
	v_pk_add_f32 v[98:99], v[112:113], v[114:115]
	v_pk_add_f32 v[112:113], v[112:113], v[114:115] neg_lo:[0,1] neg_hi:[0,1]
	v_xor_b32_e32 v114, 0x80000000, v123
	v_mov_b32_e32 v115, v122
	v_pk_add_f32 v[122:123], v[8:9], v[114:115]
	v_pk_add_f32 v[8:9], v[8:9], v[114:115] neg_lo:[0,1] neg_hi:[0,1]
	v_pk_add_f32 v[114:115], v[128:129], v[130:131]
	v_pk_add_f32 v[128:129], v[128:129], v[130:131] neg_lo:[0,1] neg_hi:[0,1]
	v_xor_b32_e32 v130, 0x80000000, v133
	v_mov_b32_e32 v131, v132
	v_pk_add_f32 v[132:133], v[116:117], v[130:131]
	v_pk_add_f32 v[116:117], v[116:117], v[130:131] neg_lo:[0,1] neg_hi:[0,1]
	v_pk_add_f32 v[130:131], v[138:139], v[136:137]
	v_pk_add_f32 v[136:137], v[138:139], v[136:137] neg_lo:[0,1] neg_hi:[0,1]
	v_xor_b32_e32 v138, 0x80000000, v127
	v_mov_b32_e32 v139, v126
	v_pk_add_f32 v[126:127], v[4:5], v[138:139]
	v_pk_add_f32 v[4:5], v[4:5], v[138:139] neg_lo:[0,1] neg_hi:[0,1]
	v_pk_add_f32 v[138:139], v[134:135], v[124:125]
	v_pk_add_f32 v[124:125], v[134:135], v[124:125] neg_lo:[0,1] neg_hi:[0,1]
	v_xor_b32_e32 v134, 0x80000000, v119
	v_mov_b32_e32 v135, v118
	v_pk_add_f32 v[118:119], v[108:109], v[134:135]
	v_pk_add_f32 v[108:109], v[108:109], v[134:135] neg_lo:[0,1] neg_hi:[0,1]
	v_pk_add_f32 v[134:135], v[120:121], v[110:111]
	v_pk_add_f32 v[110:111], v[120:121], v[110:111] neg_lo:[0,1] neg_hi:[0,1]
	v_xor_b32_e32 v120, 0x80000000, v103
	v_mov_b32_e32 v121, v102
	v_pk_add_f32 v[102:103], v[10:11], v[120:121]
	v_pk_add_f32 v[10:11], v[10:11], v[120:121] neg_lo:[0,1] neg_hi:[0,1]
	v_pk_add_f32 v[120:121], v[106:107], v[100:101]
	v_pk_add_f32 v[100:101], v[106:107], v[100:101] neg_lo:[0,1] neg_hi:[0,1]
	v_xor_b32_e32 v106, 0x80000000, v1
	v_mov_b32_e32 v107, v0
	v_pk_add_f32 v[0:1], v[94:95], v[106:107]
	v_pk_add_f32 v[94:95], v[94:95], v[106:107] neg_lo:[0,1] neg_hi:[0,1]
	v_pk_add_f32 v[106:107], v[92:93], v[86:87]
	v_pk_add_f32 v[86:87], v[92:93], v[86:87] neg_lo:[0,1] neg_hi:[0,1]
	v_pk_mul_f32 v[92:93], v[104:105], s[96:97]
	s_nop 0
	v_pk_fma_f32 v[92:93], v[104:105], s[94:95], v[92:93] op_sel:[0,0,1] op_sel_hi:[1,0,0]
	s_nop 0
	v_pk_add_f32 v[104:105], v[90:91], v[92:93]
	v_pk_add_f32 v[90:91], v[90:91], v[92:93] neg_lo:[0,1] neg_hi:[0,1]
; __device__ __forceinline__ f2 cmulc(f2 a, float wr, float wi) { const f2 s = __builtin_shufflevector(a, a, 1, 0); return s * (f2){wi, -wi} + a * (f2){wr, wr}; }
; __device__ __forceinline__ void ifft32(f2 (&x)[32]) {
;     ...
; #pragma unroll
;     for (int h = 1; h <= 16; h <<= 1) {
; #pragma unroll
;         for (int i0 = 0; i0 < 32; i0 += 2 * h) {
; #pragma unroll
;             for (int j = 0; j < h; ++j) {
;                 const int i = i0 + j, k = i + h, m = j * (32 / h);
;                 const f2 a = x[i], y = x[k];
;                 f2 b;
;                 if (m == 0) b = y;
;                 else if (m == 16) b = (f2){-y.y, y.x};
;                 else b = cmulc(y, TWR[m], TWI[m]);
;                 x[i] = a + b; x[k] = a - b;
;             }
;         }
;     }
	v_xor_b32_e32 v92, 0x80000000, v97
	v_mov_b32_e32 v93, v96
	v_pk_add_f32 v[96:97], v[2:3], v[92:93]
	v_pk_add_f32 v[2:3], v[2:3], v[92:93] neg_lo:[0,1] neg_hi:[0,1]
	v_pk_mul_f32 v[92:93], v[88:89], s[96:97]
	s_nop 0
	v_pk_fma_f32 v[88:89], v[88:89], s[94:95], v[92:93] op_sel:[0,0,1] op_sel_hi:[1,0,0] neg_lo:[1,0,0] neg_hi:[1,0,0]
	s_nop 0
	v_pk_add_f32 v[92:93], v[6:7], v[88:89]
	v_pk_add_f32 v[6:7], v[6:7], v[88:89] neg_lo:[0,1] neg_hi:[0,1]
	v_pk_add_f32 v[88:89], v[98:99], v[114:115]
	v_pk_add_f32 v[98:99], v[98:99], v[114:115] neg_lo:[0,1] neg_hi:[0,1]
	v_pk_mul_f32 v[114:115], v[132:133], s[96:97]
	s_nop 0
	v_pk_fma_f32 v[114:115], v[132:133], s[94:95], v[114:115] op_sel:[0,0,1] op_sel_hi:[1,0,0]
	s_nop 0
	v_pk_add_f32 v[132:133], v[122:123], v[114:115]
	v_pk_add_f32 v[114:115], v[122:123], v[114:115] neg_lo:[0,1] neg_hi:[0,1]
	v_xor_b32_e32 v122, 0x80000000, v129
	v_mov_b32_e32 v123, v128
	v_pk_add_f32 v[128:129], v[112:113], v[122:123]
	v_pk_add_f32 v[112:113], v[112:113], v[122:123] neg_lo:[0,1] neg_hi:[0,1]
	v_pk_mul_f32 v[122:123], v[116:117], s[96:97]
	s_nop 0
	v_pk_fma_f32 v[116:117], v[116:117], s[94:95], v[122:123] op_sel:[0,0,1] op_sel_hi:[1,0,0] neg_lo:[1,0,0] neg_hi:[1,0,0]
	s_nop 0
	v_pk_add_f32 v[122:123], v[8:9], v[116:117]
	v_pk_add_f32 v[8:9], v[8:9], v[116:117] neg_lo:[0,1] neg_hi:[0,1]
	v_pk_add_f32 v[116:117], v[130:131], v[138:139]
	v_pk_add_f32 v[130:131], v[130:131], v[138:139] neg_lo:[0,1] neg_hi:[0,1]
	v_pk_mul_f32 v[138:139], v[118:119], s[96:97]
	s_nop 0
	v_pk_fma_f32 v[118:119], v[118:119], s[94:95], v[138:139] op_sel:[0,0,1] op_sel_hi:[1,0,0]
	s_nop 0
	v_pk_add_f32 v[138:139], v[126:127], v[118:119]
	v_pk_add_f32 v[118:119], v[126:127], v[118:119] neg_lo:[0,1] neg_hi:[0,1]
	v_xor_b32_e32 v126, 0x80000000, v125
	v_mov_b32_e32 v127, v124
	v_pk_add_f32 v[124:125], v[136:137], v[126:127]
	v_pk_add_f32 v[126:127], v[136:137], v[126:127] neg_lo:[0,1] neg_hi:[0,1]
	v_pk_mul_f32 v[136:137], v[108:109], s[96:97]
	s_nop 0
	v_pk_fma_f32 v[108:109], v[108:109], s[94:95], v[136:137] op_sel:[0,0,1] op_sel_hi:[1,0,0] neg_lo:[1,0,0] neg_hi:[1,0,0]
	s_nop 0
	v_pk_add_f32 v[136:137], v[4:5], v[108:109]
	v_pk_add_f32 v[4:5], v[4:5], v[108:109] neg_lo:[0,1] neg_hi:[0,1]
	v_pk_add_f32 v[108:109], v[134:135], v[120:121]
	v_pk_add_f32 v[120:121], v[134:135], v[120:121] neg_lo:[0,1] neg_hi:[0,1]
	v_pk_mul_f32 v[134:135], v[0:1], s[96:97]
	s_nop 0
	v_pk_fma_f32 v[0:1], v[0:1], s[94:95], v[134:135] op_sel:[0,0,1] op_sel_hi:[1,0,0]
	s_nop 0
	v_pk_add_f32 v[134:135], v[102:103], v[0:1]
	v_pk_add_f32 v[0:1], v[102:103], v[0:1] neg_lo:[0,1] neg_hi:[0,1]
	v_xor_b32_e32 v102, 0x80000000, v101
	v_mov_b32_e32 v103, v100
	v_pk_add_f32 v[100:101], v[110:111], v[102:103]
	v_pk_add_f32 v[102:103], v[110:111], v[102:103] neg_lo:[0,1] neg_hi:[0,1]
	v_pk_mul_f32 v[110:111], v[94:95], s[96:97]
	s_nop 0
	v_pk_fma_f32 v[94:95], v[94:95], s[94:95], v[110:111] op_sel:[0,0,1] op_sel_hi:[1,0,0] neg_lo:[1,0,0] neg_hi:[1,0,0]
	s_nop 0
	v_pk_add_f32 v[110:111], v[10:11], v[94:95]
	v_pk_add_f32 v[10:11], v[10:11], v[94:95] neg_lo:[0,1] neg_hi:[0,1]
	v_pk_add_f32 v[94:95], v[106:107], v[88:89]
	v_pk_add_f32 v[88:89], v[106:107], v[88:89] neg_lo:[0,1] neg_hi:[0,1]
	v_pk_mul_f32 v[106:107], v[132:133], s[6:7]
	s_nop 0
	v_pk_fma_f32 v[106:107], v[132:133], s[56:57], v[106:107] op_sel:[0,0,1] op_sel_hi:[1,0,0]
	s_mov_b32 s57, s66
	v_pk_add_f32 v[132:133], v[104:105], v[106:107]
	v_pk_add_f32 v[104:105], v[104:105], v[106:107] neg_lo:[0,1] neg_hi:[0,1]
	v_pk_mul_f32 v[106:107], v[128:129], s[96:97]
	s_nop 0
	v_pk_fma_f32 v[106:107], v[128:129], s[94:95], v[106:107] op_sel:[0,0,1] op_sel_hi:[1,0,0]
	s_nop 0
	v_pk_add_f32 v[128:129], v[96:97], v[106:107]
	v_pk_add_f32 v[96:97], v[96:97], v[106:107] neg_lo:[0,1] neg_hi:[0,1]
	v_pk_mul_f32 v[106:107], v[122:123], s[56:57]
	s_nop 0
	v_pk_fma_f32 v[106:107], v[122:123], s[84:85], v[106:107] op_sel:[0,0,1] op_sel_hi:[1,0,0]
	s_nop 0
	v_pk_add_f32 v[122:123], v[92:93], v[106:107]
	v_pk_add_f32 v[92:93], v[92:93], v[106:107] neg_lo:[0,1] neg_hi:[0,1]
	v_xor_b32_e32 v106, 0x80000000, v99
	v_mov_b32_e32 v107, v98
	v_pk_add_f32 v[98:99], v[86:87], v[106:107]
	v_pk_add_f32 v[86:87], v[86:87], v[106:107] neg_lo:[0,1] neg_hi:[0,1]
	v_pk_mul_f32 v[106:107], v[114:115], s[56:57]
	s_nop 0
	v_pk_fma_f32 v[106:107], v[114:115], s[84:85], v[106:107] op_sel:[0,0,1] op_sel_hi:[1,0,0] neg_lo:[1,0,0] neg_hi:[1,0,0]
	s_nop 0
	v_pk_add_f32 v[114:115], v[90:91], v[106:107]
	v_pk_add_f32 v[90:91], v[90:91], v[106:107] neg_lo:[0,1] neg_hi:[0,1]
	v_pk_mul_f32 v[106:107], v[112:113], s[96:97]
	s_nop 0
	v_pk_fma_f32 v[106:107], v[112:113], s[94:95], v[106:107] op_sel:[0,0,1] op_sel_hi:[1,0,0] neg_lo:[1,0,0] neg_hi:[1,0,0]
	s_nop 0
	v_pk_add_f32 v[112:113], v[2:3], v[106:107]
	v_pk_add_f32 v[2:3], v[2:3], v[106:107] neg_lo:[0,1] neg_hi:[0,1]
	v_pk_mul_f32 v[106:107], v[8:9], s[6:7]
	s_nop 0
	v_pk_fma_f32 v[8:9], v[8:9], s[56:57], v[106:107] op_sel:[0,0,1] op_sel_hi:[1,0,0] neg_lo:[1,0,0] neg_hi:[1,0,0]
	s_nop 0
	v_pk_add_f32 v[106:107], v[6:7], v[8:9]
	v_pk_add_f32 v[6:7], v[6:7], v[8:9] neg_lo:[0,1] neg_hi:[0,1]
	v_pk_add_f32 v[8:9], v[116:117], v[108:109]
	v_pk_add_f32 v[108:109], v[116:117], v[108:109] neg_lo:[0,1] neg_hi:[0,1]
	v_pk_mul_f32 v[116:117], v[134:135], s[6:7]
	s_nop 0
	v_pk_fma_f32 v[116:117], v[134:135], s[56:57], v[116:117] op_sel:[0,0,1] op_sel_hi:[1,0,0]
	s_nop 0
	v_pk_add_f32 v[134:135], v[138:139], v[116:117]
	v_pk_add_f32 v[116:117], v[138:139], v[116:117] neg_lo:[0,1] neg_hi:[0,1]
	v_pk_mul_f32 v[138:139], v[100:101], s[96:97]
	s_nop 0
	v_pk_fma_f32 v[100:101], v[100:101], s[94:95], v[138:139] op_sel:[0,0,1] op_sel_hi:[1,0,0]
; __device__ __forceinline__ f2 cmulc(f2 a, float wr, float wi) { const f2 s = __builtin_shufflevector(a, a, 1, 0); return s * (f2){wi, -wi} + a * (f2){wr, wr}; }
; __device__ __forceinline__ void ifft32(f2 (&x)[32]) {
;     ...
; #pragma unroll
;     for (int h = 1; h <= 16; h <<= 1) {
; #pragma unroll
;         for (int i0 = 0; i0 < 32; i0 += 2 * h) {
; #pragma unroll
;             for (int j = 0; j < h; ++j) {
;                 const int i = i0 + j, k = i + h, m = j * (32 / h);
;                 const f2 a = x[i], y = x[k];
;                 f2 b;
;                 if (m == 0) b = y;
;                 else if (m == 16) b = (f2){-y.y, y.x};
;                 else b = cmulc(y, TWR[m], TWI[m]);
;                 x[i] = a + b; x[k] = a - b;
;             }
;         }
;     }
; __device__ __forceinline__ void fft_inverse(f2 (&x)[32], LAS f2* X, int t, LAS const float* W1, LAS const M2C* MC) {
;     ...
; #pragma unroll
;     for (int m = 0; m < 16; ++m) { wp[16 * m] = x[m]; wp1[16 * m] = x[m + 16]; }
	s_nop 0
	v_pk_add_f32 v[138:139], v[124:125], v[100:101]
	v_pk_add_f32 v[100:101], v[124:125], v[100:101] neg_lo:[0,1] neg_hi:[0,1]
	v_pk_mul_f32 v[124:125], v[110:111], s[56:57]
	s_nop 0
	v_pk_fma_f32 v[110:111], v[110:111], s[84:85], v[124:125] op_sel:[0,0,1] op_sel_hi:[1,0,0]
	s_nop 0
	v_pk_add_f32 v[124:125], v[136:137], v[110:111]
	v_pk_add_f32 v[110:111], v[136:137], v[110:111] neg_lo:[0,1] neg_hi:[0,1]
	v_xor_b32_e32 v136, 0x80000000, v121
	v_mov_b32_e32 v137, v120
	v_pk_add_f32 v[120:121], v[130:131], v[136:137]
	v_pk_add_f32 v[130:131], v[130:131], v[136:137] neg_lo:[0,1] neg_hi:[0,1]
	v_pk_mul_f32 v[136:137], v[0:1], s[56:57]
	s_nop 0
	v_pk_fma_f32 v[0:1], v[0:1], s[84:85], v[136:137] op_sel:[0,0,1] op_sel_hi:[1,0,0] neg_lo:[1,0,0] neg_hi:[1,0,0]
	s_nop 0
	v_pk_add_f32 v[136:137], v[118:119], v[0:1]
	v_pk_add_f32 v[0:1], v[118:119], v[0:1] neg_lo:[0,1] neg_hi:[0,1]
	v_pk_mul_f32 v[118:119], v[102:103], s[96:97]
	s_nop 0
	v_pk_fma_f32 v[102:103], v[102:103], s[94:95], v[118:119] op_sel:[0,0,1] op_sel_hi:[1,0,0] neg_lo:[1,0,0] neg_hi:[1,0,0]
	s_nop 0
	v_pk_add_f32 v[118:119], v[126:127], v[102:103]
	v_pk_add_f32 v[102:103], v[126:127], v[102:103] neg_lo:[0,1] neg_hi:[0,1]
	v_pk_mul_f32 v[126:127], v[10:11], s[6:7]
	s_nop 0
	v_pk_fma_f32 v[10:11], v[10:11], s[56:57], v[126:127] op_sel:[0,0,1] op_sel_hi:[1,0,0] neg_lo:[1,0,0] neg_hi:[1,0,0]
	s_nop 0
	v_pk_add_f32 v[126:127], v[4:5], v[10:11]
	v_pk_add_f32 v[4:5], v[4:5], v[10:11] neg_lo:[0,1] neg_hi:[0,1]
	v_pk_add_f32 v[10:11], v[94:95], v[8:9]
	ds_write_b64 v214, v[10:11]
	v_pk_add_f32 v[8:9], v[94:95], v[8:9] neg_lo:[0,1] neg_hi:[0,1]
	ds_write_b64 v215, v[8:9]
	v_pk_mul_f32 v[94:95], v[134:135], s[76:77]
	s_nop 0
	v_pk_fma_f32 v[94:95], v[134:135], s[52:53], v[94:95] op_sel:[0,0,1] op_sel_hi:[1,0,0]
	s_mov_b32 s53, s78
	v_pk_add_f32 v[134:135], v[132:133], v[94:95]
	ds_write_b64 v214, v[134:135] offset:128
	v_pk_add_f32 v[94:95], v[132:133], v[94:95] neg_lo:[0,1] neg_hi:[0,1]
	ds_write_b64 v215, v[94:95] offset:128
	v_pk_mul_f32 v[132:133], v[138:139], s[6:7]
	s_nop 0
	v_pk_fma_f32 v[132:133], v[138:139], s[56:57], v[132:133] op_sel:[0,0,1] op_sel_hi:[1,0,0]
	s_nop 0
	v_pk_add_f32 v[138:139], v[128:129], v[132:133]
	ds_write_b64 v214, v[138:139] offset:256
	v_pk_add_f32 v[128:129], v[128:129], v[132:133] neg_lo:[0,1] neg_hi:[0,1]
	ds_write_b64 v215, v[128:129] offset:256
	v_pk_mul_f32 v[132:133], v[124:125], s[20:21]
	s_nop 0
	v_pk_fma_f32 v[124:125], v[124:125], s[60:61], v[132:133] op_sel:[0,0,1] op_sel_hi:[1,0,0]
	s_mov_b32 s61, s64
	v_pk_add_f32 v[132:133], v[122:123], v[124:125]
	ds_write_b64 v214, v[132:133] offset:384
	v_pk_add_f32 v[122:123], v[122:123], v[124:125] neg_lo:[0,1] neg_hi:[0,1]
	ds_write_b64 v215, v[122:123] offset:384
	v_pk_mul_f32 v[124:125], v[120:121], s[96:97]
	s_nop 0
	v_pk_fma_f32 v[120:121], v[120:121], s[94:95], v[124:125] op_sel:[0,0,1] op_sel_hi:[1,0,0]
	s_nop 0
	v_pk_add_f32 v[124:125], v[98:99], v[120:121]
	ds_write_b64 v214, v[124:125] offset:512
	v_pk_add_f32 v[98:99], v[98:99], v[120:121] neg_lo:[0,1] neg_hi:[0,1]
	ds_write_b64 v215, v[98:99] offset:512
	v_pk_mul_f32 v[120:121], v[136:137], s[60:61]
	s_nop 0
	v_pk_fma_f32 v[120:121], v[136:137], s[86:87], v[120:121] op_sel:[0,0,1] op_sel_hi:[1,0,0]
	s_nop 0
	v_pk_add_f32 v[136:137], v[114:115], v[120:121]
	ds_write_b64 v214, v[136:137] offset:640
	v_pk_add_f32 v[114:115], v[114:115], v[120:121] neg_lo:[0,1] neg_hi:[0,1]
	ds_write_b64 v215, v[114:115] offset:640
	v_pk_mul_f32 v[120:121], v[118:119], s[56:57]
	s_nop 0
	v_pk_fma_f32 v[118:119], v[118:119], s[84:85], v[120:121] op_sel:[0,0,1] op_sel_hi:[1,0,0]
	s_nop 0
	v_pk_add_f32 v[120:121], v[112:113], v[118:119]
	ds_write_b64 v214, v[120:121] offset:768
	v_pk_add_f32 v[112:113], v[112:113], v[118:119] neg_lo:[0,1] neg_hi:[0,1]
	ds_write_b64 v215, v[112:113] offset:768
	v_pk_mul_f32 v[118:119], v[126:127], s[52:53]
	s_nop 0
	v_pk_fma_f32 v[118:119], v[126:127], s[10:11], v[118:119] op_sel:[0,0,1] op_sel_hi:[1,0,0]
	s_nop 0
	v_pk_add_f32 v[126:127], v[106:107], v[118:119]
	ds_write_b64 v214, v[126:127] offset:896
	v_pk_add_f32 v[106:107], v[106:107], v[118:119] neg_lo:[0,1] neg_hi:[0,1]
	ds_write_b64 v215, v[106:107] offset:896
	v_xor_b32_e32 v118, 0x80000000, v109
	v_mov_b32_e32 v119, v108
	v_pk_add_f32 v[108:109], v[88:89], v[118:119]
	ds_write_b64 v214, v[108:109] offset:1024
	v_pk_add_f32 v[88:89], v[88:89], v[118:119] neg_lo:[0,1] neg_hi:[0,1]
	ds_write_b64 v215, v[88:89] offset:1024
	v_pk_mul_f32 v[118:119], v[116:117], s[52:53]
	s_nop 0
	v_pk_fma_f32 v[116:117], v[116:117], s[10:11], v[118:119] op_sel:[0,0,1] op_sel_hi:[1,0,0] neg_lo:[1,0,0] neg_hi:[1,0,0]
	s_nop 0
	v_pk_add_f32 v[118:119], v[104:105], v[116:117]
	ds_write_b64 v214, v[118:119] offset:1152
	v_pk_add_f32 v[104:105], v[104:105], v[116:117] neg_lo:[0,1] neg_hi:[0,1]
	ds_write_b64 v215, v[104:105] offset:1152
	v_pk_mul_f32 v[116:117], v[100:101], s[56:57]
	s_nop 0
	v_pk_fma_f32 v[100:101], v[100:101], s[84:85], v[116:117] op_sel:[0,0,1] op_sel_hi:[1,0,0] neg_lo:[1,0,0] neg_hi:[1,0,0]
	s_nop 0
	v_pk_add_f32 v[116:117], v[96:97], v[100:101]
	ds_write_b64 v214, v[116:117] offset:1280
	v_pk_add_f32 v[96:97], v[96:97], v[100:101] neg_lo:[0,1] neg_hi:[0,1]
	ds_write_b64 v215, v[96:97] offset:1280
	v_pk_mul_f32 v[100:101], v[110:111], s[60:61]
	s_nop 0
	v_pk_fma_f32 v[100:101], v[110:111], s[86:87], v[100:101] op_sel:[0,0,1] op_sel_hi:[1,0,0] neg_lo:[1,0,0] neg_hi:[1,0,0]
	s_nop 0
	v_pk_add_f32 v[110:111], v[92:93], v[100:101]
	ds_write_b64 v214, v[110:111] offset:1408
	v_pk_add_f32 v[92:93], v[92:93], v[100:101] neg_lo:[0,1] neg_hi:[0,1]
	ds_write_b64 v215, v[92:93] offset:1408
; #define LBAR() do { asm volatile("s_waitcnt lgkmcnt(0)" ::: "memory"); __builtin_amdgcn_s_barrier(); asm volatile("" ::: "memory"); } while (0)
; template <bool CONJ> __device__ __forceinline__ void twiddle32(f2 (&x)[32], float wr, float wi) {
;     asm volatile("" : "+v"(wr), "+v"(wi));
;     f2 c = (f2){wr, CONJ ? -wi : wi}; const f2 w = c;
; #pragma unroll
;     for (int k = 1; k < 32; ++k) { const int p = brev5(k); x[p] = cmulr(x[p], c); if (k < 31) c = cmulr(c, w); }
; }
; __device__ __forceinline__ void fft_inverse(f2 (&x)[32], LAS f2* X, int t, LAS const float* W1, LAS const M2C* MC) {
;     ...
; #pragma unroll
;     for (int m = 0; m < 16; ++m) { wp[16 * m] = x[m]; wp1[16 * m] = x[m + 16]; }
;     LBAR();
; #pragma unroll
;     for (int k = 0; k < 16; ++k) { x[brev5(k)] = rp[k * XP]; x[brev5(k + 16)] = rp1[k * XP]; }
;     LBAR();
;     { const float wr = W1[0], wi = W1[1]; twiddle32<true>(x, wr * wr - wi * wi, 2.f * wr * wi); }
	v_pk_mul_f32 v[100:101], v[130:131], s[96:97]
	s_nop 0
	v_pk_fma_f32 v[100:101], v[130:131], s[94:95], v[100:101] op_sel:[0,0,1] op_sel_hi:[1,0,0] neg_lo:[1,0,0] neg_hi:[1,0,0]
	s_nop 0
	v_pk_add_f32 v[130:131], v[86:87], v[100:101]
	ds_write_b64 v214, v[130:131] offset:1536
	v_pk_add_f32 v[86:87], v[86:87], v[100:101] neg_lo:[0,1] neg_hi:[0,1]
	ds_write_b64 v215, v[86:87] offset:1536
	v_pk_mul_f32 v[100:101], v[0:1], s[20:21]
	s_nop 0
	v_pk_fma_f32 v[0:1], v[0:1], s[60:61], v[100:101] op_sel:[0,0,1] op_sel_hi:[1,0,0] neg_lo:[1,0,0] neg_hi:[1,0,0]
	s_nop 0
	v_pk_add_f32 v[100:101], v[90:91], v[0:1]
	ds_write_b64 v214, v[100:101] offset:1664
	v_pk_add_f32 v[0:1], v[90:91], v[0:1] neg_lo:[0,1] neg_hi:[0,1]
	ds_write_b64 v215, v[0:1] offset:1664
	v_pk_mul_f32 v[90:91], v[102:103], s[6:7]
	s_nop 0
	v_pk_fma_f32 v[90:91], v[102:103], s[56:57], v[90:91] op_sel:[0,0,1] op_sel_hi:[1,0,0] neg_lo:[1,0,0] neg_hi:[1,0,0]
	s_nop 0
	v_pk_add_f32 v[102:103], v[2:3], v[90:91]
	ds_write_b64 v214, v[102:103] offset:1792
	v_pk_add_f32 v[2:3], v[2:3], v[90:91] neg_lo:[0,1] neg_hi:[0,1]
	ds_write_b64 v215, v[2:3] offset:1792
	v_pk_mul_f32 v[90:91], v[4:5], s[76:77]
	s_nop 0
	v_pk_fma_f32 v[4:5], v[4:5], s[52:53], v[90:91] op_sel:[0,0,1] op_sel_hi:[1,0,0] neg_lo:[1,0,0] neg_hi:[1,0,0]
	s_nop 0
	v_pk_add_f32 v[90:91], v[6:7], v[4:5]
	ds_write_b64 v214, v[90:91] offset:1920
	v_pk_add_f32 v[4:5], v[6:7], v[4:5] neg_lo:[0,1] neg_hi:[0,1]
	ds_write_b64 v215, v[4:5] offset:1920
	s_waitcnt lgkmcnt(0)
	s_barrier
	ds_read_b64 v[0:1], v213
	ds_read_b64 v[2:3], v213 offset:4224
	ds_read_b64 v[4:5], v213 offset:8448
	ds_read_b64 v[6:7], v213 offset:12672
	ds_read_b64 v[8:9], v213 offset:16896
	ds_read_b64 v[10:11], v213 offset:21120
	ds_read_b64 v[86:87], v213 offset:25344
	ds_read_b64 v[88:89], v213 offset:29568
	ds_read_b64 v[90:91], v213 offset:33792
	ds_read_b64 v[92:93], v213 offset:38016
	ds_read_b64 v[94:95], v213 offset:42240
	ds_read_b64 v[96:97], v213 offset:46464
	ds_read_b64 v[98:99], v213 offset:50688
	ds_read_b64 v[100:101], v213 offset:54912
	ds_read_b64 v[102:103], v213 offset:59136
	ds_read_b64 v[104:105], v213 offset:63360
	ds_read_b64 v[106:107], v212
	ds_read_b64 v[108:109], v212 offset:4224
	ds_read_b64 v[110:111], v212 offset:8448
	ds_read_b64 v[112:113], v212 offset:12672
	ds_read_b64 v[114:115], v212 offset:16896
	ds_read_b64 v[116:117], v212 offset:21120
	ds_read_b64 v[118:119], v212 offset:25344
	ds_read_b64 v[120:121], v212 offset:29568
	ds_read_b64 v[122:123], v212 offset:33792
	ds_read_b64 v[124:125], v212 offset:38016
	ds_read_b64 v[126:127], v212 offset:42240
	ds_read_b64 v[128:129], v212 offset:46464
	ds_read_b64 v[130:131], v212 offset:50688
	ds_read_b64 v[132:133], v212 offset:54912
	ds_read_b64 v[134:135], v212 offset:59136
	ds_read_b64 v[136:137], v212 offset:63360
	s_waitcnt lgkmcnt(0)
	s_barrier
	ds_read_b64 v[138:139], v211
	s_waitcnt lgkmcnt(0)
	v_pk_mul_f32 v[140:141], v[138:139], v[138:139]
	v_add_f32_e32 v13, v138, v138
	v_sub_f32_e32 v140, v140, v141
	v_mul_f32_e32 v13, v13, v139
	s_nop 0
	v_xor_b32_e32 v141, 0x80000000, v13
	v_pk_mul_f32 v[138:139], v[2:3], v[140:141] op_sel_hi:[1,0]
	s_nop 0
	v_pk_fma_f32 v[2:3], v[2:3], v[140:141], v[138:139] op_sel:[1,1,0] op_sel_hi:[0,1,1] neg_lo:[0,1,0]
	v_pk_mul_f32 v[138:139], v[140:141], v[140:141] op_sel_hi:[1,0]
	s_nop 0
	v_pk_fma_f32 v[138:139], v[140:141], v[140:141], v[138:139] op_sel:[1,1,0] op_sel_hi:[0,1,1] neg_lo:[0,1,0]
	s_nop 0
	v_pk_mul_f32 v[142:143], v[4:5], v[138:139] op_sel_hi:[1,0]
	s_nop 0
	v_pk_fma_f32 v[4:5], v[4:5], v[138:139], v[142:143] op_sel:[1,1,0] op_sel_hi:[0,1,1] neg_lo:[0,1,0]
	v_pk_mul_f32 v[142:143], v[138:139], v[140:141] op_sel_hi:[1,0]
	s_nop 0
	v_pk_fma_f32 v[138:139], v[138:139], v[140:141], v[142:143] op_sel:[1,1,0] op_sel_hi:[0,1,1] neg_lo:[0,1,0]
	s_nop 0
	v_pk_mul_f32 v[142:143], v[6:7], v[138:139] op_sel_hi:[1,0]
	s_nop 0
	v_pk_fma_f32 v[6:7], v[6:7], v[138:139], v[142:143] op_sel:[1,1,0] op_sel_hi:[0,1,1] neg_lo:[0,1,0]
	v_pk_mul_f32 v[142:143], v[138:139], v[140:141] op_sel_hi:[1,0]
	s_nop 0
	v_pk_fma_f32 v[138:139], v[138:139], v[140:141], v[142:143] op_sel:[1,1,0] op_sel_hi:[0,1,1] neg_lo:[0,1,0]
	s_nop 0
	v_pk_mul_f32 v[142:143], v[8:9], v[138:139] op_sel_hi:[1,0]
	s_nop 0
	v_pk_fma_f32 v[8:9], v[8:9], v[138:139], v[142:143] op_sel:[1,1,0] op_sel_hi:[0,1,1] neg_lo:[0,1,0]
	v_pk_mul_f32 v[142:143], v[138:139], v[140:141] op_sel_hi:[1,0]
	s_nop 0
	v_pk_fma_f32 v[138:139], v[138:139], v[140:141], v[142:143] op_sel:[1,1,0] op_sel_hi:[0,1,1] neg_lo:[0,1,0]
	s_nop 0
	v_pk_mul_f32 v[142:143], v[10:11], v[138:139] op_sel_hi:[1,0]
	s_nop 0
	v_pk_fma_f32 v[10:11], v[10:11], v[138:139], v[142:143] op_sel:[1,1,0] op_sel_hi:[0,1,1] neg_lo:[0,1,0]
	v_pk_mul_f32 v[142:143], v[138:139], v[140:141] op_sel_hi:[1,0]
	s_nop 0
	v_pk_fma_f32 v[138:139], v[138:139], v[140:141], v[142:143] op_sel:[1,1,0] op_sel_hi:[0,1,1] neg_lo:[0,1,0]
	s_nop 0
	v_pk_mul_f32 v[142:143], v[86:87], v[138:139] op_sel_hi:[1,0]
	s_nop 0
	v_pk_fma_f32 v[86:87], v[86:87], v[138:139], v[142:143] op_sel:[1,1,0] op_sel_hi:[0,1,1] neg_lo:[0,1,0]
	v_pk_mul_f32 v[142:143], v[138:139], v[140:141] op_sel_hi:[1,0]
	s_nop 0
	v_pk_fma_f32 v[138:139], v[138:139], v[140:141], v[142:143] op_sel:[1,1,0] op_sel_hi:[0,1,1] neg_lo:[0,1,0]
	s_nop 0
	v_pk_mul_f32 v[142:143], v[88:89], v[138:139] op_sel_hi:[1,0]
	s_nop 0
	v_pk_fma_f32 v[88:89], v[88:89], v[138:139], v[142:143] op_sel:[1,1,0] op_sel_hi:[0,1,1] neg_lo:[0,1,0]
	v_pk_mul_f32 v[142:143], v[138:139], v[140:141] op_sel_hi:[1,0]
	s_nop 0
	v_pk_fma_f32 v[138:139], v[138:139], v[140:141], v[142:143] op_sel:[1,1,0] op_sel_hi:[0,1,1] neg_lo:[0,1,0]
; template <bool CONJ> __device__ __forceinline__ void twiddle32(f2 (&x)[32], float wr, float wi) {
;     asm volatile("" : "+v"(wr), "+v"(wi));
;     f2 c = (f2){wr, CONJ ? -wi : wi}; const f2 w = c;
; #pragma unroll
;     for (int k = 1; k < 32; ++k) { const int p = brev5(k); x[p] = cmulr(x[p], c); if (k < 31) c = cmulr(c, w); }
; }
	s_nop 0
	v_pk_mul_f32 v[142:143], v[90:91], v[138:139] op_sel_hi:[1,0]
	s_nop 0
	v_pk_fma_f32 v[90:91], v[90:91], v[138:139], v[142:143] op_sel:[1,1,0] op_sel_hi:[0,1,1] neg_lo:[0,1,0]
	v_pk_mul_f32 v[142:143], v[138:139], v[140:141] op_sel_hi:[1,0]
	s_nop 0
	v_pk_fma_f32 v[138:139], v[138:139], v[140:141], v[142:143] op_sel:[1,1,0] op_sel_hi:[0,1,1] neg_lo:[0,1,0]
	s_nop 0
	v_pk_mul_f32 v[142:143], v[92:93], v[138:139] op_sel_hi:[1,0]
	s_nop 0
	v_pk_fma_f32 v[92:93], v[92:93], v[138:139], v[142:143] op_sel:[1,1,0] op_sel_hi:[0,1,1] neg_lo:[0,1,0]
	v_pk_mul_f32 v[142:143], v[138:139], v[140:141] op_sel_hi:[1,0]
	s_nop 0
	v_pk_fma_f32 v[138:139], v[138:139], v[140:141], v[142:143] op_sel:[1,1,0] op_sel_hi:[0,1,1] neg_lo:[0,1,0]
	s_nop 0
	v_pk_mul_f32 v[142:143], v[94:95], v[138:139] op_sel_hi:[1,0]
	s_nop 0
	v_pk_fma_f32 v[94:95], v[94:95], v[138:139], v[142:143] op_sel:[1,1,0] op_sel_hi:[0,1,1] neg_lo:[0,1,0]
	v_pk_mul_f32 v[142:143], v[138:139], v[140:141] op_sel_hi:[1,0]
	s_nop 0
	v_pk_fma_f32 v[138:139], v[138:139], v[140:141], v[142:143] op_sel:[1,1,0] op_sel_hi:[0,1,1] neg_lo:[0,1,0]
	s_nop 0
	v_pk_mul_f32 v[142:143], v[96:97], v[138:139] op_sel_hi:[1,0]
	s_nop 0
	v_pk_fma_f32 v[96:97], v[96:97], v[138:139], v[142:143] op_sel:[1,1,0] op_sel_hi:[0,1,1] neg_lo:[0,1,0]
	v_pk_mul_f32 v[142:143], v[138:139], v[140:141] op_sel_hi:[1,0]
	s_nop 0
	v_pk_fma_f32 v[138:139], v[138:139], v[140:141], v[142:143] op_sel:[1,1,0] op_sel_hi:[0,1,1] neg_lo:[0,1,0]
	s_nop 0
	v_pk_mul_f32 v[142:143], v[98:99], v[138:139] op_sel_hi:[1,0]
	s_nop 0
	v_pk_fma_f32 v[98:99], v[98:99], v[138:139], v[142:143] op_sel:[1,1,0] op_sel_hi:[0,1,1] neg_lo:[0,1,0]
	v_pk_mul_f32 v[142:143], v[138:139], v[140:141] op_sel_hi:[1,0]
	s_nop 0
	v_pk_fma_f32 v[138:139], v[138:139], v[140:141], v[142:143] op_sel:[1,1,0] op_sel_hi:[0,1,1] neg_lo:[0,1,0]
	s_nop 0
	v_pk_mul_f32 v[142:143], v[100:101], v[138:139] op_sel_hi:[1,0]
	s_nop 0
	v_pk_fma_f32 v[100:101], v[100:101], v[138:139], v[142:143] op_sel:[1,1,0] op_sel_hi:[0,1,1] neg_lo:[0,1,0]
	v_pk_mul_f32 v[142:143], v[138:139], v[140:141] op_sel_hi:[1,0]
	s_nop 0
	v_pk_fma_f32 v[138:139], v[138:139], v[140:141], v[142:143] op_sel:[1,1,0] op_sel_hi:[0,1,1] neg_lo:[0,1,0]
	s_nop 0
	v_pk_mul_f32 v[142:143], v[102:103], v[138:139] op_sel_hi:[1,0]
	s_nop 0
	v_pk_fma_f32 v[102:103], v[102:103], v[138:139], v[142:143] op_sel:[1,1,0] op_sel_hi:[0,1,1] neg_lo:[0,1,0]
	v_pk_mul_f32 v[142:143], v[138:139], v[140:141] op_sel_hi:[1,0]
	s_nop 0
	v_pk_fma_f32 v[138:139], v[138:139], v[140:141], v[142:143] op_sel:[1,1,0] op_sel_hi:[0,1,1] neg_lo:[0,1,0]
	s_nop 0
	v_pk_mul_f32 v[142:143], v[104:105], v[138:139] op_sel_hi:[1,0]
	s_nop 0
	v_pk_fma_f32 v[104:105], v[104:105], v[138:139], v[142:143] op_sel:[1,1,0] op_sel_hi:[0,1,1] neg_lo:[0,1,0]
	v_pk_mul_f32 v[142:143], v[138:139], v[140:141] op_sel_hi:[1,0]
	s_nop 0
	v_pk_fma_f32 v[138:139], v[138:139], v[140:141], v[142:143] op_sel:[1,1,0] op_sel_hi:[0,1,1] neg_lo:[0,1,0]
	s_nop 0
	v_pk_mul_f32 v[142:143], v[106:107], v[138:139] op_sel_hi:[1,0]
	s_nop 0
	v_pk_fma_f32 v[106:107], v[106:107], v[138:139], v[142:143] op_sel:[1,1,0] op_sel_hi:[0,1,1] neg_lo:[0,1,0]
	v_pk_mul_f32 v[142:143], v[138:139], v[140:141] op_sel_hi:[1,0]
	s_nop 0
	v_pk_fma_f32 v[138:139], v[138:139], v[140:141], v[142:143] op_sel:[1,1,0] op_sel_hi:[0,1,1] neg_lo:[0,1,0]
	s_nop 0
	v_pk_mul_f32 v[142:143], v[108:109], v[138:139] op_sel_hi:[1,0]
	s_nop 0
	v_pk_fma_f32 v[108:109], v[108:109], v[138:139], v[142:143] op_sel:[1,1,0] op_sel_hi:[0,1,1] neg_lo:[0,1,0]
	v_pk_mul_f32 v[142:143], v[138:139], v[140:141] op_sel_hi:[1,0]
	s_nop 0
	v_pk_fma_f32 v[138:139], v[138:139], v[140:141], v[142:143] op_sel:[1,1,0] op_sel_hi:[0,1,1] neg_lo:[0,1,0]
	s_nop 0
	v_pk_mul_f32 v[142:143], v[110:111], v[138:139] op_sel_hi:[1,0]
	s_nop 0
	v_pk_fma_f32 v[110:111], v[110:111], v[138:139], v[142:143] op_sel:[1,1,0] op_sel_hi:[0,1,1] neg_lo:[0,1,0]
	v_pk_mul_f32 v[142:143], v[138:139], v[140:141] op_sel_hi:[1,0]
	s_nop 0
	v_pk_fma_f32 v[138:139], v[138:139], v[140:141], v[142:143] op_sel:[1,1,0] op_sel_hi:[0,1,1] neg_lo:[0,1,0]
	s_nop 0
	v_pk_mul_f32 v[142:143], v[112:113], v[138:139] op_sel_hi:[1,0]
	s_nop 0
	v_pk_fma_f32 v[112:113], v[112:113], v[138:139], v[142:143] op_sel:[1,1,0] op_sel_hi:[0,1,1] neg_lo:[0,1,0]
	v_pk_mul_f32 v[142:143], v[138:139], v[140:141] op_sel_hi:[1,0]
	s_nop 0
	v_pk_fma_f32 v[138:139], v[138:139], v[140:141], v[142:143] op_sel:[1,1,0] op_sel_hi:[0,1,1] neg_lo:[0,1,0]
	s_nop 0
	v_pk_mul_f32 v[142:143], v[114:115], v[138:139] op_sel_hi:[1,0]
	s_nop 0
	v_pk_fma_f32 v[114:115], v[114:115], v[138:139], v[142:143] op_sel:[1,1,0] op_sel_hi:[0,1,1] neg_lo:[0,1,0]
	v_pk_mul_f32 v[142:143], v[138:139], v[140:141] op_sel_hi:[1,0]
	s_nop 0
	v_pk_fma_f32 v[138:139], v[138:139], v[140:141], v[142:143] op_sel:[1,1,0] op_sel_hi:[0,1,1] neg_lo:[0,1,0]
	s_nop 0
	v_pk_mul_f32 v[142:143], v[116:117], v[138:139] op_sel_hi:[1,0]
	s_nop 0
	v_pk_fma_f32 v[116:117], v[116:117], v[138:139], v[142:143] op_sel:[1,1,0] op_sel_hi:[0,1,1] neg_lo:[0,1,0]
	v_pk_mul_f32 v[142:143], v[138:139], v[140:141] op_sel_hi:[1,0]
	s_nop 0
	v_pk_fma_f32 v[138:139], v[138:139], v[140:141], v[142:143] op_sel:[1,1,0] op_sel_hi:[0,1,1] neg_lo:[0,1,0]
	s_nop 0
	v_pk_mul_f32 v[142:143], v[118:119], v[138:139] op_sel_hi:[1,0]
	s_nop 0
	v_pk_fma_f32 v[118:119], v[118:119], v[138:139], v[142:143] op_sel:[1,1,0] op_sel_hi:[0,1,1] neg_lo:[0,1,0]
	v_pk_mul_f32 v[142:143], v[138:139], v[140:141] op_sel_hi:[1,0]
	s_nop 0
	v_pk_fma_f32 v[138:139], v[138:139], v[140:141], v[142:143] op_sel:[1,1,0] op_sel_hi:[0,1,1] neg_lo:[0,1,0]
	s_nop 0
	v_pk_mul_f32 v[142:143], v[120:121], v[138:139] op_sel_hi:[1,0]
; __device__ __forceinline__ f2 cmulc(f2 a, float wr, float wi) { const f2 s = __builtin_shufflevector(a, a, 1, 0); return s * (f2){wi, -wi} + a * (f2){wr, wr}; }
; __device__ __forceinline__ void ifft32(f2 (&x)[32]) {
;     ...
; #pragma unroll
;     for (int h = 1; h <= 16; h <<= 1) {
; #pragma unroll
;         for (int i0 = 0; i0 < 32; i0 += 2 * h) {
; #pragma unroll
;             for (int j = 0; j < h; ++j) {
;                 const int i = i0 + j, k = i + h, m = j * (32 / h);
;                 const f2 a = x[i], y = x[k];
;                 f2 b;
;                 if (m == 0) b = y;
;                 else if (m == 16) b = (f2){-y.y, y.x};
;                 else b = cmulc(y, TWR[m], TWI[m]);
;                 x[i] = a + b; x[k] = a - b;
;             }
;         }
;     }
; template <bool CONJ> __device__ __forceinline__ void twiddle32(f2 (&x)[32], float wr, float wi) {
;     asm volatile("" : "+v"(wr), "+v"(wi));
;     f2 c = (f2){wr, CONJ ? -wi : wi}; const f2 w = c;
; #pragma unroll
;     for (int k = 1; k < 32; ++k) { const int p = brev5(k); x[p] = cmulr(x[p], c); if (k < 31) c = cmulr(c, w); }
; }
	s_nop 0
	v_pk_fma_f32 v[120:121], v[120:121], v[138:139], v[142:143] op_sel:[1,1,0] op_sel_hi:[0,1,1] neg_lo:[0,1,0]
	v_pk_mul_f32 v[142:143], v[138:139], v[140:141] op_sel_hi:[1,0]
	s_nop 0
	v_pk_fma_f32 v[138:139], v[138:139], v[140:141], v[142:143] op_sel:[1,1,0] op_sel_hi:[0,1,1] neg_lo:[0,1,0]
	s_nop 0
	v_pk_mul_f32 v[142:143], v[122:123], v[138:139] op_sel_hi:[1,0]
	s_nop 0
	v_pk_fma_f32 v[122:123], v[122:123], v[138:139], v[142:143] op_sel:[1,1,0] op_sel_hi:[0,1,1] neg_lo:[0,1,0]
	v_pk_mul_f32 v[142:143], v[138:139], v[140:141] op_sel_hi:[1,0]
	s_nop 0
	v_pk_fma_f32 v[138:139], v[138:139], v[140:141], v[142:143] op_sel:[1,1,0] op_sel_hi:[0,1,1] neg_lo:[0,1,0]
	s_nop 0
	v_pk_mul_f32 v[142:143], v[124:125], v[138:139] op_sel_hi:[1,0]
	s_nop 0
	v_pk_fma_f32 v[124:125], v[124:125], v[138:139], v[142:143] op_sel:[1,1,0] op_sel_hi:[0,1,1] neg_lo:[0,1,0]
	v_pk_mul_f32 v[142:143], v[138:139], v[140:141] op_sel_hi:[1,0]
	s_nop 0
	v_pk_fma_f32 v[138:139], v[138:139], v[140:141], v[142:143] op_sel:[1,1,0] op_sel_hi:[0,1,1] neg_lo:[0,1,0]
	s_nop 0
	v_pk_mul_f32 v[142:143], v[126:127], v[138:139] op_sel_hi:[1,0]
	s_nop 0
	v_pk_fma_f32 v[126:127], v[126:127], v[138:139], v[142:143] op_sel:[1,1,0] op_sel_hi:[0,1,1] neg_lo:[0,1,0]
	v_pk_mul_f32 v[142:143], v[138:139], v[140:141] op_sel_hi:[1,0]
	s_nop 0
	v_pk_fma_f32 v[138:139], v[138:139], v[140:141], v[142:143] op_sel:[1,1,0] op_sel_hi:[0,1,1] neg_lo:[0,1,0]
	s_nop 0
	v_pk_mul_f32 v[142:143], v[128:129], v[138:139] op_sel_hi:[1,0]
	s_nop 0
	v_pk_fma_f32 v[128:129], v[128:129], v[138:139], v[142:143] op_sel:[1,1,0] op_sel_hi:[0,1,1] neg_lo:[0,1,0]
	v_pk_mul_f32 v[142:143], v[138:139], v[140:141] op_sel_hi:[1,0]
	s_nop 0
	v_pk_fma_f32 v[138:139], v[138:139], v[140:141], v[142:143] op_sel:[1,1,0] op_sel_hi:[0,1,1] neg_lo:[0,1,0]
	s_nop 0
	v_pk_mul_f32 v[142:143], v[130:131], v[138:139] op_sel_hi:[1,0]
	s_nop 0
	v_pk_fma_f32 v[130:131], v[130:131], v[138:139], v[142:143] op_sel:[1,1,0] op_sel_hi:[0,1,1] neg_lo:[0,1,0]
	v_pk_mul_f32 v[142:143], v[138:139], v[140:141] op_sel_hi:[1,0]
	s_nop 0
	v_pk_fma_f32 v[138:139], v[138:139], v[140:141], v[142:143] op_sel:[1,1,0] op_sel_hi:[0,1,1] neg_lo:[0,1,0]
	s_nop 0
	v_pk_mul_f32 v[142:143], v[132:133], v[138:139] op_sel_hi:[1,0]
	s_nop 0
	v_pk_fma_f32 v[132:133], v[132:133], v[138:139], v[142:143] op_sel:[1,1,0] op_sel_hi:[0,1,1] neg_lo:[0,1,0]
	v_pk_mul_f32 v[142:143], v[138:139], v[140:141] op_sel_hi:[1,0]
	s_nop 0
	v_pk_fma_f32 v[138:139], v[138:139], v[140:141], v[142:143] op_sel:[1,1,0] op_sel_hi:[0,1,1] neg_lo:[0,1,0]
	s_nop 0
	v_pk_mul_f32 v[142:143], v[134:135], v[138:139] op_sel_hi:[1,0]
	s_nop 0
	v_pk_fma_f32 v[134:135], v[134:135], v[138:139], v[142:143] op_sel:[1,1,0] op_sel_hi:[0,1,1] neg_lo:[0,1,0]
	v_pk_mul_f32 v[142:143], v[138:139], v[140:141] op_sel_hi:[1,0]
	s_nop 0
	v_pk_fma_f32 v[138:139], v[138:139], v[140:141], v[142:143] op_sel:[1,1,0] op_sel_hi:[0,1,1] neg_lo:[0,1,0]
	s_nop 0
	v_pk_mul_f32 v[140:141], v[136:137], v[138:139] op_sel_hi:[1,0]
	s_nop 0
	v_pk_fma_f32 v[136:137], v[136:137], v[138:139], v[140:141] op_sel:[1,1,0] op_sel_hi:[0,1,1] neg_lo:[0,1,0]
	v_pk_add_f32 v[138:139], v[0:1], v[106:107]
	v_pk_add_f32 v[0:1], v[0:1], v[106:107] neg_lo:[0,1] neg_hi:[0,1]
	v_pk_add_f32 v[106:107], v[90:91], v[122:123]
	v_pk_add_f32 v[90:91], v[90:91], v[122:123] neg_lo:[0,1] neg_hi:[0,1]
	v_pk_add_f32 v[122:123], v[8:9], v[114:115]
	v_pk_add_f32 v[8:9], v[8:9], v[114:115] neg_lo:[0,1] neg_hi:[0,1]
	v_pk_add_f32 v[114:115], v[98:99], v[130:131]
	v_pk_add_f32 v[98:99], v[98:99], v[130:131] neg_lo:[0,1] neg_hi:[0,1]
	v_pk_add_f32 v[130:131], v[4:5], v[110:111]
	v_pk_add_f32 v[4:5], v[4:5], v[110:111] neg_lo:[0,1] neg_hi:[0,1]
	v_pk_add_f32 v[110:111], v[94:95], v[126:127]
	v_pk_add_f32 v[94:95], v[94:95], v[126:127] neg_lo:[0,1] neg_hi:[0,1]
	v_pk_add_f32 v[126:127], v[86:87], v[118:119]
	v_pk_add_f32 v[86:87], v[86:87], v[118:119] neg_lo:[0,1] neg_hi:[0,1]
	v_pk_add_f32 v[118:119], v[102:103], v[134:135]
	v_pk_add_f32 v[102:103], v[102:103], v[134:135] neg_lo:[0,1] neg_hi:[0,1]
	v_pk_add_f32 v[134:135], v[2:3], v[108:109]
	v_pk_add_f32 v[2:3], v[2:3], v[108:109] neg_lo:[0,1] neg_hi:[0,1]
	v_pk_add_f32 v[108:109], v[92:93], v[124:125]
	v_pk_add_f32 v[92:93], v[92:93], v[124:125] neg_lo:[0,1] neg_hi:[0,1]
	v_pk_add_f32 v[124:125], v[10:11], v[116:117]
	v_pk_add_f32 v[10:11], v[10:11], v[116:117] neg_lo:[0,1] neg_hi:[0,1]
	v_pk_add_f32 v[116:117], v[100:101], v[132:133]
	v_pk_add_f32 v[100:101], v[100:101], v[132:133] neg_lo:[0,1] neg_hi:[0,1]
	v_pk_add_f32 v[132:133], v[6:7], v[112:113]
	v_pk_add_f32 v[6:7], v[6:7], v[112:113] neg_lo:[0,1] neg_hi:[0,1]
	v_pk_add_f32 v[112:113], v[96:97], v[128:129]
	v_pk_add_f32 v[96:97], v[96:97], v[128:129] neg_lo:[0,1] neg_hi:[0,1]
	v_pk_add_f32 v[128:129], v[88:89], v[120:121]
	v_pk_add_f32 v[88:89], v[88:89], v[120:121] neg_lo:[0,1] neg_hi:[0,1]
	v_pk_add_f32 v[120:121], v[104:105], v[136:137]
	v_pk_add_f32 v[104:105], v[104:105], v[136:137] neg_lo:[0,1] neg_hi:[0,1]
	v_pk_add_f32 v[136:137], v[138:139], v[106:107]
	v_pk_add_f32 v[106:107], v[138:139], v[106:107] neg_lo:[0,1] neg_hi:[0,1]
	v_xor_b32_e32 v138, 0x80000000, v91
	v_mov_b32_e32 v139, v90
	v_pk_add_f32 v[90:91], v[0:1], v[138:139]
	v_pk_add_f32 v[0:1], v[0:1], v[138:139] neg_lo:[0,1] neg_hi:[0,1]
	v_pk_add_f32 v[138:139], v[122:123], v[114:115]
	v_pk_add_f32 v[114:115], v[122:123], v[114:115] neg_lo:[0,1] neg_hi:[0,1]
	v_xor_b32_e32 v122, 0x80000000, v99
	v_mov_b32_e32 v123, v98
	v_pk_add_f32 v[98:99], v[8:9], v[122:123]
	v_pk_add_f32 v[8:9], v[8:9], v[122:123] neg_lo:[0,1] neg_hi:[0,1]
	v_pk_add_f32 v[122:123], v[130:131], v[110:111]
; __device__ __forceinline__ f2 cmulc(f2 a, float wr, float wi) { const f2 s = __builtin_shufflevector(a, a, 1, 0); return s * (f2){wi, -wi} + a * (f2){wr, wr}; }
; __device__ __forceinline__ void ifft32(f2 (&x)[32]) {
;     ...
; #pragma unroll
;     for (int h = 1; h <= 16; h <<= 1) {
; #pragma unroll
;         for (int i0 = 0; i0 < 32; i0 += 2 * h) {
; #pragma unroll
;             for (int j = 0; j < h; ++j) {
;                 const int i = i0 + j, k = i + h, m = j * (32 / h);
;                 const f2 a = x[i], y = x[k];
;                 f2 b;
;                 if (m == 0) b = y;
;                 else if (m == 16) b = (f2){-y.y, y.x};
;                 else b = cmulc(y, TWR[m], TWI[m]);
;                 x[i] = a + b; x[k] = a - b;
;             }
;         }
;     }
	v_pk_add_f32 v[110:111], v[130:131], v[110:111] neg_lo:[0,1] neg_hi:[0,1]
	v_xor_b32_e32 v130, 0x80000000, v95
	v_mov_b32_e32 v131, v94
	v_pk_add_f32 v[94:95], v[4:5], v[130:131]
	v_pk_add_f32 v[4:5], v[4:5], v[130:131] neg_lo:[0,1] neg_hi:[0,1]
	v_pk_add_f32 v[130:131], v[126:127], v[118:119]
	v_pk_add_f32 v[118:119], v[126:127], v[118:119] neg_lo:[0,1] neg_hi:[0,1]
	v_xor_b32_e32 v126, 0x80000000, v103
	v_mov_b32_e32 v127, v102
	v_pk_add_f32 v[102:103], v[86:87], v[126:127]
	v_pk_add_f32 v[86:87], v[86:87], v[126:127] neg_lo:[0,1] neg_hi:[0,1]
	v_pk_add_f32 v[126:127], v[134:135], v[108:109]
	v_pk_add_f32 v[108:109], v[134:135], v[108:109] neg_lo:[0,1] neg_hi:[0,1]
	v_xor_b32_e32 v134, 0x80000000, v93
	v_mov_b32_e32 v135, v92
	v_pk_add_f32 v[92:93], v[2:3], v[134:135]
	v_pk_add_f32 v[2:3], v[2:3], v[134:135] neg_lo:[0,1] neg_hi:[0,1]
	v_pk_add_f32 v[134:135], v[124:125], v[116:117]
	v_pk_add_f32 v[116:117], v[124:125], v[116:117] neg_lo:[0,1] neg_hi:[0,1]
	v_xor_b32_e32 v124, 0x80000000, v101
	v_mov_b32_e32 v125, v100
	v_pk_add_f32 v[100:101], v[10:11], v[124:125]
	v_pk_add_f32 v[10:11], v[10:11], v[124:125] neg_lo:[0,1] neg_hi:[0,1]
	v_pk_add_f32 v[124:125], v[132:133], v[112:113]
	v_pk_add_f32 v[112:113], v[132:133], v[112:113] neg_lo:[0,1] neg_hi:[0,1]
	v_xor_b32_e32 v132, 0x80000000, v97
	v_mov_b32_e32 v133, v96
	v_pk_add_f32 v[96:97], v[6:7], v[132:133]
	v_pk_add_f32 v[6:7], v[6:7], v[132:133] neg_lo:[0,1] neg_hi:[0,1]
	v_pk_add_f32 v[132:133], v[128:129], v[120:121]
	v_pk_add_f32 v[120:121], v[128:129], v[120:121] neg_lo:[0,1] neg_hi:[0,1]
	v_xor_b32_e32 v128, 0x80000000, v105
	v_mov_b32_e32 v129, v104
	v_pk_add_f32 v[104:105], v[88:89], v[128:129]
	v_pk_add_f32 v[88:89], v[88:89], v[128:129] neg_lo:[0,1] neg_hi:[0,1]
	v_pk_add_f32 v[128:129], v[136:137], v[138:139]
	v_pk_add_f32 v[136:137], v[136:137], v[138:139] neg_lo:[0,1] neg_hi:[0,1]
	v_pk_mul_f32 v[138:139], v[98:99], s[96:97]
	s_nop 0
	v_pk_fma_f32 v[98:99], v[98:99], s[94:95], v[138:139] op_sel:[0,0,1] op_sel_hi:[1,0,0]
	s_nop 0
	v_pk_add_f32 v[138:139], v[90:91], v[98:99]
	v_pk_add_f32 v[90:91], v[90:91], v[98:99] neg_lo:[0,1] neg_hi:[0,1]
	v_xor_b32_e32 v98, 0x80000000, v115
	v_mov_b32_e32 v99, v114
	v_pk_add_f32 v[114:115], v[106:107], v[98:99]
	v_pk_add_f32 v[98:99], v[106:107], v[98:99] neg_lo:[0,1] neg_hi:[0,1]
	v_pk_mul_f32 v[106:107], v[8:9], s[96:97]
	s_nop 0
	v_pk_fma_f32 v[8:9], v[8:9], s[94:95], v[106:107] op_sel:[0,0,1] op_sel_hi:[1,0,0] neg_lo:[1,0,0] neg_hi:[1,0,0]
	s_nop 0
	v_pk_add_f32 v[106:107], v[0:1], v[8:9]
	v_pk_add_f32 v[0:1], v[0:1], v[8:9] neg_lo:[0,1] neg_hi:[0,1]
	v_pk_add_f32 v[8:9], v[122:123], v[130:131]
	v_pk_add_f32 v[122:123], v[122:123], v[130:131] neg_lo:[0,1] neg_hi:[0,1]
	v_pk_mul_f32 v[130:131], v[102:103], s[96:97]
	s_nop 0
	v_pk_fma_f32 v[102:103], v[102:103], s[94:95], v[130:131] op_sel:[0,0,1] op_sel_hi:[1,0,0]
	s_nop 0
	v_pk_add_f32 v[130:131], v[94:95], v[102:103]
	v_pk_add_f32 v[94:95], v[94:95], v[102:103] neg_lo:[0,1] neg_hi:[0,1]
	v_xor_b32_e32 v102, 0x80000000, v119
	v_mov_b32_e32 v103, v118
	v_pk_add_f32 v[118:119], v[110:111], v[102:103]
	v_pk_add_f32 v[102:103], v[110:111], v[102:103] neg_lo:[0,1] neg_hi:[0,1]
	v_pk_mul_f32 v[110:111], v[86:87], s[96:97]
	s_nop 0
	v_pk_fma_f32 v[86:87], v[86:87], s[94:95], v[110:111] op_sel:[0,0,1] op_sel_hi:[1,0,0] neg_lo:[1,0,0] neg_hi:[1,0,0]
	s_nop 0
	v_pk_add_f32 v[110:111], v[4:5], v[86:87]
	v_pk_add_f32 v[4:5], v[4:5], v[86:87] neg_lo:[0,1] neg_hi:[0,1]
	v_pk_add_f32 v[86:87], v[126:127], v[134:135]
	v_pk_add_f32 v[126:127], v[126:127], v[134:135] neg_lo:[0,1] neg_hi:[0,1]
	v_pk_mul_f32 v[134:135], v[100:101], s[96:97]
	s_nop 0
	v_pk_fma_f32 v[100:101], v[100:101], s[94:95], v[134:135] op_sel:[0,0,1] op_sel_hi:[1,0,0]
	s_nop 0
	v_pk_add_f32 v[134:135], v[92:93], v[100:101]
	v_pk_add_f32 v[92:93], v[92:93], v[100:101] neg_lo:[0,1] neg_hi:[0,1]
	v_xor_b32_e32 v100, 0x80000000, v117
	v_mov_b32_e32 v101, v116
	v_pk_add_f32 v[116:117], v[108:109], v[100:101]
	v_pk_add_f32 v[100:101], v[108:109], v[100:101] neg_lo:[0,1] neg_hi:[0,1]
	v_pk_mul_f32 v[108:109], v[10:11], s[96:97]
	s_nop 0
	v_pk_fma_f32 v[10:11], v[10:11], s[94:95], v[108:109] op_sel:[0,0,1] op_sel_hi:[1,0,0] neg_lo:[1,0,0] neg_hi:[1,0,0]
	s_nop 0
	v_pk_add_f32 v[108:109], v[2:3], v[10:11]
	v_pk_add_f32 v[2:3], v[2:3], v[10:11] neg_lo:[0,1] neg_hi:[0,1]
	v_pk_add_f32 v[10:11], v[124:125], v[132:133]
	v_pk_add_f32 v[124:125], v[124:125], v[132:133] neg_lo:[0,1] neg_hi:[0,1]
	v_pk_mul_f32 v[132:133], v[104:105], s[96:97]
	s_nop 0
	v_pk_fma_f32 v[104:105], v[104:105], s[94:95], v[132:133] op_sel:[0,0,1] op_sel_hi:[1,0,0]
	s_nop 0
	v_pk_add_f32 v[132:133], v[96:97], v[104:105]
	v_pk_add_f32 v[96:97], v[96:97], v[104:105] neg_lo:[0,1] neg_hi:[0,1]
	v_xor_b32_e32 v104, 0x80000000, v121
	v_mov_b32_e32 v105, v120
	v_pk_add_f32 v[120:121], v[112:113], v[104:105]
	v_pk_add_f32 v[104:105], v[112:113], v[104:105] neg_lo:[0,1] neg_hi:[0,1]
	v_pk_mul_f32 v[112:113], v[88:89], s[96:97]
	s_nop 0
	v_pk_fma_f32 v[88:89], v[88:89], s[94:95], v[112:113] op_sel:[0,0,1] op_sel_hi:[1,0,0] neg_lo:[1,0,0] neg_hi:[1,0,0]
	s_nop 0
	v_pk_add_f32 v[112:113], v[6:7], v[88:89]
	v_pk_add_f32 v[6:7], v[6:7], v[88:89] neg_lo:[0,1] neg_hi:[0,1]
	v_pk_add_f32 v[88:89], v[128:129], v[8:9]
	v_pk_add_f32 v[8:9], v[128:129], v[8:9] neg_lo:[0,1] neg_hi:[0,1]
	v_pk_mul_f32 v[128:129], v[130:131], s[6:7]
	s_nop 0
	v_pk_fma_f32 v[128:129], v[130:131], s[56:57], v[128:129] op_sel:[0,0,1] op_sel_hi:[1,0,0]
	s_nop 0
	v_pk_add_f32 v[130:131], v[138:139], v[128:129]
	v_pk_add_f32 v[138:139], v[138:139], v[128:129] neg_lo:[0,1] neg_hi:[0,1]
	v_pk_mul_f32 v[128:129], v[118:119], s[96:97]
; __device__ __forceinline__ f2 cmulc(f2 a, float wr, float wi) { const f2 s = __builtin_shufflevector(a, a, 1, 0); return s * (f2){wi, -wi} + a * (f2){wr, wr}; }
; __device__ __forceinline__ void ifft32(f2 (&x)[32]) {
;     ...
; #pragma unroll
;     for (int h = 1; h <= 16; h <<= 1) {
; #pragma unroll
;         for (int i0 = 0; i0 < 32; i0 += 2 * h) {
; #pragma unroll
;             for (int j = 0; j < h; ++j) {
;                 const int i = i0 + j, k = i + h, m = j * (32 / h);
;                 const f2 a = x[i], y = x[k];
;                 f2 b;
;                 if (m == 0) b = y;
;                 else if (m == 16) b = (f2){-y.y, y.x};
;                 else b = cmulc(y, TWR[m], TWI[m]);
;                 x[i] = a + b; x[k] = a - b;
;             }
;         }
;     }
	s_nop 0
	v_pk_fma_f32 v[118:119], v[118:119], s[94:95], v[128:129] op_sel:[0,0,1] op_sel_hi:[1,0,0]
	s_nop 0
	v_pk_add_f32 v[140:141], v[114:115], v[118:119]
	v_pk_add_f32 v[142:143], v[114:115], v[118:119] neg_lo:[0,1] neg_hi:[0,1]
	v_pk_mul_f32 v[118:119], v[94:95], s[56:57]
	v_pk_mul_f32 v[114:115], v[110:111], s[56:57]
	v_pk_fma_f32 v[94:95], v[94:95], s[84:85], v[118:119] op_sel:[0,0,1] op_sel_hi:[1,0,0] neg_lo:[1,0,0] neg_hi:[1,0,0]
	v_pk_fma_f32 v[110:111], v[110:111], s[84:85], v[114:115] op_sel:[0,0,1] op_sel_hi:[1,0,0]
	v_pk_add_f32 v[144:145], v[90:91], v[94:95]
	v_pk_add_f32 v[146:147], v[90:91], v[94:95] neg_lo:[0,1] neg_hi:[0,1]
	v_pk_mul_f32 v[90:91], v[102:103], s[96:97]
	v_pk_add_f32 v[114:115], v[106:107], v[110:111]
	v_pk_fma_f32 v[90:91], v[102:103], s[94:95], v[90:91] op_sel:[0,0,1] op_sel_hi:[1,0,0] neg_lo:[1,0,0] neg_hi:[1,0,0]
	v_pk_add_f32 v[106:107], v[106:107], v[110:111] neg_lo:[0,1] neg_hi:[0,1]
	v_pk_add_f32 v[94:95], v[98:99], v[90:91]
	v_pk_add_f32 v[148:149], v[98:99], v[90:91] neg_lo:[0,1] neg_hi:[0,1]
	v_pk_mul_f32 v[90:91], v[4:5], s[6:7]
	v_xor_b32_e32 v110, 0x80000000, v123
	v_pk_fma_f32 v[4:5], v[4:5], s[56:57], v[90:91] op_sel:[0,0,1] op_sel_hi:[1,0,0] neg_lo:[1,0,0] neg_hi:[1,0,0]
	v_pk_mul_f32 v[90:91], v[120:121], s[96:97]
	v_pk_add_f32 v[212:213], v[0:1], v[4:5]
	v_pk_fma_f32 v[90:91], v[120:121], s[94:95], v[90:91] op_sel:[0,0,1] op_sel_hi:[1,0,0]
	v_pk_add_f32 v[214:215], v[0:1], v[4:5] neg_lo:[0,1] neg_hi:[0,1]
	v_pk_add_f32 v[102:103], v[116:117], v[90:91]
	v_pk_add_f32 v[120:121], v[116:117], v[90:91] neg_lo:[0,1] neg_hi:[0,1]
	v_pk_mul_f32 v[90:91], v[112:113], s[56:57]
	v_pk_add_f32 v[0:1], v[86:87], v[10:11]
	v_pk_fma_f32 v[90:91], v[112:113], s[84:85], v[90:91] op_sel:[0,0,1] op_sel_hi:[1,0,0]
	v_pk_add_f32 v[4:5], v[86:87], v[10:11] neg_lo:[0,1] neg_hi:[0,1]
	v_pk_mul_f32 v[10:11], v[132:133], s[6:7]
	v_pk_add_f32 v[112:113], v[108:109], v[90:91]
	v_pk_add_f32 v[108:109], v[108:109], v[90:91] neg_lo:[0,1] neg_hi:[0,1]
	v_xor_b32_e32 v90, 0x80000000, v125
	v_mov_b32_e32 v91, v124
	v_pk_fma_f32 v[10:11], v[132:133], s[56:57], v[10:11] op_sel:[0,0,1] op_sel_hi:[1,0,0]
	v_pk_add_f32 v[116:117], v[126:127], v[90:91]
	v_pk_add_f32 v[216:217], v[126:127], v[90:91] neg_lo:[0,1] neg_hi:[0,1]
	v_pk_mul_f32 v[90:91], v[96:97], s[56:57]
	v_pk_add_f32 v[86:87], v[134:135], v[10:11]
	v_pk_fma_f32 v[90:91], v[96:97], s[84:85], v[90:91] op_sel:[0,0,1] op_sel_hi:[1,0,0] neg_lo:[1,0,0] neg_hi:[1,0,0]
	v_pk_add_f32 v[128:129], v[88:89], v[0:1]
	v_pk_add_f32 v[96:97], v[92:93], v[90:91]
	v_pk_add_f32 v[218:219], v[92:93], v[90:91] neg_lo:[0,1] neg_hi:[0,1]
	v_pk_mul_f32 v[90:91], v[104:105], s[96:97]
	v_pk_add_f32 v[98:99], v[88:89], v[0:1] neg_lo:[0,1] neg_hi:[0,1]
	v_pk_mul_f32 v[0:1], v[86:87], s[76:77]
	v_pk_fma_f32 v[90:91], v[104:105], s[94:95], v[90:91] op_sel:[0,0,1] op_sel_hi:[1,0,0] neg_lo:[1,0,0] neg_hi:[1,0,0]
	v_pk_fma_f32 v[0:1], v[86:87], s[52:53], v[0:1] op_sel:[0,0,1] op_sel_hi:[1,0,0]
	v_pk_add_f32 v[92:93], v[100:101], v[90:91]
	v_pk_add_f32 v[222:223], v[100:101], v[90:91] neg_lo:[0,1] neg_hi:[0,1]
	v_pk_add_f32 v[132:133], v[130:131], v[0:1]
	v_pk_add_f32 v[100:101], v[130:131], v[0:1] neg_lo:[0,1] neg_hi:[0,1]
	v_pk_mul_f32 v[0:1], v[102:103], s[6:7]
	v_pk_add_f32 v[10:11], v[134:135], v[10:11] neg_lo:[0,1] neg_hi:[0,1]
	v_pk_fma_f32 v[0:1], v[102:103], s[56:57], v[0:1] op_sel:[0,0,1] op_sel_hi:[1,0,0]
	v_mov_b32_e32 v111, v122
	v_pk_add_f32 v[134:135], v[140:141], v[0:1]
	v_pk_add_f32 v[102:103], v[140:141], v[0:1] neg_lo:[0,1] neg_hi:[0,1]
	v_pk_mul_f32 v[0:1], v[112:113], s[20:21]
	v_pk_add_f32 v[122:123], v[136:137], v[110:111]
	v_pk_fma_f32 v[0:1], v[112:113], s[60:61], v[0:1] op_sel:[0,0,1] op_sel_hi:[1,0,0]
	v_pk_add_f32 v[110:111], v[136:137], v[110:111] neg_lo:[0,1] neg_hi:[0,1]
	v_pk_add_f32 v[136:137], v[114:115], v[0:1]
	v_pk_add_f32 v[104:105], v[114:115], v[0:1] neg_lo:[0,1] neg_hi:[0,1]
	v_pk_mul_f32 v[0:1], v[116:117], s[96:97]
	v_pk_mul_f32 v[90:91], v[6:7], s[6:7]
	v_pk_fma_f32 v[0:1], v[116:117], s[94:95], v[0:1] op_sel:[0,0,1] op_sel_hi:[1,0,0]
	v_pk_fma_f32 v[6:7], v[6:7], s[56:57], v[90:91] op_sel:[0,0,1] op_sel_hi:[1,0,0] neg_lo:[1,0,0] neg_hi:[1,0,0]
	v_pk_add_f32 v[118:119], v[122:123], v[0:1]
	v_pk_add_f32 v[86:87], v[122:123], v[0:1] neg_lo:[0,1] neg_hi:[0,1]
	v_pk_mul_f32 v[0:1], v[96:97], s[60:61]
	v_pk_add_f32 v[124:125], v[2:3], v[6:7]
	v_pk_fma_f32 v[0:1], v[96:97], s[86:87], v[0:1] op_sel:[0,0,1] op_sel_hi:[1,0,0]
	v_pk_add_f32 v[6:7], v[2:3], v[6:7] neg_lo:[0,1] neg_hi:[0,1]
	v_pk_add_f32 v[122:123], v[144:145], v[0:1]
	v_pk_add_f32 v[90:91], v[144:145], v[0:1] neg_lo:[0,1] neg_hi:[0,1]
	v_pk_mul_f32 v[0:1], v[92:93], s[56:57]
	v_pk_mul_f32 v[2:3], v[218:219], s[20:21]
	v_pk_fma_f32 v[0:1], v[92:93], s[84:85], v[0:1] op_sel:[0,0,1] op_sel_hi:[1,0,0]
	v_pk_mul_f32 v[112:113], v[6:7], s[76:77]
	v_pk_add_f32 v[126:127], v[94:95], v[0:1]
	v_pk_add_f32 v[94:95], v[94:95], v[0:1] neg_lo:[0,1] neg_hi:[0,1]
	v_pk_mul_f32 v[0:1], v[124:125], s[52:53]
	v_pk_fma_f32 v[2:3], v[218:219], s[60:61], v[2:3] op_sel:[0,0,1] op_sel_hi:[1,0,0] neg_lo:[1,0,0] neg_hi:[1,0,0]
	v_pk_fma_f32 v[0:1], v[124:125], s[10:11], v[0:1] op_sel:[0,0,1] op_sel_hi:[1,0,0]
	v_pk_fma_f32 v[6:7], v[6:7], s[52:53], v[112:113] op_sel:[0,0,1] op_sel_hi:[1,0,0] neg_lo:[1,0,0] neg_hi:[1,0,0]
	v_pk_add_f32 v[130:131], v[212:213], v[0:1]
	v_pk_add_f32 v[96:97], v[212:213], v[0:1] neg_lo:[0,1] neg_hi:[0,1]
	v_xor_b32_e32 v0, 0x80000000, v5
	v_mov_b32_e32 v1, v4
	v_pk_add_f32 v[114:115], v[8:9], v[0:1]
	v_pk_add_f32 v[8:9], v[8:9], v[0:1] neg_lo:[0,1] neg_hi:[0,1]
	v_pk_mul_f32 v[0:1], v[10:11], s[52:53]
; #define LAS __attribute__((address_space(3)))
; __device__ __forceinline__ float bflo(unsigned w) { return __uint_as_float(w << 16); }
; __device__ __forceinline__ float bfhi(unsigned w) { return __uint_as_float(w & 0xffff0000u); }
; __device__ __forceinline__ f2 cmulc(f2 a, float wr, float wi) { const f2 s = __builtin_shufflevector(a, a, 1, 0); return s * (f2){wi, -wi} + a * (f2){wr, wr}; }
; __device__ __forceinline__ void ifft32(f2 (&x)[32]) {
;     ...
;     for (int h = 1; h <= 16; h <<= 1) {
; #pragma unroll
;         for (int i0 = 0; i0 < 32; i0 += 2 * h) {
; #pragma unroll
;             for (int j = 0; j < h; ++j) {
;                 const int i = i0 + j, k = i + h, m = j * (32 / h);
;                 const f2 a = x[i], y = x[k];
;                 f2 b;
;                 if (m == 0) b = y;
;                 else if (m == 16) b = (f2){-y.y, y.x};
;                 else b = cmulc(y, TWR[m], TWI[m]);
;                 x[i] = a + b; x[k] = a - b;
;             }
; template <int VAR> __device__ __forceinline__ void hyena_conv_phase(const Frame& F, const bf16* ZT, const bf16* GT, const float* conv_w, const float* conv_b, const float* skip, float* gscr, float* zscr, bf16* UT) {
;     ...
;                     twiddleN<true>(x, W1[0], W1[1]);
;                     LAS float* x0p = X + t; LAS float* x1p = X + SEQL + t; asm volatile("" : "+v"(x0p), "+v"(x1p));
; #pragma unroll
;                     for (int g = 0; g < 8; ++g) { const v4u w = *py; py += 512; asm volatile("" : "+v"(py));
;                         x0p[512 * (4 * g)] = x[4 * g].x + bflo(w.x); x1p[512 * (4 * g)] = x[4 * g].y + bfhi(w.x); x0p[512 * (4 * g + 1)] = x[4 * g + 1].x + bflo(w.y); x1p[512 * (4 * g + 1)] = x[4 * g + 1].y + bfhi(w.y);
;                         x0p[512 * (4 * g + 2)] = x[4 * g + 2].x + bflo(w.z); x1p[512 * (4 * g + 2)] = x[4 * g + 2].y + bfhi(w.z); x0p[512 * (4 * g + 3)] = x[4 * g + 3].x + bflo(w.w); x1p[512 * (4 * g + 3)] = x[4 * g + 3].y + bfhi(w.w); }
	v_pk_mul_f32 v[4:5], v[222:223], s[6:7]
	v_pk_fma_f32 v[0:1], v[10:11], s[10:11], v[0:1] op_sel:[0,0,1] op_sel_hi:[1,0,0] neg_lo:[1,0,0] neg_hi:[1,0,0]
	v_pk_fma_f32 v[4:5], v[222:223], s[56:57], v[4:5] op_sel:[0,0,1] op_sel_hi:[1,0,0] neg_lo:[1,0,0] neg_hi:[1,0,0]
	v_pk_add_f32 v[116:117], v[138:139], v[0:1]
	v_pk_add_f32 v[10:11], v[138:139], v[0:1] neg_lo:[0,1] neg_hi:[0,1]
	v_pk_mul_f32 v[0:1], v[120:121], s[56:57]
	v_pk_add_f32 v[112:113], v[214:215], v[6:7]
	v_pk_fma_f32 v[0:1], v[120:121], s[84:85], v[0:1] op_sel:[0,0,1] op_sel_hi:[1,0,0] neg_lo:[1,0,0] neg_hi:[1,0,0]
	v_pk_add_f32 v[6:7], v[214:215], v[6:7] neg_lo:[0,1] neg_hi:[0,1]
	v_pk_add_f32 v[120:121], v[142:143], v[0:1]
	v_pk_add_f32 v[88:89], v[142:143], v[0:1] neg_lo:[0,1] neg_hi:[0,1]
	v_pk_mul_f32 v[0:1], v[108:109], s[60:61]
	s_mov_b64 s[6:7], -1
	v_pk_fma_f32 v[0:1], v[108:109], s[86:87], v[0:1] op_sel:[0,0,1] op_sel_hi:[1,0,0] neg_lo:[1,0,0] neg_hi:[1,0,0]
	v_pk_add_f32 v[108:109], v[146:147], v[2:3]
	v_pk_add_f32 v[124:125], v[106:107], v[0:1]
	v_pk_add_f32 v[92:93], v[106:107], v[0:1] neg_lo:[0,1] neg_hi:[0,1]
	v_pk_mul_f32 v[0:1], v[216:217], s[96:97]
	v_pk_add_f32 v[2:3], v[146:147], v[2:3] neg_lo:[0,1] neg_hi:[0,1]
	v_pk_fma_f32 v[0:1], v[216:217], s[94:95], v[0:1] op_sel:[0,0,1] op_sel_hi:[1,0,0] neg_lo:[1,0,0] neg_hi:[1,0,0]
	v_lshl_add_u64 v[138:139], v[84:85], 0, s[26:27]
	v_pk_add_f32 v[106:107], v[110:111], v[0:1]
	v_pk_add_f32 v[0:1], v[110:111], v[0:1] neg_lo:[0,1] neg_hi:[0,1]
	v_pk_add_f32 v[110:111], v[148:149], v[4:5]
	v_pk_add_f32 v[4:5], v[148:149], v[4:5] neg_lo:[0,1] neg_hi:[0,1]
	s_cbranch_vccz .LBB0_342
	v_lshlrev_b32_e32 v13, 2, v12
	ds_read_b64 v[142:143], v211
	v_mov_b32_e32 v141, 0x3dc8bd36
	v_mov_b32_e32 v140, 0x3f7ec46d
	v_add_u32_e32 v12, 0, v13
	v_add_u32_e32 v13, s85, v13
	s_waitcnt lgkmcnt(0)
	global_load_dwordx4 v[144:147], v[84:85], off
	v_mov_b64_e32 v[148:149], v[138:139]
	global_load_dwordx4 v[212:215], v[148:149], off
	v_lshl_add_u64 v[254:255], v[138:139], 0, s[26:27]
	global_load_dwordx4 v[236:239], v[254:255], off
	v_lshl_add_u64 v[254:255], v[254:255], 0, s[26:27]
	global_load_dwordx4 v[240:243], v[254:255], off
	v_lshl_add_u64 v[254:255], v[254:255], 0, s[26:27]
	global_load_dwordx4 v[244:247], v[254:255], off
	v_lshl_add_u64 v[254:255], v[254:255], 0, s[26:27]
	global_load_dwordx4 v[250:253], v[254:255], off
	v_lshl_add_u64 v[254:255], v[254:255], 0, s[26:27]
	v_xor_b32_e32 v143, 0x80000000, v143
	v_pk_mul_f32 v[216:217], v[128:129], v[142:143] op_sel_hi:[1,0]
	v_pk_mul_f32 v[218:219], v[142:143], v[140:141] op_sel_hi:[1,0]
	v_lshl_add_u64 v[148:149], v[148:149], 0, s[26:27]
	v_pk_fma_f32 v[216:217], v[128:129], v[142:143], v[216:217] op_sel:[1,1,0] op_sel_hi:[0,1,1] neg_lo:[0,1,0]
	v_pk_fma_f32 v[142:143], v[142:143], v[140:141], v[218:219] op_sel:[1,1,0] op_sel_hi:[0,1,1] neg_lo:[0,1,0]
	s_mov_b64 s[6:7], 0
	v_pk_mul_f32 v[218:219], v[132:133], v[142:143] op_sel_hi:[1,0]
	v_pk_mul_f32 v[222:223], v[142:143], v[140:141] op_sel_hi:[1,0]
	s_waitcnt vmcnt(5)
	v_lshlrev_b32_e32 v16, 16, v144
	v_pk_fma_f32 v[218:219], v[132:133], v[142:143], v[218:219] op_sel:[1,1,0] op_sel_hi:[0,1,1] neg_lo:[0,1,0]
	v_pk_fma_f32 v[142:143], v[142:143], v[140:141], v[222:223] op_sel:[1,1,0] op_sel_hi:[0,1,1] neg_lo:[0,1,0]
	v_lshlrev_b32_e32 v211, 16, v147
	v_pk_mul_f32 v[222:223], v[134:135], v[142:143] op_sel_hi:[1,0]
	v_pk_mul_f32 v[224:225], v[142:143], v[140:141] op_sel_hi:[1,0]
	v_and_b32_e32 v147, 0xffff0000, v147
	v_pk_fma_f32 v[222:223], v[134:135], v[142:143], v[222:223] op_sel:[1,1,0] op_sel_hi:[0,1,1] neg_lo:[0,1,0]
	v_pk_fma_f32 v[142:143], v[142:143], v[140:141], v[224:225] op_sel:[1,1,0] op_sel_hi:[0,1,1] neg_lo:[0,1,0]
	v_add_f32_e32 v16, v216, v16
	v_pk_mul_f32 v[224:225], v[136:137], v[142:143] op_sel_hi:[1,0]
	v_pk_mul_f32 v[226:227], v[142:143], v[140:141] op_sel_hi:[1,0]
	s_waitcnt vmcnt(4)
	v_lshlrev_b32_e32 v216, 16, v212
	v_pk_fma_f32 v[224:225], v[136:137], v[142:143], v[224:225] op_sel:[1,1,0] op_sel_hi:[0,1,1] neg_lo:[0,1,0]
	v_pk_fma_f32 v[142:143], v[142:143], v[140:141], v[226:227] op_sel:[1,1,0] op_sel_hi:[0,1,1] neg_lo:[0,1,0]
	v_and_b32_e32 v212, 0xffff0000, v212
	v_pk_mul_f32 v[226:227], v[118:119], v[142:143] op_sel_hi:[1,0]
	v_pk_mul_f32 v[228:229], v[142:143], v[140:141] op_sel_hi:[1,0]
	v_add_f32_e32 v211, v224, v211
	v_pk_fma_f32 v[226:227], v[118:119], v[142:143], v[226:227] op_sel:[1,1,0] op_sel_hi:[0,1,1] neg_lo:[0,1,0]
	v_pk_fma_f32 v[142:143], v[142:143], v[140:141], v[228:229] op_sel:[1,1,0] op_sel_hi:[0,1,1] neg_lo:[0,1,0]
	v_add_f32_e32 v147, v225, v147
	v_pk_mul_f32 v[228:229], v[122:123], v[142:143] op_sel_hi:[1,0]
	v_pk_mul_f32 v[230:231], v[142:143], v[140:141] op_sel_hi:[1,0]
	v_add_f32_e32 v212, v227, v212
	v_pk_fma_f32 v[228:229], v[122:123], v[142:143], v[228:229] op_sel:[1,1,0] op_sel_hi:[0,1,1] neg_lo:[0,1,0]
	v_pk_fma_f32 v[142:143], v[142:143], v[140:141], v[230:231] op_sel:[1,1,0] op_sel_hi:[0,1,1] neg_lo:[0,1,0]
	s_nop 0
	v_pk_mul_f32 v[230:231], v[126:127], v[142:143] op_sel_hi:[1,0]
	v_pk_mul_f32 v[232:233], v[142:143], v[140:141] op_sel_hi:[1,0]
	s_nop 0
	v_pk_fma_f32 v[230:231], v[126:127], v[142:143], v[230:231] op_sel:[1,1,0] op_sel_hi:[0,1,1] neg_lo:[0,1,0]
	v_pk_fma_f32 v[232:233], v[142:143], v[140:141], v[232:233] op_sel:[1,1,0] op_sel_hi:[0,1,1] neg_lo:[0,1,0]
	s_nop 0
	v_pk_mul_f32 v[142:143], v[130:131], v[232:233] op_sel_hi:[1,0]
	s_nop 0
	v_pk_fma_f32 v[234:235], v[130:131], v[232:233], v[142:143] op_sel:[1,1,0] op_sel_hi:[0,1,1] neg_lo:[0,1,0]
	v_and_b32_e32 v142, 0xffff0000, v144
	v_lshlrev_b32_e32 v143, 16, v145
	v_and_b32_e32 v144, 0xffff0000, v145
; #define LAS __attribute__((address_space(3)))
; __device__ __forceinline__ float bflo(unsigned w) { return __uint_as_float(w << 16); }
; __device__ __forceinline__ float bfhi(unsigned w) { return __uint_as_float(w & 0xffff0000u); }
; template <int VAR> __device__ __forceinline__ void hyena_conv_phase(const Frame& F, const bf16* ZT, const bf16* GT, const float* conv_w, const float* conv_b, const float* skip, float* gscr, float* zscr, bf16* UT) {
;     ...
;                     twiddleN<true>(x, W1[0], W1[1]);
;                     LAS float* x0p = X + t; LAS float* x1p = X + SEQL + t; asm volatile("" : "+v"(x0p), "+v"(x1p));
; #pragma unroll
;                     for (int g = 0; g < 8; ++g) { const v4u w = *py; py += 512; asm volatile("" : "+v"(py));
;                         x0p[512 * (4 * g)] = x[4 * g].x + bflo(w.x); x1p[512 * (4 * g)] = x[4 * g].y + bfhi(w.x); x0p[512 * (4 * g + 1)] = x[4 * g + 1].x + bflo(w.y); x1p[512 * (4 * g + 1)] = x[4 * g + 1].y + bfhi(w.y);
;                         x0p[512 * (4 * g + 2)] = x[4 * g + 2].x + bflo(w.z); x1p[512 * (4 * g + 2)] = x[4 * g + 2].y + bfhi(w.z); x0p[512 * (4 * g + 3)] = x[4 * g + 3].x + bflo(w.w); x1p[512 * (4 * g + 3)] = x[4 * g + 3].y + bfhi(w.w); }
	v_lshlrev_b32_e32 v145, 16, v146
	v_and_b32_e32 v146, 0xffff0000, v146
	v_add_f32_e32 v146, v223, v146
	v_add_f32_e32 v142, v217, v142
	v_add_f32_e32 v143, v218, v143
	v_add_f32_e32 v144, v219, v144
	v_add_f32_e32 v145, v222, v145
	ds_write_b32 v12, v16
	ds_write_b32 v13, v142
	ds_write_b32 v12, v143 offset:2048
	ds_write_b32 v13, v144 offset:2048
	ds_write_b32 v12, v145 offset:4096
	ds_write_b32 v13, v146 offset:4096
	ds_write_b32 v12, v211 offset:6144
	ds_write_b32 v13, v147 offset:6144
	v_lshlrev_b32_e32 v16, 16, v213
	v_and_b32_e32 v146, 0xffff0000, v213
	v_lshlrev_b32_e32 v213, 16, v215
	s_nop 0
	v_lshlrev_b32_e32 v147, 16, v214
	v_and_b32_e32 v211, 0xffff0000, v214
	v_and_b32_e32 v214, 0xffff0000, v215
	v_add_f32_e32 v215, v226, v216
	v_add_f32_e32 v213, v234, v213
	v_add_f32_e32 v16, v228, v16
	v_add_f32_e32 v146, v229, v146
	v_add_f32_e32 v147, v230, v147
	v_add_f32_e32 v211, v231, v211
	v_add_f32_e32 v214, v235, v214
	ds_write_b32 v12, v215 offset:8192
	ds_write_b32 v13, v212 offset:8192
	ds_write_b32 v12, v16 offset:10240
	ds_write_b32 v13, v146 offset:10240
	ds_write_b32 v12, v147 offset:12288
	ds_write_b32 v13, v211 offset:12288
	ds_write_b32 v12, v213 offset:14336
	ds_write_b32 v13, v214 offset:14336
	v_lshl_add_u64 v[212:213], v[148:149], 0, s[26:27]
	s_nop 0
	v_pk_mul_f32 v[214:215], v[232:233], v[140:141] op_sel_hi:[1,0]
	v_lshl_add_u64 v[212:213], v[212:213], 0, s[26:27]
	v_pk_fma_f32 v[214:215], v[232:233], v[140:141], v[214:215] op_sel:[1,1,0] op_sel_hi:[0,1,1] neg_lo:[0,1,0]
	s_waitcnt vmcnt(3)
	v_mov_b32_e32 v142, v236
	v_mov_b32_e32 v143, v237
	v_mov_b32_e32 v144, v238
	v_mov_b32_e32 v145, v239
	global_load_dwordx4 v[236:239], v[254:255], off
	v_lshl_add_u64 v[254:255], v[254:255], 0, s[26:27]
	v_lshlrev_b32_e32 v16, 16, v142
	v_pk_mul_f32 v[216:217], v[114:115], v[214:215] op_sel_hi:[1,0]
	v_pk_mul_f32 v[218:219], v[214:215], v[140:141] op_sel_hi:[1,0]
	v_and_b32_e32 v142, 0xffff0000, v142
	v_pk_fma_f32 v[216:217], v[114:115], v[214:215], v[216:217] op_sel:[1,1,0] op_sel_hi:[0,1,1] neg_lo:[0,1,0]
	v_pk_fma_f32 v[214:215], v[214:215], v[140:141], v[218:219] op_sel:[1,1,0] op_sel_hi:[0,1,1] neg_lo:[0,1,0]
	v_lshlrev_b32_e32 v211, 16, v143
	v_pk_mul_f32 v[218:219], v[116:117], v[214:215] op_sel_hi:[1,0]
	v_pk_mul_f32 v[222:223], v[214:215], v[140:141] op_sel_hi:[1,0]
	v_and_b32_e32 v143, 0xffff0000, v143
	v_pk_fma_f32 v[218:219], v[116:117], v[214:215], v[218:219] op_sel:[1,1,0] op_sel_hi:[0,1,1] neg_lo:[0,1,0]
	v_pk_fma_f32 v[214:215], v[214:215], v[140:141], v[222:223] op_sel:[1,1,0] op_sel_hi:[0,1,1] neg_lo:[0,1,0]
	v_lshlrev_b32_e32 v234, 16, v144
	v_pk_mul_f32 v[222:223], v[120:121], v[214:215] op_sel_hi:[1,0]
	v_pk_mul_f32 v[224:225], v[214:215], v[140:141] op_sel_hi:[1,0]
	v_and_b32_e32 v144, 0xffff0000, v144
	v_pk_fma_f32 v[222:223], v[120:121], v[214:215], v[222:223] op_sel:[1,1,0] op_sel_hi:[0,1,1] neg_lo:[0,1,0]
	v_pk_fma_f32 v[214:215], v[214:215], v[140:141], v[224:225] op_sel:[1,1,0] op_sel_hi:[0,1,1] neg_lo:[0,1,0]
	v_lshlrev_b32_e32 v235, 16, v145
	v_pk_mul_f32 v[224:225], v[124:125], v[214:215] op_sel_hi:[1,0]
	v_pk_mul_f32 v[226:227], v[214:215], v[140:141] op_sel_hi:[1,0]
	v_and_b32_e32 v145, 0xffff0000, v145
	v_pk_fma_f32 v[224:225], v[124:125], v[214:215], v[224:225] op_sel:[1,1,0] op_sel_hi:[0,1,1] neg_lo:[0,1,0]
	v_pk_fma_f32 v[214:215], v[214:215], v[140:141], v[226:227] op_sel:[1,1,0] op_sel_hi:[0,1,1] neg_lo:[0,1,0]
	v_add_f32_e32 v16, v216, v16
	v_pk_mul_f32 v[226:227], v[106:107], v[214:215] op_sel_hi:[1,0]
	v_pk_mul_f32 v[228:229], v[214:215], v[140:141] op_sel_hi:[1,0]
	v_add_f32_e32 v142, v217, v142
	v_pk_fma_f32 v[226:227], v[106:107], v[214:215], v[226:227] op_sel:[1,1,0] op_sel_hi:[0,1,1] neg_lo:[0,1,0]
	v_pk_fma_f32 v[214:215], v[214:215], v[140:141], v[228:229] op_sel:[1,1,0] op_sel_hi:[0,1,1] neg_lo:[0,1,0]
	v_add_f32_e32 v211, v218, v211
	v_pk_mul_f32 v[228:229], v[108:109], v[214:215] op_sel_hi:[1,0]
	v_pk_mul_f32 v[230:231], v[214:215], v[140:141] op_sel_hi:[1,0]
	v_add_f32_e32 v143, v219, v143
	v_pk_fma_f32 v[228:229], v[108:109], v[214:215], v[228:229] op_sel:[1,1,0] op_sel_hi:[0,1,1] neg_lo:[0,1,0]
	v_pk_fma_f32 v[214:215], v[214:215], v[140:141], v[230:231] op_sel:[1,1,0] op_sel_hi:[0,1,1] neg_lo:[0,1,0]
	v_add_f32_e32 v216, v222, v234
	v_pk_mul_f32 v[230:231], v[110:111], v[214:215] op_sel_hi:[1,0]
	v_pk_mul_f32 v[232:233], v[214:215], v[140:141] op_sel_hi:[1,0]
	v_add_f32_e32 v144, v223, v144
	v_add_f32_e32 v217, v224, v235
	v_add_f32_e32 v145, v225, v145
	v_pk_fma_f32 v[230:231], v[110:111], v[214:215], v[230:231] op_sel:[1,1,0] op_sel_hi:[0,1,1] neg_lo:[0,1,0]
	v_pk_fma_f32 v[214:215], v[214:215], v[140:141], v[232:233] op_sel:[1,1,0] op_sel_hi:[0,1,1] neg_lo:[0,1,0]
	ds_write_b32 v12, v16 offset:16384
	ds_write_b32 v13, v142 offset:16384
	ds_write_b32 v12, v211 offset:18432
	ds_write_b32 v13, v143 offset:18432
	ds_write_b32 v12, v216 offset:20480
	ds_write_b32 v13, v144 offset:20480
	ds_write_b32 v12, v217 offset:22528
	ds_write_b32 v13, v145 offset:22528
	v_pk_mul_f32 v[232:233], v[112:113], v[214:215] op_sel_hi:[1,0]
	s_waitcnt vmcnt(3)
; #define LAS __attribute__((address_space(3)))
; __device__ __forceinline__ float bflo(unsigned w) { return __uint_as_float(w << 16); }
; __device__ __forceinline__ float bfhi(unsigned w) { return __uint_as_float(w & 0xffff0000u); }
; template <int VAR> __device__ __forceinline__ void hyena_conv_phase(const Frame& F, const bf16* ZT, const bf16* GT, const float* conv_w, const float* conv_b, const float* skip, float* gscr, float* zscr, bf16* UT) {
;     ...
;                     twiddleN<true>(x, W1[0], W1[1]);
;                     LAS float* x0p = X + t; LAS float* x1p = X + SEQL + t; asm volatile("" : "+v"(x0p), "+v"(x1p));
; #pragma unroll
;                     for (int g = 0; g < 8; ++g) { const v4u w = *py; py += 512; asm volatile("" : "+v"(py));
;                         x0p[512 * (4 * g)] = x[4 * g].x + bflo(w.x); x1p[512 * (4 * g)] = x[4 * g].y + bfhi(w.x); x0p[512 * (4 * g + 1)] = x[4 * g + 1].x + bflo(w.y); x1p[512 * (4 * g + 1)] = x[4 * g + 1].y + bfhi(w.y);
;                         x0p[512 * (4 * g + 2)] = x[4 * g + 2].x + bflo(w.z); x1p[512 * (4 * g + 2)] = x[4 * g + 2].y + bfhi(w.z); x0p[512 * (4 * g + 3)] = x[4 * g + 3].x + bflo(w.w); x1p[512 * (4 * g + 3)] = x[4 * g + 3].y + bfhi(w.w); }
	v_mov_b32_e32 v146, v240
	v_mov_b32_e32 v147, v241
	v_mov_b32_e32 v148, v242
	v_mov_b32_e32 v149, v243
	global_load_dwordx4 v[240:243], v[254:255], off
	v_lshlrev_b32_e32 v16, 16, v146
	v_and_b32_e32 v146, 0xffff0000, v146
	s_nop 0
	v_lshlrev_b32_e32 v211, 16, v147
	v_and_b32_e32 v147, 0xffff0000, v147
	v_lshlrev_b32_e32 v216, 16, v148
	v_and_b32_e32 v148, 0xffff0000, v148
	v_lshlrev_b32_e32 v217, 16, v149
	v_and_b32_e32 v149, 0xffff0000, v149
	v_pk_fma_f32 v[232:233], v[112:113], v[214:215], v[232:233] op_sel:[1,1,0] op_sel_hi:[0,1,1] neg_lo:[0,1,0]
	v_add_f32_e32 v16, v226, v16
	v_add_f32_e32 v146, v227, v146
	v_add_f32_e32 v147, v229, v147
	v_add_f32_e32 v148, v231, v148
	v_add_f32_e32 v149, v233, v149
	v_lshl_add_u64 v[212:213], v[212:213], 0, s[26:27]
	v_add_f32_e32 v211, v228, v211
	v_add_f32_e32 v216, v230, v216
	v_add_f32_e32 v217, v232, v217
	ds_write_b32 v12, v16 offset:24576
	ds_write_b32 v13, v146 offset:24576
	ds_write_b32 v12, v211 offset:26624
	ds_write_b32 v13, v147 offset:26624
	ds_write_b32 v12, v216 offset:28672
	ds_write_b32 v13, v148 offset:28672
	ds_write_b32 v12, v217 offset:30720
	ds_write_b32 v13, v149 offset:30720
	s_nop 0
	v_pk_mul_f32 v[216:217], v[214:215], v[140:141] op_sel_hi:[1,0]
	v_lshl_add_u64 v[212:213], v[212:213], 0, s[26:27]
	v_pk_fma_f32 v[214:215], v[214:215], v[140:141], v[216:217] op_sel:[1,1,0] op_sel_hi:[0,1,1] neg_lo:[0,1,0]
	s_waitcnt vmcnt(3)
	v_mov_b32_e32 v142, v244
	v_mov_b32_e32 v143, v245
	v_mov_b32_e32 v144, v246
	v_mov_b32_e32 v145, v247
	v_lshlrev_b32_e32 v16, 16, v142
	v_pk_mul_f32 v[216:217], v[98:99], v[214:215] op_sel_hi:[1,0]
	v_pk_mul_f32 v[218:219], v[214:215], v[140:141] op_sel_hi:[1,0]
	v_and_b32_e32 v142, 0xffff0000, v142
	v_pk_fma_f32 v[216:217], v[98:99], v[214:215], v[216:217] op_sel:[1,1,0] op_sel_hi:[0,1,1] neg_lo:[0,1,0]
	v_pk_fma_f32 v[214:215], v[214:215], v[140:141], v[218:219] op_sel:[1,1,0] op_sel_hi:[0,1,1] neg_lo:[0,1,0]
	v_lshlrev_b32_e32 v211, 16, v143
	v_pk_mul_f32 v[218:219], v[100:101], v[214:215] op_sel_hi:[1,0]
	v_pk_mul_f32 v[222:223], v[214:215], v[140:141] op_sel_hi:[1,0]
	v_and_b32_e32 v143, 0xffff0000, v143
	v_pk_fma_f32 v[218:219], v[100:101], v[214:215], v[218:219] op_sel:[1,1,0] op_sel_hi:[0,1,1] neg_lo:[0,1,0]
	v_pk_fma_f32 v[214:215], v[214:215], v[140:141], v[222:223] op_sel:[1,1,0] op_sel_hi:[0,1,1] neg_lo:[0,1,0]
	v_lshlrev_b32_e32 v234, 16, v144
	v_pk_mul_f32 v[222:223], v[102:103], v[214:215] op_sel_hi:[1,0]
	v_pk_mul_f32 v[224:225], v[214:215], v[140:141] op_sel_hi:[1,0]
	v_and_b32_e32 v144, 0xffff0000, v144
	v_pk_fma_f32 v[222:223], v[102:103], v[214:215], v[222:223] op_sel:[1,1,0] op_sel_hi:[0,1,1] neg_lo:[0,1,0]
	v_pk_fma_f32 v[214:215], v[214:215], v[140:141], v[224:225] op_sel:[1,1,0] op_sel_hi:[0,1,1] neg_lo:[0,1,0]
	v_lshlrev_b32_e32 v235, 16, v145
	v_pk_mul_f32 v[224:225], v[104:105], v[214:215] op_sel_hi:[1,0]
	v_pk_mul_f32 v[226:227], v[214:215], v[140:141] op_sel_hi:[1,0]
	v_and_b32_e32 v145, 0xffff0000, v145
	v_pk_fma_f32 v[224:225], v[104:105], v[214:215], v[224:225] op_sel:[1,1,0] op_sel_hi:[0,1,1] neg_lo:[0,1,0]
	v_pk_fma_f32 v[214:215], v[214:215], v[140:141], v[226:227] op_sel:[1,1,0] op_sel_hi:[0,1,1] neg_lo:[0,1,0]
	v_add_f32_e32 v16, v216, v16
	v_pk_mul_f32 v[226:227], v[86:87], v[214:215] op_sel_hi:[1,0]
	v_pk_mul_f32 v[228:229], v[214:215], v[140:141] op_sel_hi:[1,0]
	v_add_f32_e32 v142, v217, v142
	v_pk_fma_f32 v[226:227], v[86:87], v[214:215], v[226:227] op_sel:[1,1,0] op_sel_hi:[0,1,1] neg_lo:[0,1,0]
	v_pk_fma_f32 v[214:215], v[214:215], v[140:141], v[228:229] op_sel:[1,1,0] op_sel_hi:[0,1,1] neg_lo:[0,1,0]
	v_add_f32_e32 v211, v218, v211
	v_pk_mul_f32 v[228:229], v[90:91], v[214:215] op_sel_hi:[1,0]
	v_pk_mul_f32 v[230:231], v[214:215], v[140:141] op_sel_hi:[1,0]
	v_add_f32_e32 v143, v219, v143
	v_pk_fma_f32 v[228:229], v[90:91], v[214:215], v[228:229] op_sel:[1,1,0] op_sel_hi:[0,1,1] neg_lo:[0,1,0]
	v_pk_fma_f32 v[214:215], v[214:215], v[140:141], v[230:231] op_sel:[1,1,0] op_sel_hi:[0,1,1] neg_lo:[0,1,0]
	v_add_f32_e32 v216, v222, v234
	v_pk_mul_f32 v[230:231], v[94:95], v[214:215] op_sel_hi:[1,0]
	v_pk_mul_f32 v[232:233], v[214:215], v[140:141] op_sel_hi:[1,0]
	v_add_f32_e32 v144, v223, v144
	v_add_f32_e32 v217, v224, v235
	v_add_f32_e32 v145, v225, v145
	v_pk_fma_f32 v[230:231], v[94:95], v[214:215], v[230:231] op_sel:[1,1,0] op_sel_hi:[0,1,1] neg_lo:[0,1,0]
	v_pk_fma_f32 v[214:215], v[214:215], v[140:141], v[232:233] op_sel:[1,1,0] op_sel_hi:[0,1,1] neg_lo:[0,1,0]
	ds_write_b32 v12, v16 offset:32768
	ds_write_b32 v13, v142 offset:32768
	ds_write_b32 v12, v211 offset:34816
	ds_write_b32 v13, v143 offset:34816
	ds_write_b32 v12, v216 offset:36864
	ds_write_b32 v13, v144 offset:36864
	ds_write_b32 v12, v217 offset:38912
	ds_write_b32 v13, v145 offset:38912
	v_pk_mul_f32 v[232:233], v[96:97], v[214:215] op_sel_hi:[1,0]
	s_waitcnt vmcnt(2)
; #define LAS __attribute__((address_space(3)))
; __device__ __forceinline__ float bflo(unsigned w) { return __uint_as_float(w << 16); }
; __device__ __forceinline__ float bfhi(unsigned w) { return __uint_as_float(w & 0xffff0000u); }
; template <int VAR> __device__ __forceinline__ void hyena_conv_phase(const Frame& F, const bf16* ZT, const bf16* GT, const float* conv_w, const float* conv_b, const float* skip, float* gscr, float* zscr, bf16* UT) {
;     ...
;                     twiddleN<true>(x, W1[0], W1[1]);
;                     LAS float* x0p = X + t; LAS float* x1p = X + SEQL + t; asm volatile("" : "+v"(x0p), "+v"(x1p));
; #pragma unroll
;                     for (int g = 0; g < 8; ++g) { const v4u w = *py; py += 512; asm volatile("" : "+v"(py));
;                         x0p[512 * (4 * g)] = x[4 * g].x + bflo(w.x); x1p[512 * (4 * g)] = x[4 * g].y + bfhi(w.x); x0p[512 * (4 * g + 1)] = x[4 * g + 1].x + bflo(w.y); x1p[512 * (4 * g + 1)] = x[4 * g + 1].y + bfhi(w.y);
;                         x0p[512 * (4 * g + 2)] = x[4 * g + 2].x + bflo(w.z); x1p[512 * (4 * g + 2)] = x[4 * g + 2].y + bfhi(w.z); x0p[512 * (4 * g + 3)] = x[4 * g + 3].x + bflo(w.w); x1p[512 * (4 * g + 3)] = x[4 * g + 3].y + bfhi(w.w); }
	v_mov_b32_e32 v146, v250
	v_mov_b32_e32 v147, v251
	v_mov_b32_e32 v148, v252
	v_mov_b32_e32 v149, v253
	v_lshlrev_b32_e32 v16, 16, v146
	v_and_b32_e32 v146, 0xffff0000, v146
	s_nop 0
	v_lshlrev_b32_e32 v211, 16, v147
	v_and_b32_e32 v147, 0xffff0000, v147
	v_lshlrev_b32_e32 v216, 16, v148
	v_and_b32_e32 v148, 0xffff0000, v148
	v_lshlrev_b32_e32 v217, 16, v149
	v_and_b32_e32 v149, 0xffff0000, v149
	v_pk_fma_f32 v[232:233], v[96:97], v[214:215], v[232:233] op_sel:[1,1,0] op_sel_hi:[0,1,1] neg_lo:[0,1,0]
	v_add_f32_e32 v16, v226, v16
	v_add_f32_e32 v146, v227, v146
	v_add_f32_e32 v147, v229, v147
	v_add_f32_e32 v148, v231, v148
	v_add_f32_e32 v149, v233, v149
	v_lshl_add_u64 v[212:213], v[212:213], 0, s[26:27]
	v_add_f32_e32 v211, v228, v211
	v_add_f32_e32 v216, v230, v216
	v_add_f32_e32 v217, v232, v217
	ds_write_b32 v12, v16 offset:40960
	ds_write_b32 v13, v146 offset:40960
	ds_write_b32 v12, v211 offset:43008
	ds_write_b32 v13, v147 offset:43008
	ds_write_b32 v12, v216 offset:45056
	ds_write_b32 v13, v148 offset:45056
	ds_write_b32 v12, v217 offset:47104
	ds_write_b32 v13, v149 offset:47104
	s_nop 0
	v_pk_mul_f32 v[216:217], v[214:215], v[140:141] op_sel_hi:[1,0]
	v_lshl_add_u64 v[212:213], v[212:213], 0, s[26:27]
	v_pk_fma_f32 v[214:215], v[214:215], v[140:141], v[216:217] op_sel:[1,1,0] op_sel_hi:[0,1,1] neg_lo:[0,1,0]
	s_waitcnt vmcnt(1)
	v_mov_b32_e32 v142, v236
	v_mov_b32_e32 v143, v237
	v_mov_b32_e32 v144, v238
	v_mov_b32_e32 v145, v239
	v_lshlrev_b32_e32 v16, 16, v142
	v_pk_mul_f32 v[216:217], v[8:9], v[214:215] op_sel_hi:[1,0]
	v_pk_mul_f32 v[218:219], v[214:215], v[140:141] op_sel_hi:[1,0]
	v_and_b32_e32 v142, 0xffff0000, v142
	v_pk_fma_f32 v[216:217], v[8:9], v[214:215], v[216:217] op_sel:[1,1,0] op_sel_hi:[0,1,1] neg_lo:[0,1,0]
	v_pk_fma_f32 v[214:215], v[214:215], v[140:141], v[218:219] op_sel:[1,1,0] op_sel_hi:[0,1,1] neg_lo:[0,1,0]
	v_lshlrev_b32_e32 v211, 16, v143
	v_pk_mul_f32 v[218:219], v[10:11], v[214:215] op_sel_hi:[1,0]
	v_pk_mul_f32 v[222:223], v[214:215], v[140:141] op_sel_hi:[1,0]
	v_and_b32_e32 v143, 0xffff0000, v143
	v_pk_fma_f32 v[218:219], v[10:11], v[214:215], v[218:219] op_sel:[1,1,0] op_sel_hi:[0,1,1] neg_lo:[0,1,0]
	v_pk_fma_f32 v[214:215], v[214:215], v[140:141], v[222:223] op_sel:[1,1,0] op_sel_hi:[0,1,1] neg_lo:[0,1,0]
	v_add_f32_e32 v16, v216, v16
	v_pk_mul_f32 v[222:223], v[88:89], v[214:215] op_sel_hi:[1,0]
	v_pk_mul_f32 v[224:225], v[214:215], v[140:141] op_sel_hi:[1,0]
	v_add_f32_e32 v142, v217, v142
	v_pk_fma_f32 v[222:223], v[88:89], v[214:215], v[222:223] op_sel:[1,1,0] op_sel_hi:[0,1,1] neg_lo:[0,1,0]
	v_pk_fma_f32 v[214:215], v[214:215], v[140:141], v[224:225] op_sel:[1,1,0] op_sel_hi:[0,1,1] neg_lo:[0,1,0]
	v_add_f32_e32 v211, v218, v211
	v_pk_mul_f32 v[224:225], v[92:93], v[214:215] op_sel_hi:[1,0]
	v_pk_mul_f32 v[226:227], v[214:215], v[140:141] op_sel_hi:[1,0]
	v_add_f32_e32 v143, v219, v143
	v_pk_fma_f32 v[224:225], v[92:93], v[214:215], v[224:225] op_sel:[1,1,0] op_sel_hi:[0,1,1] neg_lo:[0,1,0]
	v_pk_fma_f32 v[214:215], v[214:215], v[140:141], v[226:227] op_sel:[1,1,0] op_sel_hi:[0,1,1] neg_lo:[0,1,0]
	s_nop 0
	v_pk_mul_f32 v[226:227], v[0:1], v[214:215] op_sel_hi:[1,0]
	v_pk_mul_f32 v[228:229], v[214:215], v[140:141] op_sel_hi:[1,0]
	s_nop 0
	v_pk_fma_f32 v[226:227], v[0:1], v[214:215], v[226:227] op_sel:[1,1,0] op_sel_hi:[0,1,1] neg_lo:[0,1,0]
	v_pk_fma_f32 v[214:215], v[214:215], v[140:141], v[228:229] op_sel:[1,1,0] op_sel_hi:[0,1,1] neg_lo:[0,1,0]
	s_nop 0
	v_pk_mul_f32 v[228:229], v[2:3], v[214:215] op_sel_hi:[1,0]
	v_pk_mul_f32 v[230:231], v[214:215], v[140:141] op_sel_hi:[1,0]
	s_nop 0
	v_pk_fma_f32 v[228:229], v[2:3], v[214:215], v[228:229] op_sel:[1,1,0] op_sel_hi:[0,1,1] neg_lo:[0,1,0]
	v_pk_fma_f32 v[214:215], v[214:215], v[140:141], v[230:231] op_sel:[1,1,0] op_sel_hi:[0,1,1] neg_lo:[0,1,0]
	s_nop 0
	v_pk_mul_f32 v[230:231], v[4:5], v[214:215] op_sel_hi:[1,0]
	v_pk_mul_f32 v[232:233], v[214:215], v[140:141] op_sel_hi:[1,0]
	s_nop 0
	v_pk_fma_f32 v[230:231], v[4:5], v[214:215], v[230:231] op_sel:[1,1,0] op_sel_hi:[0,1,1] neg_lo:[0,1,0]
	v_pk_fma_f32 v[140:141], v[214:215], v[140:141], v[232:233] op_sel:[1,1,0] op_sel_hi:[0,1,1] neg_lo:[0,1,0]
	s_nop 0
	v_pk_mul_f32 v[214:215], v[6:7], v[140:141] op_sel_hi:[1,0]
	s_nop 0
	v_pk_fma_f32 v[140:141], v[6:7], v[140:141], v[214:215] op_sel:[1,1,0] op_sel_hi:[0,1,1] neg_lo:[0,1,0]
	v_lshlrev_b32_e32 v214, 16, v144
	v_and_b32_e32 v144, 0xffff0000, v144
	v_lshlrev_b32_e32 v215, 16, v145
	v_and_b32_e32 v145, 0xffff0000, v145
	v_add_f32_e32 v214, v222, v214
	v_add_f32_e32 v144, v223, v144
	v_add_f32_e32 v215, v224, v215
	v_add_f32_e32 v145, v225, v145
	ds_write_b32 v12, v16 offset:49152
	ds_write_b32 v13, v142 offset:49152
	ds_write_b32 v12, v211 offset:51200
	ds_write_b32 v13, v143 offset:51200
	ds_write_b32 v12, v214 offset:53248
	ds_write_b32 v13, v144 offset:53248
	ds_write_b32 v12, v215 offset:55296
	ds_write_b32 v13, v145 offset:55296
	s_waitcnt vmcnt(0)
	v_mov_b32_e32 v146, v240
	v_mov_b32_e32 v147, v241
	v_mov_b32_e32 v148, v242
	v_mov_b32_e32 v149, v243
	v_lshlrev_b32_e32 v16, 16, v146
	v_and_b32_e32 v142, 0xffff0000, v146
	v_lshlrev_b32_e32 v143, 16, v147
	v_and_b32_e32 v144, 0xffff0000, v147
	v_add_f32_e32 v16, v226, v16
	v_add_f32_e32 v142, v227, v142
	v_add_f32_e32 v143, v228, v143
	v_add_f32_e32 v144, v229, v144
	ds_write_b32 v12, v16 offset:57344
	ds_write_b32 v13, v142 offset:57344
	ds_write_b32 v12, v143 offset:59392
	ds_write_b32 v13, v144 offset:59392
	v_lshlrev_b32_e32 v16, 16, v148
	v_add_f32_e32 v16, v230, v16
	ds_write_b32 v12, v16 offset:61440
	v_and_b32_e32 v16, 0xffff0000, v148
	v_add_f32_e32 v16, v231, v16
	ds_write_b32 v13, v16 offset:61440
	v_lshlrev_b32_e32 v16, 16, v149
	v_add_f32_e32 v16, v140, v16
	ds_write_b32 v12, v16 offset:63488
	v_and_b32_e32 v12, 0xffff0000, v149
	v_add_f32_e32 v12, v141, v12
	ds_write_b32 v13, v12 offset:63488
